# drop redundant L1 invalidate in the 4 panel-exchange epilogues (sc1 both sides); 16 loads in flight per weight-transpose item; delete no-op canonicalising v_max in FF1 epilogues
# speedup vs baseline: 1.0074x; 1.0074x over previous
; #define LAS __attribute__((address_space(3)))
; #define GAS __attribute__((address_space(1)))
; #define LDS_WAIT() asm volatile("s_waitcnt lgkmcnt(0)" ::: "memory")
; __device__ __forceinline__ void transpose_item(const float* W, int ldw, int src_col0, bf16_t* WT, int Kd, int dst_row0, int k0, float scale, LAS float* scr, int lane) {
;     const int kr = lane >> 4, c4 = lane & 15;
; #pragma unroll 8
;     for (int i = 0; i < 16; ++i) { const int kk = 4 * i + kr; const f32x4 v = __builtin_nontemporal_load((const GAS f32x4*)(W + (size_t)(k0 + kk) * ldw + src_col0 + 4 * c4)) * scale;
;         LAS float* d = scr + kk * 65 + 4 * c4; d[0] = v.x; d[1] = v.y; d[2] = v.z; d[3] = v.w; }
;     LDS_WAIT(); asm volatile("" ::: "memory");
; template <int PART> __device__ __forceinline__ void phase_convert(Frame& F) {
;     ...
;         { const int nblk = D / 64, kb = r / nblk, nb = r % nblk;
;             transpose_item(F.in[21] + (size_t)l * DFF * D, D, nb * 64, W2 + (size_t)l * D * DFF, DFF, nb * 64, kb * 64, 1.f, scr, F.lane); }
.LBB0_14:
	v_add_u32_e32 v25, s4, v2
	v_add_u32_e32 v26, 0xffffe000, v25
	v_add_u32_e32 v28, 0xffffe004, v25
	v_add_u32_e32 v30, 0xffffe008, v25
	v_add_u32_e32 v32, 0xffffe00c, v25
	v_add_u32_e32 v34, 0xffffe010, v25
	v_add_u32_e32 v36, 0xffffe014, v25
	v_add_u32_e32 v66, 0xffffe018, v25
	v_add_u32_e32 v68, 0xffffe01c, v25
	v_ashrrev_i32_e32 v27, 31, v26
	v_ashrrev_i32_e32 v29, 31, v28
	v_ashrrev_i32_e32 v31, 31, v30
	v_ashrrev_i32_e32 v33, 31, v32
	v_ashrrev_i32_e32 v35, 31, v34
	v_ashrrev_i32_e32 v37, 31, v36
	v_ashrrev_i32_e32 v67, 31, v66
	v_ashrrev_i32_e32 v69, 31, v68
	v_lshlrev_b64 v[26:27], 12, v[26:27]
	v_lshlrev_b64 v[28:29], 12, v[28:29]
	v_lshlrev_b64 v[30:31], 12, v[30:31]
	v_lshlrev_b64 v[32:33], 12, v[32:33]
	v_lshlrev_b64 v[34:35], 12, v[34:35]
	v_lshlrev_b64 v[36:37], 12, v[36:37]
	v_lshlrev_b64 v[66:67], 12, v[66:67]
	v_lshlrev_b64 v[68:69], 12, v[68:69]
	v_lshl_add_u64 v[26:27], v[22:23], 0, v[26:27]
	v_lshl_add_u64 v[70:71], v[22:23], 0, v[28:29]
	v_lshl_add_u64 v[72:73], v[22:23], 0, v[30:31]
	v_lshl_add_u64 v[74:75], v[22:23], 0, v[32:33]
	v_lshl_add_u64 v[76:77], v[22:23], 0, v[34:35]
	v_lshl_add_u64 v[78:79], v[22:23], 0, v[36:37]
	v_lshl_add_u64 v[80:81], v[22:23], 0, v[66:67]
	v_lshl_add_u64 v[82:83], v[22:23], 0, v[68:69]
	global_load_dwordx4 v[26:29], v[26:27], off nt
	s_nop 0
	global_load_dwordx4 v[30:33], v[70:71], off nt
	global_load_dwordx4 v[34:37], v[72:73], off nt
	global_load_dwordx4 v[66:69], v[74:75], off nt
	s_nop 0
	global_load_dwordx4 v[70:73], v[76:77], off nt
	s_nop 0
	global_load_dwordx4 v[74:77], v[78:79], off nt
	s_nop 0
	global_load_dwordx4 v[78:81], v[80:81], off nt
	s_nop 0
	global_load_dwordx4 v[82:85], v[82:83], off nt
	s_add_i32 s4, s4, 32
	v_add_u32_e32 v141, s4, v2
	v_add_u32_e32 v142, 0xffffe000, v141
	v_add_u32_e32 v144, 0xffffe004, v141
	v_add_u32_e32 v146, 0xffffe008, v141
	v_add_u32_e32 v148, 0xffffe00c, v141
	v_add_u32_e32 v150, 0xffffe010, v141
	v_add_u32_e32 v152, 0xffffe014, v141
	v_add_u32_e32 v182, 0xffffe018, v141
	v_add_u32_e32 v184, 0xffffe01c, v141
	v_ashrrev_i32_e32 v143, 31, v142
	v_ashrrev_i32_e32 v145, 31, v144
	v_ashrrev_i32_e32 v147, 31, v146
	v_ashrrev_i32_e32 v149, 31, v148
	v_ashrrev_i32_e32 v151, 31, v150
	v_ashrrev_i32_e32 v153, 31, v152
	v_ashrrev_i32_e32 v183, 31, v182
	v_ashrrev_i32_e32 v185, 31, v184
	v_lshlrev_b64 v[142:143], 12, v[142:143]
	v_lshlrev_b64 v[144:145], 12, v[144:145]
	v_lshlrev_b64 v[146:147], 12, v[146:147]
	v_lshlrev_b64 v[148:149], 12, v[148:149]
	v_lshlrev_b64 v[150:151], 12, v[150:151]
	v_lshlrev_b64 v[152:153], 12, v[152:153]
	v_lshlrev_b64 v[182:183], 12, v[182:183]
	v_lshlrev_b64 v[184:185], 12, v[184:185]
	v_lshl_add_u64 v[142:143], v[22:23], 0, v[142:143]
	v_lshl_add_u64 v[186:187], v[22:23], 0, v[144:145]
	v_lshl_add_u64 v[188:189], v[22:23], 0, v[146:147]
	v_lshl_add_u64 v[190:191], v[22:23], 0, v[148:149]
	v_lshl_add_u64 v[192:193], v[22:23], 0, v[150:151]
	v_lshl_add_u64 v[194:195], v[22:23], 0, v[152:153]
	v_lshl_add_u64 v[196:197], v[22:23], 0, v[182:183]
	v_lshl_add_u64 v[198:199], v[22:23], 0, v[184:185]
	global_load_dwordx4 v[142:145], v[142:143], off nt
	s_nop 0
	global_load_dwordx4 v[146:149], v[186:187], off nt
	global_load_dwordx4 v[150:153], v[188:189], off nt
	global_load_dwordx4 v[182:185], v[190:191], off nt
	s_nop 0
	global_load_dwordx4 v[186:189], v[192:193], off nt
	s_nop 0
	global_load_dwordx4 v[190:193], v[194:195], off nt
	s_nop 0
	global_load_dwordx4 v[194:197], v[196:197], off nt
	s_nop 0
	global_load_dwordx4 v[198:201], v[198:199], off nt
	v_add_u32_e32 v25, 0x410, v24
	v_add_u32_e32 v86, 0x418, v24
	v_add_u32_e32 v87, 0x820, v24
	v_add_u32_e32 v88, 0x828, v24
	v_add_u32_e32 v89, 0xc30, v24
	v_add_u32_e32 v90, 0xc38, v24
	v_add_u32_e32 v91, 0x1040, v24
	v_add_u32_e32 v92, 0x1048, v24
	v_add_u32_e32 v93, 0x1450, v24
	v_add_u32_e32 v94, 0x1458, v24
	v_add_u32_e32 v95, 0x1860, v24
	v_add_u32_e32 v96, 0x1868, v24
	v_add_u32_e32 v97, 0x1c70, v24
	v_add_u32_e32 v98, 0x1c78, v24
	s_waitcnt vmcnt(15)
	ds_write2_b32 v24, v26, v27 offset1:1
	ds_write2_b32 v24, v28, v29 offset0:2 offset1:3
	s_waitcnt vmcnt(14)
	ds_write2_b32 v25, v30, v31 offset1:1
	ds_write2_b32 v86, v32, v33 offset1:1
	s_waitcnt vmcnt(13)
	ds_write2_b32 v87, v34, v35 offset1:1
	ds_write2_b32 v88, v36, v37 offset1:1
	s_waitcnt vmcnt(12)
	ds_write2_b32 v89, v66, v67 offset1:1
	ds_write2_b32 v90, v68, v69 offset1:1
	s_waitcnt vmcnt(11)
	ds_write2_b32 v91, v70, v71 offset1:1
	ds_write2_b32 v92, v72, v73 offset1:1
	s_waitcnt vmcnt(10)
	ds_write2_b32 v93, v74, v75 offset1:1
	ds_write2_b32 v94, v76, v77 offset1:1
	s_waitcnt vmcnt(9)
	ds_write2_b32 v95, v78, v79 offset1:1
	ds_write2_b32 v96, v80, v81 offset1:1
	s_waitcnt vmcnt(8)
	ds_write2_b32 v97, v82, v83 offset1:1
	ds_write2_b32 v98, v84, v85 offset1:1
	v_add_u32_e32 v24, 0x2080, v24
	s_add_i32 s4, s4, 32
	v_add_u32_e32 v25, 0x410, v24
	v_add_u32_e32 v86, 0x418, v24
	v_add_u32_e32 v87, 0x820, v24
	v_add_u32_e32 v88, 0x828, v24
	v_add_u32_e32 v89, 0xc30, v24
	v_add_u32_e32 v90, 0xc38, v24
	v_add_u32_e32 v91, 0x1040, v24
	v_add_u32_e32 v92, 0x1048, v24
	v_add_u32_e32 v93, 0x1450, v24
	v_add_u32_e32 v94, 0x1458, v24
	v_add_u32_e32 v95, 0x1860, v24
	v_add_u32_e32 v96, 0x1868, v24
	v_add_u32_e32 v97, 0x1c70, v24
	v_add_u32_e32 v98, 0x1c78, v24
	s_waitcnt vmcnt(7)
	ds_write2_b32 v24, v142, v143 offset1:1
	ds_write2_b32 v24, v144, v145 offset0:2 offset1:3
	s_waitcnt vmcnt(6)
	ds_write2_b32 v25, v146, v147 offset1:1
	ds_write2_b32 v86, v148, v149 offset1:1
	s_waitcnt vmcnt(5)
	ds_write2_b32 v87, v150, v151 offset1:1
	ds_write2_b32 v88, v152, v153 offset1:1
	s_waitcnt vmcnt(4)
; #define LAS __attribute__((address_space(3)))
; #define GAS __attribute__((address_space(1)))
; __device__ __forceinline__ unsigned pk2(float lo, float hi) { return f2bf(lo) | (f2bf(hi) << 16); }
; #define LDS_WAIT() asm volatile("s_waitcnt lgkmcnt(0)" ::: "memory")
; __device__ __forceinline__ void transpose_item(const float* W, int ldw, int src_col0, bf16_t* WT, int Kd, int dst_row0, int k0, float scale, LAS float* scr, int lane) {
;     ...
;         LAS float* d = scr + kk * 65 + 4 * c4; d[0] = v.x; d[1] = v.y; d[2] = v.z; d[3] = v.w; }
;     LDS_WAIT(); asm volatile("" ::: "memory");
;     const int c = lane & 7;
; #pragma unroll
;     for (int j = 0; j < 8; ++j) { const int n = (lane >> 3) + 8 * j; const LAS float* sp = scr + (8 * c) * 65 + n;
;         u32x4 o; o.x = pk2(sp[0 * 65], sp[1 * 65]); o.y = pk2(sp[2 * 65], sp[3 * 65]); o.z = pk2(sp[4 * 65], sp[5 * 65]); o.w = pk2(sp[6 * 65], sp[7 * 65]);
;         *(GAS u32x4*)(WT + (size_t)(dst_row0 + n) * Kd + k0 + 8 * c) = o; }
;     LDS_WAIT(); asm volatile("" ::: "memory");
	ds_write2_b32 v89, v182, v183 offset1:1
	ds_write2_b32 v90, v184, v185 offset1:1
	s_waitcnt vmcnt(3)
	ds_write2_b32 v91, v186, v187 offset1:1
	ds_write2_b32 v92, v188, v189 offset1:1
	s_waitcnt vmcnt(2)
	ds_write2_b32 v93, v190, v191 offset1:1
	ds_write2_b32 v94, v192, v193 offset1:1
	s_waitcnt vmcnt(1)
	ds_write2_b32 v95, v194, v195 offset1:1
	ds_write2_b32 v96, v196, v197 offset1:1
	s_waitcnt vmcnt(0)
	ds_write2_b32 v97, v198, v199 offset1:1
	ds_write2_b32 v98, v200, v201 offset1:1
	v_add_u32_e32 v24, 0x2080, v24
	s_waitcnt lgkmcnt(0)
	ds_read2_b32 v[28:29], v38 offset1:8
	ds_read2_b32 v[30:31], v38 offset0:65 offset1:73
	ds_read2_b32 v[32:33], v38 offset0:130 offset1:138
	ds_read2_b32 v[34:35], v38 offset0:195 offset1:203
	v_add_u32_e32 v74, 0x400, v38
	s_waitcnt lgkmcnt(3)
	v_bfe_u32 v2, v28, 16, 1
	v_add3_u32 v2, v28, v2, s17
	s_waitcnt lgkmcnt(2)
	v_bfe_u32 v24, v30, 16, 1
	ds_read2_b32 v[36:37], v74 offset0:4 offset1:12
	v_lshrrev_b32_e32 v2, 16, v2
	v_add3_u32 v24, v30, v24, s17
	ds_read2_b32 v[66:67], v74 offset0:69 offset1:77
	v_and_or_b32 v24, v24, s18, v2
	s_waitcnt lgkmcnt(3)
	v_bfe_u32 v2, v32, 16, 1
	v_add3_u32 v2, v32, v2, s17
	s_waitcnt lgkmcnt(2)
	v_bfe_u32 v25, v34, 16, 1
	ds_read2_b32 v[68:69], v74 offset0:134 offset1:142
	v_lshrrev_b32_e32 v2, 16, v2
	v_add3_u32 v25, v34, v25, s17
	ds_read2_b32 v[70:71], v74 offset0:199 offset1:207
	v_and_or_b32 v25, v25, s18, v2
	s_waitcnt lgkmcnt(3)
	v_bfe_u32 v2, v36, 16, 1
	v_add3_u32 v2, v36, v2, s17
	s_waitcnt lgkmcnt(2)
	v_bfe_u32 v26, v66, 16, 1
	v_lshrrev_b32_e32 v2, 16, v2
	v_add3_u32 v26, v66, v26, s17
	s_lshl_b32 s4, s10, 2
	v_and_or_b32 v26, v26, s18, v2
	s_waitcnt lgkmcnt(1)
	v_bfe_u32 v2, v68, 16, 1
	s_and_b32 s4, s4, 0x7fffffc0
	v_add3_u32 v2, v68, v2, s17
	s_waitcnt lgkmcnt(0)
	v_bfe_u32 v27, v70, 16, 1
	s_addk_i32 s4, 0xe000
	v_lshrrev_b32_e32 v2, 16, v2
	v_add3_u32 v27, v70, v27, s17
	v_lshl_add_u64 v[22:23], s[4:5], 1, v[6:7]
	v_and_or_b32 v27, v27, s18, v2
	v_add_lshl_u32 v2, v1, s8, 13
	v_lshl_add_u64 v[72:73], v[22:23], 0, v[2:3]
	v_bfe_u32 v2, v29, 16, 1
	global_store_dwordx4 v[72:73], v[24:27], off
	v_add3_u32 v2, v29, v2, s17
	v_lshrrev_b32_e32 v2, 16, v2
	v_bfe_u32 v24, v31, 16, 1
	v_add3_u32 v24, v31, v24, s17
	v_and_or_b32 v24, v24, s18, v2
	v_bfe_u32 v2, v33, 16, 1
	v_add3_u32 v2, v33, v2, s17
	v_bfe_u32 v25, v35, 16, 1
	v_lshrrev_b32_e32 v2, 16, v2
	v_add3_u32 v25, v35, v25, s17
	v_and_or_b32 v25, v25, s18, v2
	v_bfe_u32 v2, v37, 16, 1
	v_add3_u32 v2, v37, v2, s17
	v_bfe_u32 v26, v67, 16, 1
	v_lshrrev_b32_e32 v2, 16, v2
	v_add3_u32 v26, v67, v26, s17
	v_and_or_b32 v26, v26, s18, v2
	v_bfe_u32 v2, v69, 16, 1
	v_add3_u32 v2, v69, v2, s17
	v_bfe_u32 v27, v71, 16, 1
	v_lshrrev_b32_e32 v2, 16, v2
	v_add3_u32 v27, v71, v27, s17
	v_and_or_b32 v27, v27, s18, v2
	v_add_lshl_u32 v2, v39, s8, 13
	ds_read2_b32 v[28:29], v38 offset0:16 offset1:24
	v_lshl_add_u64 v[30:31], v[22:23], 0, v[2:3]
	global_store_dwordx4 v[30:31], v[24:27], off
	ds_read2_b32 v[30:31], v38 offset0:81 offset1:89
	ds_read2_b32 v[32:33], v38 offset0:146 offset1:154
	ds_read2_b32 v[34:35], v38 offset0:211 offset1:219
	s_waitcnt lgkmcnt(3)
	v_bfe_u32 v2, v28, 16, 1
	v_add3_u32 v2, v28, v2, s17
	s_waitcnt lgkmcnt(2)
	v_bfe_u32 v24, v30, 16, 1
	ds_read2_b32 v[36:37], v74 offset0:20 offset1:28
	v_lshrrev_b32_e32 v2, 16, v2
	v_add3_u32 v24, v30, v24, s17
	ds_read2_b32 v[66:67], v74 offset0:85 offset1:93
	v_and_or_b32 v24, v24, s18, v2
	s_waitcnt lgkmcnt(3)
	v_bfe_u32 v2, v32, 16, 1
	v_add3_u32 v2, v32, v2, s17
	s_waitcnt lgkmcnt(2)
	v_bfe_u32 v25, v34, 16, 1
	ds_read2_b32 v[68:69], v74 offset0:150 offset1:158
	v_lshrrev_b32_e32 v2, 16, v2
	v_add3_u32 v25, v34, v25, s17
	ds_read2_b32 v[70:71], v74 offset0:215 offset1:223
	v_and_or_b32 v25, v25, s18, v2
	s_waitcnt lgkmcnt(3)
	v_bfe_u32 v2, v36, 16, 1
	v_add3_u32 v2, v36, v2, s17
	s_waitcnt lgkmcnt(2)
	v_bfe_u32 v26, v66, 16, 1
	v_lshrrev_b32_e32 v2, 16, v2
	v_add3_u32 v26, v66, v26, s17
	v_and_or_b32 v26, v26, s18, v2
	s_waitcnt lgkmcnt(1)
	v_bfe_u32 v2, v68, 16, 1
	v_add3_u32 v2, v68, v2, s17
	s_waitcnt lgkmcnt(0)
	v_bfe_u32 v27, v70, 16, 1
	v_lshrrev_b32_e32 v2, 16, v2
	v_add3_u32 v27, v70, v27, s17
	v_and_or_b32 v27, v27, s18, v2
	v_add_lshl_u32 v2, v40, s8, 13
	v_lshl_add_u64 v[72:73], v[22:23], 0, v[2:3]
	v_bfe_u32 v2, v29, 16, 1
	global_store_dwordx4 v[72:73], v[24:27], off
	v_add3_u32 v2, v29, v2, s17
	v_lshrrev_b32_e32 v2, 16, v2
	v_bfe_u32 v24, v31, 16, 1
	v_add3_u32 v24, v31, v24, s17
	v_and_or_b32 v24, v24, s18, v2
	v_bfe_u32 v2, v33, 16, 1
	v_add3_u32 v2, v33, v2, s17
	v_bfe_u32 v25, v35, 16, 1
	v_lshrrev_b32_e32 v2, 16, v2
	v_add3_u32 v25, v35, v25, s17
	v_and_or_b32 v25, v25, s18, v2
	v_bfe_u32 v2, v37, 16, 1
	v_add3_u32 v2, v37, v2, s17
	v_bfe_u32 v26, v67, 16, 1
	v_lshrrev_b32_e32 v2, 16, v2
	v_add3_u32 v26, v67, v26, s17
	v_and_or_b32 v26, v26, s18, v2
	v_bfe_u32 v2, v69, 16, 1
	v_add3_u32 v2, v69, v2, s17
	v_bfe_u32 v27, v71, 16, 1
	v_lshrrev_b32_e32 v2, 16, v2
	v_add3_u32 v27, v71, v27, s17
	v_and_or_b32 v27, v27, s18, v2
	v_add_lshl_u32 v2, v41, s8, 13
	ds_read2_b32 v[28:29], v38 offset0:32 offset1:40
	v_lshl_add_u64 v[30:31], v[22:23], 0, v[2:3]
	global_store_dwordx4 v[30:31], v[24:27], off
	ds_read2_b32 v[30:31], v38 offset0:97 offset1:105
	ds_read2_b32 v[32:33], v38 offset0:162 offset1:170
	ds_read2_b32 v[34:35], v38 offset0:227 offset1:235
	s_waitcnt lgkmcnt(3)
; #define LAS __attribute__((address_space(3)))
; #define GAS __attribute__((address_space(1)))
; __device__ __forceinline__ unsigned pk2(float lo, float hi) { return f2bf(lo) | (f2bf(hi) << 16); }
; #define LDS_WAIT() asm volatile("s_waitcnt lgkmcnt(0)" ::: "memory")
; __device__ __forceinline__ void transpose_item(const float* W, int ldw, int src_col0, bf16_t* WT, int Kd, int dst_row0, int k0, float scale, LAS float* scr, int lane) {
;     ...
;     for (int j = 0; j < 8; ++j) { const int n = (lane >> 3) + 8 * j; const LAS float* sp = scr + (8 * c) * 65 + n;
;         u32x4 o; o.x = pk2(sp[0 * 65], sp[1 * 65]); o.y = pk2(sp[2 * 65], sp[3 * 65]); o.z = pk2(sp[4 * 65], sp[5 * 65]); o.w = pk2(sp[6 * 65], sp[7 * 65]);
;         *(GAS u32x4*)(WT + (size_t)(dst_row0 + n) * Kd + k0 + 8 * c) = o; }
;     LDS_WAIT(); asm volatile("" ::: "memory");
	v_bfe_u32 v2, v28, 16, 1
	v_add3_u32 v2, v28, v2, s17
	s_waitcnt lgkmcnt(2)
	v_bfe_u32 v24, v30, 16, 1
	ds_read2_b32 v[36:37], v74 offset0:36 offset1:44
	v_lshrrev_b32_e32 v2, 16, v2
	v_add3_u32 v24, v30, v24, s17
	ds_read2_b32 v[66:67], v74 offset0:101 offset1:109
	v_and_or_b32 v24, v24, s18, v2
	s_waitcnt lgkmcnt(3)
	v_bfe_u32 v2, v32, 16, 1
	v_add3_u32 v2, v32, v2, s17
	s_waitcnt lgkmcnt(2)
	v_bfe_u32 v25, v34, 16, 1
	ds_read2_b32 v[68:69], v74 offset0:166 offset1:174
	v_lshrrev_b32_e32 v2, 16, v2
	v_add3_u32 v25, v34, v25, s17
	ds_read2_b32 v[70:71], v74 offset0:231 offset1:239
	v_and_or_b32 v25, v25, s18, v2
	s_waitcnt lgkmcnt(3)
	v_bfe_u32 v2, v36, 16, 1
	v_add3_u32 v2, v36, v2, s17
	s_waitcnt lgkmcnt(2)
	v_bfe_u32 v26, v66, 16, 1
	v_lshrrev_b32_e32 v2, 16, v2
	v_add3_u32 v26, v66, v26, s17
	v_and_or_b32 v26, v26, s18, v2
	s_waitcnt lgkmcnt(1)
	v_bfe_u32 v2, v68, 16, 1
	v_add3_u32 v2, v68, v2, s17
	s_waitcnt lgkmcnt(0)
	v_bfe_u32 v27, v70, 16, 1
	v_lshrrev_b32_e32 v2, 16, v2
	v_add3_u32 v27, v70, v27, s17
	v_and_or_b32 v27, v27, s18, v2
	v_add_lshl_u32 v2, v42, s8, 13
	v_lshl_add_u64 v[72:73], v[22:23], 0, v[2:3]
	v_bfe_u32 v2, v29, 16, 1
	global_store_dwordx4 v[72:73], v[24:27], off
	v_add3_u32 v2, v29, v2, s17
	v_lshrrev_b32_e32 v2, 16, v2
	v_bfe_u32 v24, v31, 16, 1
	v_add3_u32 v24, v31, v24, s17
	v_and_or_b32 v24, v24, s18, v2
	v_bfe_u32 v2, v33, 16, 1
	v_add3_u32 v2, v33, v2, s17
	v_bfe_u32 v25, v35, 16, 1
	v_lshrrev_b32_e32 v2, 16, v2
	v_add3_u32 v25, v35, v25, s17
	v_and_or_b32 v25, v25, s18, v2
	v_bfe_u32 v2, v37, 16, 1
	v_add3_u32 v2, v37, v2, s17
	v_bfe_u32 v26, v67, 16, 1
	v_lshrrev_b32_e32 v2, 16, v2
	v_add3_u32 v26, v67, v26, s17
	v_and_or_b32 v26, v26, s18, v2
	v_bfe_u32 v2, v69, 16, 1
	v_add3_u32 v2, v69, v2, s17
	v_bfe_u32 v27, v71, 16, 1
	v_lshrrev_b32_e32 v2, 16, v2
	v_add3_u32 v27, v71, v27, s17
	v_and_or_b32 v27, v27, s18, v2
	v_add_lshl_u32 v2, v43, s8, 13
	ds_read2_b32 v[28:29], v38 offset0:48 offset1:56
	v_lshl_add_u64 v[30:31], v[22:23], 0, v[2:3]
	global_store_dwordx4 v[30:31], v[24:27], off
	ds_read2_b32 v[30:31], v38 offset0:113 offset1:121
	ds_read2_b32 v[32:33], v38 offset0:178 offset1:186
	ds_read2_b32 v[34:35], v38 offset0:243 offset1:251
	s_waitcnt lgkmcnt(3)
	v_bfe_u32 v2, v28, 16, 1
	v_add3_u32 v2, v28, v2, s17
	s_waitcnt lgkmcnt(2)
	v_bfe_u32 v24, v30, 16, 1
	ds_read2_b32 v[36:37], v74 offset0:52 offset1:60
	v_lshrrev_b32_e32 v2, 16, v2
	v_add3_u32 v24, v30, v24, s17
	ds_read2_b32 v[66:67], v74 offset0:117 offset1:125
	v_and_or_b32 v24, v24, s18, v2
	s_waitcnt lgkmcnt(3)
	v_bfe_u32 v2, v32, 16, 1
	v_add3_u32 v2, v32, v2, s17
	s_waitcnt lgkmcnt(2)
	v_bfe_u32 v25, v34, 16, 1
	ds_read2_b32 v[68:69], v74 offset0:182 offset1:190
	v_lshrrev_b32_e32 v2, 16, v2
	v_add3_u32 v25, v34, v25, s17
	ds_read2_b32 v[70:71], v74 offset0:247 offset1:255
	v_and_or_b32 v25, v25, s18, v2
	s_waitcnt lgkmcnt(3)
	v_bfe_u32 v2, v36, 16, 1
	v_add3_u32 v2, v36, v2, s17
	s_waitcnt lgkmcnt(2)
	v_bfe_u32 v26, v66, 16, 1
	v_lshrrev_b32_e32 v2, 16, v2
	v_add3_u32 v26, v66, v26, s17
	v_and_or_b32 v26, v26, s18, v2
	s_waitcnt lgkmcnt(1)
	v_bfe_u32 v2, v68, 16, 1
	v_add3_u32 v2, v68, v2, s17
	s_waitcnt lgkmcnt(0)
	v_bfe_u32 v27, v70, 16, 1
	v_lshrrev_b32_e32 v2, 16, v2
	v_add3_u32 v27, v70, v27, s17
	v_and_or_b32 v27, v27, s18, v2
	v_add_lshl_u32 v2, v44, s8, 13
	v_lshl_add_u64 v[72:73], v[22:23], 0, v[2:3]
	v_bfe_u32 v2, v29, 16, 1
	global_store_dwordx4 v[72:73], v[24:27], off
	v_add3_u32 v2, v29, v2, s17
	v_lshrrev_b32_e32 v2, 16, v2
	v_bfe_u32 v24, v31, 16, 1
	v_add3_u32 v24, v31, v24, s17
	v_and_or_b32 v24, v24, s18, v2
	v_bfe_u32 v2, v33, 16, 1
	v_add3_u32 v2, v33, v2, s17
	v_bfe_u32 v25, v35, 16, 1
	v_lshrrev_b32_e32 v2, 16, v2
	v_add3_u32 v25, v35, v25, s17
	v_and_or_b32 v25, v25, s18, v2
	v_bfe_u32 v2, v37, 16, 1
	v_add3_u32 v2, v37, v2, s17
	v_bfe_u32 v26, v67, 16, 1
	v_lshrrev_b32_e32 v2, 16, v2
	v_add3_u32 v26, v67, v26, s17
	v_and_or_b32 v26, v26, s18, v2
	v_bfe_u32 v2, v69, 16, 1
	v_add3_u32 v2, v69, v2, s17
	v_bfe_u32 v27, v71, 16, 1
	v_lshrrev_b32_e32 v2, 16, v2
	v_add3_u32 v27, v71, v27, s17
	v_and_or_b32 v27, v27, s18, v2
	v_add_lshl_u32 v2, v45, s8, 13
	v_lshl_add_u64 v[22:23], v[22:23], 0, v[2:3]
	global_store_dwordx4 v[22:23], v[24:27], off
	s_waitcnt lgkmcnt(0)
	s_mov_b64 s[8:9], 0

; #define LAS __attribute__((address_space(3)))
; #define GAS __attribute__((address_space(1)))
; #define LDS_WAIT() asm volatile("s_waitcnt lgkmcnt(0)" ::: "memory")
; __device__ __forceinline__ void transpose_item(const float* W, int ldw, int src_col0, bf16_t* WT, int Kd, int dst_row0, int k0, float scale, LAS float* scr, int lane) {
;     const int kr = lane >> 4, c4 = lane & 15;
; #pragma unroll 8
;     for (int i = 0; i < 16; ++i) { const int kk = 4 * i + kr; const f32x4 v = __builtin_nontemporal_load((const GAS f32x4*)(W + (size_t)(k0 + kk) * ldw + src_col0 + 4 * c4)) * scale;
;         LAS float* d = scr + kk * 65 + 4 * c4; d[0] = v.x; d[1] = v.y; d[2] = v.z; d[3] = v.w; }
;     LDS_WAIT(); asm volatile("" ::: "memory");
; template <int PART> __device__ __forceinline__ void phase_convert(Frame& F) {
;     ...
;         if (r < I_1) { const int nblk = DFF / 64, kb = r / nblk, nb = r % nblk;
;             transpose_item(F.in[20] + (size_t)l * D * DFF, DFF, nb * 64, W1 + (size_t)l * DFF * D, D, nb * 64, kb * 64, 1.f, scr, F.lane); continue; } r -= I_1;
.LBB0_18:
	v_lshl_add_u64 v[66:67], v[36:37], 0, s[8:9]
	v_lshl_add_u64 v[70:71], v[34:35], 0, s[8:9]
	v_lshl_add_u64 v[74:75], v[32:33], 0, s[8:9]
	v_lshl_add_u64 v[78:79], v[30:31], 0, s[8:9]
	v_lshl_add_u64 v[82:83], v[28:29], 0, s[8:9]
	v_lshl_add_u64 v[86:87], v[26:27], 0, s[8:9]
	v_lshl_add_u64 v[90:91], v[24:25], 0, s[8:9]
	v_lshl_add_u64 v[94:95], v[22:23], 0, s[8:9]
	global_load_dwordx4 v[66:69], v[66:67], off nt
	s_nop 0
	global_load_dwordx4 v[70:73], v[70:71], off nt
	s_nop 0
	global_load_dwordx4 v[74:77], v[74:75], off nt
	s_nop 0
	global_load_dwordx4 v[78:81], v[78:79], off nt
	s_nop 0
	global_load_dwordx4 v[82:85], v[82:83], off nt
	s_nop 0
	global_load_dwordx4 v[86:89], v[86:87], off nt
	s_nop 0
	global_load_dwordx4 v[90:93], v[90:91], off nt
	s_nop 0
	global_load_dwordx4 v[94:97], v[94:95], off nt
	s_add_u32 s8, s8, 0x80000
	s_addc_u32 s9, s9, 0
	v_lshl_add_u64 v[182:183], v[36:37], 0, s[8:9]
	v_lshl_add_u64 v[186:187], v[34:35], 0, s[8:9]
	v_lshl_add_u64 v[190:191], v[32:33], 0, s[8:9]
	v_lshl_add_u64 v[194:195], v[30:31], 0, s[8:9]
	v_lshl_add_u64 v[198:199], v[28:29], 0, s[8:9]
	v_lshl_add_u64 v[202:203], v[26:27], 0, s[8:9]
	v_lshl_add_u64 v[206:207], v[24:25], 0, s[8:9]
	v_lshl_add_u64 v[210:211], v[22:23], 0, s[8:9]
	global_load_dwordx4 v[182:185], v[182:183], off nt
	s_nop 0
	global_load_dwordx4 v[186:189], v[186:187], off nt
	s_nop 0
	global_load_dwordx4 v[190:193], v[190:191], off nt
	s_nop 0
	global_load_dwordx4 v[194:197], v[194:195], off nt
	s_nop 0
	global_load_dwordx4 v[198:201], v[198:199], off nt
	s_nop 0
	global_load_dwordx4 v[202:205], v[202:203], off nt
	s_nop 0
	global_load_dwordx4 v[206:209], v[206:207], off nt
	s_nop 0
	global_load_dwordx4 v[210:213], v[210:211], off nt
	v_add_u32_e32 v98, 0x410, v2
	v_add_u32_e32 v99, 0x418, v2
	v_add_u32_e32 v100, 0x820, v2
	v_add_u32_e32 v101, 0x828, v2
	v_add_u32_e32 v102, 0xc30, v2
	v_add_u32_e32 v103, 0xc38, v2
	v_add_u32_e32 v104, 0x1040, v2
	v_add_u32_e32 v105, 0x1048, v2
	v_add_u32_e32 v106, 0x1450, v2
	v_add_u32_e32 v107, 0x1458, v2
	v_add_u32_e32 v108, 0x1860, v2
	v_add_u32_e32 v109, 0x1868, v2
	v_add_u32_e32 v110, 0x1c70, v2
	v_add_u32_e32 v111, 0x1c78, v2
	s_waitcnt vmcnt(15)
	ds_write2_b32 v2, v66, v67 offset1:1
	ds_write2_b32 v2, v68, v69 offset0:2 offset1:3
	s_waitcnt vmcnt(14)
	ds_write2_b32 v98, v70, v71 offset1:1
	ds_write2_b32 v99, v72, v73 offset1:1
	s_waitcnt vmcnt(13)
	ds_write2_b32 v100, v74, v75 offset1:1
	ds_write2_b32 v101, v76, v77 offset1:1
	s_waitcnt vmcnt(12)
	ds_write2_b32 v102, v78, v79 offset1:1
	ds_write2_b32 v103, v80, v81 offset1:1
	s_waitcnt vmcnt(11)
	ds_write2_b32 v104, v82, v83 offset1:1
	ds_write2_b32 v105, v84, v85 offset1:1
	s_waitcnt vmcnt(10)
	ds_write2_b32 v106, v86, v87 offset1:1
	ds_write2_b32 v107, v88, v89 offset1:1
	s_waitcnt vmcnt(9)
	ds_write2_b32 v108, v90, v91 offset1:1
	ds_write2_b32 v109, v92, v93 offset1:1
	s_waitcnt vmcnt(8)
	ds_write2_b32 v110, v94, v95 offset1:1
	ds_write2_b32 v111, v96, v97 offset1:1
	v_add_u32_e32 v2, 0x2080, v2
	s_add_u32 s8, s8, 0x80000
	s_addc_u32 s9, s9, 0
	v_add_u32_e32 v98, 0x410, v2
	v_add_u32_e32 v99, 0x418, v2
	v_add_u32_e32 v100, 0x820, v2
	v_add_u32_e32 v101, 0x828, v2
	v_add_u32_e32 v102, 0xc30, v2
	v_add_u32_e32 v103, 0xc38, v2
	v_add_u32_e32 v104, 0x1040, v2
	v_add_u32_e32 v105, 0x1048, v2
	v_add_u32_e32 v106, 0x1450, v2
	v_add_u32_e32 v107, 0x1458, v2
	v_add_u32_e32 v108, 0x1860, v2
	v_add_u32_e32 v109, 0x1868, v2
	v_add_u32_e32 v110, 0x1c70, v2
	v_add_u32_e32 v111, 0x1c78, v2
	s_waitcnt vmcnt(7)
	ds_write2_b32 v2, v182, v183 offset1:1
	ds_write2_b32 v2, v184, v185 offset0:2 offset1:3
	s_waitcnt vmcnt(6)
	ds_write2_b32 v98, v186, v187 offset1:1
	ds_write2_b32 v99, v188, v189 offset1:1
	s_waitcnt vmcnt(5)
	ds_write2_b32 v100, v190, v191 offset1:1
	ds_write2_b32 v101, v192, v193 offset1:1
	s_waitcnt vmcnt(4)
	ds_write2_b32 v102, v194, v195 offset1:1
	ds_write2_b32 v103, v196, v197 offset1:1
	s_waitcnt vmcnt(3)
	ds_write2_b32 v104, v198, v199 offset1:1
	ds_write2_b32 v105, v200, v201 offset1:1
	s_waitcnt vmcnt(2)
	ds_write2_b32 v106, v202, v203 offset1:1
	ds_write2_b32 v107, v204, v205 offset1:1
	s_waitcnt vmcnt(1)
	ds_write2_b32 v108, v206, v207 offset1:1
	ds_write2_b32 v109, v208, v209 offset1:1
	s_waitcnt vmcnt(0)
	ds_write2_b32 v110, v210, v211 offset1:1
	ds_write2_b32 v111, v212, v213 offset1:1
	v_add_u32_e32 v2, 0x2080, v2
	s_waitcnt lgkmcnt(0)
	ds_read2_b32 v[28:29], v38 offset1:8
	ds_read2_b32 v[30:31], v38 offset0:65 offset1:73
	ds_read2_b32 v[32:33], v38 offset0:130 offset1:138
	ds_read2_b32 v[34:35], v38 offset0:195 offset1:203
	v_add_u32_e32 v74, 0x400, v38
	s_waitcnt lgkmcnt(3)
	v_bfe_u32 v2, v28, 16, 1
	v_add3_u32 v2, v28, v2, s17
	s_waitcnt lgkmcnt(2)
	v_bfe_u32 v24, v30, 16, 1
	ds_read2_b32 v[36:37], v74 offset0:4 offset1:12
	v_lshrrev_b32_e32 v2, 16, v2
	v_add3_u32 v24, v30, v24, s17
	ds_read2_b32 v[66:67], v74 offset0:69 offset1:77
	v_and_or_b32 v24, v24, s18, v2
	s_waitcnt lgkmcnt(3)
	v_bfe_u32 v2, v32, 16, 1
	v_add3_u32 v2, v32, v2, s17
	s_waitcnt lgkmcnt(2)
	v_bfe_u32 v25, v34, 16, 1
	ds_read2_b32 v[68:69], v74 offset0:134 offset1:142
	v_lshrrev_b32_e32 v2, 16, v2
	v_add3_u32 v25, v34, v25, s17
	ds_read2_b32 v[70:71], v74 offset0:199 offset1:207
	v_and_or_b32 v25, v25, s18, v2
	s_waitcnt lgkmcnt(3)
	v_bfe_u32 v2, v36, 16, 1
	v_add3_u32 v2, v36, v2, s17
	s_waitcnt lgkmcnt(2)
	v_bfe_u32 v26, v66, 16, 1
	v_lshrrev_b32_e32 v2, 16, v2
	v_add3_u32 v26, v66, v26, s17
	v_and_or_b32 v26, v26, s18, v2
	s_waitcnt lgkmcnt(1)
	v_bfe_u32 v2, v68, 16, 1
	s_lshl_b32 s8, s10, 6
	v_add3_u32 v2, v68, v2, s17
	s_waitcnt lgkmcnt(0)
; #define LAS __attribute__((address_space(3)))
; #define GAS __attribute__((address_space(1)))
; __device__ __forceinline__ unsigned pk2(float lo, float hi) { return f2bf(lo) | (f2bf(hi) << 16); }
; #define LDS_WAIT() asm volatile("s_waitcnt lgkmcnt(0)" ::: "memory")
; __device__ __forceinline__ void transpose_item(const float* W, int ldw, int src_col0, bf16_t* WT, int Kd, int dst_row0, int k0, float scale, LAS float* scr, int lane) {
;     ...
;     const int c = lane & 7;
; #pragma unroll
;     for (int j = 0; j < 8; ++j) { const int n = (lane >> 3) + 8 * j; const LAS float* sp = scr + (8 * c) * 65 + n;
;         u32x4 o; o.x = pk2(sp[0 * 65], sp[1 * 65]); o.y = pk2(sp[2 * 65], sp[3 * 65]); o.z = pk2(sp[4 * 65], sp[5 * 65]); o.w = pk2(sp[6 * 65], sp[7 * 65]);
;         *(GAS u32x4*)(WT + (size_t)(dst_row0 + n) * Kd + k0 + 8 * c) = o; }
;     LDS_WAIT(); asm volatile("" ::: "memory");
	v_bfe_u32 v27, v70, 16, 1
	s_and_b32 s8, s8, 0xfc0
	v_lshrrev_b32_e32 v2, 16, v2
	v_add3_u32 v27, v70, v27, s17
	s_addk_i32 s4, 0xfc00
	v_and_or_b32 v27, v27, s18, v2
	v_or_b32_e32 v2, s8, v1
	v_lshl_add_u64 v[22:23], s[4:5], 1, v[8:9]
	v_lshlrev_b32_e32 v2, 11, v2
	v_lshl_add_u64 v[72:73], v[22:23], 0, v[2:3]
	v_bfe_u32 v2, v29, 16, 1
	global_store_dwordx4 v[72:73], v[24:27], off
	v_add3_u32 v2, v29, v2, s17
	v_lshrrev_b32_e32 v2, 16, v2
	v_bfe_u32 v24, v31, 16, 1
	v_add3_u32 v24, v31, v24, s17
	v_and_or_b32 v24, v24, s18, v2
	v_bfe_u32 v2, v33, 16, 1
	v_add3_u32 v2, v33, v2, s17
	v_bfe_u32 v25, v35, 16, 1
	v_lshrrev_b32_e32 v2, 16, v2
	v_add3_u32 v25, v35, v25, s17
	v_and_or_b32 v25, v25, s18, v2
	v_bfe_u32 v2, v37, 16, 1
	v_add3_u32 v2, v37, v2, s17
	v_bfe_u32 v26, v67, 16, 1
	v_lshrrev_b32_e32 v2, 16, v2
	v_add3_u32 v26, v67, v26, s17
	v_and_or_b32 v26, v26, s18, v2
	v_bfe_u32 v2, v69, 16, 1
	v_add3_u32 v2, v69, v2, s17
	v_bfe_u32 v27, v71, 16, 1
	v_lshrrev_b32_e32 v2, 16, v2
	v_add3_u32 v27, v71, v27, s17
	v_and_or_b32 v27, v27, s18, v2
	v_or_b32_e32 v2, s8, v39
	v_lshlrev_b32_e32 v2, 11, v2
	ds_read2_b32 v[28:29], v38 offset0:16 offset1:24
	v_lshl_add_u64 v[30:31], v[22:23], 0, v[2:3]
	global_store_dwordx4 v[30:31], v[24:27], off
	ds_read2_b32 v[30:31], v38 offset0:81 offset1:89
	ds_read2_b32 v[32:33], v38 offset0:146 offset1:154
	ds_read2_b32 v[34:35], v38 offset0:211 offset1:219
	s_waitcnt lgkmcnt(3)
	v_bfe_u32 v2, v28, 16, 1
	v_add3_u32 v2, v28, v2, s17
	s_waitcnt lgkmcnt(2)
	v_bfe_u32 v24, v30, 16, 1
	ds_read2_b32 v[36:37], v74 offset0:20 offset1:28
	v_lshrrev_b32_e32 v2, 16, v2
	v_add3_u32 v24, v30, v24, s17
	ds_read2_b32 v[66:67], v74 offset0:85 offset1:93
	v_and_or_b32 v24, v24, s18, v2
	s_waitcnt lgkmcnt(3)
	v_bfe_u32 v2, v32, 16, 1
	v_add3_u32 v2, v32, v2, s17
	s_waitcnt lgkmcnt(2)
	v_bfe_u32 v25, v34, 16, 1
	ds_read2_b32 v[68:69], v74 offset0:150 offset1:158
	v_lshrrev_b32_e32 v2, 16, v2
	v_add3_u32 v25, v34, v25, s17
	ds_read2_b32 v[70:71], v74 offset0:215 offset1:223
	v_and_or_b32 v25, v25, s18, v2
	s_waitcnt lgkmcnt(3)
	v_bfe_u32 v2, v36, 16, 1
	v_add3_u32 v2, v36, v2, s17
	s_waitcnt lgkmcnt(2)
	v_bfe_u32 v26, v66, 16, 1
	v_lshrrev_b32_e32 v2, 16, v2
	v_add3_u32 v26, v66, v26, s17
	v_and_or_b32 v26, v26, s18, v2
	s_waitcnt lgkmcnt(1)
	v_bfe_u32 v2, v68, 16, 1
	v_add3_u32 v2, v68, v2, s17
	s_waitcnt lgkmcnt(0)
	v_bfe_u32 v27, v70, 16, 1
	v_lshrrev_b32_e32 v2, 16, v2
	v_add3_u32 v27, v70, v27, s17
	v_and_or_b32 v27, v27, s18, v2
	v_or_b32_e32 v2, s8, v40
	v_lshlrev_b32_e32 v2, 11, v2
	v_lshl_add_u64 v[72:73], v[22:23], 0, v[2:3]
	v_bfe_u32 v2, v29, 16, 1
	global_store_dwordx4 v[72:73], v[24:27], off
	v_add3_u32 v2, v29, v2, s17
	v_lshrrev_b32_e32 v2, 16, v2
	v_bfe_u32 v24, v31, 16, 1
	v_add3_u32 v24, v31, v24, s17
	v_and_or_b32 v24, v24, s18, v2
	v_bfe_u32 v2, v33, 16, 1
	v_add3_u32 v2, v33, v2, s17
	v_bfe_u32 v25, v35, 16, 1
	v_lshrrev_b32_e32 v2, 16, v2
	v_add3_u32 v25, v35, v25, s17
	v_and_or_b32 v25, v25, s18, v2
	v_bfe_u32 v2, v37, 16, 1
	v_add3_u32 v2, v37, v2, s17
	v_bfe_u32 v26, v67, 16, 1
	v_lshrrev_b32_e32 v2, 16, v2
	v_add3_u32 v26, v67, v26, s17
	v_and_or_b32 v26, v26, s18, v2
	v_bfe_u32 v2, v69, 16, 1
	v_add3_u32 v2, v69, v2, s17
	v_bfe_u32 v27, v71, 16, 1
	v_lshrrev_b32_e32 v2, 16, v2
	v_add3_u32 v27, v71, v27, s17
	v_and_or_b32 v27, v27, s18, v2
	v_or_b32_e32 v2, s8, v41
	v_lshlrev_b32_e32 v2, 11, v2
	ds_read2_b32 v[28:29], v38 offset0:32 offset1:40
	v_lshl_add_u64 v[30:31], v[22:23], 0, v[2:3]
	global_store_dwordx4 v[30:31], v[24:27], off
	ds_read2_b32 v[30:31], v38 offset0:97 offset1:105
	ds_read2_b32 v[32:33], v38 offset0:162 offset1:170
	ds_read2_b32 v[34:35], v38 offset0:227 offset1:235
	s_waitcnt lgkmcnt(3)
	v_bfe_u32 v2, v28, 16, 1
	v_add3_u32 v2, v28, v2, s17
	s_waitcnt lgkmcnt(2)
	v_bfe_u32 v24, v30, 16, 1
	ds_read2_b32 v[36:37], v74 offset0:36 offset1:44
	v_lshrrev_b32_e32 v2, 16, v2
	v_add3_u32 v24, v30, v24, s17
	ds_read2_b32 v[66:67], v74 offset0:101 offset1:109
	v_and_or_b32 v24, v24, s18, v2
	s_waitcnt lgkmcnt(3)
; #define LAS __attribute__((address_space(3)))
; #define GAS __attribute__((address_space(1)))
; __device__ __forceinline__ unsigned pk2(float lo, float hi) { return f2bf(lo) | (f2bf(hi) << 16); }
; #define LDS_WAIT() asm volatile("s_waitcnt lgkmcnt(0)" ::: "memory")
; __device__ __forceinline__ void transpose_item(const float* W, int ldw, int src_col0, bf16_t* WT, int Kd, int dst_row0, int k0, float scale, LAS float* scr, int lane) {
;     ...
;     const int c = lane & 7;
; #pragma unroll
;     for (int j = 0; j < 8; ++j) { const int n = (lane >> 3) + 8 * j; const LAS float* sp = scr + (8 * c) * 65 + n;
;         u32x4 o; o.x = pk2(sp[0 * 65], sp[1 * 65]); o.y = pk2(sp[2 * 65], sp[3 * 65]); o.z = pk2(sp[4 * 65], sp[5 * 65]); o.w = pk2(sp[6 * 65], sp[7 * 65]);
;         *(GAS u32x4*)(WT + (size_t)(dst_row0 + n) * Kd + k0 + 8 * c) = o; }
;     LDS_WAIT(); asm volatile("" ::: "memory");
	v_bfe_u32 v2, v32, 16, 1
	v_add3_u32 v2, v32, v2, s17
	s_waitcnt lgkmcnt(2)
	v_bfe_u32 v25, v34, 16, 1
	ds_read2_b32 v[68:69], v74 offset0:166 offset1:174
	v_lshrrev_b32_e32 v2, 16, v2
	v_add3_u32 v25, v34, v25, s17
	ds_read2_b32 v[70:71], v74 offset0:231 offset1:239
	v_and_or_b32 v25, v25, s18, v2
	s_waitcnt lgkmcnt(3)
	v_bfe_u32 v2, v36, 16, 1
	v_add3_u32 v2, v36, v2, s17
	s_waitcnt lgkmcnt(2)
	v_bfe_u32 v26, v66, 16, 1
	v_lshrrev_b32_e32 v2, 16, v2
	v_add3_u32 v26, v66, v26, s17
	v_and_or_b32 v26, v26, s18, v2
	s_waitcnt lgkmcnt(1)
	v_bfe_u32 v2, v68, 16, 1
	v_add3_u32 v2, v68, v2, s17
	s_waitcnt lgkmcnt(0)
	v_bfe_u32 v27, v70, 16, 1
	v_lshrrev_b32_e32 v2, 16, v2
	v_add3_u32 v27, v70, v27, s17
	v_and_or_b32 v27, v27, s18, v2
	v_or_b32_e32 v2, s8, v42
	v_lshlrev_b32_e32 v2, 11, v2
	v_lshl_add_u64 v[72:73], v[22:23], 0, v[2:3]
	v_bfe_u32 v2, v29, 16, 1
	global_store_dwordx4 v[72:73], v[24:27], off
	v_add3_u32 v2, v29, v2, s17
	v_lshrrev_b32_e32 v2, 16, v2
	v_bfe_u32 v24, v31, 16, 1
	v_add3_u32 v24, v31, v24, s17
	v_and_or_b32 v24, v24, s18, v2
	v_bfe_u32 v2, v33, 16, 1
	v_add3_u32 v2, v33, v2, s17
	v_bfe_u32 v25, v35, 16, 1
	v_lshrrev_b32_e32 v2, 16, v2
	v_add3_u32 v25, v35, v25, s17
	v_and_or_b32 v25, v25, s18, v2
	v_bfe_u32 v2, v37, 16, 1
	v_add3_u32 v2, v37, v2, s17
	v_bfe_u32 v26, v67, 16, 1
	v_lshrrev_b32_e32 v2, 16, v2
	v_add3_u32 v26, v67, v26, s17
	v_and_or_b32 v26, v26, s18, v2
	v_bfe_u32 v2, v69, 16, 1
	v_add3_u32 v2, v69, v2, s17
	v_bfe_u32 v27, v71, 16, 1
	v_lshrrev_b32_e32 v2, 16, v2
	v_add3_u32 v27, v71, v27, s17
	v_and_or_b32 v27, v27, s18, v2
	v_or_b32_e32 v2, s8, v43
	v_lshlrev_b32_e32 v2, 11, v2
	ds_read2_b32 v[28:29], v38 offset0:48 offset1:56
	v_lshl_add_u64 v[30:31], v[22:23], 0, v[2:3]
	global_store_dwordx4 v[30:31], v[24:27], off
	ds_read2_b32 v[30:31], v38 offset0:113 offset1:121
	ds_read2_b32 v[32:33], v38 offset0:178 offset1:186
	ds_read2_b32 v[34:35], v38 offset0:243 offset1:251
	s_waitcnt lgkmcnt(3)
	v_bfe_u32 v2, v28, 16, 1
	v_add3_u32 v2, v28, v2, s17
	s_waitcnt lgkmcnt(2)
	v_bfe_u32 v24, v30, 16, 1
	ds_read2_b32 v[36:37], v74 offset0:52 offset1:60
	v_lshrrev_b32_e32 v2, 16, v2
	v_add3_u32 v24, v30, v24, s17
	ds_read2_b32 v[66:67], v74 offset0:117 offset1:125
	v_and_or_b32 v24, v24, s18, v2
	s_waitcnt lgkmcnt(3)
	v_bfe_u32 v2, v32, 16, 1
	v_add3_u32 v2, v32, v2, s17
	s_waitcnt lgkmcnt(2)
	v_bfe_u32 v25, v34, 16, 1
	ds_read2_b32 v[68:69], v74 offset0:182 offset1:190
	v_lshrrev_b32_e32 v2, 16, v2
	v_add3_u32 v25, v34, v25, s17
	ds_read2_b32 v[70:71], v74 offset0:247 offset1:255
	v_and_or_b32 v25, v25, s18, v2
	s_waitcnt lgkmcnt(3)
	v_bfe_u32 v2, v36, 16, 1
	v_add3_u32 v2, v36, v2, s17
	s_waitcnt lgkmcnt(2)
	v_bfe_u32 v26, v66, 16, 1
	v_lshrrev_b32_e32 v2, 16, v2
	v_add3_u32 v26, v66, v26, s17
	v_and_or_b32 v26, v26, s18, v2
	s_waitcnt lgkmcnt(1)
	v_bfe_u32 v2, v68, 16, 1
	v_add3_u32 v2, v68, v2, s17
	s_waitcnt lgkmcnt(0)
	v_bfe_u32 v27, v70, 16, 1
	v_lshrrev_b32_e32 v2, 16, v2
	v_add3_u32 v27, v70, v27, s17
	v_and_or_b32 v27, v27, s18, v2
	v_or_b32_e32 v2, s8, v44
	v_lshlrev_b32_e32 v2, 11, v2
	v_lshl_add_u64 v[72:73], v[22:23], 0, v[2:3]
	v_bfe_u32 v2, v29, 16, 1
	global_store_dwordx4 v[72:73], v[24:27], off
	v_add3_u32 v2, v29, v2, s17
	v_lshrrev_b32_e32 v2, 16, v2
	v_bfe_u32 v24, v31, 16, 1
	v_add3_u32 v24, v31, v24, s17
	v_and_or_b32 v24, v24, s18, v2
	v_bfe_u32 v2, v33, 16, 1
	v_add3_u32 v2, v33, v2, s17
	v_bfe_u32 v25, v35, 16, 1
	v_lshrrev_b32_e32 v2, 16, v2
	v_add3_u32 v25, v35, v25, s17
	v_and_or_b32 v25, v25, s18, v2
	v_bfe_u32 v2, v37, 16, 1
	v_add3_u32 v2, v37, v2, s17
	v_bfe_u32 v26, v67, 16, 1
	v_lshrrev_b32_e32 v2, 16, v2
	v_add3_u32 v26, v67, v26, s17
	v_and_or_b32 v26, v26, s18, v2
	v_bfe_u32 v2, v69, 16, 1
	v_add3_u32 v2, v69, v2, s17
	v_bfe_u32 v27, v71, 16, 1
	v_lshrrev_b32_e32 v2, 16, v2
	v_add3_u32 v27, v71, v27, s17
	v_and_or_b32 v27, v27, s18, v2
	v_add_lshl_u32 v2, v45, s8, 11
	v_lshl_add_u64 v[22:23], v[22:23], 0, v[2:3]
	global_store_dwordx4 v[22:23], v[24:27], off
	s_waitcnt lgkmcnt(0)

; #define LAS __attribute__((address_space(3)))
; #define GAS __attribute__((address_space(1)))
; #define LDS_WAIT() asm volatile("s_waitcnt lgkmcnt(0)" ::: "memory")
; __device__ __forceinline__ void transpose_item(const float* W, int ldw, int src_col0, bf16_t* WT, int Kd, int dst_row0, int k0, float scale, LAS float* scr, int lane) {
;     const int kr = lane >> 4, c4 = lane & 15;
; #pragma unroll 8
;     for (int i = 0; i < 16; ++i) { const int kk = 4 * i + kr; const f32x4 v = __builtin_nontemporal_load((const GAS f32x4*)(W + (size_t)(k0 + kk) * ldw + src_col0 + 4 * c4)) * scale;
;         LAS float* d = scr + kk * 65 + 4 * c4; d[0] = v.x; d[1] = v.y; d[2] = v.z; d[3] = v.w; }
;     LDS_WAIT(); asm volatile("" ::: "memory");
; template <int PART> __device__ __forceinline__ void phase_convert(Frame& F) {
;     ...
;             if (r < I_OUT) { const int nblk = D / 64, kb = r / nblk, nb = r % nblk; transpose_item(F.in[19], D, nb * 64, WOUT, D, nb * 64, kb * 64, 1.f, scr, F.lane); continue; } r -= I_OUT;
.LBB0_23:
	v_lshl_add_u64 v[66:67], v[36:37], 0, s[8:9]
	v_lshl_add_u64 v[70:71], v[34:35], 0, s[8:9]
	v_lshl_add_u64 v[74:75], v[32:33], 0, s[8:9]
	v_lshl_add_u64 v[78:79], v[30:31], 0, s[8:9]
	v_lshl_add_u64 v[82:83], v[28:29], 0, s[8:9]
	v_lshl_add_u64 v[86:87], v[26:27], 0, s[8:9]
	v_lshl_add_u64 v[90:91], v[24:25], 0, s[8:9]
	v_lshl_add_u64 v[94:95], v[22:23], 0, s[8:9]
	global_load_dwordx4 v[66:69], v[66:67], off nt
	s_nop 0
	global_load_dwordx4 v[70:73], v[70:71], off nt
	s_nop 0
	global_load_dwordx4 v[74:77], v[74:75], off nt
	s_nop 0
	global_load_dwordx4 v[78:81], v[78:79], off nt
	s_nop 0
	global_load_dwordx4 v[82:85], v[82:83], off nt
	s_nop 0
	global_load_dwordx4 v[86:89], v[86:87], off nt
	s_nop 0
	global_load_dwordx4 v[90:93], v[90:91], off nt
	s_nop 0
	global_load_dwordx4 v[94:97], v[94:95], off nt
	s_add_u32 s8, s8, 0x20000
	s_addc_u32 s9, s9, 0
	v_lshl_add_u64 v[182:183], v[36:37], 0, s[8:9]
	v_lshl_add_u64 v[186:187], v[34:35], 0, s[8:9]
	v_lshl_add_u64 v[190:191], v[32:33], 0, s[8:9]
	v_lshl_add_u64 v[194:195], v[30:31], 0, s[8:9]
	v_lshl_add_u64 v[198:199], v[28:29], 0, s[8:9]
	v_lshl_add_u64 v[202:203], v[26:27], 0, s[8:9]
	v_lshl_add_u64 v[206:207], v[24:25], 0, s[8:9]
	v_lshl_add_u64 v[210:211], v[22:23], 0, s[8:9]
	global_load_dwordx4 v[182:185], v[182:183], off nt
	s_nop 0
	global_load_dwordx4 v[186:189], v[186:187], off nt
	s_nop 0
	global_load_dwordx4 v[190:193], v[190:191], off nt
	s_nop 0
	global_load_dwordx4 v[194:197], v[194:195], off nt
	s_nop 0
	global_load_dwordx4 v[198:201], v[198:199], off nt
	s_nop 0
	global_load_dwordx4 v[202:205], v[202:203], off nt
	s_nop 0
	global_load_dwordx4 v[206:209], v[206:207], off nt
	s_nop 0
	global_load_dwordx4 v[210:213], v[210:211], off nt
	v_add_u32_e32 v98, 0x410, v2
	v_add_u32_e32 v99, 0x418, v2
	v_add_u32_e32 v100, 0x820, v2
	v_add_u32_e32 v101, 0x828, v2
	v_add_u32_e32 v102, 0xc30, v2
	v_add_u32_e32 v103, 0xc38, v2
	v_add_u32_e32 v104, 0x1040, v2
	v_add_u32_e32 v105, 0x1048, v2
	v_add_u32_e32 v106, 0x1450, v2
	v_add_u32_e32 v107, 0x1458, v2
	v_add_u32_e32 v108, 0x1860, v2
	v_add_u32_e32 v109, 0x1868, v2
	v_add_u32_e32 v110, 0x1c70, v2
	v_add_u32_e32 v111, 0x1c78, v2
	s_waitcnt vmcnt(15)
	ds_write2_b32 v2, v66, v67 offset1:1
	ds_write2_b32 v2, v68, v69 offset0:2 offset1:3
	s_waitcnt vmcnt(14)
	ds_write2_b32 v98, v70, v71 offset1:1
	ds_write2_b32 v99, v72, v73 offset1:1
	s_waitcnt vmcnt(13)
	ds_write2_b32 v100, v74, v75 offset1:1
	ds_write2_b32 v101, v76, v77 offset1:1
	s_waitcnt vmcnt(12)
	ds_write2_b32 v102, v78, v79 offset1:1
	ds_write2_b32 v103, v80, v81 offset1:1
	s_waitcnt vmcnt(11)
	ds_write2_b32 v104, v82, v83 offset1:1
	ds_write2_b32 v105, v84, v85 offset1:1
	s_waitcnt vmcnt(10)
	ds_write2_b32 v106, v86, v87 offset1:1
	ds_write2_b32 v107, v88, v89 offset1:1
	s_waitcnt vmcnt(9)
	ds_write2_b32 v108, v90, v91 offset1:1
	ds_write2_b32 v109, v92, v93 offset1:1
	s_waitcnt vmcnt(8)
	ds_write2_b32 v110, v94, v95 offset1:1
	ds_write2_b32 v111, v96, v97 offset1:1
	v_add_u32_e32 v2, 0x2080, v2
	s_add_u32 s8, s8, 0x20000
	s_addc_u32 s9, s9, 0
	v_add_u32_e32 v98, 0x410, v2
	v_add_u32_e32 v99, 0x418, v2
	v_add_u32_e32 v100, 0x820, v2
	v_add_u32_e32 v101, 0x828, v2
	v_add_u32_e32 v102, 0xc30, v2
	v_add_u32_e32 v103, 0xc38, v2
	v_add_u32_e32 v104, 0x1040, v2
	v_add_u32_e32 v105, 0x1048, v2
	v_add_u32_e32 v106, 0x1450, v2
	v_add_u32_e32 v107, 0x1458, v2
	v_add_u32_e32 v108, 0x1860, v2
	v_add_u32_e32 v109, 0x1868, v2
	v_add_u32_e32 v110, 0x1c70, v2
	v_add_u32_e32 v111, 0x1c78, v2
	s_waitcnt vmcnt(7)
	ds_write2_b32 v2, v182, v183 offset1:1
	ds_write2_b32 v2, v184, v185 offset0:2 offset1:3
	s_waitcnt vmcnt(6)
	ds_write2_b32 v98, v186, v187 offset1:1
	ds_write2_b32 v99, v188, v189 offset1:1
	s_waitcnt vmcnt(5)
	ds_write2_b32 v100, v190, v191 offset1:1
	ds_write2_b32 v101, v192, v193 offset1:1
	s_waitcnt vmcnt(4)
	ds_write2_b32 v102, v194, v195 offset1:1
	ds_write2_b32 v103, v196, v197 offset1:1
	s_waitcnt vmcnt(3)
	ds_write2_b32 v104, v198, v199 offset1:1
	ds_write2_b32 v105, v200, v201 offset1:1
	s_waitcnt vmcnt(2)
	ds_write2_b32 v106, v202, v203 offset1:1
	ds_write2_b32 v107, v204, v205 offset1:1
	s_waitcnt vmcnt(1)
	ds_write2_b32 v108, v206, v207 offset1:1
	ds_write2_b32 v109, v208, v209 offset1:1
	s_waitcnt vmcnt(0)
	ds_write2_b32 v110, v210, v211 offset1:1
	ds_write2_b32 v111, v212, v213 offset1:1
	v_add_u32_e32 v2, 0x2080, v2
	s_waitcnt lgkmcnt(0)
	ds_read2_b32 v[28:29], v38 offset1:8
	ds_read2_b32 v[30:31], v38 offset0:65 offset1:73
	ds_read2_b32 v[32:33], v38 offset0:130 offset1:138
	ds_read2_b32 v[34:35], v38 offset0:195 offset1:203
	v_add_u32_e32 v74, 0x400, v38
	s_waitcnt lgkmcnt(3)
	v_bfe_u32 v2, v28, 16, 1
	v_add3_u32 v2, v28, v2, s17
	s_waitcnt lgkmcnt(2)
	v_bfe_u32 v24, v30, 16, 1
	ds_read2_b32 v[36:37], v74 offset0:4 offset1:12
	v_lshrrev_b32_e32 v2, 16, v2
	v_add3_u32 v24, v30, v24, s17
	ds_read2_b32 v[66:67], v74 offset0:69 offset1:77
	v_and_or_b32 v24, v24, s18, v2
	s_waitcnt lgkmcnt(3)
	v_bfe_u32 v2, v32, 16, 1
	v_add3_u32 v2, v32, v2, s17
	s_waitcnt lgkmcnt(2)
	v_bfe_u32 v25, v34, 16, 1
	ds_read2_b32 v[68:69], v74 offset0:134 offset1:142
	v_lshrrev_b32_e32 v2, 16, v2
	v_add3_u32 v25, v34, v25, s17
	ds_read2_b32 v[70:71], v74 offset0:199 offset1:207
	v_and_or_b32 v25, v25, s18, v2
	s_waitcnt lgkmcnt(3)
	v_bfe_u32 v2, v36, 16, 1
	v_add3_u32 v2, v36, v2, s17
	s_waitcnt lgkmcnt(2)
	v_bfe_u32 v26, v66, 16, 1
	v_lshrrev_b32_e32 v2, 16, v2
	v_add3_u32 v26, v66, v26, s17
	s_lshl_b32 s4, s10, 6
	v_and_or_b32 v26, v26, s18, v2
	s_waitcnt lgkmcnt(1)
	v_bfe_u32 v2, v68, 16, 1
	s_and_b32 s8, s4, 0x3c0
	s_lshl_b32 s4, s10, 2
	v_add3_u32 v2, v68, v2, s17
	s_waitcnt lgkmcnt(0)
; #define LAS __attribute__((address_space(3)))
; #define GAS __attribute__((address_space(1)))
; __device__ __forceinline__ unsigned pk2(float lo, float hi) { return f2bf(lo) | (f2bf(hi) << 16); }
; #define LDS_WAIT() asm volatile("s_waitcnt lgkmcnt(0)" ::: "memory")
; __device__ __forceinline__ void transpose_item(const float* W, int ldw, int src_col0, bf16_t* WT, int Kd, int dst_row0, int k0, float scale, LAS float* scr, int lane) {
;     ...
;     const int c = lane & 7;
; #pragma unroll
;     for (int j = 0; j < 8; ++j) { const int n = (lane >> 3) + 8 * j; const LAS float* sp = scr + (8 * c) * 65 + n;
;         u32x4 o; o.x = pk2(sp[0 * 65], sp[1 * 65]); o.y = pk2(sp[2 * 65], sp[3 * 65]); o.z = pk2(sp[4 * 65], sp[5 * 65]); o.w = pk2(sp[6 * 65], sp[7 * 65]);
;         *(GAS u32x4*)(WT + (size_t)(dst_row0 + n) * Kd + k0 + 8 * c) = o; }
;     LDS_WAIT(); asm volatile("" ::: "memory");
	v_bfe_u32 v27, v70, 16, 1
	s_and_b32 s4, s4, 0xfc0
	v_lshrrev_b32_e32 v2, 16, v2
	v_add3_u32 v27, v70, v27, s17
	s_addk_i32 s4, 0xf400
	v_and_or_b32 v27, v27, s18, v2
	v_or_b32_e32 v2, s8, v1
	v_lshl_add_u64 v[22:23], s[4:5], 1, v[10:11]
	v_lshlrev_b32_e32 v2, 11, v2
	v_lshl_add_u64 v[72:73], v[22:23], 0, v[2:3]
	v_bfe_u32 v2, v29, 16, 1
	global_store_dwordx4 v[72:73], v[24:27], off
	v_add3_u32 v2, v29, v2, s17
	v_lshrrev_b32_e32 v2, 16, v2
	v_bfe_u32 v24, v31, 16, 1
	v_add3_u32 v24, v31, v24, s17
	v_and_or_b32 v24, v24, s18, v2
	v_bfe_u32 v2, v33, 16, 1
	v_add3_u32 v2, v33, v2, s17
	v_bfe_u32 v25, v35, 16, 1
	v_lshrrev_b32_e32 v2, 16, v2
	v_add3_u32 v25, v35, v25, s17
	v_and_or_b32 v25, v25, s18, v2
	v_bfe_u32 v2, v37, 16, 1
	v_add3_u32 v2, v37, v2, s17
	v_bfe_u32 v26, v67, 16, 1
	v_lshrrev_b32_e32 v2, 16, v2
	v_add3_u32 v26, v67, v26, s17
	v_and_or_b32 v26, v26, s18, v2
	v_bfe_u32 v2, v69, 16, 1
	v_add3_u32 v2, v69, v2, s17
	v_bfe_u32 v27, v71, 16, 1
	v_lshrrev_b32_e32 v2, 16, v2
	v_add3_u32 v27, v71, v27, s17
	v_and_or_b32 v27, v27, s18, v2
	v_or_b32_e32 v2, s8, v39
	v_lshlrev_b32_e32 v2, 11, v2
	ds_read2_b32 v[28:29], v38 offset0:16 offset1:24
	v_lshl_add_u64 v[30:31], v[22:23], 0, v[2:3]
	global_store_dwordx4 v[30:31], v[24:27], off
	ds_read2_b32 v[30:31], v38 offset0:81 offset1:89
	ds_read2_b32 v[32:33], v38 offset0:146 offset1:154
	ds_read2_b32 v[34:35], v38 offset0:211 offset1:219
	s_waitcnt lgkmcnt(3)
	v_bfe_u32 v2, v28, 16, 1
	v_add3_u32 v2, v28, v2, s17
	s_waitcnt lgkmcnt(2)
	v_bfe_u32 v24, v30, 16, 1
	ds_read2_b32 v[36:37], v74 offset0:20 offset1:28
	v_lshrrev_b32_e32 v2, 16, v2
	v_add3_u32 v24, v30, v24, s17
	ds_read2_b32 v[66:67], v74 offset0:85 offset1:93
	v_and_or_b32 v24, v24, s18, v2
	s_waitcnt lgkmcnt(3)
	v_bfe_u32 v2, v32, 16, 1
	v_add3_u32 v2, v32, v2, s17
	s_waitcnt lgkmcnt(2)
	v_bfe_u32 v25, v34, 16, 1
	ds_read2_b32 v[68:69], v74 offset0:150 offset1:158
	v_lshrrev_b32_e32 v2, 16, v2
	v_add3_u32 v25, v34, v25, s17
	ds_read2_b32 v[70:71], v74 offset0:215 offset1:223
	v_and_or_b32 v25, v25, s18, v2
	s_waitcnt lgkmcnt(3)
	v_bfe_u32 v2, v36, 16, 1
	v_add3_u32 v2, v36, v2, s17
	s_waitcnt lgkmcnt(2)
	v_bfe_u32 v26, v66, 16, 1
	v_lshrrev_b32_e32 v2, 16, v2
	v_add3_u32 v26, v66, v26, s17
	v_and_or_b32 v26, v26, s18, v2
	s_waitcnt lgkmcnt(1)
	v_bfe_u32 v2, v68, 16, 1
	v_add3_u32 v2, v68, v2, s17
	s_waitcnt lgkmcnt(0)
	v_bfe_u32 v27, v70, 16, 1
	v_lshrrev_b32_e32 v2, 16, v2
	v_add3_u32 v27, v70, v27, s17
	v_and_or_b32 v27, v27, s18, v2
	v_or_b32_e32 v2, s8, v40
	v_lshlrev_b32_e32 v2, 11, v2
	v_lshl_add_u64 v[72:73], v[22:23], 0, v[2:3]
	v_bfe_u32 v2, v29, 16, 1
	global_store_dwordx4 v[72:73], v[24:27], off
	v_add3_u32 v2, v29, v2, s17
	v_lshrrev_b32_e32 v2, 16, v2
	v_bfe_u32 v24, v31, 16, 1
	v_add3_u32 v24, v31, v24, s17
	v_and_or_b32 v24, v24, s18, v2
	v_bfe_u32 v2, v33, 16, 1
	v_add3_u32 v2, v33, v2, s17
	v_bfe_u32 v25, v35, 16, 1
	v_lshrrev_b32_e32 v2, 16, v2
	v_add3_u32 v25, v35, v25, s17
	v_and_or_b32 v25, v25, s18, v2
	v_bfe_u32 v2, v37, 16, 1
	v_add3_u32 v2, v37, v2, s17
	v_bfe_u32 v26, v67, 16, 1
	v_lshrrev_b32_e32 v2, 16, v2
	v_add3_u32 v26, v67, v26, s17
	v_and_or_b32 v26, v26, s18, v2
	v_bfe_u32 v2, v69, 16, 1
	v_add3_u32 v2, v69, v2, s17
	v_bfe_u32 v27, v71, 16, 1
	v_lshrrev_b32_e32 v2, 16, v2
	v_add3_u32 v27, v71, v27, s17
	v_and_or_b32 v27, v27, s18, v2
	v_or_b32_e32 v2, s8, v41
	v_lshlrev_b32_e32 v2, 11, v2
	ds_read2_b32 v[28:29], v38 offset0:32 offset1:40
	v_lshl_add_u64 v[30:31], v[22:23], 0, v[2:3]
	global_store_dwordx4 v[30:31], v[24:27], off
	ds_read2_b32 v[30:31], v38 offset0:97 offset1:105
	ds_read2_b32 v[32:33], v38 offset0:162 offset1:170
	ds_read2_b32 v[34:35], v38 offset0:227 offset1:235
	s_waitcnt lgkmcnt(3)
	v_bfe_u32 v2, v28, 16, 1
	v_add3_u32 v2, v28, v2, s17
	s_waitcnt lgkmcnt(2)
	v_bfe_u32 v24, v30, 16, 1
	ds_read2_b32 v[36:37], v74 offset0:36 offset1:44
	v_lshrrev_b32_e32 v2, 16, v2
	v_add3_u32 v24, v30, v24, s17
	ds_read2_b32 v[66:67], v74 offset0:101 offset1:109
	v_and_or_b32 v24, v24, s18, v2
	s_waitcnt lgkmcnt(3)
; #define LAS __attribute__((address_space(3)))
; #define GAS __attribute__((address_space(1)))
; __device__ __forceinline__ unsigned pk2(float lo, float hi) { return f2bf(lo) | (f2bf(hi) << 16); }
; #define LDS_WAIT() asm volatile("s_waitcnt lgkmcnt(0)" ::: "memory")
; __device__ __forceinline__ void transpose_item(const float* W, int ldw, int src_col0, bf16_t* WT, int Kd, int dst_row0, int k0, float scale, LAS float* scr, int lane) {
;     ...
;     const int c = lane & 7;
; #pragma unroll
;     for (int j = 0; j < 8; ++j) { const int n = (lane >> 3) + 8 * j; const LAS float* sp = scr + (8 * c) * 65 + n;
;         u32x4 o; o.x = pk2(sp[0 * 65], sp[1 * 65]); o.y = pk2(sp[2 * 65], sp[3 * 65]); o.z = pk2(sp[4 * 65], sp[5 * 65]); o.w = pk2(sp[6 * 65], sp[7 * 65]);
;         *(GAS u32x4*)(WT + (size_t)(dst_row0 + n) * Kd + k0 + 8 * c) = o; }
;     LDS_WAIT(); asm volatile("" ::: "memory");
	v_bfe_u32 v2, v32, 16, 1
	v_add3_u32 v2, v32, v2, s17
	s_waitcnt lgkmcnt(2)
	v_bfe_u32 v25, v34, 16, 1
	ds_read2_b32 v[68:69], v74 offset0:166 offset1:174
	v_lshrrev_b32_e32 v2, 16, v2
	v_add3_u32 v25, v34, v25, s17
	ds_read2_b32 v[70:71], v74 offset0:231 offset1:239
	v_and_or_b32 v25, v25, s18, v2
	s_waitcnt lgkmcnt(3)
	v_bfe_u32 v2, v36, 16, 1
	v_add3_u32 v2, v36, v2, s17
	s_waitcnt lgkmcnt(2)
	v_bfe_u32 v26, v66, 16, 1
	v_lshrrev_b32_e32 v2, 16, v2
	v_add3_u32 v26, v66, v26, s17
	v_and_or_b32 v26, v26, s18, v2
	s_waitcnt lgkmcnt(1)
	v_bfe_u32 v2, v68, 16, 1
	v_add3_u32 v2, v68, v2, s17
	s_waitcnt lgkmcnt(0)
	v_bfe_u32 v27, v70, 16, 1
	v_lshrrev_b32_e32 v2, 16, v2
	v_add3_u32 v27, v70, v27, s17
	v_and_or_b32 v27, v27, s18, v2
	v_or_b32_e32 v2, s8, v42
	v_lshlrev_b32_e32 v2, 11, v2
	v_lshl_add_u64 v[72:73], v[22:23], 0, v[2:3]
	v_bfe_u32 v2, v29, 16, 1
	global_store_dwordx4 v[72:73], v[24:27], off
	v_add3_u32 v2, v29, v2, s17
	v_lshrrev_b32_e32 v2, 16, v2
	v_bfe_u32 v24, v31, 16, 1
	v_add3_u32 v24, v31, v24, s17
	v_and_or_b32 v24, v24, s18, v2
	v_bfe_u32 v2, v33, 16, 1
	v_add3_u32 v2, v33, v2, s17
	v_bfe_u32 v25, v35, 16, 1
	v_lshrrev_b32_e32 v2, 16, v2
	v_add3_u32 v25, v35, v25, s17
	v_and_or_b32 v25, v25, s18, v2
	v_bfe_u32 v2, v37, 16, 1
	v_add3_u32 v2, v37, v2, s17
	v_bfe_u32 v26, v67, 16, 1
	v_lshrrev_b32_e32 v2, 16, v2
	v_add3_u32 v26, v67, v26, s17
	v_and_or_b32 v26, v26, s18, v2
	v_bfe_u32 v2, v69, 16, 1
	v_add3_u32 v2, v69, v2, s17
	v_bfe_u32 v27, v71, 16, 1
	v_lshrrev_b32_e32 v2, 16, v2
	v_add3_u32 v27, v71, v27, s17
	v_and_or_b32 v27, v27, s18, v2
	v_or_b32_e32 v2, s8, v43
	v_lshlrev_b32_e32 v2, 11, v2
	ds_read2_b32 v[28:29], v38 offset0:48 offset1:56
	v_lshl_add_u64 v[30:31], v[22:23], 0, v[2:3]
	global_store_dwordx4 v[30:31], v[24:27], off
	ds_read2_b32 v[30:31], v38 offset0:113 offset1:121
	ds_read2_b32 v[32:33], v38 offset0:178 offset1:186
	ds_read2_b32 v[34:35], v38 offset0:243 offset1:251
	s_waitcnt lgkmcnt(3)
	v_bfe_u32 v2, v28, 16, 1
	v_add3_u32 v2, v28, v2, s17
	s_waitcnt lgkmcnt(2)
	v_bfe_u32 v24, v30, 16, 1
	ds_read2_b32 v[36:37], v74 offset0:52 offset1:60
	v_lshrrev_b32_e32 v2, 16, v2
	v_add3_u32 v24, v30, v24, s17
	ds_read2_b32 v[66:67], v74 offset0:117 offset1:125
	v_and_or_b32 v24, v24, s18, v2
	s_waitcnt lgkmcnt(3)
	v_bfe_u32 v2, v32, 16, 1
	v_add3_u32 v2, v32, v2, s17
	s_waitcnt lgkmcnt(2)
	v_bfe_u32 v25, v34, 16, 1
	ds_read2_b32 v[68:69], v74 offset0:182 offset1:190
	v_lshrrev_b32_e32 v2, 16, v2
	v_add3_u32 v25, v34, v25, s17
	ds_read2_b32 v[70:71], v74 offset0:247 offset1:255
	v_and_or_b32 v25, v25, s18, v2
	s_waitcnt lgkmcnt(3)
	v_bfe_u32 v2, v36, 16, 1
	v_add3_u32 v2, v36, v2, s17
	s_waitcnt lgkmcnt(2)
	v_bfe_u32 v26, v66, 16, 1
	v_lshrrev_b32_e32 v2, 16, v2
	v_add3_u32 v26, v66, v26, s17
	v_and_or_b32 v26, v26, s18, v2
	s_waitcnt lgkmcnt(1)
	v_bfe_u32 v2, v68, 16, 1
	v_add3_u32 v2, v68, v2, s17
	s_waitcnt lgkmcnt(0)
	v_bfe_u32 v27, v70, 16, 1
	v_lshrrev_b32_e32 v2, 16, v2
	v_add3_u32 v27, v70, v27, s17
	v_and_or_b32 v27, v27, s18, v2
	v_or_b32_e32 v2, s8, v44
	v_lshlrev_b32_e32 v2, 11, v2
	v_lshl_add_u64 v[72:73], v[22:23], 0, v[2:3]
	v_bfe_u32 v2, v29, 16, 1
	global_store_dwordx4 v[72:73], v[24:27], off
	v_add3_u32 v2, v29, v2, s17
	v_lshrrev_b32_e32 v2, 16, v2
	v_bfe_u32 v24, v31, 16, 1
	v_add3_u32 v24, v31, v24, s17
	v_and_or_b32 v24, v24, s18, v2
	v_bfe_u32 v2, v33, 16, 1
	v_add3_u32 v2, v33, v2, s17
	v_bfe_u32 v25, v35, 16, 1
	v_lshrrev_b32_e32 v2, 16, v2
	v_add3_u32 v25, v35, v25, s17
	v_and_or_b32 v25, v25, s18, v2
	v_bfe_u32 v2, v37, 16, 1
	v_add3_u32 v2, v37, v2, s17
	v_bfe_u32 v26, v67, 16, 1
	v_lshrrev_b32_e32 v2, 16, v2
	v_add3_u32 v26, v67, v26, s17
	v_and_or_b32 v26, v26, s18, v2
	v_bfe_u32 v2, v69, 16, 1
	v_add3_u32 v2, v69, v2, s17
	v_bfe_u32 v27, v71, 16, 1
	v_lshrrev_b32_e32 v2, 16, v2
	v_add3_u32 v27, v71, v27, s17
	v_and_or_b32 v27, v27, s18, v2
	v_add_lshl_u32 v2, v45, s8, 11
	v_lshl_add_u64 v[22:23], v[22:23], 0, v[2:3]
	global_store_dwordx4 v[22:23], v[24:27], off
	s_waitcnt lgkmcnt(0)

; #define LAS __attribute__((address_space(3)))
; #define GAS __attribute__((address_space(1)))
; #define LDS_WAIT() asm volatile("s_waitcnt lgkmcnt(0)" ::: "memory")
; __device__ __forceinline__ void transpose_item(const float* W, int ldw, int src_col0, bf16_t* WT, int Kd, int dst_row0, int k0, float scale, LAS float* scr, int lane) {
;     const int kr = lane >> 4, c4 = lane & 15;
; #pragma unroll 8
;     for (int i = 0; i < 16; ++i) { const int kk = 4 * i + kr; const f32x4 v = __builtin_nontemporal_load((const GAS f32x4*)(W + (size_t)(k0 + kk) * ldw + src_col0 + 4 * c4)) * scale;
;         LAS float* d = scr + kk * 65 + 4 * c4; d[0] = v.x; d[1] = v.y; d[2] = v.z; d[3] = v.w; }
;     LDS_WAIT(); asm volatile("" ::: "memory");
; template <int PART> __device__ __forceinline__ void phase_convert(Frame& F) {
;     ...
;             if (r < I_IN) { const int nblk = NQKVR / 64, kb = r / nblk, nb = r % nblk, n0 = nb * 64; const int src = n0 < 2048 ? n0 : n0 + RANK;
;                 transpose_item(F.in[15], GIN, src, WIN, D, n0, kb * 64, n0 < QKW ? 0.08838834764831845f : 1.f, scr, F.lane); continue; } r -= I_IN;
.LBB0_28:
	v_add_u32_e32 v23, s20, v2
	v_add_u32_e32 v33, 8, v23
	v_add_u32_e32 v72, 12, v23
	v_add_u32_e32 v73, 16, v23
	v_add_u32_e32 v76, 20, v23
	v_add_u32_e32 v77, 24, v23
	v_add_u32_e32 v23, 28, v23
	global_load_dwordx4 v[34:37], v[30:31], off nt
	global_load_dwordx4 v[66:69], v[28:29], off nt
	v_mad_i64_i32 v[70:71], s[22:23], v33, s19, v[24:25]
	v_mad_i64_i32 v[74:75], s[22:23], v72, s19, v[24:25]
	v_mad_i64_i32 v[78:79], s[22:23], v73, s19, v[24:25]
	v_mad_i64_i32 v[82:83], s[22:23], v76, s19, v[24:25]
	v_mad_i64_i32 v[86:87], s[22:23], v77, s19, v[24:25]
	v_mad_i64_i32 v[90:91], s[22:23], v23, s19, v[24:25]
	global_load_dwordx4 v[70:73], v[70:71], off nt
	s_nop 0
	global_load_dwordx4 v[74:77], v[74:75], off nt
	s_nop 0
	global_load_dwordx4 v[78:81], v[78:79], off nt
	s_nop 0
	global_load_dwordx4 v[82:85], v[82:83], off nt
	s_nop 0
	global_load_dwordx4 v[86:89], v[86:87], off nt
	s_nop 0
	global_load_dwordx4 v[90:93], v[90:91], off nt
	s_add_i32 s20, s20, 32
	v_lshl_add_u64 v[28:29], v[28:29], 0, s[6:7]
	v_lshl_add_u64 v[30:31], v[30:31], 0, s[6:7]
	v_add_u32_e32 v139, s20, v2
	v_add_u32_e32 v149, 8, v139
	v_add_u32_e32 v188, 12, v139
	v_add_u32_e32 v189, 16, v139
	v_add_u32_e32 v192, 20, v139
	v_add_u32_e32 v193, 24, v139
	v_add_u32_e32 v139, 28, v139
	global_load_dwordx4 v[150:153], v[30:31], off nt
	global_load_dwordx4 v[182:185], v[28:29], off nt
	v_mad_i64_i32 v[186:187], s[22:23], v149, s19, v[24:25]
	v_mad_i64_i32 v[190:191], s[22:23], v188, s19, v[24:25]
	v_mad_i64_i32 v[194:195], s[22:23], v189, s19, v[24:25]
	v_mad_i64_i32 v[198:199], s[22:23], v192, s19, v[24:25]
	v_mad_i64_i32 v[202:203], s[22:23], v193, s19, v[24:25]
	v_mad_i64_i32 v[206:207], s[22:23], v139, s19, v[24:25]
	global_load_dwordx4 v[186:189], v[186:187], off nt
	s_nop 0
	global_load_dwordx4 v[190:193], v[190:191], off nt
	s_nop 0
	global_load_dwordx4 v[194:197], v[194:195], off nt
	s_nop 0
	global_load_dwordx4 v[198:201], v[198:199], off nt
	s_nop 0
	global_load_dwordx4 v[202:205], v[202:203], off nt
	s_nop 0
	global_load_dwordx4 v[206:209], v[206:207], off nt
	v_mov_b32_e32 v23, v22
	v_add_u32_e32 v33, 0x410, v32
	v_add_u32_e32 v94, 0x418, v32
	v_add_u32_e32 v95, 0x820, v32
	v_add_u32_e32 v96, 0x828, v32
	v_add_u32_e32 v97, 0xc30, v32
	v_add_u32_e32 v98, 0xc38, v32
	v_add_u32_e32 v99, 0x1040, v32
	v_add_u32_e32 v100, 0x1048, v32
	v_add_u32_e32 v101, 0x1450, v32
	v_add_u32_e32 v102, 0x1458, v32
	v_add_u32_e32 v103, 0x1860, v32
	v_add_u32_e32 v104, 0x1868, v32
	v_add_u32_e32 v105, 0x1c70, v32
	v_add_u32_e32 v106, 0x1c78, v32
	s_waitcnt vmcnt(15)
	v_pk_mul_f32 v[36:37], v[22:23], v[36:37]
	v_pk_mul_f32 v[34:35], v[26:27], v[34:35]
	s_waitcnt vmcnt(14)
	v_pk_mul_f32 v[68:69], v[22:23], v[68:69]
	v_pk_mul_f32 v[66:67], v[26:27], v[66:67]
	ds_write2_b32 v32, v34, v35 offset1:1
	ds_write2_b32 v32, v36, v37 offset0:2 offset1:3
	ds_write2_b32 v33, v66, v67 offset1:1
	ds_write2_b32 v94, v68, v69 offset1:1
	v_add_u32_e32 v32, 0x2080, v32
	s_waitcnt vmcnt(13)
	v_pk_mul_f32 v[36:37], v[26:27], v[70:71]
	v_pk_mul_f32 v[34:35], v[22:23], v[72:73]
	s_waitcnt vmcnt(12)
	v_pk_mul_f32 v[66:67], v[22:23], v[76:77]
	v_pk_mul_f32 v[68:69], v[26:27], v[74:75]
	s_waitcnt vmcnt(11)
	v_pk_mul_f32 v[70:71], v[22:23], v[80:81]
	v_pk_mul_f32 v[72:73], v[26:27], v[78:79]
	s_waitcnt vmcnt(10)
	v_pk_mul_f32 v[74:75], v[22:23], v[84:85]
	v_pk_mul_f32 v[76:77], v[26:27], v[82:83]
	s_waitcnt vmcnt(9)
	v_pk_mul_f32 v[78:79], v[22:23], v[88:89]
	v_pk_mul_f32 v[80:81], v[26:27], v[86:87]
	s_waitcnt vmcnt(8)
	v_pk_mul_f32 v[82:83], v[22:23], v[92:93]
	v_pk_mul_f32 v[84:85], v[26:27], v[90:91]
	ds_write2_b32 v95, v36, v37 offset1:1
	ds_write2_b32 v96, v34, v35 offset1:1
	ds_write2_b32 v97, v68, v69 offset1:1
	ds_write2_b32 v98, v66, v67 offset1:1
	ds_write2_b32 v99, v72, v73 offset1:1
	ds_write2_b32 v100, v70, v71 offset1:1
	ds_write2_b32 v101, v76, v77 offset1:1
	ds_write2_b32 v102, v74, v75 offset1:1
	ds_write2_b32 v103, v80, v81 offset1:1
	ds_write2_b32 v104, v78, v79 offset1:1
	ds_write2_b32 v105, v84, v85 offset1:1
	ds_write2_b32 v106, v82, v83 offset1:1
	s_add_i32 s20, s20, 32
	v_lshl_add_u64 v[28:29], v[28:29], 0, s[6:7]
	v_lshl_add_u64 v[30:31], v[30:31], 0, s[6:7]
	v_mov_b32_e32 v23, v22
	v_add_u32_e32 v33, 0x410, v32
	v_add_u32_e32 v94, 0x418, v32
	v_add_u32_e32 v95, 0x820, v32
	v_add_u32_e32 v96, 0x828, v32
	v_add_u32_e32 v97, 0xc30, v32
	v_add_u32_e32 v98, 0xc38, v32
	v_add_u32_e32 v99, 0x1040, v32
	v_add_u32_e32 v100, 0x1048, v32
	v_add_u32_e32 v101, 0x1450, v32
	v_add_u32_e32 v102, 0x1458, v32
	v_add_u32_e32 v103, 0x1860, v32
	v_add_u32_e32 v104, 0x1868, v32
	v_add_u32_e32 v105, 0x1c70, v32
	v_add_u32_e32 v106, 0x1c78, v32
	s_waitcnt vmcnt(7)
	v_pk_mul_f32 v[152:153], v[22:23], v[152:153]
	v_pk_mul_f32 v[150:151], v[26:27], v[150:151]
	s_waitcnt vmcnt(6)
	v_pk_mul_f32 v[184:185], v[22:23], v[184:185]
	v_pk_mul_f32 v[182:183], v[26:27], v[182:183]
	ds_write2_b32 v32, v150, v151 offset1:1
	ds_write2_b32 v32, v152, v153 offset0:2 offset1:3
	ds_write2_b32 v33, v182, v183 offset1:1
	ds_write2_b32 v94, v184, v185 offset1:1
	v_add_u32_e32 v32, 0x2080, v32
	s_waitcnt vmcnt(5)
	v_pk_mul_f32 v[152:153], v[26:27], v[186:187]
	v_pk_mul_f32 v[150:151], v[22:23], v[188:189]
	s_waitcnt vmcnt(4)
	v_pk_mul_f32 v[182:183], v[22:23], v[192:193]
	v_pk_mul_f32 v[184:185], v[26:27], v[190:191]
	s_waitcnt vmcnt(3)
	v_pk_mul_f32 v[186:187], v[22:23], v[196:197]
	v_pk_mul_f32 v[188:189], v[26:27], v[194:195]
	s_waitcnt vmcnt(2)
	v_pk_mul_f32 v[190:191], v[22:23], v[200:201]
	v_pk_mul_f32 v[192:193], v[26:27], v[198:199]
	s_waitcnt vmcnt(1)
	v_pk_mul_f32 v[194:195], v[22:23], v[204:205]
	v_pk_mul_f32 v[196:197], v[26:27], v[202:203]
	s_waitcnt vmcnt(0)
; #define LAS __attribute__((address_space(3)))
; #define GAS __attribute__((address_space(1)))
; __device__ __forceinline__ unsigned pk2(float lo, float hi) { return f2bf(lo) | (f2bf(hi) << 16); }
; #define LDS_WAIT() asm volatile("s_waitcnt lgkmcnt(0)" ::: "memory")
; __device__ __forceinline__ void transpose_item(const float* W, int ldw, int src_col0, bf16_t* WT, int Kd, int dst_row0, int k0, float scale, LAS float* scr, int lane) {
;     ...
; #pragma unroll 8
;     for (int i = 0; i < 16; ++i) { const int kk = 4 * i + kr; const f32x4 v = __builtin_nontemporal_load((const GAS f32x4*)(W + (size_t)(k0 + kk) * ldw + src_col0 + 4 * c4)) * scale;
;         LAS float* d = scr + kk * 65 + 4 * c4; d[0] = v.x; d[1] = v.y; d[2] = v.z; d[3] = v.w; }
;     LDS_WAIT(); asm volatile("" ::: "memory");
;     const int c = lane & 7;
; #pragma unroll
;     for (int j = 0; j < 8; ++j) { const int n = (lane >> 3) + 8 * j; const LAS float* sp = scr + (8 * c) * 65 + n;
;         u32x4 o; o.x = pk2(sp[0 * 65], sp[1 * 65]); o.y = pk2(sp[2 * 65], sp[3 * 65]); o.z = pk2(sp[4 * 65], sp[5 * 65]); o.w = pk2(sp[6 * 65], sp[7 * 65]);
;         *(GAS u32x4*)(WT + (size_t)(dst_row0 + n) * Kd + k0 + 8 * c) = o; }
;     LDS_WAIT(); asm volatile("" ::: "memory");
	v_pk_mul_f32 v[198:199], v[22:23], v[208:209]
	v_pk_mul_f32 v[200:201], v[26:27], v[206:207]
	ds_write2_b32 v95, v152, v153 offset1:1
	ds_write2_b32 v96, v150, v151 offset1:1
	ds_write2_b32 v97, v184, v185 offset1:1
	ds_write2_b32 v98, v182, v183 offset1:1
	ds_write2_b32 v99, v188, v189 offset1:1
	ds_write2_b32 v100, v186, v187 offset1:1
	ds_write2_b32 v101, v192, v193 offset1:1
	ds_write2_b32 v102, v190, v191 offset1:1
	ds_write2_b32 v103, v196, v197 offset1:1
	ds_write2_b32 v104, v194, v195 offset1:1
	ds_write2_b32 v105, v200, v201 offset1:1
	ds_write2_b32 v106, v198, v199 offset1:1
	s_waitcnt lgkmcnt(0)
	ds_read2_b32 v[28:29], v38 offset1:8
	ds_read2_b32 v[30:31], v38 offset0:65 offset1:73
	ds_read2_b32 v[32:33], v38 offset0:130 offset1:138
	ds_read2_b32 v[34:35], v38 offset0:195 offset1:203
	v_add_u32_e32 v74, 0x400, v38
	s_waitcnt lgkmcnt(3)
	v_bfe_u32 v2, v28, 16, 1
	s_waitcnt lgkmcnt(2)
	v_bfe_u32 v24, v30, 16, 1
	v_add3_u32 v2, v28, v2, s17
	ds_read2_b32 v[36:37], v74 offset0:4 offset1:12
	v_lshrrev_b32_e32 v2, 16, v2
	v_add3_u32 v24, v30, v24, s17
	ds_read2_b32 v[66:67], v74 offset0:69 offset1:77
	v_and_or_b32 v24, v24, s18, v2
	s_waitcnt lgkmcnt(3)
	v_bfe_u32 v2, v32, 16, 1
	v_add3_u32 v2, v32, v2, s17
	s_waitcnt lgkmcnt(2)
	v_bfe_u32 v25, v34, 16, 1
	ds_read2_b32 v[68:69], v74 offset0:134 offset1:142
	v_lshrrev_b32_e32 v2, 16, v2
	v_add3_u32 v25, v34, v25, s17
	ds_read2_b32 v[70:71], v74 offset0:199 offset1:207
	v_and_or_b32 v25, v25, s18, v2
	s_waitcnt lgkmcnt(3)
	v_bfe_u32 v2, v36, 16, 1
	v_add3_u32 v2, v36, v2, s17
	s_waitcnt lgkmcnt(2)
	v_bfe_u32 v26, v66, 16, 1
	v_lshrrev_b32_e32 v2, 16, v2
	v_add3_u32 v26, v66, v26, s17
	v_and_or_b32 v26, v26, s18, v2
	s_waitcnt lgkmcnt(1)
	v_bfe_u32 v2, v68, 16, 1
	v_add_u32_e32 v72, s4, v1
	v_add3_u32 v2, v68, v2, s17
	s_waitcnt lgkmcnt(0)
	v_bfe_u32 v27, v70, 16, 1
	v_ashrrev_i32_e32 v73, 31, v72
	v_lshl_add_u64 v[22:23], s[8:9], 1, v[14:15]
	v_lshrrev_b32_e32 v2, 16, v2
	v_add3_u32 v27, v70, v27, s17
	v_lshlrev_b64 v[72:73], 11, v[72:73]
	v_and_or_b32 v27, v27, s18, v2
	v_lshl_add_u64 v[72:73], v[22:23], 0, v[72:73]
	v_bfe_u32 v2, v29, 16, 1
	global_store_dwordx4 v[72:73], v[24:27], off
	v_add3_u32 v2, v29, v2, s17
	v_lshrrev_b32_e32 v2, 16, v2
	v_bfe_u32 v24, v31, 16, 1
	v_add3_u32 v24, v31, v24, s17
	v_and_or_b32 v24, v24, s18, v2
	v_bfe_u32 v2, v33, 16, 1
	v_add3_u32 v2, v33, v2, s17
	v_bfe_u32 v25, v35, 16, 1
	v_lshrrev_b32_e32 v2, 16, v2
	v_add3_u32 v25, v35, v25, s17
	v_and_or_b32 v25, v25, s18, v2
	v_bfe_u32 v2, v37, 16, 1
	v_add3_u32 v2, v37, v2, s17
	v_bfe_u32 v26, v67, 16, 1
	v_lshrrev_b32_e32 v2, 16, v2
	v_add3_u32 v26, v67, v26, s17
	v_and_or_b32 v26, v26, s18, v2
	v_bfe_u32 v2, v69, 16, 1
	v_add_u32_e32 v28, s4, v39
	v_add3_u32 v2, v69, v2, s17
	v_bfe_u32 v27, v71, 16, 1
	v_ashrrev_i32_e32 v29, 31, v28
	v_lshrrev_b32_e32 v2, 16, v2
	v_add3_u32 v27, v71, v27, s17
	v_lshlrev_b64 v[28:29], 11, v[28:29]
	v_and_or_b32 v27, v27, s18, v2
	ds_read2_b32 v[30:31], v38 offset0:16 offset1:24
	v_lshl_add_u64 v[28:29], v[22:23], 0, v[28:29]
	global_store_dwordx4 v[28:29], v[24:27], off
	ds_read2_b32 v[28:29], v38 offset0:81 offset1:89
	ds_read2_b32 v[32:33], v38 offset0:146 offset1:154
	ds_read2_b32 v[34:35], v38 offset0:211 offset1:219
	s_waitcnt lgkmcnt(3)
	v_bfe_u32 v2, v30, 16, 1
	v_add3_u32 v2, v30, v2, s17
	s_waitcnt lgkmcnt(2)
	v_bfe_u32 v24, v28, 16, 1
	ds_read2_b32 v[36:37], v74 offset0:20 offset1:28
	v_lshrrev_b32_e32 v2, 16, v2
	v_add3_u32 v24, v28, v24, s17
	ds_read2_b32 v[66:67], v74 offset0:85 offset1:93
	v_and_or_b32 v24, v24, s18, v2
	s_waitcnt lgkmcnt(3)
	v_bfe_u32 v2, v32, 16, 1
	v_add3_u32 v2, v32, v2, s17
	s_waitcnt lgkmcnt(2)
	v_bfe_u32 v25, v34, 16, 1
	ds_read2_b32 v[68:69], v74 offset0:150 offset1:158
	v_lshrrev_b32_e32 v2, 16, v2
	v_add3_u32 v25, v34, v25, s17
	ds_read2_b32 v[70:71], v74 offset0:215 offset1:223
	v_and_or_b32 v25, v25, s18, v2
	s_waitcnt lgkmcnt(3)
	v_bfe_u32 v2, v36, 16, 1
	v_add3_u32 v2, v36, v2, s17
	s_waitcnt lgkmcnt(2)
	v_bfe_u32 v26, v66, 16, 1
	v_lshrrev_b32_e32 v2, 16, v2
	v_add3_u32 v26, v66, v26, s17
	v_and_or_b32 v26, v26, s18, v2
	s_waitcnt lgkmcnt(1)
	v_bfe_u32 v2, v68, 16, 1
	v_add_u32_e32 v72, s4, v40
	v_add3_u32 v2, v68, v2, s17
	s_waitcnt lgkmcnt(0)
	v_bfe_u32 v27, v70, 16, 1
	v_ashrrev_i32_e32 v73, 31, v72
	v_lshrrev_b32_e32 v2, 16, v2
	v_add3_u32 v27, v70, v27, s17
	v_lshlrev_b64 v[72:73], 11, v[72:73]
	v_and_or_b32 v27, v27, s18, v2
	v_lshl_add_u64 v[72:73], v[22:23], 0, v[72:73]
	v_bfe_u32 v2, v31, 16, 1
	global_store_dwordx4 v[72:73], v[24:27], off
	v_add3_u32 v2, v31, v2, s17
	v_lshrrev_b32_e32 v2, 16, v2
	v_bfe_u32 v24, v29, 16, 1
	v_add3_u32 v24, v29, v24, s17
	v_and_or_b32 v24, v24, s18, v2
	v_bfe_u32 v2, v33, 16, 1
	v_add3_u32 v2, v33, v2, s17
	v_bfe_u32 v25, v35, 16, 1
	v_lshrrev_b32_e32 v2, 16, v2
	v_add3_u32 v25, v35, v25, s17
	v_and_or_b32 v25, v25, s18, v2
	v_bfe_u32 v2, v37, 16, 1
	v_add3_u32 v2, v37, v2, s17
	v_bfe_u32 v26, v67, 16, 1
	v_lshrrev_b32_e32 v2, 16, v2
	v_add3_u32 v26, v67, v26, s17
	v_and_or_b32 v26, v26, s18, v2
	v_bfe_u32 v2, v69, 16, 1
	v_add_u32_e32 v28, s4, v41
	v_add3_u32 v2, v69, v2, s17
	v_bfe_u32 v27, v71, 16, 1
	v_ashrrev_i32_e32 v29, 31, v28
	v_lshrrev_b32_e32 v2, 16, v2
	v_add3_u32 v27, v71, v27, s17
	v_lshlrev_b64 v[28:29], 11, v[28:29]
	v_and_or_b32 v27, v27, s18, v2
	ds_read2_b32 v[30:31], v38 offset0:32 offset1:40
	v_lshl_add_u64 v[28:29], v[22:23], 0, v[28:29]
	global_store_dwordx4 v[28:29], v[24:27], off
	ds_read2_b32 v[28:29], v38 offset0:97 offset1:105
	ds_read2_b32 v[32:33], v38 offset0:162 offset1:170
	ds_read2_b32 v[34:35], v38 offset0:227 offset1:235
	s_waitcnt lgkmcnt(3)
; #define LAS __attribute__((address_space(3)))
; #define GAS __attribute__((address_space(1)))
; __device__ __forceinline__ unsigned pk2(float lo, float hi) { return f2bf(lo) | (f2bf(hi) << 16); }
; #define LDS_WAIT() asm volatile("s_waitcnt lgkmcnt(0)" ::: "memory")
; __device__ __forceinline__ void transpose_item(const float* W, int ldw, int src_col0, bf16_t* WT, int Kd, int dst_row0, int k0, float scale, LAS float* scr, int lane) {
;     ...
;     const int c = lane & 7;
; #pragma unroll
;     for (int j = 0; j < 8; ++j) { const int n = (lane >> 3) + 8 * j; const LAS float* sp = scr + (8 * c) * 65 + n;
;         u32x4 o; o.x = pk2(sp[0 * 65], sp[1 * 65]); o.y = pk2(sp[2 * 65], sp[3 * 65]); o.z = pk2(sp[4 * 65], sp[5 * 65]); o.w = pk2(sp[6 * 65], sp[7 * 65]);
;         *(GAS u32x4*)(WT + (size_t)(dst_row0 + n) * Kd + k0 + 8 * c) = o; }
;     LDS_WAIT(); asm volatile("" ::: "memory");
	v_bfe_u32 v2, v30, 16, 1
	v_add3_u32 v2, v30, v2, s17
	s_waitcnt lgkmcnt(2)
	v_bfe_u32 v24, v28, 16, 1
	ds_read2_b32 v[36:37], v74 offset0:36 offset1:44
	v_lshrrev_b32_e32 v2, 16, v2
	v_add3_u32 v24, v28, v24, s17
	ds_read2_b32 v[66:67], v74 offset0:101 offset1:109
	v_and_or_b32 v24, v24, s18, v2
	s_waitcnt lgkmcnt(3)
	v_bfe_u32 v2, v32, 16, 1
	v_add3_u32 v2, v32, v2, s17
	s_waitcnt lgkmcnt(2)
	v_bfe_u32 v25, v34, 16, 1
	ds_read2_b32 v[68:69], v74 offset0:166 offset1:174
	v_lshrrev_b32_e32 v2, 16, v2
	v_add3_u32 v25, v34, v25, s17
	ds_read2_b32 v[70:71], v74 offset0:231 offset1:239
	v_and_or_b32 v25, v25, s18, v2
	s_waitcnt lgkmcnt(3)
	v_bfe_u32 v2, v36, 16, 1
	v_add3_u32 v2, v36, v2, s17
	s_waitcnt lgkmcnt(2)
	v_bfe_u32 v26, v66, 16, 1
	v_lshrrev_b32_e32 v2, 16, v2
	v_add3_u32 v26, v66, v26, s17
	v_and_or_b32 v26, v26, s18, v2
	s_waitcnt lgkmcnt(1)
	v_bfe_u32 v2, v68, 16, 1
	v_add_u32_e32 v72, s4, v42
	v_add3_u32 v2, v68, v2, s17
	s_waitcnt lgkmcnt(0)
	v_bfe_u32 v27, v70, 16, 1
	v_ashrrev_i32_e32 v73, 31, v72
	v_lshrrev_b32_e32 v2, 16, v2
	v_add3_u32 v27, v70, v27, s17
	v_lshlrev_b64 v[72:73], 11, v[72:73]
	v_and_or_b32 v27, v27, s18, v2
	v_lshl_add_u64 v[72:73], v[22:23], 0, v[72:73]
	v_bfe_u32 v2, v31, 16, 1
	global_store_dwordx4 v[72:73], v[24:27], off
	v_add3_u32 v2, v31, v2, s17
	v_lshrrev_b32_e32 v2, 16, v2
	v_bfe_u32 v24, v29, 16, 1
	v_add3_u32 v24, v29, v24, s17
	v_and_or_b32 v24, v24, s18, v2
	v_bfe_u32 v2, v33, 16, 1
	v_add3_u32 v2, v33, v2, s17
	v_bfe_u32 v25, v35, 16, 1
	v_lshrrev_b32_e32 v2, 16, v2
	v_add3_u32 v25, v35, v25, s17
	v_and_or_b32 v25, v25, s18, v2
	v_bfe_u32 v2, v37, 16, 1
	v_add3_u32 v2, v37, v2, s17
	v_bfe_u32 v26, v67, 16, 1
	v_lshrrev_b32_e32 v2, 16, v2
	v_add3_u32 v26, v67, v26, s17
	v_and_or_b32 v26, v26, s18, v2
	v_bfe_u32 v2, v69, 16, 1
	v_add_u32_e32 v28, s4, v43
	v_add3_u32 v2, v69, v2, s17
	v_bfe_u32 v27, v71, 16, 1
	v_ashrrev_i32_e32 v29, 31, v28
	v_lshrrev_b32_e32 v2, 16, v2
	v_add3_u32 v27, v71, v27, s17
	v_lshlrev_b64 v[28:29], 11, v[28:29]
	v_and_or_b32 v27, v27, s18, v2
	ds_read2_b32 v[30:31], v38 offset0:48 offset1:56
	v_lshl_add_u64 v[28:29], v[22:23], 0, v[28:29]
	global_store_dwordx4 v[28:29], v[24:27], off
	ds_read2_b32 v[28:29], v38 offset0:113 offset1:121
	ds_read2_b32 v[32:33], v38 offset0:178 offset1:186
	ds_read2_b32 v[34:35], v38 offset0:243 offset1:251
	s_waitcnt lgkmcnt(3)
	v_bfe_u32 v2, v30, 16, 1
	v_add3_u32 v2, v30, v2, s17
	s_waitcnt lgkmcnt(2)
	v_bfe_u32 v24, v28, 16, 1
	ds_read2_b32 v[36:37], v74 offset0:52 offset1:60
	v_lshrrev_b32_e32 v2, 16, v2
	v_add3_u32 v24, v28, v24, s17
	ds_read2_b32 v[66:67], v74 offset0:117 offset1:125
	v_and_or_b32 v24, v24, s18, v2
	s_waitcnt lgkmcnt(3)
	v_bfe_u32 v2, v32, 16, 1
	v_add3_u32 v2, v32, v2, s17
	s_waitcnt lgkmcnt(2)
	v_bfe_u32 v25, v34, 16, 1
	ds_read2_b32 v[68:69], v74 offset0:182 offset1:190
	v_lshrrev_b32_e32 v2, 16, v2
	v_add3_u32 v25, v34, v25, s17
	ds_read2_b32 v[70:71], v74 offset0:247 offset1:255
	v_and_or_b32 v25, v25, s18, v2
	s_waitcnt lgkmcnt(3)
	v_bfe_u32 v2, v36, 16, 1
	v_add3_u32 v2, v36, v2, s17
	s_waitcnt lgkmcnt(2)
	v_bfe_u32 v26, v66, 16, 1
	v_lshrrev_b32_e32 v2, 16, v2
	v_add3_u32 v26, v66, v26, s17
	v_and_or_b32 v26, v26, s18, v2
	s_waitcnt lgkmcnt(1)
	v_bfe_u32 v2, v68, 16, 1
	v_add_u32_e32 v72, s4, v44
	v_add3_u32 v2, v68, v2, s17
	s_waitcnt lgkmcnt(0)
	v_bfe_u32 v27, v70, 16, 1
	v_ashrrev_i32_e32 v73, 31, v72
	v_lshrrev_b32_e32 v2, 16, v2
	v_add3_u32 v27, v70, v27, s17
	v_lshlrev_b64 v[72:73], 11, v[72:73]
	v_and_or_b32 v27, v27, s18, v2
	v_lshl_add_u64 v[72:73], v[22:23], 0, v[72:73]
	v_bfe_u32 v2, v31, 16, 1
	global_store_dwordx4 v[72:73], v[24:27], off
	v_add3_u32 v2, v31, v2, s17
	v_lshrrev_b32_e32 v2, 16, v2
	v_bfe_u32 v24, v29, 16, 1
	v_add3_u32 v24, v29, v24, s17
	v_and_or_b32 v24, v24, s18, v2
	v_bfe_u32 v2, v33, 16, 1
	v_add3_u32 v2, v33, v2, s17
	v_bfe_u32 v25, v35, 16, 1
	v_lshrrev_b32_e32 v2, 16, v2
	v_add3_u32 v25, v35, v25, s17
	v_and_or_b32 v25, v25, s18, v2
	v_bfe_u32 v2, v37, 16, 1
	v_add3_u32 v2, v37, v2, s17
	v_bfe_u32 v26, v67, 16, 1
	v_lshrrev_b32_e32 v2, 16, v2
	v_add3_u32 v26, v67, v26, s17
	v_and_or_b32 v26, v26, s18, v2
	v_bfe_u32 v2, v69, 16, 1
	v_add_u32_e32 v28, s4, v45
	v_add3_u32 v2, v69, v2, s17
	v_bfe_u32 v27, v71, 16, 1
	v_ashrrev_i32_e32 v29, 31, v28
	v_lshrrev_b32_e32 v2, 16, v2
	v_add3_u32 v27, v71, v27, s17
	v_lshlrev_b64 v[28:29], 11, v[28:29]
	v_and_or_b32 v27, v27, s18, v2
	v_lshl_add_u64 v[22:23], v[22:23], 0, v[28:29]
	global_store_dwordx4 v[22:23], v[24:27], off
	s_waitcnt lgkmcnt(0)
	s_branch .LBB0_9

; #define LAS __attribute__((address_space(3)))
; #define GAS __attribute__((address_space(1)))
; #define LDS_WAIT() asm volatile("s_waitcnt lgkmcnt(0)" ::: "memory")
; __device__ __forceinline__ void transpose_item(const float* W, int ldw, int src_col0, bf16_t* WT, int Kd, int dst_row0, int k0, float scale, LAS float* scr, int lane) {
;     const int kr = lane >> 4, c4 = lane & 15;
; #pragma unroll 8
;     for (int i = 0; i < 16; ++i) { const int kk = 4 * i + kr; const f32x4 v = __builtin_nontemporal_load((const GAS f32x4*)(W + (size_t)(k0 + kk) * ldw + src_col0 + 4 * c4)) * scale;
;         LAS float* d = scr + kk * 65 + 4 * c4; d[0] = v.x; d[1] = v.y; d[2] = v.z; d[3] = v.w; }
;     LDS_WAIT(); asm volatile("" ::: "memory");
; template <int PART> __device__ __forceinline__ void phase_convert(Frame& F) {
;     ...
;         { const int nblk = D / 64, kb = r / nblk, nb = r % nblk;
;             transpose_item(F.in[21] + (size_t)l * DFF * D, D, nb * 64, W2 + (size_t)l * D * DFF, DFF, nb * 64, kb * 64, 1.f, scr, F.lane); }
.LBB0_218:
	v_add_u32_e32 v23, s6, v0
	v_add_u32_e32 v24, 0xffffe000, v23
	v_add_u32_e32 v26, 0xffffe004, v23
	v_add_u32_e32 v28, 0xffffe008, v23
	v_add_u32_e32 v30, 0xffffe00c, v23
	v_add_u32_e32 v32, 0xffffe010, v23
	v_add_u32_e32 v34, 0xffffe014, v23
	v_add_u32_e32 v66, 0xffffe018, v23
	v_add_u32_e32 v68, 0xffffe01c, v23
	v_ashrrev_i32_e32 v25, 31, v24
	v_ashrrev_i32_e32 v27, 31, v26
	v_ashrrev_i32_e32 v29, 31, v28
	v_ashrrev_i32_e32 v31, 31, v30
	v_ashrrev_i32_e32 v33, 31, v32
	v_ashrrev_i32_e32 v35, 31, v34
	v_ashrrev_i32_e32 v67, 31, v66
	v_ashrrev_i32_e32 v69, 31, v68
	v_lshlrev_b64 v[24:25], 12, v[24:25]
	v_lshlrev_b64 v[26:27], 12, v[26:27]
	v_lshlrev_b64 v[28:29], 12, v[28:29]
	v_lshlrev_b64 v[30:31], 12, v[30:31]
	v_lshlrev_b64 v[32:33], 12, v[32:33]
	v_lshlrev_b64 v[34:35], 12, v[34:35]
	v_lshlrev_b64 v[66:67], 12, v[66:67]
	v_lshlrev_b64 v[68:69], 12, v[68:69]
	v_lshl_add_u64 v[24:25], v[20:21], 0, v[24:25]
	v_lshl_add_u64 v[70:71], v[20:21], 0, v[26:27]
	v_lshl_add_u64 v[72:73], v[20:21], 0, v[28:29]
	v_lshl_add_u64 v[74:75], v[20:21], 0, v[30:31]
	v_lshl_add_u64 v[76:77], v[20:21], 0, v[32:33]
	v_lshl_add_u64 v[78:79], v[20:21], 0, v[34:35]
	v_lshl_add_u64 v[80:81], v[20:21], 0, v[66:67]
	v_lshl_add_u64 v[82:83], v[20:21], 0, v[68:69]
	global_load_dwordx4 v[24:27], v[24:25], off nt
	s_nop 0
	global_load_dwordx4 v[28:31], v[70:71], off nt
	global_load_dwordx4 v[32:35], v[72:73], off nt
	global_load_dwordx4 v[66:69], v[74:75], off nt
	s_nop 0
	global_load_dwordx4 v[70:73], v[76:77], off nt
	s_nop 0
	global_load_dwordx4 v[74:77], v[78:79], off nt
	s_nop 0
	global_load_dwordx4 v[78:81], v[80:81], off nt
	s_nop 0
	global_load_dwordx4 v[82:85], v[82:83], off nt
	s_add_i32 s6, s6, 32
	v_add_u32_e32 v139, s6, v0
	v_add_u32_e32 v140, 0xffffe000, v139
	v_add_u32_e32 v142, 0xffffe004, v139
	v_add_u32_e32 v144, 0xffffe008, v139
	v_add_u32_e32 v146, 0xffffe00c, v139
	v_add_u32_e32 v148, 0xffffe010, v139
	v_add_u32_e32 v150, 0xffffe014, v139
	v_add_u32_e32 v182, 0xffffe018, v139
	v_add_u32_e32 v184, 0xffffe01c, v139
	v_ashrrev_i32_e32 v141, 31, v140
	v_ashrrev_i32_e32 v143, 31, v142
	v_ashrrev_i32_e32 v145, 31, v144
	v_ashrrev_i32_e32 v147, 31, v146
	v_ashrrev_i32_e32 v149, 31, v148
	v_ashrrev_i32_e32 v151, 31, v150
	v_ashrrev_i32_e32 v183, 31, v182
	v_ashrrev_i32_e32 v185, 31, v184
	v_lshlrev_b64 v[140:141], 12, v[140:141]
	v_lshlrev_b64 v[142:143], 12, v[142:143]
	v_lshlrev_b64 v[144:145], 12, v[144:145]
	v_lshlrev_b64 v[146:147], 12, v[146:147]
	v_lshlrev_b64 v[148:149], 12, v[148:149]
	v_lshlrev_b64 v[150:151], 12, v[150:151]
	v_lshlrev_b64 v[182:183], 12, v[182:183]
	v_lshlrev_b64 v[184:185], 12, v[184:185]
	v_lshl_add_u64 v[140:141], v[20:21], 0, v[140:141]
	v_lshl_add_u64 v[186:187], v[20:21], 0, v[142:143]
	v_lshl_add_u64 v[188:189], v[20:21], 0, v[144:145]
	v_lshl_add_u64 v[190:191], v[20:21], 0, v[146:147]
	v_lshl_add_u64 v[192:193], v[20:21], 0, v[148:149]
	v_lshl_add_u64 v[194:195], v[20:21], 0, v[150:151]
	v_lshl_add_u64 v[196:197], v[20:21], 0, v[182:183]
	v_lshl_add_u64 v[198:199], v[20:21], 0, v[184:185]
	global_load_dwordx4 v[140:143], v[140:141], off nt
	s_nop 0
	global_load_dwordx4 v[144:147], v[186:187], off nt
	global_load_dwordx4 v[148:151], v[188:189], off nt
	global_load_dwordx4 v[182:185], v[190:191], off nt
	s_nop 0
	global_load_dwordx4 v[186:189], v[192:193], off nt
	s_nop 0
	global_load_dwordx4 v[190:193], v[194:195], off nt
	s_nop 0
	global_load_dwordx4 v[194:197], v[196:197], off nt
	s_nop 0
	global_load_dwordx4 v[198:201], v[198:199], off nt
	v_add_u32_e32 v23, 0x410, v22
	v_add_u32_e32 v65, 0x418, v22
	v_add_u32_e32 v86, 0x820, v22
	v_add_u32_e32 v87, 0x828, v22
	v_add_u32_e32 v88, 0xc30, v22
	v_add_u32_e32 v89, 0xc38, v22
	v_add_u32_e32 v90, 0x1040, v22
	v_add_u32_e32 v91, 0x1048, v22
	v_add_u32_e32 v92, 0x1450, v22
	v_add_u32_e32 v93, 0x1458, v22
	v_add_u32_e32 v94, 0x1860, v22
	v_add_u32_e32 v95, 0x1868, v22
	v_add_u32_e32 v96, 0x1c70, v22
	v_add_u32_e32 v97, 0x1c78, v22
	s_waitcnt vmcnt(15)
	ds_write2_b32 v22, v24, v25 offset1:1
	ds_write2_b32 v22, v26, v27 offset0:2 offset1:3
	s_waitcnt vmcnt(14)
	ds_write2_b32 v23, v28, v29 offset1:1
	ds_write2_b32 v65, v30, v31 offset1:1
	s_waitcnt vmcnt(13)
	ds_write2_b32 v86, v32, v33 offset1:1
	ds_write2_b32 v87, v34, v35 offset1:1
	s_waitcnt vmcnt(12)
	ds_write2_b32 v88, v66, v67 offset1:1
	ds_write2_b32 v89, v68, v69 offset1:1
	s_waitcnt vmcnt(11)
	ds_write2_b32 v90, v70, v71 offset1:1
	ds_write2_b32 v91, v72, v73 offset1:1
	s_waitcnt vmcnt(10)
	ds_write2_b32 v92, v74, v75 offset1:1
	ds_write2_b32 v93, v76, v77 offset1:1
	s_waitcnt vmcnt(9)
	ds_write2_b32 v94, v78, v79 offset1:1
	ds_write2_b32 v95, v80, v81 offset1:1
	s_waitcnt vmcnt(8)
	ds_write2_b32 v96, v82, v83 offset1:1
	ds_write2_b32 v97, v84, v85 offset1:1
	v_add_u32_e32 v22, 0x2080, v22
	s_add_i32 s6, s6, 32
	v_add_u32_e32 v23, 0x410, v22
	v_add_u32_e32 v65, 0x418, v22
	v_add_u32_e32 v86, 0x820, v22
	v_add_u32_e32 v87, 0x828, v22
	v_add_u32_e32 v88, 0xc30, v22
	v_add_u32_e32 v89, 0xc38, v22
	v_add_u32_e32 v90, 0x1040, v22
	v_add_u32_e32 v91, 0x1048, v22
	v_add_u32_e32 v92, 0x1450, v22
	v_add_u32_e32 v93, 0x1458, v22
	v_add_u32_e32 v94, 0x1860, v22
	v_add_u32_e32 v95, 0x1868, v22
	v_add_u32_e32 v96, 0x1c70, v22
	v_add_u32_e32 v97, 0x1c78, v22
	s_waitcnt vmcnt(7)
	ds_write2_b32 v22, v140, v141 offset1:1
	ds_write2_b32 v22, v142, v143 offset0:2 offset1:3
	s_waitcnt vmcnt(6)
	ds_write2_b32 v23, v144, v145 offset1:1
	ds_write2_b32 v65, v146, v147 offset1:1
	s_waitcnt vmcnt(5)
	ds_write2_b32 v86, v148, v149 offset1:1
	ds_write2_b32 v87, v150, v151 offset1:1
	s_waitcnt vmcnt(4)
; #define LAS __attribute__((address_space(3)))
; #define GAS __attribute__((address_space(1)))
; __device__ __forceinline__ unsigned pk2(float lo, float hi) { return f2bf(lo) | (f2bf(hi) << 16); }
; #define LDS_WAIT() asm volatile("s_waitcnt lgkmcnt(0)" ::: "memory")
; __device__ __forceinline__ void transpose_item(const float* W, int ldw, int src_col0, bf16_t* WT, int Kd, int dst_row0, int k0, float scale, LAS float* scr, int lane) {
;     ...
;         LAS float* d = scr + kk * 65 + 4 * c4; d[0] = v.x; d[1] = v.y; d[2] = v.z; d[3] = v.w; }
;     LDS_WAIT(); asm volatile("" ::: "memory");
;     const int c = lane & 7;
; #pragma unroll
;     for (int j = 0; j < 8; ++j) { const int n = (lane >> 3) + 8 * j; const LAS float* sp = scr + (8 * c) * 65 + n;
;         u32x4 o; o.x = pk2(sp[0 * 65], sp[1 * 65]); o.y = pk2(sp[2 * 65], sp[3 * 65]); o.z = pk2(sp[4 * 65], sp[5 * 65]); o.w = pk2(sp[6 * 65], sp[7 * 65]);
;         *(GAS u32x4*)(WT + (size_t)(dst_row0 + n) * Kd + k0 + 8 * c) = o; }
;     LDS_WAIT(); asm volatile("" ::: "memory");
	ds_write2_b32 v88, v182, v183 offset1:1
	ds_write2_b32 v89, v184, v185 offset1:1
	s_waitcnt vmcnt(3)
	ds_write2_b32 v90, v186, v187 offset1:1
	ds_write2_b32 v91, v188, v189 offset1:1
	s_waitcnt vmcnt(2)
	ds_write2_b32 v92, v190, v191 offset1:1
	ds_write2_b32 v93, v192, v193 offset1:1
	s_waitcnt vmcnt(1)
	ds_write2_b32 v94, v194, v195 offset1:1
	ds_write2_b32 v95, v196, v197 offset1:1
	s_waitcnt vmcnt(0)
	ds_write2_b32 v96, v198, v199 offset1:1
	ds_write2_b32 v97, v200, v201 offset1:1
	v_add_u32_e32 v22, 0x2080, v22
	s_waitcnt lgkmcnt(0)
	ds_read2_b32 v[26:27], v37 offset1:8
	ds_read2_b32 v[28:29], v37 offset0:65 offset1:73
	ds_read2_b32 v[30:31], v37 offset0:130 offset1:138
	ds_read2_b32 v[32:33], v37 offset0:195 offset1:203
	v_add_u32_e32 v65, 0x400, v37
	s_waitcnt lgkmcnt(3)
	v_bfe_u32 v0, v26, 16, 1
	v_add3_u32 v0, v26, v0, s20
	s_waitcnt lgkmcnt(2)
	v_bfe_u32 v22, v28, 16, 1
	ds_read2_b32 v[34:35], v65 offset0:4 offset1:12
	v_lshrrev_b32_e32 v0, 16, v0
	v_add3_u32 v22, v28, v22, s20
	ds_read2_b32 v[66:67], v65 offset0:69 offset1:77
	v_and_or_b32 v22, v22, s21, v0
	s_waitcnt lgkmcnt(3)
	v_bfe_u32 v0, v30, 16, 1
	v_add3_u32 v0, v30, v0, s20
	s_waitcnt lgkmcnt(2)
	v_bfe_u32 v23, v32, 16, 1
	ds_read2_b32 v[68:69], v65 offset0:134 offset1:142
	v_lshrrev_b32_e32 v0, 16, v0
	v_add3_u32 v23, v32, v23, s20
	ds_read2_b32 v[70:71], v65 offset0:199 offset1:207
	v_and_or_b32 v23, v23, s21, v0
	s_waitcnt lgkmcnt(3)
	v_bfe_u32 v0, v34, 16, 1
	v_add3_u32 v0, v34, v0, s20
	s_waitcnt lgkmcnt(2)
	v_bfe_u32 v24, v66, 16, 1
	v_lshrrev_b32_e32 v0, 16, v0
	v_add3_u32 v24, v66, v24, s20
	s_lshl_b32 s6, s13, 2
	v_and_or_b32 v24, v24, s21, v0
	s_waitcnt lgkmcnt(1)
	v_bfe_u32 v0, v68, 16, 1
	s_and_b32 s6, s6, 0x7fffffc0
	v_add3_u32 v0, v68, v0, s20
	s_waitcnt lgkmcnt(0)
	v_bfe_u32 v25, v70, 16, 1
	s_addk_i32 s6, 0xe000
	v_lshrrev_b32_e32 v0, 16, v0
	v_add3_u32 v25, v70, v25, s20
	v_lshl_add_u64 v[20:21], s[6:7], 1, v[4:5]
	v_and_or_b32 v25, v25, s21, v0
	v_add_lshl_u32 v0, v36, s10, 13
	v_lshl_add_u64 v[72:73], v[20:21], 0, v[0:1]
	v_bfe_u32 v0, v27, 16, 1
	global_store_dwordx4 v[72:73], v[22:25], off
	v_add3_u32 v0, v27, v0, s20
	v_lshrrev_b32_e32 v0, 16, v0
	v_bfe_u32 v22, v29, 16, 1
	v_add3_u32 v22, v29, v22, s20
	v_and_or_b32 v22, v22, s21, v0
	v_bfe_u32 v0, v31, 16, 1
	v_add3_u32 v0, v31, v0, s20
	v_bfe_u32 v23, v33, 16, 1
	v_lshrrev_b32_e32 v0, 16, v0
	v_add3_u32 v23, v33, v23, s20
	v_and_or_b32 v23, v23, s21, v0
	v_bfe_u32 v0, v35, 16, 1
	v_add3_u32 v0, v35, v0, s20
	v_bfe_u32 v24, v67, 16, 1
	v_lshrrev_b32_e32 v0, 16, v0
	v_add3_u32 v24, v67, v24, s20
	v_and_or_b32 v24, v24, s21, v0
	v_bfe_u32 v0, v69, 16, 1
	v_add3_u32 v0, v69, v0, s20
	v_bfe_u32 v25, v71, 16, 1
	v_lshrrev_b32_e32 v0, 16, v0
	v_add3_u32 v25, v71, v25, s20
	v_and_or_b32 v25, v25, s21, v0
	v_add_lshl_u32 v0, v38, s10, 13
	ds_read2_b32 v[26:27], v37 offset0:16 offset1:24
	v_lshl_add_u64 v[28:29], v[20:21], 0, v[0:1]
	global_store_dwordx4 v[28:29], v[22:25], off
	ds_read2_b32 v[28:29], v37 offset0:81 offset1:89
	ds_read2_b32 v[30:31], v37 offset0:146 offset1:154
	ds_read2_b32 v[32:33], v37 offset0:211 offset1:219
	s_waitcnt lgkmcnt(3)
	v_bfe_u32 v0, v26, 16, 1
	v_add3_u32 v0, v26, v0, s20
	s_waitcnt lgkmcnt(2)
	v_bfe_u32 v22, v28, 16, 1
	ds_read2_b32 v[34:35], v65 offset0:20 offset1:28
	v_lshrrev_b32_e32 v0, 16, v0
	v_add3_u32 v22, v28, v22, s20
	ds_read2_b32 v[66:67], v65 offset0:85 offset1:93
	v_and_or_b32 v22, v22, s21, v0
	s_waitcnt lgkmcnt(3)
	v_bfe_u32 v0, v30, 16, 1
	v_add3_u32 v0, v30, v0, s20
	s_waitcnt lgkmcnt(2)
	v_bfe_u32 v23, v32, 16, 1
	ds_read2_b32 v[68:69], v65 offset0:150 offset1:158
	v_lshrrev_b32_e32 v0, 16, v0
	v_add3_u32 v23, v32, v23, s20
	ds_read2_b32 v[70:71], v65 offset0:215 offset1:223
	v_and_or_b32 v23, v23, s21, v0
	s_waitcnt lgkmcnt(3)
	v_bfe_u32 v0, v34, 16, 1
	v_add3_u32 v0, v34, v0, s20
	s_waitcnt lgkmcnt(2)
	v_bfe_u32 v24, v66, 16, 1
	v_lshrrev_b32_e32 v0, 16, v0
	v_add3_u32 v24, v66, v24, s20
	v_and_or_b32 v24, v24, s21, v0
	s_waitcnt lgkmcnt(1)
	v_bfe_u32 v0, v68, 16, 1
	v_add3_u32 v0, v68, v0, s20
	s_waitcnt lgkmcnt(0)
	v_bfe_u32 v25, v70, 16, 1
	v_lshrrev_b32_e32 v0, 16, v0
	v_add3_u32 v25, v70, v25, s20
	v_and_or_b32 v25, v25, s21, v0
	v_add_lshl_u32 v0, v39, s10, 13
	v_lshl_add_u64 v[72:73], v[20:21], 0, v[0:1]
	v_bfe_u32 v0, v27, 16, 1
	global_store_dwordx4 v[72:73], v[22:25], off
	v_add3_u32 v0, v27, v0, s20
	v_lshrrev_b32_e32 v0, 16, v0
	v_bfe_u32 v22, v29, 16, 1
	v_add3_u32 v22, v29, v22, s20
	v_and_or_b32 v22, v22, s21, v0
	v_bfe_u32 v0, v31, 16, 1
	v_add3_u32 v0, v31, v0, s20
	v_bfe_u32 v23, v33, 16, 1
	v_lshrrev_b32_e32 v0, 16, v0
	v_add3_u32 v23, v33, v23, s20
	v_and_or_b32 v23, v23, s21, v0
	v_bfe_u32 v0, v35, 16, 1
	v_add3_u32 v0, v35, v0, s20
	v_bfe_u32 v24, v67, 16, 1
	v_lshrrev_b32_e32 v0, 16, v0
	v_add3_u32 v24, v67, v24, s20
	v_and_or_b32 v24, v24, s21, v0
	v_bfe_u32 v0, v69, 16, 1
	v_add3_u32 v0, v69, v0, s20
	v_bfe_u32 v25, v71, 16, 1
	v_lshrrev_b32_e32 v0, 16, v0
	v_add3_u32 v25, v71, v25, s20
	v_and_or_b32 v25, v25, s21, v0
	v_add_lshl_u32 v0, v40, s10, 13
	ds_read2_b32 v[26:27], v37 offset0:32 offset1:40
	v_lshl_add_u64 v[28:29], v[20:21], 0, v[0:1]
	global_store_dwordx4 v[28:29], v[22:25], off
	ds_read2_b32 v[28:29], v37 offset0:97 offset1:105
	ds_read2_b32 v[30:31], v37 offset0:162 offset1:170
	ds_read2_b32 v[32:33], v37 offset0:227 offset1:235
	s_waitcnt lgkmcnt(3)
; #define LAS __attribute__((address_space(3)))
; #define GAS __attribute__((address_space(1)))
; __device__ __forceinline__ unsigned pk2(float lo, float hi) { return f2bf(lo) | (f2bf(hi) << 16); }
; #define LDS_WAIT() asm volatile("s_waitcnt lgkmcnt(0)" ::: "memory")
; __device__ __forceinline__ void transpose_item(const float* W, int ldw, int src_col0, bf16_t* WT, int Kd, int dst_row0, int k0, float scale, LAS float* scr, int lane) {
;     ...
;     for (int j = 0; j < 8; ++j) { const int n = (lane >> 3) + 8 * j; const LAS float* sp = scr + (8 * c) * 65 + n;
;         u32x4 o; o.x = pk2(sp[0 * 65], sp[1 * 65]); o.y = pk2(sp[2 * 65], sp[3 * 65]); o.z = pk2(sp[4 * 65], sp[5 * 65]); o.w = pk2(sp[6 * 65], sp[7 * 65]);
;         *(GAS u32x4*)(WT + (size_t)(dst_row0 + n) * Kd + k0 + 8 * c) = o; }
;     LDS_WAIT(); asm volatile("" ::: "memory");
	v_bfe_u32 v0, v26, 16, 1
	v_add3_u32 v0, v26, v0, s20
	s_waitcnt lgkmcnt(2)
	v_bfe_u32 v22, v28, 16, 1
	ds_read2_b32 v[34:35], v65 offset0:36 offset1:44
	v_lshrrev_b32_e32 v0, 16, v0
	v_add3_u32 v22, v28, v22, s20
	ds_read2_b32 v[66:67], v65 offset0:101 offset1:109
	v_and_or_b32 v22, v22, s21, v0
	s_waitcnt lgkmcnt(3)
	v_bfe_u32 v0, v30, 16, 1
	v_add3_u32 v0, v30, v0, s20
	s_waitcnt lgkmcnt(2)
	v_bfe_u32 v23, v32, 16, 1
	ds_read2_b32 v[68:69], v65 offset0:166 offset1:174
	v_lshrrev_b32_e32 v0, 16, v0
	v_add3_u32 v23, v32, v23, s20
	ds_read2_b32 v[70:71], v65 offset0:231 offset1:239
	v_and_or_b32 v23, v23, s21, v0
	s_waitcnt lgkmcnt(3)
	v_bfe_u32 v0, v34, 16, 1
	v_add3_u32 v0, v34, v0, s20
	s_waitcnt lgkmcnt(2)
	v_bfe_u32 v24, v66, 16, 1
	v_lshrrev_b32_e32 v0, 16, v0
	v_add3_u32 v24, v66, v24, s20
	v_and_or_b32 v24, v24, s21, v0
	s_waitcnt lgkmcnt(1)
	v_bfe_u32 v0, v68, 16, 1
	v_add3_u32 v0, v68, v0, s20
	s_waitcnt lgkmcnt(0)
	v_bfe_u32 v25, v70, 16, 1
	v_lshrrev_b32_e32 v0, 16, v0
	v_add3_u32 v25, v70, v25, s20
	v_and_or_b32 v25, v25, s21, v0
	v_add_lshl_u32 v0, v41, s10, 13
	v_lshl_add_u64 v[72:73], v[20:21], 0, v[0:1]
	v_bfe_u32 v0, v27, 16, 1
	global_store_dwordx4 v[72:73], v[22:25], off
	v_add3_u32 v0, v27, v0, s20
	v_lshrrev_b32_e32 v0, 16, v0
	v_bfe_u32 v22, v29, 16, 1
	v_add3_u32 v22, v29, v22, s20
	v_and_or_b32 v22, v22, s21, v0
	v_bfe_u32 v0, v31, 16, 1
	v_add3_u32 v0, v31, v0, s20
	v_bfe_u32 v23, v33, 16, 1
	v_lshrrev_b32_e32 v0, 16, v0
	v_add3_u32 v23, v33, v23, s20
	v_and_or_b32 v23, v23, s21, v0
	v_bfe_u32 v0, v35, 16, 1
	v_add3_u32 v0, v35, v0, s20
	v_bfe_u32 v24, v67, 16, 1
	v_lshrrev_b32_e32 v0, 16, v0
	v_add3_u32 v24, v67, v24, s20
	v_and_or_b32 v24, v24, s21, v0
	v_bfe_u32 v0, v69, 16, 1
	v_add3_u32 v0, v69, v0, s20
	v_bfe_u32 v25, v71, 16, 1
	v_lshrrev_b32_e32 v0, 16, v0
	v_add3_u32 v25, v71, v25, s20
	v_and_or_b32 v25, v25, s21, v0
	v_add_lshl_u32 v0, v42, s10, 13
	ds_read2_b32 v[26:27], v37 offset0:48 offset1:56
	v_lshl_add_u64 v[28:29], v[20:21], 0, v[0:1]
	global_store_dwordx4 v[28:29], v[22:25], off
	ds_read2_b32 v[28:29], v37 offset0:113 offset1:121
	ds_read2_b32 v[30:31], v37 offset0:178 offset1:186
	ds_read2_b32 v[32:33], v37 offset0:243 offset1:251
	s_waitcnt lgkmcnt(3)
	v_bfe_u32 v0, v26, 16, 1
	v_add3_u32 v0, v26, v0, s20
	s_waitcnt lgkmcnt(2)
	v_bfe_u32 v22, v28, 16, 1
	ds_read2_b32 v[34:35], v65 offset0:52 offset1:60
	v_lshrrev_b32_e32 v0, 16, v0
	v_add3_u32 v22, v28, v22, s20
	ds_read2_b32 v[66:67], v65 offset0:117 offset1:125
	v_and_or_b32 v22, v22, s21, v0
	s_waitcnt lgkmcnt(3)
	v_bfe_u32 v0, v30, 16, 1
	v_add3_u32 v0, v30, v0, s20
	s_waitcnt lgkmcnt(2)
	v_bfe_u32 v23, v32, 16, 1
	ds_read2_b32 v[68:69], v65 offset0:182 offset1:190
	v_lshrrev_b32_e32 v0, 16, v0
	v_add3_u32 v23, v32, v23, s20
	ds_read2_b32 v[70:71], v65 offset0:247 offset1:255
	v_and_or_b32 v23, v23, s21, v0
	s_waitcnt lgkmcnt(3)
	v_bfe_u32 v0, v34, 16, 1
	v_add3_u32 v0, v34, v0, s20
	s_waitcnt lgkmcnt(2)
	v_bfe_u32 v24, v66, 16, 1
	v_lshrrev_b32_e32 v0, 16, v0
	v_add3_u32 v24, v66, v24, s20
	v_and_or_b32 v24, v24, s21, v0
	s_waitcnt lgkmcnt(1)
	v_bfe_u32 v0, v68, 16, 1
	v_add3_u32 v0, v68, v0, s20
	s_waitcnt lgkmcnt(0)
	v_bfe_u32 v25, v70, 16, 1
	v_lshrrev_b32_e32 v0, 16, v0
	v_add3_u32 v25, v70, v25, s20
	v_and_or_b32 v25, v25, s21, v0
	v_add_lshl_u32 v0, v43, s10, 13
	v_lshl_add_u64 v[72:73], v[20:21], 0, v[0:1]
	v_bfe_u32 v0, v27, 16, 1
	global_store_dwordx4 v[72:73], v[22:25], off
	v_add3_u32 v0, v27, v0, s20
	v_lshrrev_b32_e32 v0, 16, v0
	v_bfe_u32 v22, v29, 16, 1
	v_add3_u32 v22, v29, v22, s20
	v_and_or_b32 v22, v22, s21, v0
	v_bfe_u32 v0, v31, 16, 1
	v_add3_u32 v0, v31, v0, s20
	v_bfe_u32 v23, v33, 16, 1
	v_lshrrev_b32_e32 v0, 16, v0
	v_add3_u32 v23, v33, v23, s20
	v_and_or_b32 v23, v23, s21, v0
	v_bfe_u32 v0, v35, 16, 1
	v_add3_u32 v0, v35, v0, s20
	v_bfe_u32 v24, v67, 16, 1
	v_lshrrev_b32_e32 v0, 16, v0
	v_add3_u32 v24, v67, v24, s20
	v_and_or_b32 v24, v24, s21, v0
	v_bfe_u32 v0, v69, 16, 1
	v_add3_u32 v0, v69, v0, s20
	v_bfe_u32 v25, v71, 16, 1
	v_lshrrev_b32_e32 v0, 16, v0
	v_add3_u32 v25, v71, v25, s20
	v_and_or_b32 v25, v25, s21, v0
	v_add_lshl_u32 v0, v44, s10, 13
	v_lshl_add_u64 v[20:21], v[20:21], 0, v[0:1]
	global_store_dwordx4 v[20:21], v[22:25], off
	s_waitcnt lgkmcnt(0)
	s_mov_b64 s[10:11], 0

; #define LAS __attribute__((address_space(3)))
; #define GAS __attribute__((address_space(1)))
; #define LDS_WAIT() asm volatile("s_waitcnt lgkmcnt(0)" ::: "memory")
; __device__ __forceinline__ void transpose_item(const float* W, int ldw, int src_col0, bf16_t* WT, int Kd, int dst_row0, int k0, float scale, LAS float* scr, int lane) {
;     const int kr = lane >> 4, c4 = lane & 15;
; #pragma unroll 8
;     for (int i = 0; i < 16; ++i) { const int kk = 4 * i + kr; const f32x4 v = __builtin_nontemporal_load((const GAS f32x4*)(W + (size_t)(k0 + kk) * ldw + src_col0 + 4 * c4)) * scale;
;         LAS float* d = scr + kk * 65 + 4 * c4; d[0] = v.x; d[1] = v.y; d[2] = v.z; d[3] = v.w; }
;     LDS_WAIT(); asm volatile("" ::: "memory");
; template <int PART> __device__ __forceinline__ void phase_convert(Frame& F) {
;     ...
;         if (r < I_1) { const int nblk = DFF / 64, kb = r / nblk, nb = r % nblk;
;             transpose_item(F.in[20] + (size_t)l * D * DFF, DFF, nb * 64, W1 + (size_t)l * DFF * D, D, nb * 64, kb * 64, 1.f, scr, F.lane); continue; } r -= I_1;
.LBB0_222:
	v_lshl_add_u64 v[66:67], v[34:35], 0, s[10:11]
	v_lshl_add_u64 v[70:71], v[32:33], 0, s[10:11]
	v_lshl_add_u64 v[74:75], v[30:31], 0, s[10:11]
	v_lshl_add_u64 v[78:79], v[28:29], 0, s[10:11]
	v_lshl_add_u64 v[82:83], v[26:27], 0, s[10:11]
	v_lshl_add_u64 v[86:87], v[24:25], 0, s[10:11]
	v_lshl_add_u64 v[90:91], v[22:23], 0, s[10:11]
	v_lshl_add_u64 v[94:95], v[20:21], 0, s[10:11]
	global_load_dwordx4 v[66:69], v[66:67], off nt
	s_nop 0
	global_load_dwordx4 v[70:73], v[70:71], off nt
	s_nop 0
	global_load_dwordx4 v[74:77], v[74:75], off nt
	s_nop 0
	global_load_dwordx4 v[78:81], v[78:79], off nt
	s_nop 0
	global_load_dwordx4 v[82:85], v[82:83], off nt
	s_nop 0
	global_load_dwordx4 v[86:89], v[86:87], off nt
	s_nop 0
	global_load_dwordx4 v[90:93], v[90:91], off nt
	s_nop 0
	global_load_dwordx4 v[94:97], v[94:95], off nt
	s_add_u32 s10, s10, 0x80000
	s_addc_u32 s11, s11, 0
	v_lshl_add_u64 v[182:183], v[34:35], 0, s[10:11]
	v_lshl_add_u64 v[186:187], v[32:33], 0, s[10:11]
	v_lshl_add_u64 v[190:191], v[30:31], 0, s[10:11]
	v_lshl_add_u64 v[194:195], v[28:29], 0, s[10:11]
	v_lshl_add_u64 v[198:199], v[26:27], 0, s[10:11]
	v_lshl_add_u64 v[202:203], v[24:25], 0, s[10:11]
	v_lshl_add_u64 v[206:207], v[22:23], 0, s[10:11]
	v_lshl_add_u64 v[210:211], v[20:21], 0, s[10:11]
	global_load_dwordx4 v[182:185], v[182:183], off nt
	s_nop 0
	global_load_dwordx4 v[186:189], v[186:187], off nt
	s_nop 0
	global_load_dwordx4 v[190:193], v[190:191], off nt
	s_nop 0
	global_load_dwordx4 v[194:197], v[194:195], off nt
	s_nop 0
	global_load_dwordx4 v[198:201], v[198:199], off nt
	s_nop 0
	global_load_dwordx4 v[202:205], v[202:203], off nt
	s_nop 0
	global_load_dwordx4 v[206:209], v[206:207], off nt
	s_nop 0
	global_load_dwordx4 v[210:213], v[210:211], off nt
	v_add_u32_e32 v65, 0x410, v0
	v_add_u32_e32 v98, 0x418, v0
	v_add_u32_e32 v99, 0x820, v0
	v_add_u32_e32 v100, 0x828, v0
	v_add_u32_e32 v101, 0xc30, v0
	v_add_u32_e32 v102, 0xc38, v0
	v_add_u32_e32 v103, 0x1040, v0
	v_add_u32_e32 v104, 0x1048, v0
	v_add_u32_e32 v105, 0x1450, v0
	v_add_u32_e32 v106, 0x1458, v0
	v_add_u32_e32 v107, 0x1860, v0
	v_add_u32_e32 v108, 0x1868, v0
	v_add_u32_e32 v109, 0x1c70, v0
	v_add_u32_e32 v110, 0x1c78, v0
	s_waitcnt vmcnt(15)
	ds_write2_b32 v0, v66, v67 offset1:1
	ds_write2_b32 v0, v68, v69 offset0:2 offset1:3
	s_waitcnt vmcnt(14)
	ds_write2_b32 v65, v70, v71 offset1:1
	ds_write2_b32 v98, v72, v73 offset1:1
	s_waitcnt vmcnt(13)
	ds_write2_b32 v99, v74, v75 offset1:1
	ds_write2_b32 v100, v76, v77 offset1:1
	s_waitcnt vmcnt(12)
	ds_write2_b32 v101, v78, v79 offset1:1
	ds_write2_b32 v102, v80, v81 offset1:1
	s_waitcnt vmcnt(11)
	ds_write2_b32 v103, v82, v83 offset1:1
	ds_write2_b32 v104, v84, v85 offset1:1
	s_waitcnt vmcnt(10)
	ds_write2_b32 v105, v86, v87 offset1:1
	ds_write2_b32 v106, v88, v89 offset1:1
	s_waitcnt vmcnt(9)
	ds_write2_b32 v107, v90, v91 offset1:1
	ds_write2_b32 v108, v92, v93 offset1:1
	s_waitcnt vmcnt(8)
	ds_write2_b32 v109, v94, v95 offset1:1
	ds_write2_b32 v110, v96, v97 offset1:1
	v_add_u32_e32 v0, 0x2080, v0
	s_add_u32 s10, s10, 0x80000
	s_addc_u32 s11, s11, 0
	v_add_u32_e32 v65, 0x410, v0
	v_add_u32_e32 v98, 0x418, v0
	v_add_u32_e32 v99, 0x820, v0
	v_add_u32_e32 v100, 0x828, v0
	v_add_u32_e32 v101, 0xc30, v0
	v_add_u32_e32 v102, 0xc38, v0
	v_add_u32_e32 v103, 0x1040, v0
	v_add_u32_e32 v104, 0x1048, v0
	v_add_u32_e32 v105, 0x1450, v0
	v_add_u32_e32 v106, 0x1458, v0
	v_add_u32_e32 v107, 0x1860, v0
	v_add_u32_e32 v108, 0x1868, v0
	v_add_u32_e32 v109, 0x1c70, v0
	v_add_u32_e32 v110, 0x1c78, v0
	s_waitcnt vmcnt(7)
	ds_write2_b32 v0, v182, v183 offset1:1
	ds_write2_b32 v0, v184, v185 offset0:2 offset1:3
	s_waitcnt vmcnt(6)
	ds_write2_b32 v65, v186, v187 offset1:1
	ds_write2_b32 v98, v188, v189 offset1:1
	s_waitcnt vmcnt(5)
	ds_write2_b32 v99, v190, v191 offset1:1
	ds_write2_b32 v100, v192, v193 offset1:1
	s_waitcnt vmcnt(4)
	ds_write2_b32 v101, v194, v195 offset1:1
	ds_write2_b32 v102, v196, v197 offset1:1
	s_waitcnt vmcnt(3)
	ds_write2_b32 v103, v198, v199 offset1:1
	ds_write2_b32 v104, v200, v201 offset1:1
	s_waitcnt vmcnt(2)
	ds_write2_b32 v105, v202, v203 offset1:1
	ds_write2_b32 v106, v204, v205 offset1:1
	s_waitcnt vmcnt(1)
	ds_write2_b32 v107, v206, v207 offset1:1
	ds_write2_b32 v108, v208, v209 offset1:1
	s_waitcnt vmcnt(0)
	ds_write2_b32 v109, v210, v211 offset1:1
	ds_write2_b32 v110, v212, v213 offset1:1
	v_add_u32_e32 v0, 0x2080, v0
	s_waitcnt lgkmcnt(0)
	ds_read2_b32 v[26:27], v37 offset1:8
	ds_read2_b32 v[28:29], v37 offset0:65 offset1:73
	ds_read2_b32 v[30:31], v37 offset0:130 offset1:138
	ds_read2_b32 v[32:33], v37 offset0:195 offset1:203
	v_add_u32_e32 v65, 0x400, v37
	s_waitcnt lgkmcnt(3)
	v_bfe_u32 v0, v26, 16, 1
	v_add3_u32 v0, v26, v0, s20
	s_waitcnt lgkmcnt(2)
	v_bfe_u32 v22, v28, 16, 1
	ds_read2_b32 v[34:35], v65 offset0:4 offset1:12
	v_lshrrev_b32_e32 v0, 16, v0
	v_add3_u32 v22, v28, v22, s20
	ds_read2_b32 v[66:67], v65 offset0:69 offset1:77
	v_and_or_b32 v22, v22, s21, v0
	s_waitcnt lgkmcnt(3)
	v_bfe_u32 v0, v30, 16, 1
	v_add3_u32 v0, v30, v0, s20
	s_waitcnt lgkmcnt(2)
	v_bfe_u32 v23, v32, 16, 1
	ds_read2_b32 v[68:69], v65 offset0:134 offset1:142
	v_lshrrev_b32_e32 v0, 16, v0
	v_add3_u32 v23, v32, v23, s20
	ds_read2_b32 v[70:71], v65 offset0:199 offset1:207
	v_and_or_b32 v23, v23, s21, v0
	s_waitcnt lgkmcnt(3)
	v_bfe_u32 v0, v34, 16, 1
	v_add3_u32 v0, v34, v0, s20
	s_waitcnt lgkmcnt(2)
	v_bfe_u32 v24, v66, 16, 1
	v_lshrrev_b32_e32 v0, 16, v0
	v_add3_u32 v24, v66, v24, s20
	v_and_or_b32 v24, v24, s21, v0
	s_waitcnt lgkmcnt(1)
	v_bfe_u32 v0, v68, 16, 1
	s_lshl_b32 s10, s13, 6
	v_add3_u32 v0, v68, v0, s20
	s_waitcnt lgkmcnt(0)
; #define LAS __attribute__((address_space(3)))
; #define GAS __attribute__((address_space(1)))
; __device__ __forceinline__ unsigned pk2(float lo, float hi) { return f2bf(lo) | (f2bf(hi) << 16); }
; #define LDS_WAIT() asm volatile("s_waitcnt lgkmcnt(0)" ::: "memory")
; __device__ __forceinline__ void transpose_item(const float* W, int ldw, int src_col0, bf16_t* WT, int Kd, int dst_row0, int k0, float scale, LAS float* scr, int lane) {
;     ...
;     const int c = lane & 7;
; #pragma unroll
;     for (int j = 0; j < 8; ++j) { const int n = (lane >> 3) + 8 * j; const LAS float* sp = scr + (8 * c) * 65 + n;
;         u32x4 o; o.x = pk2(sp[0 * 65], sp[1 * 65]); o.y = pk2(sp[2 * 65], sp[3 * 65]); o.z = pk2(sp[4 * 65], sp[5 * 65]); o.w = pk2(sp[6 * 65], sp[7 * 65]);
;         *(GAS u32x4*)(WT + (size_t)(dst_row0 + n) * Kd + k0 + 8 * c) = o; }
;     LDS_WAIT(); asm volatile("" ::: "memory");
	v_bfe_u32 v25, v70, 16, 1
	s_and_b32 s10, s10, 0xfc0
	v_lshrrev_b32_e32 v0, 16, v0
	v_add3_u32 v25, v70, v25, s20
	s_addk_i32 s6, 0xfc00
	v_and_or_b32 v25, v25, s21, v0
	v_or_b32_e32 v0, s10, v36
	v_lshl_add_u64 v[20:21], s[6:7], 1, v[6:7]
	v_lshlrev_b32_e32 v0, 11, v0
	v_lshl_add_u64 v[72:73], v[20:21], 0, v[0:1]
	v_bfe_u32 v0, v27, 16, 1
	global_store_dwordx4 v[72:73], v[22:25], off
	v_add3_u32 v0, v27, v0, s20
	v_lshrrev_b32_e32 v0, 16, v0
	v_bfe_u32 v22, v29, 16, 1
	v_add3_u32 v22, v29, v22, s20
	v_and_or_b32 v22, v22, s21, v0
	v_bfe_u32 v0, v31, 16, 1
	v_add3_u32 v0, v31, v0, s20
	v_bfe_u32 v23, v33, 16, 1
	v_lshrrev_b32_e32 v0, 16, v0
	v_add3_u32 v23, v33, v23, s20
	v_and_or_b32 v23, v23, s21, v0
	v_bfe_u32 v0, v35, 16, 1
	v_add3_u32 v0, v35, v0, s20
	v_bfe_u32 v24, v67, 16, 1
	v_lshrrev_b32_e32 v0, 16, v0
	v_add3_u32 v24, v67, v24, s20
	v_and_or_b32 v24, v24, s21, v0
	v_bfe_u32 v0, v69, 16, 1
	v_add3_u32 v0, v69, v0, s20
	v_bfe_u32 v25, v71, 16, 1
	v_lshrrev_b32_e32 v0, 16, v0
	v_add3_u32 v25, v71, v25, s20
	v_and_or_b32 v25, v25, s21, v0
	v_or_b32_e32 v0, s10, v38
	v_lshlrev_b32_e32 v0, 11, v0
	ds_read2_b32 v[26:27], v37 offset0:16 offset1:24
	v_lshl_add_u64 v[28:29], v[20:21], 0, v[0:1]
	global_store_dwordx4 v[28:29], v[22:25], off
	ds_read2_b32 v[28:29], v37 offset0:81 offset1:89
	ds_read2_b32 v[30:31], v37 offset0:146 offset1:154
	ds_read2_b32 v[32:33], v37 offset0:211 offset1:219
	s_waitcnt lgkmcnt(3)
	v_bfe_u32 v0, v26, 16, 1
	v_add3_u32 v0, v26, v0, s20
	s_waitcnt lgkmcnt(2)
	v_bfe_u32 v22, v28, 16, 1
	ds_read2_b32 v[34:35], v65 offset0:20 offset1:28
	v_lshrrev_b32_e32 v0, 16, v0
	v_add3_u32 v22, v28, v22, s20
	ds_read2_b32 v[66:67], v65 offset0:85 offset1:93
	v_and_or_b32 v22, v22, s21, v0
	s_waitcnt lgkmcnt(3)
	v_bfe_u32 v0, v30, 16, 1
	v_add3_u32 v0, v30, v0, s20
	s_waitcnt lgkmcnt(2)
	v_bfe_u32 v23, v32, 16, 1
	ds_read2_b32 v[68:69], v65 offset0:150 offset1:158
	v_lshrrev_b32_e32 v0, 16, v0
	v_add3_u32 v23, v32, v23, s20
	ds_read2_b32 v[70:71], v65 offset0:215 offset1:223
	v_and_or_b32 v23, v23, s21, v0
	s_waitcnt lgkmcnt(3)
	v_bfe_u32 v0, v34, 16, 1
	v_add3_u32 v0, v34, v0, s20
	s_waitcnt lgkmcnt(2)
	v_bfe_u32 v24, v66, 16, 1
	v_lshrrev_b32_e32 v0, 16, v0
	v_add3_u32 v24, v66, v24, s20
	v_and_or_b32 v24, v24, s21, v0
	s_waitcnt lgkmcnt(1)
	v_bfe_u32 v0, v68, 16, 1
	v_add3_u32 v0, v68, v0, s20
	s_waitcnt lgkmcnt(0)
	v_bfe_u32 v25, v70, 16, 1
	v_lshrrev_b32_e32 v0, 16, v0
	v_add3_u32 v25, v70, v25, s20
	v_and_or_b32 v25, v25, s21, v0
	v_or_b32_e32 v0, s10, v39
	v_lshlrev_b32_e32 v0, 11, v0
	v_lshl_add_u64 v[72:73], v[20:21], 0, v[0:1]
	v_bfe_u32 v0, v27, 16, 1
	global_store_dwordx4 v[72:73], v[22:25], off
	v_add3_u32 v0, v27, v0, s20
	v_lshrrev_b32_e32 v0, 16, v0
	v_bfe_u32 v22, v29, 16, 1
	v_add3_u32 v22, v29, v22, s20
	v_and_or_b32 v22, v22, s21, v0
	v_bfe_u32 v0, v31, 16, 1
	v_add3_u32 v0, v31, v0, s20
	v_bfe_u32 v23, v33, 16, 1
	v_lshrrev_b32_e32 v0, 16, v0
	v_add3_u32 v23, v33, v23, s20
	v_and_or_b32 v23, v23, s21, v0
	v_bfe_u32 v0, v35, 16, 1
	v_add3_u32 v0, v35, v0, s20
	v_bfe_u32 v24, v67, 16, 1
	v_lshrrev_b32_e32 v0, 16, v0
	v_add3_u32 v24, v67, v24, s20
	v_and_or_b32 v24, v24, s21, v0
	v_bfe_u32 v0, v69, 16, 1
	v_add3_u32 v0, v69, v0, s20
	v_bfe_u32 v25, v71, 16, 1
	v_lshrrev_b32_e32 v0, 16, v0
	v_add3_u32 v25, v71, v25, s20
	v_and_or_b32 v25, v25, s21, v0
	v_or_b32_e32 v0, s10, v40
	v_lshlrev_b32_e32 v0, 11, v0
	ds_read2_b32 v[26:27], v37 offset0:32 offset1:40
	v_lshl_add_u64 v[28:29], v[20:21], 0, v[0:1]
	global_store_dwordx4 v[28:29], v[22:25], off
	ds_read2_b32 v[28:29], v37 offset0:97 offset1:105
	ds_read2_b32 v[30:31], v37 offset0:162 offset1:170
	ds_read2_b32 v[32:33], v37 offset0:227 offset1:235
	s_waitcnt lgkmcnt(3)
	v_bfe_u32 v0, v26, 16, 1
	v_add3_u32 v0, v26, v0, s20
	s_waitcnt lgkmcnt(2)
	v_bfe_u32 v22, v28, 16, 1
	ds_read2_b32 v[34:35], v65 offset0:36 offset1:44
	v_lshrrev_b32_e32 v0, 16, v0
	v_add3_u32 v22, v28, v22, s20
	ds_read2_b32 v[66:67], v65 offset0:101 offset1:109
	v_and_or_b32 v22, v22, s21, v0
	s_waitcnt lgkmcnt(3)
; #define LAS __attribute__((address_space(3)))
; #define GAS __attribute__((address_space(1)))
; __device__ __forceinline__ unsigned pk2(float lo, float hi) { return f2bf(lo) | (f2bf(hi) << 16); }
; #define LDS_WAIT() asm volatile("s_waitcnt lgkmcnt(0)" ::: "memory")
; __device__ __forceinline__ void transpose_item(const float* W, int ldw, int src_col0, bf16_t* WT, int Kd, int dst_row0, int k0, float scale, LAS float* scr, int lane) {
;     ...
;     const int c = lane & 7;
; #pragma unroll
;     for (int j = 0; j < 8; ++j) { const int n = (lane >> 3) + 8 * j; const LAS float* sp = scr + (8 * c) * 65 + n;
;         u32x4 o; o.x = pk2(sp[0 * 65], sp[1 * 65]); o.y = pk2(sp[2 * 65], sp[3 * 65]); o.z = pk2(sp[4 * 65], sp[5 * 65]); o.w = pk2(sp[6 * 65], sp[7 * 65]);
;         *(GAS u32x4*)(WT + (size_t)(dst_row0 + n) * Kd + k0 + 8 * c) = o; }
;     LDS_WAIT(); asm volatile("" ::: "memory");
	v_bfe_u32 v0, v30, 16, 1
	v_add3_u32 v0, v30, v0, s20
	s_waitcnt lgkmcnt(2)
	v_bfe_u32 v23, v32, 16, 1
	ds_read2_b32 v[68:69], v65 offset0:166 offset1:174
	v_lshrrev_b32_e32 v0, 16, v0
	v_add3_u32 v23, v32, v23, s20
	ds_read2_b32 v[70:71], v65 offset0:231 offset1:239
	v_and_or_b32 v23, v23, s21, v0
	s_waitcnt lgkmcnt(3)
	v_bfe_u32 v0, v34, 16, 1
	v_add3_u32 v0, v34, v0, s20
	s_waitcnt lgkmcnt(2)
	v_bfe_u32 v24, v66, 16, 1
	v_lshrrev_b32_e32 v0, 16, v0
	v_add3_u32 v24, v66, v24, s20
	v_and_or_b32 v24, v24, s21, v0
	s_waitcnt lgkmcnt(1)
	v_bfe_u32 v0, v68, 16, 1
	v_add3_u32 v0, v68, v0, s20
	s_waitcnt lgkmcnt(0)
	v_bfe_u32 v25, v70, 16, 1
	v_lshrrev_b32_e32 v0, 16, v0
	v_add3_u32 v25, v70, v25, s20
	v_and_or_b32 v25, v25, s21, v0
	v_or_b32_e32 v0, s10, v41
	v_lshlrev_b32_e32 v0, 11, v0
	v_lshl_add_u64 v[72:73], v[20:21], 0, v[0:1]
	v_bfe_u32 v0, v27, 16, 1
	global_store_dwordx4 v[72:73], v[22:25], off
	v_add3_u32 v0, v27, v0, s20
	v_lshrrev_b32_e32 v0, 16, v0
	v_bfe_u32 v22, v29, 16, 1
	v_add3_u32 v22, v29, v22, s20
	v_and_or_b32 v22, v22, s21, v0
	v_bfe_u32 v0, v31, 16, 1
	v_add3_u32 v0, v31, v0, s20
	v_bfe_u32 v23, v33, 16, 1
	v_lshrrev_b32_e32 v0, 16, v0
	v_add3_u32 v23, v33, v23, s20
	v_and_or_b32 v23, v23, s21, v0
	v_bfe_u32 v0, v35, 16, 1
	v_add3_u32 v0, v35, v0, s20
	v_bfe_u32 v24, v67, 16, 1
	v_lshrrev_b32_e32 v0, 16, v0
	v_add3_u32 v24, v67, v24, s20
	v_and_or_b32 v24, v24, s21, v0
	v_bfe_u32 v0, v69, 16, 1
	v_add3_u32 v0, v69, v0, s20
	v_bfe_u32 v25, v71, 16, 1
	v_lshrrev_b32_e32 v0, 16, v0
	v_add3_u32 v25, v71, v25, s20
	v_and_or_b32 v25, v25, s21, v0
	v_or_b32_e32 v0, s10, v42
	v_lshlrev_b32_e32 v0, 11, v0
	ds_read2_b32 v[26:27], v37 offset0:48 offset1:56
	v_lshl_add_u64 v[28:29], v[20:21], 0, v[0:1]
	global_store_dwordx4 v[28:29], v[22:25], off
	ds_read2_b32 v[28:29], v37 offset0:113 offset1:121
	ds_read2_b32 v[30:31], v37 offset0:178 offset1:186
	ds_read2_b32 v[32:33], v37 offset0:243 offset1:251
	s_waitcnt lgkmcnt(3)
	v_bfe_u32 v0, v26, 16, 1
	v_add3_u32 v0, v26, v0, s20
	s_waitcnt lgkmcnt(2)
	v_bfe_u32 v22, v28, 16, 1
	ds_read2_b32 v[34:35], v65 offset0:52 offset1:60
	v_lshrrev_b32_e32 v0, 16, v0
	v_add3_u32 v22, v28, v22, s20
	ds_read2_b32 v[66:67], v65 offset0:117 offset1:125
	v_and_or_b32 v22, v22, s21, v0
	s_waitcnt lgkmcnt(3)
	v_bfe_u32 v0, v30, 16, 1
	v_add3_u32 v0, v30, v0, s20
	s_waitcnt lgkmcnt(2)
	v_bfe_u32 v23, v32, 16, 1
	ds_read2_b32 v[68:69], v65 offset0:182 offset1:190
	v_lshrrev_b32_e32 v0, 16, v0
	v_add3_u32 v23, v32, v23, s20
	ds_read2_b32 v[70:71], v65 offset0:247 offset1:255
	v_and_or_b32 v23, v23, s21, v0
	s_waitcnt lgkmcnt(3)
	v_bfe_u32 v0, v34, 16, 1
	v_add3_u32 v0, v34, v0, s20
	s_waitcnt lgkmcnt(2)
	v_bfe_u32 v24, v66, 16, 1
	v_lshrrev_b32_e32 v0, 16, v0
	v_add3_u32 v24, v66, v24, s20
	v_and_or_b32 v24, v24, s21, v0
	s_waitcnt lgkmcnt(1)
	v_bfe_u32 v0, v68, 16, 1
	v_add3_u32 v0, v68, v0, s20
	s_waitcnt lgkmcnt(0)
	v_bfe_u32 v25, v70, 16, 1
	v_lshrrev_b32_e32 v0, 16, v0
	v_add3_u32 v25, v70, v25, s20
	v_and_or_b32 v25, v25, s21, v0
	v_or_b32_e32 v0, s10, v43
	v_lshlrev_b32_e32 v0, 11, v0
	v_lshl_add_u64 v[72:73], v[20:21], 0, v[0:1]
	v_bfe_u32 v0, v27, 16, 1
	global_store_dwordx4 v[72:73], v[22:25], off
	v_add3_u32 v0, v27, v0, s20
	v_lshrrev_b32_e32 v0, 16, v0
	v_bfe_u32 v22, v29, 16, 1
	v_add3_u32 v22, v29, v22, s20
	v_and_or_b32 v22, v22, s21, v0
	v_bfe_u32 v0, v31, 16, 1
	v_add3_u32 v0, v31, v0, s20
	v_bfe_u32 v23, v33, 16, 1
	v_lshrrev_b32_e32 v0, 16, v0
	v_add3_u32 v23, v33, v23, s20
	v_and_or_b32 v23, v23, s21, v0
	v_bfe_u32 v0, v35, 16, 1
	v_add3_u32 v0, v35, v0, s20
	v_bfe_u32 v24, v67, 16, 1
	v_lshrrev_b32_e32 v0, 16, v0
	v_add3_u32 v24, v67, v24, s20
	v_and_or_b32 v24, v24, s21, v0
	v_bfe_u32 v0, v69, 16, 1
	v_add3_u32 v0, v69, v0, s20
	v_bfe_u32 v25, v71, 16, 1
	v_lshrrev_b32_e32 v0, 16, v0
	v_add3_u32 v25, v71, v25, s20
	v_and_or_b32 v25, v25, s21, v0
	v_add_lshl_u32 v0, v44, s10, 11
	v_lshl_add_u64 v[20:21], v[20:21], 0, v[0:1]
	global_store_dwordx4 v[20:21], v[22:25], off
	s_waitcnt lgkmcnt(0)

; #define LAS __attribute__((address_space(3)))
; #define GAS __attribute__((address_space(1)))
; #define LDS_WAIT() asm volatile("s_waitcnt lgkmcnt(0)" ::: "memory")
; __device__ __forceinline__ void transpose_item(const float* W, int ldw, int src_col0, bf16_t* WT, int Kd, int dst_row0, int k0, float scale, LAS float* scr, int lane) {
;     const int kr = lane >> 4, c4 = lane & 15;
; #pragma unroll 8
;     for (int i = 0; i < 16; ++i) { const int kk = 4 * i + kr; const f32x4 v = __builtin_nontemporal_load((const GAS f32x4*)(W + (size_t)(k0 + kk) * ldw + src_col0 + 4 * c4)) * scale;
;         LAS float* d = scr + kk * 65 + 4 * c4; d[0] = v.x; d[1] = v.y; d[2] = v.z; d[3] = v.w; }
;     LDS_WAIT(); asm volatile("" ::: "memory");
; template <int PART> __device__ __forceinline__ void phase_convert(Frame& F) {
;     ...
;             if (r < I_OUT) { const int nblk = D / 64, kb = r / nblk, nb = r % nblk; transpose_item(F.in[19], D, nb * 64, WOUT, D, nb * 64, kb * 64, 1.f, scr, F.lane); continue; } r -= I_OUT;
.LBB0_227:
	v_lshl_add_u64 v[66:67], v[34:35], 0, s[10:11]
	v_lshl_add_u64 v[70:71], v[32:33], 0, s[10:11]
	v_lshl_add_u64 v[74:75], v[30:31], 0, s[10:11]
	v_lshl_add_u64 v[78:79], v[28:29], 0, s[10:11]
	v_lshl_add_u64 v[82:83], v[26:27], 0, s[10:11]
	v_lshl_add_u64 v[86:87], v[24:25], 0, s[10:11]
	v_lshl_add_u64 v[90:91], v[22:23], 0, s[10:11]
	v_lshl_add_u64 v[94:95], v[20:21], 0, s[10:11]
	global_load_dwordx4 v[66:69], v[66:67], off nt
	s_nop 0
	global_load_dwordx4 v[70:73], v[70:71], off nt
	s_nop 0
	global_load_dwordx4 v[74:77], v[74:75], off nt
	s_nop 0
	global_load_dwordx4 v[78:81], v[78:79], off nt
	s_nop 0
	global_load_dwordx4 v[82:85], v[82:83], off nt
	s_nop 0
	global_load_dwordx4 v[86:89], v[86:87], off nt
	s_nop 0
	global_load_dwordx4 v[90:93], v[90:91], off nt
	s_nop 0
	global_load_dwordx4 v[94:97], v[94:95], off nt
	s_add_u32 s10, s10, 0x20000
	s_addc_u32 s11, s11, 0
	v_lshl_add_u64 v[182:183], v[34:35], 0, s[10:11]
	v_lshl_add_u64 v[186:187], v[32:33], 0, s[10:11]
	v_lshl_add_u64 v[190:191], v[30:31], 0, s[10:11]
	v_lshl_add_u64 v[194:195], v[28:29], 0, s[10:11]
	v_lshl_add_u64 v[198:199], v[26:27], 0, s[10:11]
	v_lshl_add_u64 v[202:203], v[24:25], 0, s[10:11]
	v_lshl_add_u64 v[206:207], v[22:23], 0, s[10:11]
	v_lshl_add_u64 v[210:211], v[20:21], 0, s[10:11]
	global_load_dwordx4 v[182:185], v[182:183], off nt
	s_nop 0
	global_load_dwordx4 v[186:189], v[186:187], off nt
	s_nop 0
	global_load_dwordx4 v[190:193], v[190:191], off nt
	s_nop 0
	global_load_dwordx4 v[194:197], v[194:195], off nt
	s_nop 0
	global_load_dwordx4 v[198:201], v[198:199], off nt
	s_nop 0
	global_load_dwordx4 v[202:205], v[202:203], off nt
	s_nop 0
	global_load_dwordx4 v[206:209], v[206:207], off nt
	s_nop 0
	global_load_dwordx4 v[210:213], v[210:211], off nt
	v_add_u32_e32 v65, 0x410, v0
	v_add_u32_e32 v98, 0x418, v0
	v_add_u32_e32 v99, 0x820, v0
	v_add_u32_e32 v100, 0x828, v0
	v_add_u32_e32 v101, 0xc30, v0
	v_add_u32_e32 v102, 0xc38, v0
	v_add_u32_e32 v103, 0x1040, v0
	v_add_u32_e32 v104, 0x1048, v0
	v_add_u32_e32 v105, 0x1450, v0
	v_add_u32_e32 v106, 0x1458, v0
	v_add_u32_e32 v107, 0x1860, v0
	v_add_u32_e32 v108, 0x1868, v0
	v_add_u32_e32 v109, 0x1c70, v0
	v_add_u32_e32 v110, 0x1c78, v0
	s_waitcnt vmcnt(15)
	ds_write2_b32 v0, v66, v67 offset1:1
	ds_write2_b32 v0, v68, v69 offset0:2 offset1:3
	s_waitcnt vmcnt(14)
	ds_write2_b32 v65, v70, v71 offset1:1
	ds_write2_b32 v98, v72, v73 offset1:1
	s_waitcnt vmcnt(13)
	ds_write2_b32 v99, v74, v75 offset1:1
	ds_write2_b32 v100, v76, v77 offset1:1
	s_waitcnt vmcnt(12)
	ds_write2_b32 v101, v78, v79 offset1:1
	ds_write2_b32 v102, v80, v81 offset1:1
	s_waitcnt vmcnt(11)
	ds_write2_b32 v103, v82, v83 offset1:1
	ds_write2_b32 v104, v84, v85 offset1:1
	s_waitcnt vmcnt(10)
	ds_write2_b32 v105, v86, v87 offset1:1
	ds_write2_b32 v106, v88, v89 offset1:1
	s_waitcnt vmcnt(9)
	ds_write2_b32 v107, v90, v91 offset1:1
	ds_write2_b32 v108, v92, v93 offset1:1
	s_waitcnt vmcnt(8)
	ds_write2_b32 v109, v94, v95 offset1:1
	ds_write2_b32 v110, v96, v97 offset1:1
	v_add_u32_e32 v0, 0x2080, v0
	s_add_u32 s10, s10, 0x20000
	s_addc_u32 s11, s11, 0
	v_add_u32_e32 v65, 0x410, v0
	v_add_u32_e32 v98, 0x418, v0
	v_add_u32_e32 v99, 0x820, v0
	v_add_u32_e32 v100, 0x828, v0
	v_add_u32_e32 v101, 0xc30, v0
	v_add_u32_e32 v102, 0xc38, v0
	v_add_u32_e32 v103, 0x1040, v0
	v_add_u32_e32 v104, 0x1048, v0
	v_add_u32_e32 v105, 0x1450, v0
	v_add_u32_e32 v106, 0x1458, v0
	v_add_u32_e32 v107, 0x1860, v0
	v_add_u32_e32 v108, 0x1868, v0
	v_add_u32_e32 v109, 0x1c70, v0
	v_add_u32_e32 v110, 0x1c78, v0
	s_waitcnt vmcnt(7)
	ds_write2_b32 v0, v182, v183 offset1:1
	ds_write2_b32 v0, v184, v185 offset0:2 offset1:3
	s_waitcnt vmcnt(6)
	ds_write2_b32 v65, v186, v187 offset1:1
	ds_write2_b32 v98, v188, v189 offset1:1
	s_waitcnt vmcnt(5)
	ds_write2_b32 v99, v190, v191 offset1:1
	ds_write2_b32 v100, v192, v193 offset1:1
	s_waitcnt vmcnt(4)
	ds_write2_b32 v101, v194, v195 offset1:1
	ds_write2_b32 v102, v196, v197 offset1:1
	s_waitcnt vmcnt(3)
	ds_write2_b32 v103, v198, v199 offset1:1
	ds_write2_b32 v104, v200, v201 offset1:1
	s_waitcnt vmcnt(2)
	ds_write2_b32 v105, v202, v203 offset1:1
	ds_write2_b32 v106, v204, v205 offset1:1
	s_waitcnt vmcnt(1)
	ds_write2_b32 v107, v206, v207 offset1:1
	ds_write2_b32 v108, v208, v209 offset1:1
	s_waitcnt vmcnt(0)
	ds_write2_b32 v109, v210, v211 offset1:1
	ds_write2_b32 v110, v212, v213 offset1:1
	v_add_u32_e32 v0, 0x2080, v0
	s_waitcnt lgkmcnt(0)
	ds_read2_b32 v[26:27], v37 offset1:8
	ds_read2_b32 v[28:29], v37 offset0:65 offset1:73
	ds_read2_b32 v[30:31], v37 offset0:130 offset1:138
	ds_read2_b32 v[32:33], v37 offset0:195 offset1:203
	v_add_u32_e32 v65, 0x400, v37
	s_waitcnt lgkmcnt(3)
	v_bfe_u32 v0, v26, 16, 1
	v_add3_u32 v0, v26, v0, s20
	s_waitcnt lgkmcnt(2)
	v_bfe_u32 v22, v28, 16, 1
	ds_read2_b32 v[34:35], v65 offset0:4 offset1:12
	v_lshrrev_b32_e32 v0, 16, v0
	v_add3_u32 v22, v28, v22, s20
	ds_read2_b32 v[66:67], v65 offset0:69 offset1:77
	v_and_or_b32 v22, v22, s21, v0
	s_waitcnt lgkmcnt(3)
	v_bfe_u32 v0, v30, 16, 1
	v_add3_u32 v0, v30, v0, s20
	s_waitcnt lgkmcnt(2)
	v_bfe_u32 v23, v32, 16, 1
	ds_read2_b32 v[68:69], v65 offset0:134 offset1:142
	v_lshrrev_b32_e32 v0, 16, v0
	v_add3_u32 v23, v32, v23, s20
	ds_read2_b32 v[70:71], v65 offset0:199 offset1:207
	v_and_or_b32 v23, v23, s21, v0
	s_waitcnt lgkmcnt(3)
	v_bfe_u32 v0, v34, 16, 1
	v_add3_u32 v0, v34, v0, s20
	s_waitcnt lgkmcnt(2)
	v_bfe_u32 v24, v66, 16, 1
	v_lshrrev_b32_e32 v0, 16, v0
	v_add3_u32 v24, v66, v24, s20
	s_lshl_b32 s6, s13, 6
	v_and_or_b32 v24, v24, s21, v0
	s_waitcnt lgkmcnt(1)
	v_bfe_u32 v0, v68, 16, 1
	s_and_b32 s10, s6, 0x3c0
	s_lshl_b32 s6, s13, 2
	v_add3_u32 v0, v68, v0, s20
	s_waitcnt lgkmcnt(0)
; #define LAS __attribute__((address_space(3)))
; #define GAS __attribute__((address_space(1)))
; __device__ __forceinline__ unsigned pk2(float lo, float hi) { return f2bf(lo) | (f2bf(hi) << 16); }
; #define LDS_WAIT() asm volatile("s_waitcnt lgkmcnt(0)" ::: "memory")
; __device__ __forceinline__ void transpose_item(const float* W, int ldw, int src_col0, bf16_t* WT, int Kd, int dst_row0, int k0, float scale, LAS float* scr, int lane) {
;     ...
;     const int c = lane & 7;
; #pragma unroll
;     for (int j = 0; j < 8; ++j) { const int n = (lane >> 3) + 8 * j; const LAS float* sp = scr + (8 * c) * 65 + n;
;         u32x4 o; o.x = pk2(sp[0 * 65], sp[1 * 65]); o.y = pk2(sp[2 * 65], sp[3 * 65]); o.z = pk2(sp[4 * 65], sp[5 * 65]); o.w = pk2(sp[6 * 65], sp[7 * 65]);
;         *(GAS u32x4*)(WT + (size_t)(dst_row0 + n) * Kd + k0 + 8 * c) = o; }
;     LDS_WAIT(); asm volatile("" ::: "memory");
	v_bfe_u32 v25, v70, 16, 1
	s_and_b32 s6, s6, 0xfc0
	v_lshrrev_b32_e32 v0, 16, v0
	v_add3_u32 v25, v70, v25, s20
	s_addk_i32 s6, 0xf400
	v_and_or_b32 v25, v25, s21, v0
	v_or_b32_e32 v0, s10, v36
	v_lshl_add_u64 v[20:21], s[6:7], 1, v[8:9]
	v_lshlrev_b32_e32 v0, 11, v0
	v_lshl_add_u64 v[72:73], v[20:21], 0, v[0:1]
	v_bfe_u32 v0, v27, 16, 1
	global_store_dwordx4 v[72:73], v[22:25], off
	v_add3_u32 v0, v27, v0, s20
	v_lshrrev_b32_e32 v0, 16, v0
	v_bfe_u32 v22, v29, 16, 1
	v_add3_u32 v22, v29, v22, s20
	v_and_or_b32 v22, v22, s21, v0
	v_bfe_u32 v0, v31, 16, 1
	v_add3_u32 v0, v31, v0, s20
	v_bfe_u32 v23, v33, 16, 1
	v_lshrrev_b32_e32 v0, 16, v0
	v_add3_u32 v23, v33, v23, s20
	v_and_or_b32 v23, v23, s21, v0
	v_bfe_u32 v0, v35, 16, 1
	v_add3_u32 v0, v35, v0, s20
	v_bfe_u32 v24, v67, 16, 1
	v_lshrrev_b32_e32 v0, 16, v0
	v_add3_u32 v24, v67, v24, s20
	v_and_or_b32 v24, v24, s21, v0
	v_bfe_u32 v0, v69, 16, 1
	v_add3_u32 v0, v69, v0, s20
	v_bfe_u32 v25, v71, 16, 1
	v_lshrrev_b32_e32 v0, 16, v0
	v_add3_u32 v25, v71, v25, s20
	v_and_or_b32 v25, v25, s21, v0
	v_or_b32_e32 v0, s10, v38
	v_lshlrev_b32_e32 v0, 11, v0
	ds_read2_b32 v[26:27], v37 offset0:16 offset1:24
	v_lshl_add_u64 v[28:29], v[20:21], 0, v[0:1]
	global_store_dwordx4 v[28:29], v[22:25], off
	ds_read2_b32 v[28:29], v37 offset0:81 offset1:89
	ds_read2_b32 v[30:31], v37 offset0:146 offset1:154
	ds_read2_b32 v[32:33], v37 offset0:211 offset1:219
	s_waitcnt lgkmcnt(3)
	v_bfe_u32 v0, v26, 16, 1
	v_add3_u32 v0, v26, v0, s20
	s_waitcnt lgkmcnt(2)
	v_bfe_u32 v22, v28, 16, 1
	ds_read2_b32 v[34:35], v65 offset0:20 offset1:28
	v_lshrrev_b32_e32 v0, 16, v0
	v_add3_u32 v22, v28, v22, s20
	ds_read2_b32 v[66:67], v65 offset0:85 offset1:93
	v_and_or_b32 v22, v22, s21, v0
	s_waitcnt lgkmcnt(3)
	v_bfe_u32 v0, v30, 16, 1
	v_add3_u32 v0, v30, v0, s20
	s_waitcnt lgkmcnt(2)
	v_bfe_u32 v23, v32, 16, 1
	ds_read2_b32 v[68:69], v65 offset0:150 offset1:158
	v_lshrrev_b32_e32 v0, 16, v0
	v_add3_u32 v23, v32, v23, s20
	ds_read2_b32 v[70:71], v65 offset0:215 offset1:223
	v_and_or_b32 v23, v23, s21, v0
	s_waitcnt lgkmcnt(3)
	v_bfe_u32 v0, v34, 16, 1
	v_add3_u32 v0, v34, v0, s20
	s_waitcnt lgkmcnt(2)
	v_bfe_u32 v24, v66, 16, 1
	v_lshrrev_b32_e32 v0, 16, v0
	v_add3_u32 v24, v66, v24, s20
	v_and_or_b32 v24, v24, s21, v0
	s_waitcnt lgkmcnt(1)
	v_bfe_u32 v0, v68, 16, 1
	v_add3_u32 v0, v68, v0, s20
	s_waitcnt lgkmcnt(0)
	v_bfe_u32 v25, v70, 16, 1
	v_lshrrev_b32_e32 v0, 16, v0
	v_add3_u32 v25, v70, v25, s20
	v_and_or_b32 v25, v25, s21, v0
	v_or_b32_e32 v0, s10, v39
	v_lshlrev_b32_e32 v0, 11, v0
	v_lshl_add_u64 v[72:73], v[20:21], 0, v[0:1]
	v_bfe_u32 v0, v27, 16, 1
	global_store_dwordx4 v[72:73], v[22:25], off
	v_add3_u32 v0, v27, v0, s20
	v_lshrrev_b32_e32 v0, 16, v0
	v_bfe_u32 v22, v29, 16, 1
	v_add3_u32 v22, v29, v22, s20
	v_and_or_b32 v22, v22, s21, v0
	v_bfe_u32 v0, v31, 16, 1
	v_add3_u32 v0, v31, v0, s20
	v_bfe_u32 v23, v33, 16, 1
	v_lshrrev_b32_e32 v0, 16, v0
	v_add3_u32 v23, v33, v23, s20
	v_and_or_b32 v23, v23, s21, v0
	v_bfe_u32 v0, v35, 16, 1
	v_add3_u32 v0, v35, v0, s20
	v_bfe_u32 v24, v67, 16, 1
	v_lshrrev_b32_e32 v0, 16, v0
	v_add3_u32 v24, v67, v24, s20
	v_and_or_b32 v24, v24, s21, v0
	v_bfe_u32 v0, v69, 16, 1
	v_add3_u32 v0, v69, v0, s20
	v_bfe_u32 v25, v71, 16, 1
	v_lshrrev_b32_e32 v0, 16, v0
	v_add3_u32 v25, v71, v25, s20
	v_and_or_b32 v25, v25, s21, v0
	v_or_b32_e32 v0, s10, v40
	v_lshlrev_b32_e32 v0, 11, v0
	ds_read2_b32 v[26:27], v37 offset0:32 offset1:40
	v_lshl_add_u64 v[28:29], v[20:21], 0, v[0:1]
	global_store_dwordx4 v[28:29], v[22:25], off
	ds_read2_b32 v[28:29], v37 offset0:97 offset1:105
	ds_read2_b32 v[30:31], v37 offset0:162 offset1:170
	ds_read2_b32 v[32:33], v37 offset0:227 offset1:235
	s_waitcnt lgkmcnt(3)
	v_bfe_u32 v0, v26, 16, 1
	v_add3_u32 v0, v26, v0, s20
	s_waitcnt lgkmcnt(2)
	v_bfe_u32 v22, v28, 16, 1
	ds_read2_b32 v[34:35], v65 offset0:36 offset1:44
	v_lshrrev_b32_e32 v0, 16, v0
	v_add3_u32 v22, v28, v22, s20
	ds_read2_b32 v[66:67], v65 offset0:101 offset1:109
	v_and_or_b32 v22, v22, s21, v0
	s_waitcnt lgkmcnt(3)
; #define LAS __attribute__((address_space(3)))
; #define GAS __attribute__((address_space(1)))
; __device__ __forceinline__ unsigned pk2(float lo, float hi) { return f2bf(lo) | (f2bf(hi) << 16); }
; #define LDS_WAIT() asm volatile("s_waitcnt lgkmcnt(0)" ::: "memory")
; __device__ __forceinline__ void transpose_item(const float* W, int ldw, int src_col0, bf16_t* WT, int Kd, int dst_row0, int k0, float scale, LAS float* scr, int lane) {
;     ...
;     const int c = lane & 7;
; #pragma unroll
;     for (int j = 0; j < 8; ++j) { const int n = (lane >> 3) + 8 * j; const LAS float* sp = scr + (8 * c) * 65 + n;
;         u32x4 o; o.x = pk2(sp[0 * 65], sp[1 * 65]); o.y = pk2(sp[2 * 65], sp[3 * 65]); o.z = pk2(sp[4 * 65], sp[5 * 65]); o.w = pk2(sp[6 * 65], sp[7 * 65]);
;         *(GAS u32x4*)(WT + (size_t)(dst_row0 + n) * Kd + k0 + 8 * c) = o; }
;     LDS_WAIT(); asm volatile("" ::: "memory");
	v_bfe_u32 v0, v30, 16, 1
	v_add3_u32 v0, v30, v0, s20
	s_waitcnt lgkmcnt(2)
	v_bfe_u32 v23, v32, 16, 1
	ds_read2_b32 v[68:69], v65 offset0:166 offset1:174
	v_lshrrev_b32_e32 v0, 16, v0
	v_add3_u32 v23, v32, v23, s20
	ds_read2_b32 v[70:71], v65 offset0:231 offset1:239
	v_and_or_b32 v23, v23, s21, v0
	s_waitcnt lgkmcnt(3)
	v_bfe_u32 v0, v34, 16, 1
	v_add3_u32 v0, v34, v0, s20
	s_waitcnt lgkmcnt(2)
	v_bfe_u32 v24, v66, 16, 1
	v_lshrrev_b32_e32 v0, 16, v0
	v_add3_u32 v24, v66, v24, s20
	v_and_or_b32 v24, v24, s21, v0
	s_waitcnt lgkmcnt(1)
	v_bfe_u32 v0, v68, 16, 1
	v_add3_u32 v0, v68, v0, s20
	s_waitcnt lgkmcnt(0)
	v_bfe_u32 v25, v70, 16, 1
	v_lshrrev_b32_e32 v0, 16, v0
	v_add3_u32 v25, v70, v25, s20
	v_and_or_b32 v25, v25, s21, v0
	v_or_b32_e32 v0, s10, v41
	v_lshlrev_b32_e32 v0, 11, v0
	v_lshl_add_u64 v[72:73], v[20:21], 0, v[0:1]
	v_bfe_u32 v0, v27, 16, 1
	global_store_dwordx4 v[72:73], v[22:25], off
	v_add3_u32 v0, v27, v0, s20
	v_lshrrev_b32_e32 v0, 16, v0
	v_bfe_u32 v22, v29, 16, 1
	v_add3_u32 v22, v29, v22, s20
	v_and_or_b32 v22, v22, s21, v0
	v_bfe_u32 v0, v31, 16, 1
	v_add3_u32 v0, v31, v0, s20
	v_bfe_u32 v23, v33, 16, 1
	v_lshrrev_b32_e32 v0, 16, v0
	v_add3_u32 v23, v33, v23, s20
	v_and_or_b32 v23, v23, s21, v0
	v_bfe_u32 v0, v35, 16, 1
	v_add3_u32 v0, v35, v0, s20
	v_bfe_u32 v24, v67, 16, 1
	v_lshrrev_b32_e32 v0, 16, v0
	v_add3_u32 v24, v67, v24, s20
	v_and_or_b32 v24, v24, s21, v0
	v_bfe_u32 v0, v69, 16, 1
	v_add3_u32 v0, v69, v0, s20
	v_bfe_u32 v25, v71, 16, 1
	v_lshrrev_b32_e32 v0, 16, v0
	v_add3_u32 v25, v71, v25, s20
	v_and_or_b32 v25, v25, s21, v0
	v_or_b32_e32 v0, s10, v42
	v_lshlrev_b32_e32 v0, 11, v0
	ds_read2_b32 v[26:27], v37 offset0:48 offset1:56
	v_lshl_add_u64 v[28:29], v[20:21], 0, v[0:1]
	global_store_dwordx4 v[28:29], v[22:25], off
	ds_read2_b32 v[28:29], v37 offset0:113 offset1:121
	ds_read2_b32 v[30:31], v37 offset0:178 offset1:186
	ds_read2_b32 v[32:33], v37 offset0:243 offset1:251
	s_waitcnt lgkmcnt(3)
	v_bfe_u32 v0, v26, 16, 1
	v_add3_u32 v0, v26, v0, s20
	s_waitcnt lgkmcnt(2)
	v_bfe_u32 v22, v28, 16, 1
	ds_read2_b32 v[34:35], v65 offset0:52 offset1:60
	v_lshrrev_b32_e32 v0, 16, v0
	v_add3_u32 v22, v28, v22, s20
	ds_read2_b32 v[66:67], v65 offset0:117 offset1:125
	v_and_or_b32 v22, v22, s21, v0
	s_waitcnt lgkmcnt(3)
	v_bfe_u32 v0, v30, 16, 1
	v_add3_u32 v0, v30, v0, s20
	s_waitcnt lgkmcnt(2)
	v_bfe_u32 v23, v32, 16, 1
	ds_read2_b32 v[68:69], v65 offset0:182 offset1:190
	v_lshrrev_b32_e32 v0, 16, v0
	v_add3_u32 v23, v32, v23, s20
	ds_read2_b32 v[70:71], v65 offset0:247 offset1:255
	v_and_or_b32 v23, v23, s21, v0
	s_waitcnt lgkmcnt(3)
	v_bfe_u32 v0, v34, 16, 1
	v_add3_u32 v0, v34, v0, s20
	s_waitcnt lgkmcnt(2)
	v_bfe_u32 v24, v66, 16, 1
	v_lshrrev_b32_e32 v0, 16, v0
	v_add3_u32 v24, v66, v24, s20
	v_and_or_b32 v24, v24, s21, v0
	s_waitcnt lgkmcnt(1)
	v_bfe_u32 v0, v68, 16, 1
	v_add3_u32 v0, v68, v0, s20
	s_waitcnt lgkmcnt(0)
	v_bfe_u32 v25, v70, 16, 1
	v_lshrrev_b32_e32 v0, 16, v0
	v_add3_u32 v25, v70, v25, s20
	v_and_or_b32 v25, v25, s21, v0
	v_or_b32_e32 v0, s10, v43
	v_lshlrev_b32_e32 v0, 11, v0
	v_lshl_add_u64 v[72:73], v[20:21], 0, v[0:1]
	v_bfe_u32 v0, v27, 16, 1
	global_store_dwordx4 v[72:73], v[22:25], off
	v_add3_u32 v0, v27, v0, s20
	v_lshrrev_b32_e32 v0, 16, v0
	v_bfe_u32 v22, v29, 16, 1
	v_add3_u32 v22, v29, v22, s20
	v_and_or_b32 v22, v22, s21, v0
	v_bfe_u32 v0, v31, 16, 1
	v_add3_u32 v0, v31, v0, s20
	v_bfe_u32 v23, v33, 16, 1
	v_lshrrev_b32_e32 v0, 16, v0
	v_add3_u32 v23, v33, v23, s20
	v_and_or_b32 v23, v23, s21, v0
	v_bfe_u32 v0, v35, 16, 1
	v_add3_u32 v0, v35, v0, s20
	v_bfe_u32 v24, v67, 16, 1
	v_lshrrev_b32_e32 v0, 16, v0
	v_add3_u32 v24, v67, v24, s20
	v_and_or_b32 v24, v24, s21, v0
	v_bfe_u32 v0, v69, 16, 1
	v_add3_u32 v0, v69, v0, s20
	v_bfe_u32 v25, v71, 16, 1
	v_lshrrev_b32_e32 v0, 16, v0
	v_add3_u32 v25, v71, v25, s20
	v_and_or_b32 v25, v25, s21, v0
	v_add_lshl_u32 v0, v44, s10, 11
	v_lshl_add_u64 v[20:21], v[20:21], 0, v[0:1]
	global_store_dwordx4 v[20:21], v[22:25], off
	s_waitcnt lgkmcnt(0)

; #define LAS __attribute__((address_space(3)))
; #define GAS __attribute__((address_space(1)))
; #define LDS_WAIT() asm volatile("s_waitcnt lgkmcnt(0)" ::: "memory")
; __device__ __forceinline__ void transpose_item(const float* W, int ldw, int src_col0, bf16_t* WT, int Kd, int dst_row0, int k0, float scale, LAS float* scr, int lane) {
;     const int kr = lane >> 4, c4 = lane & 15;
; #pragma unroll 8
;     for (int i = 0; i < 16; ++i) { const int kk = 4 * i + kr; const f32x4 v = __builtin_nontemporal_load((const GAS f32x4*)(W + (size_t)(k0 + kk) * ldw + src_col0 + 4 * c4)) * scale;
;         LAS float* d = scr + kk * 65 + 4 * c4; d[0] = v.x; d[1] = v.y; d[2] = v.z; d[3] = v.w; }
;     LDS_WAIT(); asm volatile("" ::: "memory");
; template <int PART> __device__ __forceinline__ void phase_convert(Frame& F) {
;     ...
;             if (r < I_IN) { const int nblk = NQKVR / 64, kb = r / nblk, nb = r % nblk, n0 = nb * 64; const int src = n0 < 2048 ? n0 : n0 + RANK;
;                 transpose_item(F.in[15], GIN, src, WIN, D, n0, kb * 64, n0 < QKW ? 0.08838834764831845f : 1.f, scr, F.lane); continue; } r -= I_IN;
.LBB0_232:
	v_add_u32_e32 v21, s23, v0
	v_add_u32_e32 v31, 8, v21
	v_add_u32_e32 v65, 12, v21
	v_add_u32_e32 v72, 16, v21
	v_add_u32_e32 v73, 20, v21
	v_add_u32_e32 v76, 24, v21
	v_add_u32_e32 v21, 28, v21
	global_load_dwordx4 v[32:35], v[28:29], off nt
	global_load_dwordx4 v[66:69], v[26:27], off nt
	v_mad_i64_i32 v[70:71], s[24:25], v31, s22, v[22:23]
	v_mad_i64_i32 v[74:75], s[24:25], v65, s22, v[22:23]
	v_mad_i64_i32 v[78:79], s[24:25], v72, s22, v[22:23]
	v_mad_i64_i32 v[82:83], s[24:25], v73, s22, v[22:23]
	v_mad_i64_i32 v[86:87], s[24:25], v76, s22, v[22:23]
	v_mad_i64_i32 v[90:91], s[24:25], v21, s22, v[22:23]
	global_load_dwordx4 v[70:73], v[70:71], off nt
	s_nop 0
	global_load_dwordx4 v[74:77], v[74:75], off nt
	s_nop 0
	global_load_dwordx4 v[78:81], v[78:79], off nt
	s_nop 0
	global_load_dwordx4 v[82:85], v[82:83], off nt
	s_nop 0
	global_load_dwordx4 v[86:89], v[86:87], off nt
	s_nop 0
	global_load_dwordx4 v[90:93], v[90:91], off nt
	s_add_i32 s23, s23, 32
	v_lshl_add_u64 v[26:27], v[26:27], 0, s[8:9]
	v_lshl_add_u64 v[28:29], v[28:29], 0, s[8:9]
	v_add_u32_e32 v137, s23, v0
	v_add_u32_e32 v147, 8, v137
	v_add_u32_e32 v181, 12, v137
	v_add_u32_e32 v188, 16, v137
	v_add_u32_e32 v189, 20, v137
	v_add_u32_e32 v192, 24, v137
	v_add_u32_e32 v137, 28, v137
	global_load_dwordx4 v[148:151], v[28:29], off nt
	global_load_dwordx4 v[182:185], v[26:27], off nt
	v_mad_i64_i32 v[186:187], s[24:25], v147, s22, v[22:23]
	v_mad_i64_i32 v[190:191], s[24:25], v181, s22, v[22:23]
	v_mad_i64_i32 v[194:195], s[24:25], v188, s22, v[22:23]
	v_mad_i64_i32 v[198:199], s[24:25], v189, s22, v[22:23]
	v_mad_i64_i32 v[202:203], s[24:25], v192, s22, v[22:23]
	v_mad_i64_i32 v[206:207], s[24:25], v137, s22, v[22:23]
	global_load_dwordx4 v[186:189], v[186:187], off nt
	s_nop 0
	global_load_dwordx4 v[190:193], v[190:191], off nt
	s_nop 0
	global_load_dwordx4 v[194:197], v[194:195], off nt
	s_nop 0
	global_load_dwordx4 v[198:201], v[198:199], off nt
	s_nop 0
	global_load_dwordx4 v[202:205], v[202:203], off nt
	s_nop 0
	global_load_dwordx4 v[206:209], v[206:207], off nt
	v_mov_b32_e32 v21, v20
	v_add_u32_e32 v31, 0x410, v30
	v_add_u32_e32 v65, 0x418, v30
	v_add_u32_e32 v94, 0x820, v30
	v_add_u32_e32 v95, 0x828, v30
	v_add_u32_e32 v96, 0xc30, v30
	v_add_u32_e32 v97, 0xc38, v30
	v_add_u32_e32 v98, 0x1040, v30
	v_add_u32_e32 v99, 0x1048, v30
	v_add_u32_e32 v100, 0x1450, v30
	v_add_u32_e32 v101, 0x1458, v30
	v_add_u32_e32 v102, 0x1860, v30
	v_add_u32_e32 v103, 0x1868, v30
	v_add_u32_e32 v104, 0x1c70, v30
	v_add_u32_e32 v105, 0x1c78, v30
	s_waitcnt vmcnt(15)
	v_pk_mul_f32 v[34:35], v[20:21], v[34:35]
	v_pk_mul_f32 v[32:33], v[24:25], v[32:33]
	s_waitcnt vmcnt(14)
	v_pk_mul_f32 v[68:69], v[20:21], v[68:69]
	v_pk_mul_f32 v[66:67], v[24:25], v[66:67]
	ds_write2_b32 v30, v32, v33 offset1:1
	ds_write2_b32 v30, v34, v35 offset0:2 offset1:3
	ds_write2_b32 v31, v66, v67 offset1:1
	ds_write2_b32 v65, v68, v69 offset1:1
	v_add_u32_e32 v30, 0x2080, v30
	s_waitcnt vmcnt(13)
	v_pk_mul_f32 v[34:35], v[24:25], v[70:71]
	v_pk_mul_f32 v[32:33], v[20:21], v[72:73]
	s_waitcnt vmcnt(12)
	v_pk_mul_f32 v[66:67], v[20:21], v[76:77]
	v_pk_mul_f32 v[68:69], v[24:25], v[74:75]
	s_waitcnt vmcnt(11)
	v_pk_mul_f32 v[70:71], v[20:21], v[80:81]
	v_pk_mul_f32 v[72:73], v[24:25], v[78:79]
	s_waitcnt vmcnt(10)
	v_pk_mul_f32 v[74:75], v[20:21], v[84:85]
	v_pk_mul_f32 v[76:77], v[24:25], v[82:83]
	s_waitcnt vmcnt(9)
	v_pk_mul_f32 v[78:79], v[20:21], v[88:89]
	v_pk_mul_f32 v[80:81], v[24:25], v[86:87]
	s_waitcnt vmcnt(8)
	v_pk_mul_f32 v[82:83], v[20:21], v[92:93]
	v_pk_mul_f32 v[84:85], v[24:25], v[90:91]
	ds_write2_b32 v94, v34, v35 offset1:1
	ds_write2_b32 v95, v32, v33 offset1:1
	ds_write2_b32 v96, v68, v69 offset1:1
	ds_write2_b32 v97, v66, v67 offset1:1
	ds_write2_b32 v98, v72, v73 offset1:1
	ds_write2_b32 v99, v70, v71 offset1:1
	ds_write2_b32 v100, v76, v77 offset1:1
	ds_write2_b32 v101, v74, v75 offset1:1
	ds_write2_b32 v102, v80, v81 offset1:1
	ds_write2_b32 v103, v78, v79 offset1:1
	ds_write2_b32 v104, v84, v85 offset1:1
	ds_write2_b32 v105, v82, v83 offset1:1
	s_add_i32 s23, s23, 32
	v_lshl_add_u64 v[26:27], v[26:27], 0, s[8:9]
	v_lshl_add_u64 v[28:29], v[28:29], 0, s[8:9]
	v_mov_b32_e32 v21, v20
	v_add_u32_e32 v31, 0x410, v30
	v_add_u32_e32 v65, 0x418, v30
	v_add_u32_e32 v94, 0x820, v30
	v_add_u32_e32 v95, 0x828, v30
	v_add_u32_e32 v96, 0xc30, v30
	v_add_u32_e32 v97, 0xc38, v30
	v_add_u32_e32 v98, 0x1040, v30
	v_add_u32_e32 v99, 0x1048, v30
	v_add_u32_e32 v100, 0x1450, v30
	v_add_u32_e32 v101, 0x1458, v30
	v_add_u32_e32 v102, 0x1860, v30
	v_add_u32_e32 v103, 0x1868, v30
	v_add_u32_e32 v104, 0x1c70, v30
	v_add_u32_e32 v105, 0x1c78, v30
	s_waitcnt vmcnt(7)
	v_pk_mul_f32 v[150:151], v[20:21], v[150:151]
	v_pk_mul_f32 v[148:149], v[24:25], v[148:149]
	s_waitcnt vmcnt(6)
	v_pk_mul_f32 v[184:185], v[20:21], v[184:185]
	v_pk_mul_f32 v[182:183], v[24:25], v[182:183]
	ds_write2_b32 v30, v148, v149 offset1:1
	ds_write2_b32 v30, v150, v151 offset0:2 offset1:3
	ds_write2_b32 v31, v182, v183 offset1:1
	ds_write2_b32 v65, v184, v185 offset1:1
	v_add_u32_e32 v30, 0x2080, v30
	s_waitcnt vmcnt(5)
	v_pk_mul_f32 v[150:151], v[24:25], v[186:187]
	v_pk_mul_f32 v[148:149], v[20:21], v[188:189]
	s_waitcnt vmcnt(4)
	v_pk_mul_f32 v[182:183], v[20:21], v[192:193]
	v_pk_mul_f32 v[184:185], v[24:25], v[190:191]
	s_waitcnt vmcnt(3)
	v_pk_mul_f32 v[186:187], v[20:21], v[196:197]
	v_pk_mul_f32 v[188:189], v[24:25], v[194:195]
	s_waitcnt vmcnt(2)
	v_pk_mul_f32 v[190:191], v[20:21], v[200:201]
	v_pk_mul_f32 v[192:193], v[24:25], v[198:199]
	s_waitcnt vmcnt(1)
	v_pk_mul_f32 v[194:195], v[20:21], v[204:205]
	v_pk_mul_f32 v[196:197], v[24:25], v[202:203]
	s_waitcnt vmcnt(0)
; #define LAS __attribute__((address_space(3)))
; #define GAS __attribute__((address_space(1)))
; __device__ __forceinline__ unsigned pk2(float lo, float hi) { return f2bf(lo) | (f2bf(hi) << 16); }
; #define LDS_WAIT() asm volatile("s_waitcnt lgkmcnt(0)" ::: "memory")
; __device__ __forceinline__ void transpose_item(const float* W, int ldw, int src_col0, bf16_t* WT, int Kd, int dst_row0, int k0, float scale, LAS float* scr, int lane) {
;     ...
; #pragma unroll 8
;     for (int i = 0; i < 16; ++i) { const int kk = 4 * i + kr; const f32x4 v = __builtin_nontemporal_load((const GAS f32x4*)(W + (size_t)(k0 + kk) * ldw + src_col0 + 4 * c4)) * scale;
;         LAS float* d = scr + kk * 65 + 4 * c4; d[0] = v.x; d[1] = v.y; d[2] = v.z; d[3] = v.w; }
;     LDS_WAIT(); asm volatile("" ::: "memory");
;     const int c = lane & 7;
; #pragma unroll
;     for (int j = 0; j < 8; ++j) { const int n = (lane >> 3) + 8 * j; const LAS float* sp = scr + (8 * c) * 65 + n;
;         u32x4 o; o.x = pk2(sp[0 * 65], sp[1 * 65]); o.y = pk2(sp[2 * 65], sp[3 * 65]); o.z = pk2(sp[4 * 65], sp[5 * 65]); o.w = pk2(sp[6 * 65], sp[7 * 65]);
;         *(GAS u32x4*)(WT + (size_t)(dst_row0 + n) * Kd + k0 + 8 * c) = o; }
;     LDS_WAIT(); asm volatile("" ::: "memory");
	v_pk_mul_f32 v[198:199], v[20:21], v[208:209]
	v_pk_mul_f32 v[200:201], v[24:25], v[206:207]
	ds_write2_b32 v94, v150, v151 offset1:1
	ds_write2_b32 v95, v148, v149 offset1:1
	ds_write2_b32 v96, v184, v185 offset1:1
	ds_write2_b32 v97, v182, v183 offset1:1
	ds_write2_b32 v98, v188, v189 offset1:1
	ds_write2_b32 v99, v186, v187 offset1:1
	ds_write2_b32 v100, v192, v193 offset1:1
	ds_write2_b32 v101, v190, v191 offset1:1
	ds_write2_b32 v102, v196, v197 offset1:1
	ds_write2_b32 v103, v194, v195 offset1:1
	ds_write2_b32 v104, v200, v201 offset1:1
	ds_write2_b32 v105, v198, v199 offset1:1
	s_waitcnt lgkmcnt(0)
	ds_read2_b32 v[26:27], v37 offset1:8
	ds_read2_b32 v[28:29], v37 offset0:65 offset1:73
	ds_read2_b32 v[30:31], v37 offset0:130 offset1:138
	ds_read2_b32 v[32:33], v37 offset0:195 offset1:203
	v_add_u32_e32 v65, 0x400, v37
	s_waitcnt lgkmcnt(3)
	v_bfe_u32 v0, v26, 16, 1
	s_waitcnt lgkmcnt(2)
	v_bfe_u32 v22, v28, 16, 1
	v_add3_u32 v0, v26, v0, s20
	ds_read2_b32 v[34:35], v65 offset0:4 offset1:12
	v_lshrrev_b32_e32 v0, 16, v0
	v_add3_u32 v22, v28, v22, s20
	ds_read2_b32 v[66:67], v65 offset0:69 offset1:77
	v_and_or_b32 v22, v22, s21, v0
	s_waitcnt lgkmcnt(3)
	v_bfe_u32 v0, v30, 16, 1
	v_add3_u32 v0, v30, v0, s20
	s_waitcnt lgkmcnt(2)
	v_bfe_u32 v23, v32, 16, 1
	ds_read2_b32 v[68:69], v65 offset0:134 offset1:142
	v_lshrrev_b32_e32 v0, 16, v0
	v_add3_u32 v23, v32, v23, s20
	ds_read2_b32 v[70:71], v65 offset0:199 offset1:207
	v_and_or_b32 v23, v23, s21, v0
	s_waitcnt lgkmcnt(3)
	v_bfe_u32 v0, v34, 16, 1
	v_add3_u32 v0, v34, v0, s20
	s_waitcnt lgkmcnt(2)
	v_bfe_u32 v24, v66, 16, 1
	v_lshrrev_b32_e32 v0, 16, v0
	v_add3_u32 v24, v66, v24, s20
	v_and_or_b32 v24, v24, s21, v0
	s_waitcnt lgkmcnt(1)
	v_bfe_u32 v0, v68, 16, 1
	v_add_u32_e32 v72, s6, v36
	v_add3_u32 v0, v68, v0, s20
	s_waitcnt lgkmcnt(0)
	v_bfe_u32 v25, v70, 16, 1
	v_ashrrev_i32_e32 v73, 31, v72
	v_lshl_add_u64 v[20:21], s[10:11], 1, v[12:13]
	v_lshrrev_b32_e32 v0, 16, v0
	v_add3_u32 v25, v70, v25, s20
	v_lshlrev_b64 v[72:73], 11, v[72:73]
	v_and_or_b32 v25, v25, s21, v0
	v_lshl_add_u64 v[72:73], v[20:21], 0, v[72:73]
	v_bfe_u32 v0, v27, 16, 1
	global_store_dwordx4 v[72:73], v[22:25], off
	v_add3_u32 v0, v27, v0, s20
	v_lshrrev_b32_e32 v0, 16, v0
	v_bfe_u32 v22, v29, 16, 1
	v_add3_u32 v22, v29, v22, s20
	v_and_or_b32 v22, v22, s21, v0
	v_bfe_u32 v0, v31, 16, 1
	v_add3_u32 v0, v31, v0, s20
	v_bfe_u32 v23, v33, 16, 1
	v_lshrrev_b32_e32 v0, 16, v0
	v_add3_u32 v23, v33, v23, s20
	v_and_or_b32 v23, v23, s21, v0
	v_bfe_u32 v0, v35, 16, 1
	v_add3_u32 v0, v35, v0, s20
	v_bfe_u32 v24, v67, 16, 1
	v_lshrrev_b32_e32 v0, 16, v0
	v_add3_u32 v24, v67, v24, s20
	v_and_or_b32 v24, v24, s21, v0
	v_bfe_u32 v0, v69, 16, 1
	v_add_u32_e32 v26, s6, v38
	v_add3_u32 v0, v69, v0, s20
	v_bfe_u32 v25, v71, 16, 1
	v_ashrrev_i32_e32 v27, 31, v26
	v_lshrrev_b32_e32 v0, 16, v0
	v_add3_u32 v25, v71, v25, s20
	v_lshlrev_b64 v[26:27], 11, v[26:27]
	v_and_or_b32 v25, v25, s21, v0
	ds_read2_b32 v[28:29], v37 offset0:16 offset1:24
	v_lshl_add_u64 v[26:27], v[20:21], 0, v[26:27]
	global_store_dwordx4 v[26:27], v[22:25], off
	ds_read2_b32 v[26:27], v37 offset0:81 offset1:89
	ds_read2_b32 v[30:31], v37 offset0:146 offset1:154
	ds_read2_b32 v[32:33], v37 offset0:211 offset1:219
	s_waitcnt lgkmcnt(3)
	v_bfe_u32 v0, v28, 16, 1
	v_add3_u32 v0, v28, v0, s20
	s_waitcnt lgkmcnt(2)
	v_bfe_u32 v22, v26, 16, 1
	ds_read2_b32 v[34:35], v65 offset0:20 offset1:28
	v_lshrrev_b32_e32 v0, 16, v0
	v_add3_u32 v22, v26, v22, s20
	ds_read2_b32 v[66:67], v65 offset0:85 offset1:93
	v_and_or_b32 v22, v22, s21, v0
	s_waitcnt lgkmcnt(3)
	v_bfe_u32 v0, v30, 16, 1
	v_add3_u32 v0, v30, v0, s20
	s_waitcnt lgkmcnt(2)
	v_bfe_u32 v23, v32, 16, 1
	ds_read2_b32 v[68:69], v65 offset0:150 offset1:158
	v_lshrrev_b32_e32 v0, 16, v0
	v_add3_u32 v23, v32, v23, s20
	ds_read2_b32 v[70:71], v65 offset0:215 offset1:223
	v_and_or_b32 v23, v23, s21, v0
	s_waitcnt lgkmcnt(3)
	v_bfe_u32 v0, v34, 16, 1
	v_add3_u32 v0, v34, v0, s20
	s_waitcnt lgkmcnt(2)
	v_bfe_u32 v24, v66, 16, 1
	v_lshrrev_b32_e32 v0, 16, v0
	v_add3_u32 v24, v66, v24, s20
	v_and_or_b32 v24, v24, s21, v0
	s_waitcnt lgkmcnt(1)
	v_bfe_u32 v0, v68, 16, 1
	v_add_u32_e32 v72, s6, v39
	v_add3_u32 v0, v68, v0, s20
	s_waitcnt lgkmcnt(0)
	v_bfe_u32 v25, v70, 16, 1
	v_ashrrev_i32_e32 v73, 31, v72
	v_lshrrev_b32_e32 v0, 16, v0
	v_add3_u32 v25, v70, v25, s20
	v_lshlrev_b64 v[72:73], 11, v[72:73]
	v_and_or_b32 v25, v25, s21, v0
	v_lshl_add_u64 v[72:73], v[20:21], 0, v[72:73]
	v_bfe_u32 v0, v29, 16, 1
	global_store_dwordx4 v[72:73], v[22:25], off
	v_add3_u32 v0, v29, v0, s20
	v_lshrrev_b32_e32 v0, 16, v0
	v_bfe_u32 v22, v27, 16, 1
	v_add3_u32 v22, v27, v22, s20
	v_and_or_b32 v22, v22, s21, v0
	v_bfe_u32 v0, v31, 16, 1
	v_add3_u32 v0, v31, v0, s20
	v_bfe_u32 v23, v33, 16, 1
	v_lshrrev_b32_e32 v0, 16, v0
	v_add3_u32 v23, v33, v23, s20
	v_and_or_b32 v23, v23, s21, v0
	v_bfe_u32 v0, v35, 16, 1
	v_add3_u32 v0, v35, v0, s20
	v_bfe_u32 v24, v67, 16, 1
	v_lshrrev_b32_e32 v0, 16, v0
	v_add3_u32 v24, v67, v24, s20
	v_and_or_b32 v24, v24, s21, v0
	v_bfe_u32 v0, v69, 16, 1
	v_add_u32_e32 v26, s6, v40
	v_add3_u32 v0, v69, v0, s20
	v_bfe_u32 v25, v71, 16, 1
	v_ashrrev_i32_e32 v27, 31, v26
	v_lshrrev_b32_e32 v0, 16, v0
	v_add3_u32 v25, v71, v25, s20
	v_lshlrev_b64 v[26:27], 11, v[26:27]
	v_and_or_b32 v25, v25, s21, v0
	ds_read2_b32 v[28:29], v37 offset0:32 offset1:40
	v_lshl_add_u64 v[26:27], v[20:21], 0, v[26:27]
	global_store_dwordx4 v[26:27], v[22:25], off
	ds_read2_b32 v[26:27], v37 offset0:97 offset1:105
	ds_read2_b32 v[30:31], v37 offset0:162 offset1:170
	ds_read2_b32 v[32:33], v37 offset0:227 offset1:235
	s_waitcnt lgkmcnt(3)
; #define LAS __attribute__((address_space(3)))
; #define GAS __attribute__((address_space(1)))
; __device__ __forceinline__ unsigned pk2(float lo, float hi) { return f2bf(lo) | (f2bf(hi) << 16); }
; #define LDS_WAIT() asm volatile("s_waitcnt lgkmcnt(0)" ::: "memory")
; __device__ __forceinline__ void transpose_item(const float* W, int ldw, int src_col0, bf16_t* WT, int Kd, int dst_row0, int k0, float scale, LAS float* scr, int lane) {
;     ...
;     const int c = lane & 7;
; #pragma unroll
;     for (int j = 0; j < 8; ++j) { const int n = (lane >> 3) + 8 * j; const LAS float* sp = scr + (8 * c) * 65 + n;
;         u32x4 o; o.x = pk2(sp[0 * 65], sp[1 * 65]); o.y = pk2(sp[2 * 65], sp[3 * 65]); o.z = pk2(sp[4 * 65], sp[5 * 65]); o.w = pk2(sp[6 * 65], sp[7 * 65]);
;         *(GAS u32x4*)(WT + (size_t)(dst_row0 + n) * Kd + k0 + 8 * c) = o; }
;     LDS_WAIT(); asm volatile("" ::: "memory");
	v_bfe_u32 v0, v28, 16, 1
	v_add3_u32 v0, v28, v0, s20
	s_waitcnt lgkmcnt(2)
	v_bfe_u32 v22, v26, 16, 1
	ds_read2_b32 v[34:35], v65 offset0:36 offset1:44
	v_lshrrev_b32_e32 v0, 16, v0
	v_add3_u32 v22, v26, v22, s20
	ds_read2_b32 v[66:67], v65 offset0:101 offset1:109
	v_and_or_b32 v22, v22, s21, v0
	s_waitcnt lgkmcnt(3)
	v_bfe_u32 v0, v30, 16, 1
	v_add3_u32 v0, v30, v0, s20
	s_waitcnt lgkmcnt(2)
	v_bfe_u32 v23, v32, 16, 1
	ds_read2_b32 v[68:69], v65 offset0:166 offset1:174
	v_lshrrev_b32_e32 v0, 16, v0
	v_add3_u32 v23, v32, v23, s20
	ds_read2_b32 v[70:71], v65 offset0:231 offset1:239
	v_and_or_b32 v23, v23, s21, v0
	s_waitcnt lgkmcnt(3)
	v_bfe_u32 v0, v34, 16, 1
	v_add3_u32 v0, v34, v0, s20
	s_waitcnt lgkmcnt(2)
	v_bfe_u32 v24, v66, 16, 1
	v_lshrrev_b32_e32 v0, 16, v0
	v_add3_u32 v24, v66, v24, s20
	v_and_or_b32 v24, v24, s21, v0
	s_waitcnt lgkmcnt(1)
	v_bfe_u32 v0, v68, 16, 1
	v_add_u32_e32 v72, s6, v41
	v_add3_u32 v0, v68, v0, s20
	s_waitcnt lgkmcnt(0)
	v_bfe_u32 v25, v70, 16, 1
	v_ashrrev_i32_e32 v73, 31, v72
	v_lshrrev_b32_e32 v0, 16, v0
	v_add3_u32 v25, v70, v25, s20
	v_lshlrev_b64 v[72:73], 11, v[72:73]
	v_and_or_b32 v25, v25, s21, v0
	v_lshl_add_u64 v[72:73], v[20:21], 0, v[72:73]
	v_bfe_u32 v0, v29, 16, 1
	global_store_dwordx4 v[72:73], v[22:25], off
	v_add3_u32 v0, v29, v0, s20
	v_lshrrev_b32_e32 v0, 16, v0
	v_bfe_u32 v22, v27, 16, 1
	v_add3_u32 v22, v27, v22, s20
	v_and_or_b32 v22, v22, s21, v0
	v_bfe_u32 v0, v31, 16, 1
	v_add3_u32 v0, v31, v0, s20
	v_bfe_u32 v23, v33, 16, 1
	v_lshrrev_b32_e32 v0, 16, v0
	v_add3_u32 v23, v33, v23, s20
	v_and_or_b32 v23, v23, s21, v0
	v_bfe_u32 v0, v35, 16, 1
	v_add3_u32 v0, v35, v0, s20
	v_bfe_u32 v24, v67, 16, 1
	v_lshrrev_b32_e32 v0, 16, v0
	v_add3_u32 v24, v67, v24, s20
	v_and_or_b32 v24, v24, s21, v0
	v_bfe_u32 v0, v69, 16, 1
	v_add_u32_e32 v26, s6, v42
	v_add3_u32 v0, v69, v0, s20
	v_bfe_u32 v25, v71, 16, 1
	v_ashrrev_i32_e32 v27, 31, v26
	v_lshrrev_b32_e32 v0, 16, v0
	v_add3_u32 v25, v71, v25, s20
	v_lshlrev_b64 v[26:27], 11, v[26:27]
	v_and_or_b32 v25, v25, s21, v0
	ds_read2_b32 v[28:29], v37 offset0:48 offset1:56
	v_lshl_add_u64 v[26:27], v[20:21], 0, v[26:27]
	global_store_dwordx4 v[26:27], v[22:25], off
	ds_read2_b32 v[26:27], v37 offset0:113 offset1:121
	ds_read2_b32 v[30:31], v37 offset0:178 offset1:186
	ds_read2_b32 v[32:33], v37 offset0:243 offset1:251
	s_waitcnt lgkmcnt(3)
	v_bfe_u32 v0, v28, 16, 1
	v_add3_u32 v0, v28, v0, s20
	s_waitcnt lgkmcnt(2)
	v_bfe_u32 v22, v26, 16, 1
	ds_read2_b32 v[34:35], v65 offset0:52 offset1:60
	v_lshrrev_b32_e32 v0, 16, v0
	v_add3_u32 v22, v26, v22, s20
	ds_read2_b32 v[66:67], v65 offset0:117 offset1:125
	v_and_or_b32 v22, v22, s21, v0
	s_waitcnt lgkmcnt(3)
	v_bfe_u32 v0, v30, 16, 1
	v_add3_u32 v0, v30, v0, s20
	s_waitcnt lgkmcnt(2)
	v_bfe_u32 v23, v32, 16, 1
	ds_read2_b32 v[68:69], v65 offset0:182 offset1:190
	v_lshrrev_b32_e32 v0, 16, v0
	v_add3_u32 v23, v32, v23, s20
	ds_read2_b32 v[70:71], v65 offset0:247 offset1:255
	v_and_or_b32 v23, v23, s21, v0
	s_waitcnt lgkmcnt(3)
	v_bfe_u32 v0, v34, 16, 1
	v_add3_u32 v0, v34, v0, s20
	s_waitcnt lgkmcnt(2)
	v_bfe_u32 v24, v66, 16, 1
	v_lshrrev_b32_e32 v0, 16, v0
	v_add3_u32 v24, v66, v24, s20
	v_and_or_b32 v24, v24, s21, v0
	s_waitcnt lgkmcnt(1)
	v_bfe_u32 v0, v68, 16, 1
	v_add_u32_e32 v72, s6, v43
	v_add3_u32 v0, v68, v0, s20
	s_waitcnt lgkmcnt(0)
	v_bfe_u32 v25, v70, 16, 1
	v_ashrrev_i32_e32 v73, 31, v72
	v_lshrrev_b32_e32 v0, 16, v0
	v_add3_u32 v25, v70, v25, s20
	v_lshlrev_b64 v[72:73], 11, v[72:73]
	v_and_or_b32 v25, v25, s21, v0
	v_lshl_add_u64 v[72:73], v[20:21], 0, v[72:73]
	v_bfe_u32 v0, v29, 16, 1
	global_store_dwordx4 v[72:73], v[22:25], off
	v_add3_u32 v0, v29, v0, s20
	v_lshrrev_b32_e32 v0, 16, v0
	v_bfe_u32 v22, v27, 16, 1
	v_add3_u32 v22, v27, v22, s20
	v_and_or_b32 v22, v22, s21, v0
	v_bfe_u32 v0, v31, 16, 1
	v_add3_u32 v0, v31, v0, s20
	v_bfe_u32 v23, v33, 16, 1
	v_lshrrev_b32_e32 v0, 16, v0
	v_add3_u32 v23, v33, v23, s20
	v_and_or_b32 v23, v23, s21, v0
	v_bfe_u32 v0, v35, 16, 1
	v_add3_u32 v0, v35, v0, s20
	v_bfe_u32 v24, v67, 16, 1
	v_lshrrev_b32_e32 v0, 16, v0
	v_add3_u32 v24, v67, v24, s20
	v_and_or_b32 v24, v24, s21, v0
	v_bfe_u32 v0, v69, 16, 1
	v_add_u32_e32 v26, s6, v44
	v_add3_u32 v0, v69, v0, s20
	v_bfe_u32 v25, v71, 16, 1
	v_ashrrev_i32_e32 v27, 31, v26
	v_lshrrev_b32_e32 v0, 16, v0
	v_add3_u32 v25, v71, v25, s20
	v_lshlrev_b64 v[26:27], 11, v[26:27]
	v_and_or_b32 v25, v25, s21, v0
	v_lshl_add_u64 v[20:21], v[20:21], 0, v[26:27]
	global_store_dwordx4 v[20:21], v[22:25], off
	s_waitcnt lgkmcnt(0)
	s_branch .LBB0_213

; #define LAS __attribute__((address_space(3)))
; #define GAS __attribute__((address_space(1)))
; __device__ __forceinline__ void transpose_item(const float* W, int ldw, int src_col0, bf16_t* WT, int Kd, int dst_row0, int k0, float scale, LAS float* scr, int lane) {
;     ...
; #pragma unroll 8
;     for (int i = 0; i < 16; ++i) { const int kk = 4 * i + kr; const f32x4 v = __builtin_nontemporal_load((const GAS f32x4*)(W + (size_t)(k0 + kk) * ldw + src_col0 + 4 * c4)) * scale;
;         LAS float* d = scr + kk * 65 + 4 * c4; d[0] = v.x; d[1] = v.y; d[2] = v.z; d[3] = v.w; }
; template <int PART> __device__ __forceinline__ void phase_convert(Frame& F) {
;     ...
;         { const int nblk = D / 64, kb = r / nblk, nb = r % nblk;
;             transpose_item(F.in[21] + (size_t)l * DFF * D, D, nb * 64, W2 + (size_t)l * D * DFF, DFF, nb * 64, kb * 64, 1.f, scr, F.lane); }
.LBB0_251:
	v_add_u32_e32 v19, s0, v0
	v_add_u32_e32 v20, 0xffffe800, v19
	v_add_u32_e32 v22, 0xffffe804, v19
	v_add_u32_e32 v24, 0xffffe808, v19
	v_add_u32_e32 v26, 0xffffe80c, v19
	v_add_u32_e32 v28, 0xffffe810, v19
	v_add_u32_e32 v30, 0xffffe814, v19
	v_add_u32_e32 v52, 0xffffe818, v19
	v_add_u32_e32 v54, 0xffffe81c, v19
	v_ashrrev_i32_e32 v21, 31, v20
	v_ashrrev_i32_e32 v23, 31, v22
	v_ashrrev_i32_e32 v25, 31, v24
	v_ashrrev_i32_e32 v27, 31, v26
	v_ashrrev_i32_e32 v29, 31, v28
	v_ashrrev_i32_e32 v31, 31, v30
	v_ashrrev_i32_e32 v53, 31, v52
	v_ashrrev_i32_e32 v55, 31, v54
	v_lshlrev_b64 v[20:21], 12, v[20:21]
	v_lshlrev_b64 v[22:23], 12, v[22:23]
	v_lshlrev_b64 v[24:25], 12, v[24:25]
	v_lshlrev_b64 v[26:27], 12, v[26:27]
	v_lshlrev_b64 v[28:29], 12, v[28:29]
	v_lshlrev_b64 v[30:31], 12, v[30:31]
	v_lshlrev_b64 v[52:53], 12, v[52:53]
	v_lshlrev_b64 v[54:55], 12, v[54:55]
	v_lshl_add_u64 v[20:21], v[16:17], 0, v[20:21]
	v_lshl_add_u64 v[56:57], v[16:17], 0, v[22:23]
	v_lshl_add_u64 v[58:59], v[16:17], 0, v[24:25]
	v_lshl_add_u64 v[60:61], v[16:17], 0, v[26:27]
	v_lshl_add_u64 v[62:63], v[16:17], 0, v[28:29]
	v_lshl_add_u64 v[64:65], v[16:17], 0, v[30:31]
	v_lshl_add_u64 v[66:67], v[16:17], 0, v[52:53]
	v_lshl_add_u64 v[68:69], v[16:17], 0, v[54:55]
	global_load_dwordx4 v[20:23], v[20:21], off nt
	s_nop 0
	global_load_dwordx4 v[24:27], v[56:57], off nt
	global_load_dwordx4 v[28:31], v[58:59], off nt
	global_load_dwordx4 v[52:55], v[60:61], off nt
	s_nop 0
	global_load_dwordx4 v[56:59], v[62:63], off nt
	s_nop 0
	global_load_dwordx4 v[60:63], v[64:65], off nt
	s_nop 0
	global_load_dwordx4 v[64:67], v[66:67], off nt
	s_nop 0
	global_load_dwordx4 v[68:71], v[68:69], off nt
	s_add_i32 s0, s0, 32
	v_add_u32_e32 v135, s0, v0
	v_add_u32_e32 v136, 0xffffe800, v135
	v_add_u32_e32 v138, 0xffffe804, v135
	v_add_u32_e32 v140, 0xffffe808, v135
	v_add_u32_e32 v142, 0xffffe80c, v135
	v_add_u32_e32 v144, 0xffffe810, v135
	v_add_u32_e32 v146, 0xffffe814, v135
	v_add_u32_e32 v168, 0xffffe818, v135
	v_add_u32_e32 v170, 0xffffe81c, v135
	v_ashrrev_i32_e32 v137, 31, v136
	v_ashrrev_i32_e32 v139, 31, v138
	v_ashrrev_i32_e32 v141, 31, v140
	v_ashrrev_i32_e32 v143, 31, v142
	v_ashrrev_i32_e32 v145, 31, v144
	v_ashrrev_i32_e32 v147, 31, v146
	v_ashrrev_i32_e32 v169, 31, v168
	v_ashrrev_i32_e32 v171, 31, v170
	v_lshlrev_b64 v[136:137], 12, v[136:137]
	v_lshlrev_b64 v[138:139], 12, v[138:139]
	v_lshlrev_b64 v[140:141], 12, v[140:141]
	v_lshlrev_b64 v[142:143], 12, v[142:143]
	v_lshlrev_b64 v[144:145], 12, v[144:145]
	v_lshlrev_b64 v[146:147], 12, v[146:147]
	v_lshlrev_b64 v[168:169], 12, v[168:169]
	v_lshlrev_b64 v[170:171], 12, v[170:171]
	v_lshl_add_u64 v[136:137], v[16:17], 0, v[136:137]
	v_lshl_add_u64 v[172:173], v[16:17], 0, v[138:139]
	v_lshl_add_u64 v[174:175], v[16:17], 0, v[140:141]
	v_lshl_add_u64 v[176:177], v[16:17], 0, v[142:143]
	v_lshl_add_u64 v[178:179], v[16:17], 0, v[144:145]
	v_lshl_add_u64 v[180:181], v[16:17], 0, v[146:147]
	v_lshl_add_u64 v[182:183], v[16:17], 0, v[168:169]
	v_lshl_add_u64 v[184:185], v[16:17], 0, v[170:171]
	global_load_dwordx4 v[136:139], v[136:137], off nt
	s_nop 0
	global_load_dwordx4 v[140:143], v[172:173], off nt
	global_load_dwordx4 v[144:147], v[174:175], off nt
	global_load_dwordx4 v[168:171], v[176:177], off nt
	s_nop 0
	global_load_dwordx4 v[172:175], v[178:179], off nt
	s_nop 0
	global_load_dwordx4 v[176:179], v[180:181], off nt
	s_nop 0
	global_load_dwordx4 v[180:183], v[182:183], off nt
	s_nop 0
	global_load_dwordx4 v[184:187], v[184:185], off nt
	v_add_u32_e32 v19, 0x410, v18
	v_add_u32_e32 v72, 0x418, v18
	v_add_u32_e32 v73, 0x820, v18
	v_add_u32_e32 v74, 0x828, v18
	v_add_u32_e32 v75, 0xc30, v18
	v_add_u32_e32 v76, 0xc38, v18
	v_add_u32_e32 v77, 0x1040, v18
	v_add_u32_e32 v78, 0x1048, v18
	v_add_u32_e32 v79, 0x1450, v18
	v_add_u32_e32 v80, 0x1458, v18
	v_add_u32_e32 v81, 0x1860, v18
	v_add_u32_e32 v82, 0x1868, v18
	v_add_u32_e32 v83, 0x1c70, v18
	v_add_u32_e32 v84, 0x1c78, v18
	s_waitcnt vmcnt(15)
	ds_write2_b32 v18, v20, v21 offset1:1
	ds_write2_b32 v18, v22, v23 offset0:2 offset1:3
	s_waitcnt vmcnt(14)
	ds_write2_b32 v19, v24, v25 offset1:1
	ds_write2_b32 v72, v26, v27 offset1:1
	s_waitcnt vmcnt(13)
	ds_write2_b32 v73, v28, v29 offset1:1
	ds_write2_b32 v74, v30, v31 offset1:1
	s_waitcnt vmcnt(12)
	ds_write2_b32 v75, v52, v53 offset1:1
	ds_write2_b32 v76, v54, v55 offset1:1
	s_waitcnt vmcnt(11)
	ds_write2_b32 v77, v56, v57 offset1:1
	ds_write2_b32 v78, v58, v59 offset1:1
	s_waitcnt vmcnt(10)
	ds_write2_b32 v79, v60, v61 offset1:1
	ds_write2_b32 v80, v62, v63 offset1:1
	s_waitcnt vmcnt(9)
	ds_write2_b32 v81, v64, v65 offset1:1
	ds_write2_b32 v82, v66, v67 offset1:1
	s_waitcnt vmcnt(8)
	ds_write2_b32 v83, v68, v69 offset1:1
	ds_write2_b32 v84, v70, v71 offset1:1
	v_add_u32_e32 v18, 0x2080, v18
	s_add_i32 s0, s0, 32
	v_add_u32_e32 v19, 0x410, v18
	v_add_u32_e32 v72, 0x418, v18
	v_add_u32_e32 v73, 0x820, v18
	v_add_u32_e32 v74, 0x828, v18
	v_add_u32_e32 v75, 0xc30, v18
	v_add_u32_e32 v76, 0xc38, v18
	v_add_u32_e32 v77, 0x1040, v18
	v_add_u32_e32 v78, 0x1048, v18
	v_add_u32_e32 v79, 0x1450, v18
	v_add_u32_e32 v80, 0x1458, v18
	v_add_u32_e32 v81, 0x1860, v18
	v_add_u32_e32 v82, 0x1868, v18
	v_add_u32_e32 v83, 0x1c70, v18
	v_add_u32_e32 v84, 0x1c78, v18
	s_waitcnt vmcnt(7)
	ds_write2_b32 v18, v136, v137 offset1:1
	ds_write2_b32 v18, v138, v139 offset0:2 offset1:3
	s_waitcnt vmcnt(6)
	ds_write2_b32 v19, v140, v141 offset1:1
	ds_write2_b32 v72, v142, v143 offset1:1
	s_waitcnt vmcnt(5)
	ds_write2_b32 v73, v144, v145 offset1:1
	ds_write2_b32 v74, v146, v147 offset1:1
	s_waitcnt vmcnt(4)
; #define LAS __attribute__((address_space(3)))
; #define GAS __attribute__((address_space(1)))
; __device__ __forceinline__ unsigned pk2(float lo, float hi) { return f2bf(lo) | (f2bf(hi) << 16); }
; #define LDS_WAIT() asm volatile("s_waitcnt lgkmcnt(0)" ::: "memory")
; __device__ __forceinline__ void transpose_item(const float* W, int ldw, int src_col0, bf16_t* WT, int Kd, int dst_row0, int k0, float scale, LAS float* scr, int lane) {
;     ...
;     for (int i = 0; i < 16; ++i) { const int kk = 4 * i + kr; const f32x4 v = __builtin_nontemporal_load((const GAS f32x4*)(W + (size_t)(k0 + kk) * ldw + src_col0 + 4 * c4)) * scale;
;         LAS float* d = scr + kk * 65 + 4 * c4; d[0] = v.x; d[1] = v.y; d[2] = v.z; d[3] = v.w; }
;     LDS_WAIT(); asm volatile("" ::: "memory");
;     const int c = lane & 7;
; #pragma unroll
;     for (int j = 0; j < 8; ++j) { const int n = (lane >> 3) + 8 * j; const LAS float* sp = scr + (8 * c) * 65 + n;
;         u32x4 o; o.x = pk2(sp[0 * 65], sp[1 * 65]); o.y = pk2(sp[2 * 65], sp[3 * 65]); o.z = pk2(sp[4 * 65], sp[5 * 65]); o.w = pk2(sp[6 * 65], sp[7 * 65]);
;         *(GAS u32x4*)(WT + (size_t)(dst_row0 + n) * Kd + k0 + 8 * c) = o; }
	ds_write2_b32 v75, v168, v169 offset1:1
	ds_write2_b32 v76, v170, v171 offset1:1
	s_waitcnt vmcnt(3)
	ds_write2_b32 v77, v172, v173 offset1:1
	ds_write2_b32 v78, v174, v175 offset1:1
	s_waitcnt vmcnt(2)
	ds_write2_b32 v79, v176, v177 offset1:1
	ds_write2_b32 v80, v178, v179 offset1:1
	s_waitcnt vmcnt(1)
	ds_write2_b32 v81, v180, v181 offset1:1
	ds_write2_b32 v82, v182, v183 offset1:1
	s_waitcnt vmcnt(0)
	ds_write2_b32 v83, v184, v185 offset1:1
	ds_write2_b32 v84, v186, v187 offset1:1
	v_add_u32_e32 v18, 0x2080, v18
	s_waitcnt lgkmcnt(0)
	ds_read2_b32 v[22:23], v33 offset1:8
	ds_read2_b32 v[24:25], v33 offset0:65 offset1:73
	ds_read2_b32 v[26:27], v33 offset0:130 offset1:138
	ds_read2_b32 v[28:29], v33 offset0:195 offset1:203
	v_add_u32_e32 v60, 0x400, v33
	s_waitcnt lgkmcnt(3)
	v_bfe_u32 v0, v22, 16, 1
	v_add3_u32 v0, v22, v0, s21
	s_waitcnt lgkmcnt(2)
	v_bfe_u32 v18, v24, 16, 1
	ds_read2_b32 v[30:31], v60 offset0:4 offset1:12
	v_lshrrev_b32_e32 v0, 16, v0
	v_add3_u32 v18, v24, v18, s21
	ds_read2_b32 v[52:53], v60 offset0:69 offset1:77
	v_and_or_b32 v18, v18, s22, v0
	s_waitcnt lgkmcnt(3)
	v_bfe_u32 v0, v26, 16, 1
	v_add3_u32 v0, v26, v0, s21
	s_waitcnt lgkmcnt(2)
	v_bfe_u32 v19, v28, 16, 1
	ds_read2_b32 v[54:55], v60 offset0:134 offset1:142
	v_lshrrev_b32_e32 v0, 16, v0
	v_add3_u32 v19, v28, v19, s21
	ds_read2_b32 v[56:57], v60 offset0:199 offset1:207
	v_and_or_b32 v19, v19, s22, v0
	s_waitcnt lgkmcnt(3)
	v_bfe_u32 v0, v30, 16, 1
	v_add3_u32 v0, v30, v0, s21
	s_waitcnt lgkmcnt(2)
	v_bfe_u32 v20, v52, 16, 1
	v_lshrrev_b32_e32 v0, 16, v0
	v_add3_u32 v20, v52, v20, s21
	s_lshl_b32 s0, s12, 2
	v_and_or_b32 v20, v20, s22, v0
	s_waitcnt lgkmcnt(1)
	v_bfe_u32 v0, v54, 16, 1
	s_and_b32 s0, s0, 0x7fffffc0
	v_add3_u32 v0, v54, v0, s21
	s_waitcnt lgkmcnt(0)
	v_bfe_u32 v21, v56, 16, 1
	s_addk_i32 s0, 0xe800
	v_lshrrev_b32_e32 v0, 16, v0
	v_add3_u32 v21, v56, v21, s21
	v_lshl_add_u64 v[16:17], s[0:1], 1, v[4:5]
	v_and_or_b32 v21, v21, s22, v0
	v_add_lshl_u32 v0, v32, s8, 13
	v_lshl_add_u64 v[58:59], v[16:17], 0, v[0:1]
	v_bfe_u32 v0, v23, 16, 1
	global_store_dwordx4 v[58:59], v[18:21], off
	v_add3_u32 v0, v23, v0, s21
	v_lshrrev_b32_e32 v0, 16, v0
	v_bfe_u32 v18, v25, 16, 1
	v_add3_u32 v18, v25, v18, s21
	v_and_or_b32 v18, v18, s22, v0
	v_bfe_u32 v0, v27, 16, 1
	v_add3_u32 v0, v27, v0, s21
	v_bfe_u32 v19, v29, 16, 1
	v_lshrrev_b32_e32 v0, 16, v0
	v_add3_u32 v19, v29, v19, s21
	v_and_or_b32 v19, v19, s22, v0
	v_bfe_u32 v0, v31, 16, 1
	v_add3_u32 v0, v31, v0, s21
	v_bfe_u32 v20, v53, 16, 1
	v_lshrrev_b32_e32 v0, 16, v0
	v_add3_u32 v20, v53, v20, s21
	v_and_or_b32 v20, v20, s22, v0
	v_bfe_u32 v0, v55, 16, 1
	v_add3_u32 v0, v55, v0, s21
	v_bfe_u32 v21, v57, 16, 1
	v_lshrrev_b32_e32 v0, 16, v0
	v_add3_u32 v21, v57, v21, s21
	v_and_or_b32 v21, v21, s22, v0
	v_add_lshl_u32 v0, v34, s8, 13
	ds_read2_b32 v[22:23], v33 offset0:16 offset1:24
	v_lshl_add_u64 v[24:25], v[16:17], 0, v[0:1]
	global_store_dwordx4 v[24:25], v[18:21], off
	ds_read2_b32 v[24:25], v33 offset0:81 offset1:89
	ds_read2_b32 v[26:27], v33 offset0:146 offset1:154
	ds_read2_b32 v[28:29], v33 offset0:211 offset1:219
	s_waitcnt lgkmcnt(3)
	v_bfe_u32 v0, v22, 16, 1
	v_add3_u32 v0, v22, v0, s21
	s_waitcnt lgkmcnt(2)
	v_bfe_u32 v18, v24, 16, 1
	ds_read2_b32 v[30:31], v60 offset0:20 offset1:28
	v_lshrrev_b32_e32 v0, 16, v0
	v_add3_u32 v18, v24, v18, s21
	ds_read2_b32 v[52:53], v60 offset0:85 offset1:93
	v_and_or_b32 v18, v18, s22, v0
	s_waitcnt lgkmcnt(3)
	v_bfe_u32 v0, v26, 16, 1
	v_add3_u32 v0, v26, v0, s21
	s_waitcnt lgkmcnt(2)
	v_bfe_u32 v19, v28, 16, 1
	ds_read2_b32 v[54:55], v60 offset0:150 offset1:158
	v_lshrrev_b32_e32 v0, 16, v0
	v_add3_u32 v19, v28, v19, s21
	ds_read2_b32 v[56:57], v60 offset0:215 offset1:223
	v_and_or_b32 v19, v19, s22, v0
	s_waitcnt lgkmcnt(3)
	v_bfe_u32 v0, v30, 16, 1
	v_add3_u32 v0, v30, v0, s21
	s_waitcnt lgkmcnt(2)
	v_bfe_u32 v20, v52, 16, 1
	v_lshrrev_b32_e32 v0, 16, v0
	v_add3_u32 v20, v52, v20, s21
	v_and_or_b32 v20, v20, s22, v0
	s_waitcnt lgkmcnt(1)
	v_bfe_u32 v0, v54, 16, 1
	v_add3_u32 v0, v54, v0, s21
	s_waitcnt lgkmcnt(0)
	v_bfe_u32 v21, v56, 16, 1
	v_lshrrev_b32_e32 v0, 16, v0
	v_add3_u32 v21, v56, v21, s21
	v_and_or_b32 v21, v21, s22, v0
	v_add_lshl_u32 v0, v35, s8, 13
	v_lshl_add_u64 v[58:59], v[16:17], 0, v[0:1]
	v_bfe_u32 v0, v23, 16, 1
	global_store_dwordx4 v[58:59], v[18:21], off
	v_add3_u32 v0, v23, v0, s21
	v_lshrrev_b32_e32 v0, 16, v0
	v_bfe_u32 v18, v25, 16, 1
	v_add3_u32 v18, v25, v18, s21
	v_and_or_b32 v18, v18, s22, v0
	v_bfe_u32 v0, v27, 16, 1
	v_add3_u32 v0, v27, v0, s21
	v_bfe_u32 v19, v29, 16, 1
	v_lshrrev_b32_e32 v0, 16, v0
	v_add3_u32 v19, v29, v19, s21
	v_and_or_b32 v19, v19, s22, v0
	v_bfe_u32 v0, v31, 16, 1
	v_add3_u32 v0, v31, v0, s21
	v_bfe_u32 v20, v53, 16, 1
	v_lshrrev_b32_e32 v0, 16, v0
	v_add3_u32 v20, v53, v20, s21
	v_and_or_b32 v20, v20, s22, v0
	v_bfe_u32 v0, v55, 16, 1
	v_add3_u32 v0, v55, v0, s21
	v_bfe_u32 v21, v57, 16, 1
	v_lshrrev_b32_e32 v0, 16, v0
	v_add3_u32 v21, v57, v21, s21
	v_and_or_b32 v21, v21, s22, v0
	v_add_lshl_u32 v0, v36, s8, 13
	ds_read2_b32 v[22:23], v33 offset0:32 offset1:40
	v_lshl_add_u64 v[24:25], v[16:17], 0, v[0:1]
	global_store_dwordx4 v[24:25], v[18:21], off
	ds_read2_b32 v[24:25], v33 offset0:97 offset1:105
	ds_read2_b32 v[26:27], v33 offset0:162 offset1:170
	ds_read2_b32 v[28:29], v33 offset0:227 offset1:235
	s_waitcnt lgkmcnt(3)
; #define LAS __attribute__((address_space(3)))
; #define GAS __attribute__((address_space(1)))
; __device__ __forceinline__ unsigned pk2(float lo, float hi) { return f2bf(lo) | (f2bf(hi) << 16); }
; #define LDS_WAIT() asm volatile("s_waitcnt lgkmcnt(0)" ::: "memory")
; __device__ __forceinline__ void transpose_item(const float* W, int ldw, int src_col0, bf16_t* WT, int Kd, int dst_row0, int k0, float scale, LAS float* scr, int lane) {
;     ...
;     const int c = lane & 7;
; #pragma unroll
;     for (int j = 0; j < 8; ++j) { const int n = (lane >> 3) + 8 * j; const LAS float* sp = scr + (8 * c) * 65 + n;
;         u32x4 o; o.x = pk2(sp[0 * 65], sp[1 * 65]); o.y = pk2(sp[2 * 65], sp[3 * 65]); o.z = pk2(sp[4 * 65], sp[5 * 65]); o.w = pk2(sp[6 * 65], sp[7 * 65]);
;         *(GAS u32x4*)(WT + (size_t)(dst_row0 + n) * Kd + k0 + 8 * c) = o; }
;     LDS_WAIT(); asm volatile("" ::: "memory");
	v_bfe_u32 v0, v22, 16, 1
	v_add3_u32 v0, v22, v0, s21
	s_waitcnt lgkmcnt(2)
	v_bfe_u32 v18, v24, 16, 1
	ds_read2_b32 v[30:31], v60 offset0:36 offset1:44
	v_lshrrev_b32_e32 v0, 16, v0
	v_add3_u32 v18, v24, v18, s21
	ds_read2_b32 v[52:53], v60 offset0:101 offset1:109
	v_and_or_b32 v18, v18, s22, v0
	s_waitcnt lgkmcnt(3)
	v_bfe_u32 v0, v26, 16, 1
	v_add3_u32 v0, v26, v0, s21
	s_waitcnt lgkmcnt(2)
	v_bfe_u32 v19, v28, 16, 1
	ds_read2_b32 v[54:55], v60 offset0:166 offset1:174
	v_lshrrev_b32_e32 v0, 16, v0
	v_add3_u32 v19, v28, v19, s21
	ds_read2_b32 v[56:57], v60 offset0:231 offset1:239
	v_and_or_b32 v19, v19, s22, v0
	s_waitcnt lgkmcnt(3)
	v_bfe_u32 v0, v30, 16, 1
	v_add3_u32 v0, v30, v0, s21
	s_waitcnt lgkmcnt(2)
	v_bfe_u32 v20, v52, 16, 1
	v_lshrrev_b32_e32 v0, 16, v0
	v_add3_u32 v20, v52, v20, s21
	v_and_or_b32 v20, v20, s22, v0
	s_waitcnt lgkmcnt(1)
	v_bfe_u32 v0, v54, 16, 1
	v_add3_u32 v0, v54, v0, s21
	s_waitcnt lgkmcnt(0)
	v_bfe_u32 v21, v56, 16, 1
	v_lshrrev_b32_e32 v0, 16, v0
	v_add3_u32 v21, v56, v21, s21
	v_and_or_b32 v21, v21, s22, v0
	v_add_lshl_u32 v0, v37, s8, 13
	v_lshl_add_u64 v[58:59], v[16:17], 0, v[0:1]
	v_bfe_u32 v0, v23, 16, 1
	global_store_dwordx4 v[58:59], v[18:21], off
	v_add3_u32 v0, v23, v0, s21
	v_lshrrev_b32_e32 v0, 16, v0
	v_bfe_u32 v18, v25, 16, 1
	v_add3_u32 v18, v25, v18, s21
	v_and_or_b32 v18, v18, s22, v0
	v_bfe_u32 v0, v27, 16, 1
	v_add3_u32 v0, v27, v0, s21
	v_bfe_u32 v19, v29, 16, 1
	v_lshrrev_b32_e32 v0, 16, v0
	v_add3_u32 v19, v29, v19, s21
	v_and_or_b32 v19, v19, s22, v0
	v_bfe_u32 v0, v31, 16, 1
	v_add3_u32 v0, v31, v0, s21
	v_bfe_u32 v20, v53, 16, 1
	v_lshrrev_b32_e32 v0, 16, v0
	v_add3_u32 v20, v53, v20, s21
	v_and_or_b32 v20, v20, s22, v0
	v_bfe_u32 v0, v55, 16, 1
	v_add3_u32 v0, v55, v0, s21
	v_bfe_u32 v21, v57, 16, 1
	v_lshrrev_b32_e32 v0, 16, v0
	v_add3_u32 v21, v57, v21, s21
	v_and_or_b32 v21, v21, s22, v0
	v_add_lshl_u32 v0, v38, s8, 13
	ds_read2_b32 v[22:23], v33 offset0:48 offset1:56
	v_lshl_add_u64 v[24:25], v[16:17], 0, v[0:1]
	global_store_dwordx4 v[24:25], v[18:21], off
	ds_read2_b32 v[24:25], v33 offset0:113 offset1:121
	ds_read2_b32 v[26:27], v33 offset0:178 offset1:186
	ds_read2_b32 v[28:29], v33 offset0:243 offset1:251
	s_waitcnt lgkmcnt(3)
	v_bfe_u32 v0, v22, 16, 1
	v_add3_u32 v0, v22, v0, s21
	s_waitcnt lgkmcnt(2)
	v_bfe_u32 v18, v24, 16, 1
	ds_read2_b32 v[30:31], v60 offset0:52 offset1:60
	v_lshrrev_b32_e32 v0, 16, v0
	v_add3_u32 v18, v24, v18, s21
	ds_read2_b32 v[52:53], v60 offset0:117 offset1:125
	v_and_or_b32 v18, v18, s22, v0
	s_waitcnt lgkmcnt(3)
	v_bfe_u32 v0, v26, 16, 1
	v_add3_u32 v0, v26, v0, s21
	s_waitcnt lgkmcnt(2)
	v_bfe_u32 v19, v28, 16, 1
	ds_read2_b32 v[54:55], v60 offset0:182 offset1:190
	v_lshrrev_b32_e32 v0, 16, v0
	v_add3_u32 v19, v28, v19, s21
	ds_read2_b32 v[56:57], v60 offset0:247 offset1:255
	v_and_or_b32 v19, v19, s22, v0
	s_waitcnt lgkmcnt(3)
	v_bfe_u32 v0, v30, 16, 1
	v_add3_u32 v0, v30, v0, s21
	s_waitcnt lgkmcnt(2)
	v_bfe_u32 v20, v52, 16, 1
	v_lshrrev_b32_e32 v0, 16, v0
	v_add3_u32 v20, v52, v20, s21
	v_and_or_b32 v20, v20, s22, v0
	s_waitcnt lgkmcnt(1)
	v_bfe_u32 v0, v54, 16, 1
	v_add3_u32 v0, v54, v0, s21
	s_waitcnt lgkmcnt(0)
	v_bfe_u32 v21, v56, 16, 1
	v_lshrrev_b32_e32 v0, 16, v0
	v_add3_u32 v21, v56, v21, s21
	v_and_or_b32 v21, v21, s22, v0
	v_add_lshl_u32 v0, v39, s8, 13
	v_lshl_add_u64 v[58:59], v[16:17], 0, v[0:1]
	v_bfe_u32 v0, v23, 16, 1
	global_store_dwordx4 v[58:59], v[18:21], off
	v_add3_u32 v0, v23, v0, s21
	v_lshrrev_b32_e32 v0, 16, v0
	v_bfe_u32 v18, v25, 16, 1
	v_add3_u32 v18, v25, v18, s21
	v_and_or_b32 v18, v18, s22, v0
	v_bfe_u32 v0, v27, 16, 1
	v_add3_u32 v0, v27, v0, s21
	v_bfe_u32 v19, v29, 16, 1
	v_lshrrev_b32_e32 v0, 16, v0
	v_add3_u32 v19, v29, v19, s21
	v_and_or_b32 v19, v19, s22, v0
	v_bfe_u32 v0, v31, 16, 1
	v_add3_u32 v0, v31, v0, s21
	v_bfe_u32 v20, v53, 16, 1
	v_lshrrev_b32_e32 v0, 16, v0
	v_add3_u32 v20, v53, v20, s21
	v_and_or_b32 v20, v20, s22, v0
	v_bfe_u32 v0, v55, 16, 1
	v_add3_u32 v0, v55, v0, s21
	v_bfe_u32 v21, v57, 16, 1
	v_lshrrev_b32_e32 v0, 16, v0
	v_add3_u32 v21, v57, v21, s21
	v_and_or_b32 v21, v21, s22, v0
	v_add_lshl_u32 v0, v40, s8, 13
	v_lshl_add_u64 v[16:17], v[16:17], 0, v[0:1]
	global_store_dwordx4 v[16:17], v[18:21], off
	s_waitcnt lgkmcnt(0)
	s_mov_b64 s[8:9], 0

; #define LAS __attribute__((address_space(3)))
; #define GAS __attribute__((address_space(1)))
; __device__ __forceinline__ void transpose_item(const float* W, int ldw, int src_col0, bf16_t* WT, int Kd, int dst_row0, int k0, float scale, LAS float* scr, int lane) {
;     ...
; #pragma unroll 8
;     for (int i = 0; i < 16; ++i) { const int kk = 4 * i + kr; const f32x4 v = __builtin_nontemporal_load((const GAS f32x4*)(W + (size_t)(k0 + kk) * ldw + src_col0 + 4 * c4)) * scale;
;         LAS float* d = scr + kk * 65 + 4 * c4; d[0] = v.x; d[1] = v.y; d[2] = v.z; d[3] = v.w; }
; template <int PART> __device__ __forceinline__ void phase_convert(Frame& F) {
;     ...
;         if (r < I_1) { const int nblk = DFF / 64, kb = r / nblk, nb = r % nblk;
;             transpose_item(F.in[20] + (size_t)l * D * DFF, DFF, nb * 64, W1 + (size_t)l * DFF * D, D, nb * 64, kb * 64, 1.f, scr, F.lane); continue; } r -= I_1;
.LBB0_255:
	v_lshl_add_u64 v[52:53], v[30:31], 0, s[8:9]
	v_lshl_add_u64 v[56:57], v[28:29], 0, s[8:9]
	v_lshl_add_u64 v[60:61], v[26:27], 0, s[8:9]
	v_lshl_add_u64 v[64:65], v[24:25], 0, s[8:9]
	v_lshl_add_u64 v[68:69], v[22:23], 0, s[8:9]
	v_lshl_add_u64 v[72:73], v[20:21], 0, s[8:9]
	v_lshl_add_u64 v[76:77], v[18:19], 0, s[8:9]
	v_lshl_add_u64 v[80:81], v[16:17], 0, s[8:9]
	global_load_dwordx4 v[52:55], v[52:53], off nt
	s_nop 0
	global_load_dwordx4 v[56:59], v[56:57], off nt
	s_nop 0
	global_load_dwordx4 v[60:63], v[60:61], off nt
	s_nop 0
	global_load_dwordx4 v[64:67], v[64:65], off nt
	s_nop 0
	global_load_dwordx4 v[68:71], v[68:69], off nt
	s_nop 0
	global_load_dwordx4 v[72:75], v[72:73], off nt
	s_nop 0
	global_load_dwordx4 v[76:79], v[76:77], off nt
	s_nop 0
	global_load_dwordx4 v[80:83], v[80:81], off nt
	s_add_u32 s8, s8, 0x80000
	s_addc_u32 s9, s9, 0
	v_lshl_add_u64 v[168:169], v[30:31], 0, s[8:9]
	v_lshl_add_u64 v[172:173], v[28:29], 0, s[8:9]
	v_lshl_add_u64 v[176:177], v[26:27], 0, s[8:9]
	v_lshl_add_u64 v[180:181], v[24:25], 0, s[8:9]
	v_lshl_add_u64 v[184:185], v[22:23], 0, s[8:9]
	v_lshl_add_u64 v[188:189], v[20:21], 0, s[8:9]
	v_lshl_add_u64 v[192:193], v[18:19], 0, s[8:9]
	v_lshl_add_u64 v[196:197], v[16:17], 0, s[8:9]
	global_load_dwordx4 v[168:171], v[168:169], off nt
	s_nop 0
	global_load_dwordx4 v[172:175], v[172:173], off nt
	s_nop 0
	global_load_dwordx4 v[176:179], v[176:177], off nt
	s_nop 0
	global_load_dwordx4 v[180:183], v[180:181], off nt
	s_nop 0
	global_load_dwordx4 v[184:187], v[184:185], off nt
	s_nop 0
	global_load_dwordx4 v[188:191], v[188:189], off nt
	s_nop 0
	global_load_dwordx4 v[192:195], v[192:193], off nt
	s_nop 0
	global_load_dwordx4 v[196:199], v[196:197], off nt
	v_add_u32_e32 v84, 0x410, v0
	v_add_u32_e32 v85, 0x418, v0
	v_add_u32_e32 v86, 0x820, v0
	v_add_u32_e32 v87, 0x828, v0
	v_add_u32_e32 v88, 0xc30, v0
	v_add_u32_e32 v89, 0xc38, v0
	v_add_u32_e32 v90, 0x1040, v0
	v_add_u32_e32 v91, 0x1048, v0
	v_add_u32_e32 v92, 0x1450, v0
	v_add_u32_e32 v93, 0x1458, v0
	v_add_u32_e32 v94, 0x1860, v0
	v_add_u32_e32 v95, 0x1868, v0
	v_add_u32_e32 v96, 0x1c70, v0
	v_add_u32_e32 v97, 0x1c78, v0
	s_waitcnt vmcnt(15)
	ds_write2_b32 v0, v52, v53 offset1:1
	ds_write2_b32 v0, v54, v55 offset0:2 offset1:3
	s_waitcnt vmcnt(14)
	ds_write2_b32 v84, v56, v57 offset1:1
	ds_write2_b32 v85, v58, v59 offset1:1
	s_waitcnt vmcnt(13)
	ds_write2_b32 v86, v60, v61 offset1:1
	ds_write2_b32 v87, v62, v63 offset1:1
	s_waitcnt vmcnt(12)
	ds_write2_b32 v88, v64, v65 offset1:1
	ds_write2_b32 v89, v66, v67 offset1:1
	s_waitcnt vmcnt(11)
	ds_write2_b32 v90, v68, v69 offset1:1
	ds_write2_b32 v91, v70, v71 offset1:1
	s_waitcnt vmcnt(10)
	ds_write2_b32 v92, v72, v73 offset1:1
	ds_write2_b32 v93, v74, v75 offset1:1
	s_waitcnt vmcnt(9)
	ds_write2_b32 v94, v76, v77 offset1:1
	ds_write2_b32 v95, v78, v79 offset1:1
	s_waitcnt vmcnt(8)
	ds_write2_b32 v96, v80, v81 offset1:1
	ds_write2_b32 v97, v82, v83 offset1:1
	v_add_u32_e32 v0, 0x2080, v0
	s_add_u32 s8, s8, 0x80000
	s_addc_u32 s9, s9, 0
	v_add_u32_e32 v84, 0x410, v0
	v_add_u32_e32 v85, 0x418, v0
	v_add_u32_e32 v86, 0x820, v0
	v_add_u32_e32 v87, 0x828, v0
	v_add_u32_e32 v88, 0xc30, v0
	v_add_u32_e32 v89, 0xc38, v0
	v_add_u32_e32 v90, 0x1040, v0
	v_add_u32_e32 v91, 0x1048, v0
	v_add_u32_e32 v92, 0x1450, v0
	v_add_u32_e32 v93, 0x1458, v0
	v_add_u32_e32 v94, 0x1860, v0
	v_add_u32_e32 v95, 0x1868, v0
	v_add_u32_e32 v96, 0x1c70, v0
	v_add_u32_e32 v97, 0x1c78, v0
	s_waitcnt vmcnt(7)
	ds_write2_b32 v0, v168, v169 offset1:1
	ds_write2_b32 v0, v170, v171 offset0:2 offset1:3
	s_waitcnt vmcnt(6)
	ds_write2_b32 v84, v172, v173 offset1:1
	ds_write2_b32 v85, v174, v175 offset1:1
	s_waitcnt vmcnt(5)
	ds_write2_b32 v86, v176, v177 offset1:1
	ds_write2_b32 v87, v178, v179 offset1:1
	s_waitcnt vmcnt(4)
	ds_write2_b32 v88, v180, v181 offset1:1
	ds_write2_b32 v89, v182, v183 offset1:1
	s_waitcnt vmcnt(3)
	ds_write2_b32 v90, v184, v185 offset1:1
	ds_write2_b32 v91, v186, v187 offset1:1
	s_waitcnt vmcnt(2)
	ds_write2_b32 v92, v188, v189 offset1:1
	ds_write2_b32 v93, v190, v191 offset1:1
	s_waitcnt vmcnt(1)
	ds_write2_b32 v94, v192, v193 offset1:1
	ds_write2_b32 v95, v194, v195 offset1:1
	s_waitcnt vmcnt(0)
	ds_write2_b32 v96, v196, v197 offset1:1
	ds_write2_b32 v97, v198, v199 offset1:1
	v_add_u32_e32 v0, 0x2080, v0
	s_waitcnt lgkmcnt(0)
	ds_read2_b32 v[22:23], v33 offset1:8
	ds_read2_b32 v[24:25], v33 offset0:65 offset1:73
	ds_read2_b32 v[26:27], v33 offset0:130 offset1:138
	ds_read2_b32 v[28:29], v33 offset0:195 offset1:203
	v_add_u32_e32 v60, 0x400, v33
	s_waitcnt lgkmcnt(3)
	v_bfe_u32 v0, v22, 16, 1
	v_add3_u32 v0, v22, v0, s21
	s_waitcnt lgkmcnt(2)
	v_bfe_u32 v18, v24, 16, 1
	ds_read2_b32 v[30:31], v60 offset0:4 offset1:12
	v_lshrrev_b32_e32 v0, 16, v0
	v_add3_u32 v18, v24, v18, s21
	ds_read2_b32 v[52:53], v60 offset0:69 offset1:77
	v_and_or_b32 v18, v18, s22, v0
	s_waitcnt lgkmcnt(3)
	v_bfe_u32 v0, v26, 16, 1
	v_add3_u32 v0, v26, v0, s21
	s_waitcnt lgkmcnt(2)
	v_bfe_u32 v19, v28, 16, 1
	ds_read2_b32 v[54:55], v60 offset0:134 offset1:142
	v_lshrrev_b32_e32 v0, 16, v0
	v_add3_u32 v19, v28, v19, s21
	ds_read2_b32 v[56:57], v60 offset0:199 offset1:207
	v_and_or_b32 v19, v19, s22, v0
	s_waitcnt lgkmcnt(3)
	v_bfe_u32 v0, v30, 16, 1
	v_add3_u32 v0, v30, v0, s21
	s_waitcnt lgkmcnt(2)
	v_bfe_u32 v20, v52, 16, 1
	v_lshrrev_b32_e32 v0, 16, v0
	v_add3_u32 v20, v52, v20, s21
	v_and_or_b32 v20, v20, s22, v0
	s_waitcnt lgkmcnt(1)
	v_bfe_u32 v0, v54, 16, 1
	s_lshl_b32 s8, s12, 6
	v_add3_u32 v0, v54, v0, s21
	s_waitcnt lgkmcnt(0)
; #define LAS __attribute__((address_space(3)))
; #define GAS __attribute__((address_space(1)))
; __device__ __forceinline__ unsigned pk2(float lo, float hi) { return f2bf(lo) | (f2bf(hi) << 16); }
; __device__ __forceinline__ void transpose_item(const float* W, int ldw, int src_col0, bf16_t* WT, int Kd, int dst_row0, int k0, float scale, LAS float* scr, int lane) {
;     ...
;     const int c = lane & 7;
; #pragma unroll
;     for (int j = 0; j < 8; ++j) { const int n = (lane >> 3) + 8 * j; const LAS float* sp = scr + (8 * c) * 65 + n;
;         u32x4 o; o.x = pk2(sp[0 * 65], sp[1 * 65]); o.y = pk2(sp[2 * 65], sp[3 * 65]); o.z = pk2(sp[4 * 65], sp[5 * 65]); o.w = pk2(sp[6 * 65], sp[7 * 65]);
;         *(GAS u32x4*)(WT + (size_t)(dst_row0 + n) * Kd + k0 + 8 * c) = o; }
	v_bfe_u32 v21, v56, 16, 1
	s_and_b32 s8, s8, 0xfc0
	v_lshrrev_b32_e32 v0, 16, v0
	v_add3_u32 v21, v56, v21, s21
	s_addk_i32 s0, 0xfe00
	v_and_or_b32 v21, v21, s22, v0
	v_or_b32_e32 v0, s8, v32
	v_lshl_add_u64 v[16:17], s[0:1], 1, v[6:7]
	v_lshlrev_b32_e32 v0, 11, v0
	v_lshl_add_u64 v[58:59], v[16:17], 0, v[0:1]
	v_bfe_u32 v0, v23, 16, 1
	global_store_dwordx4 v[58:59], v[18:21], off
	v_add3_u32 v0, v23, v0, s21
	v_lshrrev_b32_e32 v0, 16, v0
	v_bfe_u32 v18, v25, 16, 1
	v_add3_u32 v18, v25, v18, s21
	v_and_or_b32 v18, v18, s22, v0
	v_bfe_u32 v0, v27, 16, 1
	v_add3_u32 v0, v27, v0, s21
	v_bfe_u32 v19, v29, 16, 1
	v_lshrrev_b32_e32 v0, 16, v0
	v_add3_u32 v19, v29, v19, s21
	v_and_or_b32 v19, v19, s22, v0
	v_bfe_u32 v0, v31, 16, 1
	v_add3_u32 v0, v31, v0, s21
	v_bfe_u32 v20, v53, 16, 1
	v_lshrrev_b32_e32 v0, 16, v0
	v_add3_u32 v20, v53, v20, s21
	v_and_or_b32 v20, v20, s22, v0
	v_bfe_u32 v0, v55, 16, 1
	v_add3_u32 v0, v55, v0, s21
	v_bfe_u32 v21, v57, 16, 1
	v_lshrrev_b32_e32 v0, 16, v0
	v_add3_u32 v21, v57, v21, s21
	v_and_or_b32 v21, v21, s22, v0
	v_or_b32_e32 v0, s8, v34
	v_lshlrev_b32_e32 v0, 11, v0
	ds_read2_b32 v[22:23], v33 offset0:16 offset1:24
	v_lshl_add_u64 v[24:25], v[16:17], 0, v[0:1]
	global_store_dwordx4 v[24:25], v[18:21], off
	ds_read2_b32 v[24:25], v33 offset0:81 offset1:89
	ds_read2_b32 v[26:27], v33 offset0:146 offset1:154
	ds_read2_b32 v[28:29], v33 offset0:211 offset1:219
	s_waitcnt lgkmcnt(3)
	v_bfe_u32 v0, v22, 16, 1
	v_add3_u32 v0, v22, v0, s21
	s_waitcnt lgkmcnt(2)
	v_bfe_u32 v18, v24, 16, 1
	ds_read2_b32 v[30:31], v60 offset0:20 offset1:28
	v_lshrrev_b32_e32 v0, 16, v0
	v_add3_u32 v18, v24, v18, s21
	ds_read2_b32 v[52:53], v60 offset0:85 offset1:93
	v_and_or_b32 v18, v18, s22, v0
	s_waitcnt lgkmcnt(3)
	v_bfe_u32 v0, v26, 16, 1
	v_add3_u32 v0, v26, v0, s21
	s_waitcnt lgkmcnt(2)
	v_bfe_u32 v19, v28, 16, 1
	ds_read2_b32 v[54:55], v60 offset0:150 offset1:158
	v_lshrrev_b32_e32 v0, 16, v0
	v_add3_u32 v19, v28, v19, s21
	ds_read2_b32 v[56:57], v60 offset0:215 offset1:223
	v_and_or_b32 v19, v19, s22, v0
	s_waitcnt lgkmcnt(3)
	v_bfe_u32 v0, v30, 16, 1
	v_add3_u32 v0, v30, v0, s21
	s_waitcnt lgkmcnt(2)
	v_bfe_u32 v20, v52, 16, 1
	v_lshrrev_b32_e32 v0, 16, v0
	v_add3_u32 v20, v52, v20, s21
	v_and_or_b32 v20, v20, s22, v0
	s_waitcnt lgkmcnt(1)
	v_bfe_u32 v0, v54, 16, 1
	v_add3_u32 v0, v54, v0, s21
	s_waitcnt lgkmcnt(0)
	v_bfe_u32 v21, v56, 16, 1
	v_lshrrev_b32_e32 v0, 16, v0
	v_add3_u32 v21, v56, v21, s21
	v_and_or_b32 v21, v21, s22, v0
	v_or_b32_e32 v0, s8, v35
	v_lshlrev_b32_e32 v0, 11, v0
	v_lshl_add_u64 v[58:59], v[16:17], 0, v[0:1]
	v_bfe_u32 v0, v23, 16, 1
	global_store_dwordx4 v[58:59], v[18:21], off
	v_add3_u32 v0, v23, v0, s21
	v_lshrrev_b32_e32 v0, 16, v0
	v_bfe_u32 v18, v25, 16, 1
	v_add3_u32 v18, v25, v18, s21
	v_and_or_b32 v18, v18, s22, v0
	v_bfe_u32 v0, v27, 16, 1
	v_add3_u32 v0, v27, v0, s21
	v_bfe_u32 v19, v29, 16, 1
	v_lshrrev_b32_e32 v0, 16, v0
	v_add3_u32 v19, v29, v19, s21
	v_and_or_b32 v19, v19, s22, v0
	v_bfe_u32 v0, v31, 16, 1
	v_add3_u32 v0, v31, v0, s21
	v_bfe_u32 v20, v53, 16, 1
	v_lshrrev_b32_e32 v0, 16, v0
	v_add3_u32 v20, v53, v20, s21
	v_and_or_b32 v20, v20, s22, v0
	v_bfe_u32 v0, v55, 16, 1
	v_add3_u32 v0, v55, v0, s21
	v_bfe_u32 v21, v57, 16, 1
	v_lshrrev_b32_e32 v0, 16, v0
	v_add3_u32 v21, v57, v21, s21
	v_and_or_b32 v21, v21, s22, v0
	v_or_b32_e32 v0, s8, v36
	v_lshlrev_b32_e32 v0, 11, v0
	ds_read2_b32 v[22:23], v33 offset0:32 offset1:40
	v_lshl_add_u64 v[24:25], v[16:17], 0, v[0:1]
	global_store_dwordx4 v[24:25], v[18:21], off
	ds_read2_b32 v[24:25], v33 offset0:97 offset1:105
	ds_read2_b32 v[26:27], v33 offset0:162 offset1:170
	ds_read2_b32 v[28:29], v33 offset0:227 offset1:235
	s_waitcnt lgkmcnt(3)
	v_bfe_u32 v0, v22, 16, 1
	v_add3_u32 v0, v22, v0, s21
	s_waitcnt lgkmcnt(2)
	v_bfe_u32 v18, v24, 16, 1
	ds_read2_b32 v[30:31], v60 offset0:36 offset1:44
	v_lshrrev_b32_e32 v0, 16, v0
	v_add3_u32 v18, v24, v18, s21
	ds_read2_b32 v[52:53], v60 offset0:101 offset1:109
	v_and_or_b32 v18, v18, s22, v0
	s_waitcnt lgkmcnt(3)
; #define LAS __attribute__((address_space(3)))
; #define GAS __attribute__((address_space(1)))
; __device__ __forceinline__ unsigned pk2(float lo, float hi) { return f2bf(lo) | (f2bf(hi) << 16); }
; #define LDS_WAIT() asm volatile("s_waitcnt lgkmcnt(0)" ::: "memory")
; __device__ __forceinline__ void transpose_item(const float* W, int ldw, int src_col0, bf16_t* WT, int Kd, int dst_row0, int k0, float scale, LAS float* scr, int lane) {
;     ...
;     const int c = lane & 7;
; #pragma unroll
;     for (int j = 0; j < 8; ++j) { const int n = (lane >> 3) + 8 * j; const LAS float* sp = scr + (8 * c) * 65 + n;
;         u32x4 o; o.x = pk2(sp[0 * 65], sp[1 * 65]); o.y = pk2(sp[2 * 65], sp[3 * 65]); o.z = pk2(sp[4 * 65], sp[5 * 65]); o.w = pk2(sp[6 * 65], sp[7 * 65]);
;         *(GAS u32x4*)(WT + (size_t)(dst_row0 + n) * Kd + k0 + 8 * c) = o; }
;     LDS_WAIT(); asm volatile("" ::: "memory");
	v_bfe_u32 v0, v26, 16, 1
	v_add3_u32 v0, v26, v0, s21
	s_waitcnt lgkmcnt(2)
	v_bfe_u32 v19, v28, 16, 1
	ds_read2_b32 v[54:55], v60 offset0:166 offset1:174
	v_lshrrev_b32_e32 v0, 16, v0
	v_add3_u32 v19, v28, v19, s21
	ds_read2_b32 v[56:57], v60 offset0:231 offset1:239
	v_and_or_b32 v19, v19, s22, v0
	s_waitcnt lgkmcnt(3)
	v_bfe_u32 v0, v30, 16, 1
	v_add3_u32 v0, v30, v0, s21
	s_waitcnt lgkmcnt(2)
	v_bfe_u32 v20, v52, 16, 1
	v_lshrrev_b32_e32 v0, 16, v0
	v_add3_u32 v20, v52, v20, s21
	v_and_or_b32 v20, v20, s22, v0
	s_waitcnt lgkmcnt(1)
	v_bfe_u32 v0, v54, 16, 1
	v_add3_u32 v0, v54, v0, s21
	s_waitcnt lgkmcnt(0)
	v_bfe_u32 v21, v56, 16, 1
	v_lshrrev_b32_e32 v0, 16, v0
	v_add3_u32 v21, v56, v21, s21
	v_and_or_b32 v21, v21, s22, v0
	v_or_b32_e32 v0, s8, v37
	v_lshlrev_b32_e32 v0, 11, v0
	v_lshl_add_u64 v[58:59], v[16:17], 0, v[0:1]
	v_bfe_u32 v0, v23, 16, 1
	global_store_dwordx4 v[58:59], v[18:21], off
	v_add3_u32 v0, v23, v0, s21
	v_lshrrev_b32_e32 v0, 16, v0
	v_bfe_u32 v18, v25, 16, 1
	v_add3_u32 v18, v25, v18, s21
	v_and_or_b32 v18, v18, s22, v0
	v_bfe_u32 v0, v27, 16, 1
	v_add3_u32 v0, v27, v0, s21
	v_bfe_u32 v19, v29, 16, 1
	v_lshrrev_b32_e32 v0, 16, v0
	v_add3_u32 v19, v29, v19, s21
	v_and_or_b32 v19, v19, s22, v0
	v_bfe_u32 v0, v31, 16, 1
	v_add3_u32 v0, v31, v0, s21
	v_bfe_u32 v20, v53, 16, 1
	v_lshrrev_b32_e32 v0, 16, v0
	v_add3_u32 v20, v53, v20, s21
	v_and_or_b32 v20, v20, s22, v0
	v_bfe_u32 v0, v55, 16, 1
	v_add3_u32 v0, v55, v0, s21
	v_bfe_u32 v21, v57, 16, 1
	v_lshrrev_b32_e32 v0, 16, v0
	v_add3_u32 v21, v57, v21, s21
	v_and_or_b32 v21, v21, s22, v0
	v_or_b32_e32 v0, s8, v38
	v_lshlrev_b32_e32 v0, 11, v0
	ds_read2_b32 v[22:23], v33 offset0:48 offset1:56
	v_lshl_add_u64 v[24:25], v[16:17], 0, v[0:1]
	global_store_dwordx4 v[24:25], v[18:21], off
	ds_read2_b32 v[24:25], v33 offset0:113 offset1:121
	ds_read2_b32 v[26:27], v33 offset0:178 offset1:186
	ds_read2_b32 v[28:29], v33 offset0:243 offset1:251
	s_waitcnt lgkmcnt(3)
	v_bfe_u32 v0, v22, 16, 1
	v_add3_u32 v0, v22, v0, s21
	s_waitcnt lgkmcnt(2)
	v_bfe_u32 v18, v24, 16, 1
	ds_read2_b32 v[30:31], v60 offset0:52 offset1:60
	v_lshrrev_b32_e32 v0, 16, v0
	v_add3_u32 v18, v24, v18, s21
	ds_read2_b32 v[52:53], v60 offset0:117 offset1:125
	v_and_or_b32 v18, v18, s22, v0
	s_waitcnt lgkmcnt(3)
	v_bfe_u32 v0, v26, 16, 1
	v_add3_u32 v0, v26, v0, s21
	s_waitcnt lgkmcnt(2)
	v_bfe_u32 v19, v28, 16, 1
	ds_read2_b32 v[54:55], v60 offset0:182 offset1:190
	v_lshrrev_b32_e32 v0, 16, v0
	v_add3_u32 v19, v28, v19, s21
	ds_read2_b32 v[56:57], v60 offset0:247 offset1:255
	v_and_or_b32 v19, v19, s22, v0
	s_waitcnt lgkmcnt(3)
	v_bfe_u32 v0, v30, 16, 1
	v_add3_u32 v0, v30, v0, s21
	s_waitcnt lgkmcnt(2)
	v_bfe_u32 v20, v52, 16, 1
	v_lshrrev_b32_e32 v0, 16, v0
	v_add3_u32 v20, v52, v20, s21
	v_and_or_b32 v20, v20, s22, v0
	s_waitcnt lgkmcnt(1)
	v_bfe_u32 v0, v54, 16, 1
	v_add3_u32 v0, v54, v0, s21
	s_waitcnt lgkmcnt(0)
	v_bfe_u32 v21, v56, 16, 1
	v_lshrrev_b32_e32 v0, 16, v0
	v_add3_u32 v21, v56, v21, s21
	v_and_or_b32 v21, v21, s22, v0
	v_or_b32_e32 v0, s8, v39
	v_lshlrev_b32_e32 v0, 11, v0
	v_lshl_add_u64 v[58:59], v[16:17], 0, v[0:1]
	v_bfe_u32 v0, v23, 16, 1
	global_store_dwordx4 v[58:59], v[18:21], off
	v_add3_u32 v0, v23, v0, s21
	v_lshrrev_b32_e32 v0, 16, v0
	v_bfe_u32 v18, v25, 16, 1
	v_add3_u32 v18, v25, v18, s21
	v_and_or_b32 v18, v18, s22, v0
	v_bfe_u32 v0, v27, 16, 1
	v_add3_u32 v0, v27, v0, s21
	v_bfe_u32 v19, v29, 16, 1
	v_lshrrev_b32_e32 v0, 16, v0
	v_add3_u32 v19, v29, v19, s21
	v_and_or_b32 v19, v19, s22, v0
	v_bfe_u32 v0, v31, 16, 1
	v_add3_u32 v0, v31, v0, s21
	v_bfe_u32 v20, v53, 16, 1
	v_lshrrev_b32_e32 v0, 16, v0
	v_add3_u32 v20, v53, v20, s21
	v_and_or_b32 v20, v20, s22, v0
	v_bfe_u32 v0, v55, 16, 1
	v_add3_u32 v0, v55, v0, s21
	v_bfe_u32 v21, v57, 16, 1
	v_lshrrev_b32_e32 v0, 16, v0
	v_add3_u32 v21, v57, v21, s21
	v_and_or_b32 v21, v21, s22, v0
	v_add_lshl_u32 v0, v40, s8, 11
	v_lshl_add_u64 v[16:17], v[16:17], 0, v[0:1]
	global_store_dwordx4 v[16:17], v[18:21], off
	s_waitcnt lgkmcnt(0)

; #define LAS __attribute__((address_space(3)))
; #define GAS __attribute__((address_space(1)))
; __device__ __forceinline__ void transpose_item(const float* W, int ldw, int src_col0, bf16_t* WT, int Kd, int dst_row0, int k0, float scale, LAS float* scr, int lane) {
;     ...
; #pragma unroll 8
;     for (int i = 0; i < 16; ++i) { const int kk = 4 * i + kr; const f32x4 v = __builtin_nontemporal_load((const GAS f32x4*)(W + (size_t)(k0 + kk) * ldw + src_col0 + 4 * c4)) * scale;
;         LAS float* d = scr + kk * 65 + 4 * c4; d[0] = v.x; d[1] = v.y; d[2] = v.z; d[3] = v.w; }
; template <int PART> __device__ __forceinline__ void phase_convert(Frame& F) {
;     ...
;             if (r < I_GLU) { const int nblk = 2 * D / 64, kb = r / nblk, nb = r % nblk, n0 = nb * 64;
;                 const int isg = n0 >= D, nn = isg ? n0 - D : n0, drow = 256 * (nn / 128) + 128 * isg + (nn % 128);
;                 transpose_item(F.in[14], 2 * D, n0, WGLU, D, drow, kb * 64, 1.f, scr, F.lane); continue; } r -= I_GLU;
.LBB0_260:
	v_add_u32_e32 v25, s11, v0
	v_add_u32_e32 v30, 12, v25
	v_add_u32_e32 v60, 16, v25
	v_add_u32_e32 v62, 20, v25
	v_add_u32_e32 v64, 24, v25
	v_add_u32_e32 v66, 28, v25
	v_ashrrev_i32_e32 v31, 31, v30
	v_ashrrev_i32_e32 v61, 31, v60
	v_ashrrev_i32_e32 v63, 31, v62
	v_ashrrev_i32_e32 v65, 31, v64
	v_ashrrev_i32_e32 v67, 31, v66
	v_lshlrev_b64 v[30:31], 13, v[30:31]
	v_lshlrev_b64 v[60:61], 13, v[60:61]
	v_lshlrev_b64 v[62:63], 13, v[62:63]
	v_lshlrev_b64 v[64:65], 13, v[64:65]
	v_lshlrev_b64 v[66:67], 13, v[66:67]
	global_load_dwordx4 v[26:29], v[22:23], off nt
	global_load_dwordx4 v[52:55], v[20:21], off nt
	global_load_dwordx4 v[56:59], v[18:19], off nt
	v_lshl_add_u64 v[30:31], v[16:17], 0, v[30:31]
	v_lshl_add_u64 v[68:69], v[16:17], 0, v[60:61]
	v_lshl_add_u64 v[70:71], v[16:17], 0, v[62:63]
	v_lshl_add_u64 v[72:73], v[16:17], 0, v[64:65]
	v_lshl_add_u64 v[76:77], v[16:17], 0, v[66:67]
	global_load_dwordx4 v[60:63], v[30:31], off nt
	global_load_dwordx4 v[64:67], v[68:69], off nt
	s_nop 0
	global_load_dwordx4 v[68:71], v[70:71], off nt
	s_nop 0
	global_load_dwordx4 v[72:75], v[72:73], off nt
	s_nop 0
	global_load_dwordx4 v[76:79], v[76:77], off nt
	s_add_i32 s11, s11, 32
	v_lshl_add_u64 v[18:19], v[18:19], 0, s[6:7]
	v_lshl_add_u64 v[20:21], v[20:21], 0, s[6:7]
	v_lshl_add_u64 v[22:23], v[22:23], 0, s[6:7]
	v_add_u32_e32 v141, s11, v0
	v_add_u32_e32 v146, 12, v141
	v_add_u32_e32 v176, 16, v141
	v_add_u32_e32 v178, 20, v141
	v_add_u32_e32 v180, 24, v141
	v_add_u32_e32 v182, 28, v141
	v_ashrrev_i32_e32 v147, 31, v146
	v_ashrrev_i32_e32 v177, 31, v176
	v_ashrrev_i32_e32 v179, 31, v178
	v_ashrrev_i32_e32 v181, 31, v180
	v_ashrrev_i32_e32 v183, 31, v182
	v_lshlrev_b64 v[146:147], 13, v[146:147]
	v_lshlrev_b64 v[176:177], 13, v[176:177]
	v_lshlrev_b64 v[178:179], 13, v[178:179]
	v_lshlrev_b64 v[180:181], 13, v[180:181]
	v_lshlrev_b64 v[182:183], 13, v[182:183]
	global_load_dwordx4 v[142:145], v[22:23], off nt
	global_load_dwordx4 v[168:171], v[20:21], off nt
	global_load_dwordx4 v[172:175], v[18:19], off nt
	v_lshl_add_u64 v[146:147], v[16:17], 0, v[146:147]
	v_lshl_add_u64 v[184:185], v[16:17], 0, v[176:177]
	v_lshl_add_u64 v[186:187], v[16:17], 0, v[178:179]
	v_lshl_add_u64 v[188:189], v[16:17], 0, v[180:181]
	v_lshl_add_u64 v[192:193], v[16:17], 0, v[182:183]
	global_load_dwordx4 v[176:179], v[146:147], off nt
	global_load_dwordx4 v[180:183], v[184:185], off nt
	s_nop 0
	global_load_dwordx4 v[184:187], v[186:187], off nt
	s_nop 0
	global_load_dwordx4 v[188:191], v[188:189], off nt
	s_nop 0
	global_load_dwordx4 v[192:195], v[192:193], off nt
	v_add_u32_e32 v25, 0x410, v24
	v_add_u32_e32 v30, 0x418, v24
	v_add_u32_e32 v31, 0x820, v24
	v_add_u32_e32 v80, 0x828, v24
	v_add_u32_e32 v81, 0xc30, v24
	v_add_u32_e32 v82, 0xc38, v24
	v_add_u32_e32 v83, 0x1040, v24
	v_add_u32_e32 v84, 0x1048, v24
	v_add_u32_e32 v85, 0x1450, v24
	v_add_u32_e32 v86, 0x1458, v24
	v_add_u32_e32 v87, 0x1860, v24
	v_add_u32_e32 v88, 0x1868, v24
	v_add_u32_e32 v89, 0x1c70, v24
	v_add_u32_e32 v90, 0x1c78, v24
	s_waitcnt vmcnt(15)
	ds_write2_b32 v24, v26, v27 offset1:1
	ds_write2_b32 v24, v28, v29 offset0:2 offset1:3
	s_waitcnt vmcnt(14)
	ds_write2_b32 v25, v52, v53 offset1:1
	ds_write2_b32 v30, v54, v55 offset1:1
	s_waitcnt vmcnt(13)
	ds_write2_b32 v31, v56, v57 offset1:1
	ds_write2_b32 v80, v58, v59 offset1:1
	v_add_u32_e32 v24, 0x2080, v24
	s_waitcnt vmcnt(12)
	ds_write2_b32 v81, v60, v61 offset1:1
	ds_write2_b32 v82, v62, v63 offset1:1
	s_waitcnt vmcnt(11)
	ds_write2_b32 v83, v64, v65 offset1:1
	ds_write2_b32 v84, v66, v67 offset1:1
	s_waitcnt vmcnt(10)
	ds_write2_b32 v85, v68, v69 offset1:1
	ds_write2_b32 v86, v70, v71 offset1:1
	s_waitcnt vmcnt(9)
	ds_write2_b32 v87, v72, v73 offset1:1
	ds_write2_b32 v88, v74, v75 offset1:1
	s_waitcnt vmcnt(8)
	ds_write2_b32 v89, v76, v77 offset1:1
	ds_write2_b32 v90, v78, v79 offset1:1
	s_add_i32 s11, s11, 32
	v_lshl_add_u64 v[18:19], v[18:19], 0, s[6:7]
	v_lshl_add_u64 v[20:21], v[20:21], 0, s[6:7]
	v_lshl_add_u64 v[22:23], v[22:23], 0, s[6:7]
	v_add_u32_e32 v25, 0x410, v24
	v_add_u32_e32 v30, 0x418, v24
	v_add_u32_e32 v31, 0x820, v24
	v_add_u32_e32 v80, 0x828, v24
	v_add_u32_e32 v81, 0xc30, v24
	v_add_u32_e32 v82, 0xc38, v24
	v_add_u32_e32 v83, 0x1040, v24
	v_add_u32_e32 v84, 0x1048, v24
	v_add_u32_e32 v85, 0x1450, v24
	v_add_u32_e32 v86, 0x1458, v24
	v_add_u32_e32 v87, 0x1860, v24
	v_add_u32_e32 v88, 0x1868, v24
	v_add_u32_e32 v89, 0x1c70, v24
	v_add_u32_e32 v90, 0x1c78, v24
	s_waitcnt vmcnt(7)
	ds_write2_b32 v24, v142, v143 offset1:1
	ds_write2_b32 v24, v144, v145 offset0:2 offset1:3
	s_waitcnt vmcnt(6)
	ds_write2_b32 v25, v168, v169 offset1:1
	ds_write2_b32 v30, v170, v171 offset1:1
	s_waitcnt vmcnt(5)
	ds_write2_b32 v31, v172, v173 offset1:1
	ds_write2_b32 v80, v174, v175 offset1:1
	v_add_u32_e32 v24, 0x2080, v24
	s_waitcnt vmcnt(4)
	ds_write2_b32 v81, v176, v177 offset1:1
	ds_write2_b32 v82, v178, v179 offset1:1
	s_waitcnt vmcnt(3)
	ds_write2_b32 v83, v180, v181 offset1:1
	ds_write2_b32 v84, v182, v183 offset1:1
	s_waitcnt vmcnt(2)
	ds_write2_b32 v85, v184, v185 offset1:1
	ds_write2_b32 v86, v186, v187 offset1:1
	s_waitcnt vmcnt(1)
	ds_write2_b32 v87, v188, v189 offset1:1
	ds_write2_b32 v88, v190, v191 offset1:1
	s_waitcnt vmcnt(0)
	ds_write2_b32 v89, v192, v193 offset1:1
	ds_write2_b32 v90, v194, v195 offset1:1
	s_waitcnt lgkmcnt(0)
	ds_read2_b32 v[22:23], v33 offset1:8
	ds_read2_b32 v[24:25], v33 offset0:65 offset1:73
	s_add_i32 s11, s10, 0xfc00
	ds_read2_b32 v[26:27], v33 offset0:130 offset1:138
	s_cmp_gt_i32 s0, 15
	ds_read2_b32 v[28:29], v33 offset0:195 offset1:203
	s_cselect_b32 s0, s11, s10
	s_waitcnt lgkmcnt(3)
; #define LAS __attribute__((address_space(3)))
; #define GAS __attribute__((address_space(1)))
; __device__ __forceinline__ unsigned pk2(float lo, float hi) { return f2bf(lo) | (f2bf(hi) << 16); }
; __device__ __forceinline__ void transpose_item(const float* W, int ldw, int src_col0, bf16_t* WT, int Kd, int dst_row0, int k0, float scale, LAS float* scr, int lane) {
;     ...
;     const int c = lane & 7;
; #pragma unroll
;     for (int j = 0; j < 8; ++j) { const int n = (lane >> 3) + 8 * j; const LAS float* sp = scr + (8 * c) * 65 + n;
;         u32x4 o; o.x = pk2(sp[0 * 65], sp[1 * 65]); o.y = pk2(sp[2 * 65], sp[3 * 65]); o.z = pk2(sp[4 * 65], sp[5 * 65]); o.w = pk2(sp[6 * 65], sp[7 * 65]);
;         *(GAS u32x4*)(WT + (size_t)(dst_row0 + n) * Kd + k0 + 8 * c) = o; }
; template <int PART> __device__ __forceinline__ void phase_convert(Frame& F) {
;     ...
;             if (r < I_GLU) { const int nblk = 2 * D / 64, kb = r / nblk, nb = r % nblk, n0 = nb * 64;
;                 const int isg = n0 >= D, nn = isg ? n0 - D : n0, drow = 256 * (nn / 128) + 128 * isg + (nn % 128);
	v_bfe_u32 v0, v22, 16, 1
	v_add_u32_e32 v60, 0x400, v33
	s_sext_i32_i16 s10, s0
	v_add3_u32 v0, v22, v0, s21
	s_waitcnt lgkmcnt(2)
	v_bfe_u32 v18, v24, 16, 1
	ds_read2_b32 v[30:31], v60 offset0:4 offset1:12
	s_cselect_b32 s11, 0x80, 0
	s_bfe_u32 s10, s10, 0x70018
	v_lshrrev_b32_e32 v0, 16, v0
	v_add3_u32 v18, v24, v18, s21
	ds_read2_b32 v[52:53], v60 offset0:69 offset1:77
	s_add_i32 s10, s0, s10
	v_and_or_b32 v18, v18, s22, v0
	s_waitcnt lgkmcnt(3)
	v_bfe_u32 v0, v26, 16, 1
	s_sext_i32_i16 s23, s10
	s_and_b32 s10, s10, 0xff80
	v_add3_u32 v0, v26, v0, s21
	s_waitcnt lgkmcnt(2)
	v_bfe_u32 v19, v28, 16, 1
	ds_read2_b32 v[54:55], v60 offset0:134 offset1:142
	s_sub_i32 s0, s0, s10
	v_lshrrev_b32_e32 v0, 16, v0
	v_add3_u32 v19, v28, v19, s21
	ds_read2_b32 v[56:57], v60 offset0:199 offset1:207
	s_sext_i32_i16 s0, s0
	s_lshl_b32 s10, s23, 1
	v_and_or_b32 v19, v19, s22, v0
	s_waitcnt lgkmcnt(3)
	v_bfe_u32 v0, v30, 16, 1
	s_add_i32 s0, s11, s0
	s_and_b32 s10, s10, 0xffffff00
	v_add3_u32 v0, v30, v0, s21
	s_waitcnt lgkmcnt(2)
	v_bfe_u32 v20, v52, 16, 1
	s_add_i32 s0, s0, s10
	v_lshrrev_b32_e32 v0, 16, v0
	v_add3_u32 v20, v52, v20, s21
	v_and_or_b32 v20, v20, s22, v0
	s_waitcnt lgkmcnt(1)
	v_bfe_u32 v0, v54, 16, 1
	v_add_u32_e32 v58, s0, v32
	v_add3_u32 v0, v54, v0, s21
	s_waitcnt lgkmcnt(0)
	v_bfe_u32 v21, v56, 16, 1
	v_ashrrev_i32_e32 v59, 31, v58
	v_lshl_add_u64 v[16:17], s[8:9], 1, v[10:11]
	v_lshrrev_b32_e32 v0, 16, v0
	v_add3_u32 v21, v56, v21, s21
	v_lshlrev_b64 v[58:59], 11, v[58:59]
	v_and_or_b32 v21, v21, s22, v0
	v_lshl_add_u64 v[58:59], v[16:17], 0, v[58:59]
	v_bfe_u32 v0, v23, 16, 1
	global_store_dwordx4 v[58:59], v[18:21], off
	v_add3_u32 v0, v23, v0, s21
	v_lshrrev_b32_e32 v0, 16, v0
	v_bfe_u32 v18, v25, 16, 1
	v_add3_u32 v18, v25, v18, s21
	v_and_or_b32 v18, v18, s22, v0
	v_bfe_u32 v0, v27, 16, 1
	v_add3_u32 v0, v27, v0, s21
	v_bfe_u32 v19, v29, 16, 1
	v_lshrrev_b32_e32 v0, 16, v0
	v_add3_u32 v19, v29, v19, s21
	v_and_or_b32 v19, v19, s22, v0
	v_bfe_u32 v0, v31, 16, 1
	v_add3_u32 v0, v31, v0, s21
	v_bfe_u32 v20, v53, 16, 1
	v_lshrrev_b32_e32 v0, 16, v0
	v_add3_u32 v20, v53, v20, s21
	v_and_or_b32 v20, v20, s22, v0
	v_bfe_u32 v0, v55, 16, 1
	v_add_u32_e32 v22, s0, v34
	v_add3_u32 v0, v55, v0, s21
	v_bfe_u32 v21, v57, 16, 1
	v_ashrrev_i32_e32 v23, 31, v22
	v_lshrrev_b32_e32 v0, 16, v0
	v_add3_u32 v21, v57, v21, s21
	v_lshlrev_b64 v[22:23], 11, v[22:23]
	v_and_or_b32 v21, v21, s22, v0
	ds_read2_b32 v[24:25], v33 offset0:16 offset1:24
	v_lshl_add_u64 v[22:23], v[16:17], 0, v[22:23]
	global_store_dwordx4 v[22:23], v[18:21], off
	ds_read2_b32 v[22:23], v33 offset0:81 offset1:89
	ds_read2_b32 v[26:27], v33 offset0:146 offset1:154
	ds_read2_b32 v[28:29], v33 offset0:211 offset1:219
	s_waitcnt lgkmcnt(3)
	v_bfe_u32 v0, v24, 16, 1
	v_add3_u32 v0, v24, v0, s21
	s_waitcnt lgkmcnt(2)
	v_bfe_u32 v18, v22, 16, 1
	ds_read2_b32 v[30:31], v60 offset0:20 offset1:28
	v_lshrrev_b32_e32 v0, 16, v0
	v_add3_u32 v18, v22, v18, s21
	ds_read2_b32 v[52:53], v60 offset0:85 offset1:93
	v_and_or_b32 v18, v18, s22, v0
	s_waitcnt lgkmcnt(3)
	v_bfe_u32 v0, v26, 16, 1
	v_add3_u32 v0, v26, v0, s21
	s_waitcnt lgkmcnt(2)
	v_bfe_u32 v19, v28, 16, 1
	ds_read2_b32 v[54:55], v60 offset0:150 offset1:158
	v_lshrrev_b32_e32 v0, 16, v0
	v_add3_u32 v19, v28, v19, s21
	ds_read2_b32 v[56:57], v60 offset0:215 offset1:223
	v_and_or_b32 v19, v19, s22, v0
	s_waitcnt lgkmcnt(3)
	v_bfe_u32 v0, v30, 16, 1
	v_add3_u32 v0, v30, v0, s21
	s_waitcnt lgkmcnt(2)
	v_bfe_u32 v20, v52, 16, 1
	v_lshrrev_b32_e32 v0, 16, v0
	v_add3_u32 v20, v52, v20, s21
	v_and_or_b32 v20, v20, s22, v0
	s_waitcnt lgkmcnt(1)
	v_bfe_u32 v0, v54, 16, 1
	v_add_u32_e32 v58, s0, v35
	v_add3_u32 v0, v54, v0, s21
	s_waitcnt lgkmcnt(0)
	v_bfe_u32 v21, v56, 16, 1
	v_ashrrev_i32_e32 v59, 31, v58
	v_lshrrev_b32_e32 v0, 16, v0
	v_add3_u32 v21, v56, v21, s21
	v_lshlrev_b64 v[58:59], 11, v[58:59]
	v_and_or_b32 v21, v21, s22, v0
	v_lshl_add_u64 v[58:59], v[16:17], 0, v[58:59]
	v_bfe_u32 v0, v25, 16, 1
	global_store_dwordx4 v[58:59], v[18:21], off
	v_add3_u32 v0, v25, v0, s21
	v_lshrrev_b32_e32 v0, 16, v0
	v_bfe_u32 v18, v23, 16, 1
	v_add3_u32 v18, v23, v18, s21
	v_and_or_b32 v18, v18, s22, v0
	v_bfe_u32 v0, v27, 16, 1
	v_add3_u32 v0, v27, v0, s21
	v_bfe_u32 v19, v29, 16, 1
	v_lshrrev_b32_e32 v0, 16, v0
	v_add3_u32 v19, v29, v19, s21
	v_and_or_b32 v19, v19, s22, v0
	v_bfe_u32 v0, v31, 16, 1
	v_add3_u32 v0, v31, v0, s21
	v_bfe_u32 v20, v53, 16, 1
	v_lshrrev_b32_e32 v0, 16, v0
	v_add3_u32 v20, v53, v20, s21
	v_and_or_b32 v20, v20, s22, v0
	v_bfe_u32 v0, v55, 16, 1
	v_add_u32_e32 v22, s0, v36
	v_add3_u32 v0, v55, v0, s21
	v_bfe_u32 v21, v57, 16, 1
	v_ashrrev_i32_e32 v23, 31, v22
	v_lshrrev_b32_e32 v0, 16, v0
	v_add3_u32 v21, v57, v21, s21
	v_lshlrev_b64 v[22:23], 11, v[22:23]
	v_and_or_b32 v21, v21, s22, v0
	ds_read2_b32 v[24:25], v33 offset0:32 offset1:40
	v_lshl_add_u64 v[22:23], v[16:17], 0, v[22:23]
	global_store_dwordx4 v[22:23], v[18:21], off
	ds_read2_b32 v[22:23], v33 offset0:97 offset1:105
	ds_read2_b32 v[26:27], v33 offset0:162 offset1:170
	ds_read2_b32 v[28:29], v33 offset0:227 offset1:235
	s_waitcnt lgkmcnt(3)
; #define LAS __attribute__((address_space(3)))
; #define GAS __attribute__((address_space(1)))
; __device__ __forceinline__ unsigned pk2(float lo, float hi) { return f2bf(lo) | (f2bf(hi) << 16); }
; #define LDS_WAIT() asm volatile("s_waitcnt lgkmcnt(0)" ::: "memory")
; __device__ __forceinline__ void transpose_item(const float* W, int ldw, int src_col0, bf16_t* WT, int Kd, int dst_row0, int k0, float scale, LAS float* scr, int lane) {
;     ...
;     const int c = lane & 7;
; #pragma unroll
;     for (int j = 0; j < 8; ++j) { const int n = (lane >> 3) + 8 * j; const LAS float* sp = scr + (8 * c) * 65 + n;
;         u32x4 o; o.x = pk2(sp[0 * 65], sp[1 * 65]); o.y = pk2(sp[2 * 65], sp[3 * 65]); o.z = pk2(sp[4 * 65], sp[5 * 65]); o.w = pk2(sp[6 * 65], sp[7 * 65]);
;         *(GAS u32x4*)(WT + (size_t)(dst_row0 + n) * Kd + k0 + 8 * c) = o; }
;     LDS_WAIT(); asm volatile("" ::: "memory");
	v_bfe_u32 v0, v24, 16, 1
	v_add3_u32 v0, v24, v0, s21
	s_waitcnt lgkmcnt(2)
	v_bfe_u32 v18, v22, 16, 1
	ds_read2_b32 v[30:31], v60 offset0:36 offset1:44
	v_lshrrev_b32_e32 v0, 16, v0
	v_add3_u32 v18, v22, v18, s21
	ds_read2_b32 v[52:53], v60 offset0:101 offset1:109
	v_and_or_b32 v18, v18, s22, v0
	s_waitcnt lgkmcnt(3)
	v_bfe_u32 v0, v26, 16, 1
	v_add3_u32 v0, v26, v0, s21
	s_waitcnt lgkmcnt(2)
	v_bfe_u32 v19, v28, 16, 1
	ds_read2_b32 v[54:55], v60 offset0:166 offset1:174
	v_lshrrev_b32_e32 v0, 16, v0
	v_add3_u32 v19, v28, v19, s21
	ds_read2_b32 v[56:57], v60 offset0:231 offset1:239
	v_and_or_b32 v19, v19, s22, v0
	s_waitcnt lgkmcnt(3)
	v_bfe_u32 v0, v30, 16, 1
	v_add3_u32 v0, v30, v0, s21
	s_waitcnt lgkmcnt(2)
	v_bfe_u32 v20, v52, 16, 1
	v_lshrrev_b32_e32 v0, 16, v0
	v_add3_u32 v20, v52, v20, s21
	v_and_or_b32 v20, v20, s22, v0
	s_waitcnt lgkmcnt(1)
	v_bfe_u32 v0, v54, 16, 1
	v_add_u32_e32 v58, s0, v37
	v_add3_u32 v0, v54, v0, s21
	s_waitcnt lgkmcnt(0)
	v_bfe_u32 v21, v56, 16, 1
	v_ashrrev_i32_e32 v59, 31, v58
	v_lshrrev_b32_e32 v0, 16, v0
	v_add3_u32 v21, v56, v21, s21
	v_lshlrev_b64 v[58:59], 11, v[58:59]
	v_and_or_b32 v21, v21, s22, v0
	v_lshl_add_u64 v[58:59], v[16:17], 0, v[58:59]
	v_bfe_u32 v0, v25, 16, 1
	global_store_dwordx4 v[58:59], v[18:21], off
	v_add3_u32 v0, v25, v0, s21
	v_lshrrev_b32_e32 v0, 16, v0
	v_bfe_u32 v18, v23, 16, 1
	v_add3_u32 v18, v23, v18, s21
	v_and_or_b32 v18, v18, s22, v0
	v_bfe_u32 v0, v27, 16, 1
	v_add3_u32 v0, v27, v0, s21
	v_bfe_u32 v19, v29, 16, 1
	v_lshrrev_b32_e32 v0, 16, v0
	v_add3_u32 v19, v29, v19, s21
	v_and_or_b32 v19, v19, s22, v0
	v_bfe_u32 v0, v31, 16, 1
	v_add3_u32 v0, v31, v0, s21
	v_bfe_u32 v20, v53, 16, 1
	v_lshrrev_b32_e32 v0, 16, v0
	v_add3_u32 v20, v53, v20, s21
	v_and_or_b32 v20, v20, s22, v0
	v_bfe_u32 v0, v55, 16, 1
	v_add_u32_e32 v22, s0, v38
	v_add3_u32 v0, v55, v0, s21
	v_bfe_u32 v21, v57, 16, 1
	v_ashrrev_i32_e32 v23, 31, v22
	v_lshrrev_b32_e32 v0, 16, v0
	v_add3_u32 v21, v57, v21, s21
	v_lshlrev_b64 v[22:23], 11, v[22:23]
	v_and_or_b32 v21, v21, s22, v0
	ds_read2_b32 v[24:25], v33 offset0:48 offset1:56
	v_lshl_add_u64 v[22:23], v[16:17], 0, v[22:23]
	global_store_dwordx4 v[22:23], v[18:21], off
	ds_read2_b32 v[22:23], v33 offset0:113 offset1:121
	ds_read2_b32 v[26:27], v33 offset0:178 offset1:186
	ds_read2_b32 v[28:29], v33 offset0:243 offset1:251
	s_waitcnt lgkmcnt(3)
	v_bfe_u32 v0, v24, 16, 1
	v_add3_u32 v0, v24, v0, s21
	s_waitcnt lgkmcnt(2)
	v_bfe_u32 v18, v22, 16, 1
	ds_read2_b32 v[30:31], v60 offset0:52 offset1:60
	v_lshrrev_b32_e32 v0, 16, v0
	v_add3_u32 v18, v22, v18, s21
	ds_read2_b32 v[52:53], v60 offset0:117 offset1:125
	v_and_or_b32 v18, v18, s22, v0
	s_waitcnt lgkmcnt(3)
	v_bfe_u32 v0, v26, 16, 1
	v_add3_u32 v0, v26, v0, s21
	s_waitcnt lgkmcnt(2)
	v_bfe_u32 v19, v28, 16, 1
	ds_read2_b32 v[54:55], v60 offset0:182 offset1:190
	v_lshrrev_b32_e32 v0, 16, v0
	v_add3_u32 v19, v28, v19, s21
	ds_read2_b32 v[56:57], v60 offset0:247 offset1:255
	v_and_or_b32 v19, v19, s22, v0
	s_waitcnt lgkmcnt(3)
	v_bfe_u32 v0, v30, 16, 1
	v_add3_u32 v0, v30, v0, s21
	s_waitcnt lgkmcnt(2)
	v_bfe_u32 v20, v52, 16, 1
	v_lshrrev_b32_e32 v0, 16, v0
	v_add3_u32 v20, v52, v20, s21
	v_and_or_b32 v20, v20, s22, v0
	s_waitcnt lgkmcnt(1)
	v_bfe_u32 v0, v54, 16, 1
	v_add_u32_e32 v58, s0, v39
	v_add3_u32 v0, v54, v0, s21
	s_waitcnt lgkmcnt(0)
	v_bfe_u32 v21, v56, 16, 1
	v_ashrrev_i32_e32 v59, 31, v58
	v_lshrrev_b32_e32 v0, 16, v0
	v_add3_u32 v21, v56, v21, s21
	v_lshlrev_b64 v[58:59], 11, v[58:59]
	v_and_or_b32 v21, v21, s22, v0
	v_lshl_add_u64 v[58:59], v[16:17], 0, v[58:59]
	v_bfe_u32 v0, v25, 16, 1
	global_store_dwordx4 v[58:59], v[18:21], off
	v_add3_u32 v0, v25, v0, s21
	v_lshrrev_b32_e32 v0, 16, v0
	v_bfe_u32 v18, v23, 16, 1
	v_add3_u32 v18, v23, v18, s21
	v_and_or_b32 v18, v18, s22, v0
	v_bfe_u32 v0, v27, 16, 1
	v_add3_u32 v0, v27, v0, s21
	v_bfe_u32 v19, v29, 16, 1
	v_lshrrev_b32_e32 v0, 16, v0
	v_add3_u32 v19, v29, v19, s21
	v_and_or_b32 v19, v19, s22, v0
	v_bfe_u32 v0, v31, 16, 1
	v_add3_u32 v0, v31, v0, s21
	v_bfe_u32 v20, v53, 16, 1
	v_lshrrev_b32_e32 v0, 16, v0
	v_add3_u32 v20, v53, v20, s21
	v_and_or_b32 v20, v20, s22, v0
	v_bfe_u32 v0, v55, 16, 1
	v_add_u32_e32 v22, s0, v40
	v_add3_u32 v0, v55, v0, s21
	v_bfe_u32 v21, v57, 16, 1
	v_ashrrev_i32_e32 v23, 31, v22
	v_lshrrev_b32_e32 v0, 16, v0
	v_add3_u32 v21, v57, v21, s21
	v_lshlrev_b64 v[22:23], 11, v[22:23]
	v_and_or_b32 v21, v21, s22, v0
	v_lshl_add_u64 v[16:17], v[16:17], 0, v[22:23]
	global_store_dwordx4 v[16:17], v[18:21], off
	s_waitcnt lgkmcnt(0)
	s_branch .LBB0_247

;     __device__ __forceinline__ void epi(AccT& acc, const Unit& u, LAS unsigned char* lds, int wr, int wc, int fr, int fq) const {
;     ...
;             __builtin_amdgcn_fence(__ATOMIC_ACQUIRE, "agent");
;             if (lane == 0) flag[0] = dead ? 1u : 0u;
.LBB0_455:
	s_waitcnt vmcnt(0)
	s_and_b64 exec, exec, s[8:9]
	v_cndmask_b32_e64 v2, 0, 1, s[62:63]
	v_mov_b32_e32 v3, s74
	ds_write_b32 v3, v2

; __device__ __forceinline__ unsigned cvt_pk_bf16(float lo, float hi) { const f32x2 v = {lo, hi}; const bf16x2_t b = __builtin_convertvector(v, bf16x2_t); return __builtin_bit_cast(unsigned, b); }
;     __device__ __forceinline__ void epi(AccT& acc, const Unit& u, LAS unsigned char* lds, int wr, int wc, int fr, int fq) const {
;     ...
;         for (int ai = 0; ai < 2; ++ai)
; #pragma unroll
;             for (int m = 0; m < 4; ++m) { const int r = ai * 128 + wr * 64 + m * 16 + fr; const float rs = bad ? qnan : Sl[r]; const size_t grow = (size_t)(u.pm * 256 + r);
;                 const f32x4 x0 = acc[ai][0][m][0], x1 = acc[ai][0][m][1]; const f32x4 h0 = x0 * rs * sv[0] + tv[0], h1 = x1 * rs * sv[1] + tv[1]; u32x4 q, p;
;                 q.x = cvt_pk_bf16(x0[0], x0[1]); q.y = cvt_pk_bf16(x0[2], x0[3]); q.z = cvt_pk_bf16(x1[0], x1[1]); q.w = cvt_pk_bf16(x1[2], x1[3]);
;                 p.x = cvt_pk_bf16(h0[0], h0[1]); p.y = cvt_pk_bf16(h0[2], h0[3]); p.z = cvt_pk_bf16(h1[0], h1[1]); p.w = cvt_pk_bf16(h1[2], h1[3]);
;                 *(u32x4*)(XH + grow * (2 * D) + col0) = q; *(u32x4*)(H + grow * D + col0) = p; }
.LBB0_462:
	s_waitcnt vmcnt(3)
	v_pk_add_f32 v[22:23], v[22:23], 1.0 op_sel_hi:[1,0]
	s_waitcnt vmcnt(2)
	v_pk_add_f32 v[18:19], v[18:19], 1.0 op_sel_hi:[1,0]
	v_pk_add_f32 v[20:21], v[20:21], 1.0 op_sel_hi:[1,0]
	v_pk_mul_f32 v[14:15], v[14:15], v[22:23]
	v_pk_add_f32 v[16:17], v[16:17], 1.0 op_sel_hi:[1,0]
	v_pk_mul_f32 v[10:11], v[10:11], v[18:19]
	s_waitcnt lgkmcnt(0)
	v_pk_mul_f32 v[18:19], v[136:137], v[54:55] op_sel_hi:[1,0]
	v_pk_mul_f32 v[12:13], v[12:13], v[20:21]
	v_pk_mul_f32 v[8:9], v[8:9], v[16:17]
	v_pk_mul_f32 v[16:17], v[124:125], v[54:55] op_sel_hi:[1,0]
	s_waitcnt vmcnt(0)
	v_pk_fma_f32 v[22:23], v[14:15], v[18:19], v[6:7]
	v_pk_mul_f32 v[18:19], v[128:129], v[54:55] op_sel_hi:[1,0]
	v_pk_fma_f32 v[20:21], v[12:13], v[16:17], v[4:5]
	v_pk_mul_f32 v[16:17], v[126:127], v[54:55] op_sel_hi:[1,0]
	v_pk_fma_f32 v[54:55], v[10:11], v[18:19], v[2:3]
	v_pk_fma_f32 v[60:61], v[8:9], v[16:17], v[0:1]
	v_cvt_pk_bf16_f32 v16, v124, v125
	v_cvt_pk_bf16_f32 v17, v136, v137
	v_cvt_pk_bf16_f32 v18, v126, v127
	v_cvt_pk_bf16_f32 v19, v128, v129
	v_cvt_pk_bf16_f32 v20, v20, v21
	v_cvt_pk_bf16_f32 v21, v22, v23
	v_cvt_pk_bf16_f32 v23, v54, v55
	v_lshl_add_u64 v[54:55], v[200:201], 0, v[208:209]
	global_store_dwordx4 v[54:55], v[16:19], off
	v_cvt_pk_bf16_f32 v22, v60, v61
	s_andn2_b64 vcc, exec, s[14:15]
	v_lshlrev_b64 v[16:17], 11, v[206:207]
	v_cndmask_b32_e64 v18, 0, 1, s[14:15]
	v_lshl_add_u64 v[16:17], v[202:203], 0, v[16:17]
	v_cmp_ne_u32_e64 s[12:13], 1, v18
	global_store_dwordx4 v[16:17], v[20:23], off
	s_cbranch_vccnz .LBB0_464
	ds_read_b32 v52, v220
.LBB0_464:
	s_waitcnt lgkmcnt(0)
	v_pk_mul_f32 v[18:19], v[106:107], v[52:53] op_sel_hi:[1,0]
	v_add_u32_e32 v54, s20, v219
	v_pk_mul_f32 v[16:17], v[104:105], v[52:53] op_sel_hi:[1,0]
	v_pk_fma_f32 v[22:23], v[14:15], v[18:19], v[6:7]
	v_pk_mul_f32 v[18:19], v[98:99], v[52:53] op_sel_hi:[1,0]
	v_ashrrev_i32_e32 v55, 31, v54
	v_pk_fma_f32 v[20:21], v[12:13], v[16:17], v[4:5]
	v_pk_mul_f32 v[16:17], v[96:97], v[52:53] op_sel_hi:[1,0]
	v_pk_fma_f32 v[52:53], v[10:11], v[18:19], v[2:3]
	v_cvt_pk_bf16_f32 v20, v20, v21
	v_cvt_pk_bf16_f32 v21, v22, v23
	v_cvt_pk_bf16_f32 v23, v52, v53
	v_lshlrev_b64 v[52:53], 12, v[54:55]
	v_pk_fma_f32 v[60:61], v[8:9], v[16:17], v[0:1]
	v_cvt_pk_bf16_f32 v16, v104, v105
	v_cvt_pk_bf16_f32 v17, v106, v107
	v_cvt_pk_bf16_f32 v18, v96, v97
	v_cvt_pk_bf16_f32 v19, v98, v99
	v_lshl_add_u64 v[52:53], v[200:201], 0, v[52:53]
	global_store_dwordx4 v[52:53], v[16:19], off
	v_cvt_pk_bf16_f32 v22, v60, v61
	s_and_b64 vcc, exec, s[12:13]
	v_lshlrev_b64 v[16:17], 11, v[54:55]
	v_lshl_add_u64 v[16:17], v[202:203], 0, v[16:17]
	global_store_dwordx4 v[16:17], v[20:23], off
	v_mov_b32_e32 v16, 0x7fc00000
	v_mov_b32_e32 v18, 0x7fc00000
	s_cbranch_vccnz .LBB0_466
	ds_read_b32 v18, v222
.LBB0_466:
	s_waitcnt lgkmcnt(0)
	v_pk_mul_f32 v[20:21], v[88:89], v[18:19] op_sel_hi:[1,0]
	v_pk_mul_f32 v[52:53], v[90:91], v[18:19] op_sel_hi:[1,0]
	v_add_u32_e32 v22, s20, v221
	v_pk_fma_f32 v[54:55], v[14:15], v[52:53], v[6:7]
	v_pk_fma_f32 v[52:53], v[12:13], v[20:21], v[4:5]
	v_pk_mul_f32 v[20:21], v[80:81], v[18:19] op_sel_hi:[1,0]
	v_pk_mul_f32 v[18:19], v[82:83], v[18:19] op_sel_hi:[1,0]
	v_ashrrev_i32_e32 v23, 31, v22
	v_pk_fma_f32 v[60:61], v[10:11], v[18:19], v[2:3]
	v_cvt_pk_bf16_f32 v52, v52, v53
	v_cvt_pk_bf16_f32 v53, v54, v55
	v_cvt_pk_bf16_f32 v55, v60, v61
	v_lshlrev_b64 v[60:61], 12, v[22:23]
	v_pk_fma_f32 v[62:63], v[8:9], v[20:21], v[0:1]
	v_cvt_pk_bf16_f32 v18, v88, v89
	v_cvt_pk_bf16_f32 v19, v90, v91
	v_cvt_pk_bf16_f32 v20, v80, v81
	v_cvt_pk_bf16_f32 v21, v82, v83
	v_lshl_add_u64 v[60:61], v[200:201], 0, v[60:61]
	global_store_dwordx4 v[60:61], v[18:21], off
	v_cvt_pk_bf16_f32 v54, v62, v63
	s_and_b64 vcc, exec, s[12:13]
	v_lshlrev_b64 v[18:19], 11, v[22:23]
	v_lshl_add_u64 v[18:19], v[202:203], 0, v[18:19]
	global_store_dwordx4 v[18:19], v[52:55], off
	s_cbranch_vccnz .LBB0_468
	ds_read_b32 v16, v224
.LBB0_468:
	s_waitcnt lgkmcnt(0)
	v_pk_mul_f32 v[18:19], v[72:73], v[16:17] op_sel_hi:[1,0]
	v_pk_mul_f32 v[20:21], v[74:75], v[16:17] op_sel_hi:[1,0]
	v_add_u32_e32 v52, s20, v223
	v_pk_fma_f32 v[22:23], v[14:15], v[20:21], v[6:7]
	v_pk_fma_f32 v[20:21], v[12:13], v[18:19], v[4:5]
	v_pk_mul_f32 v[18:19], v[64:65], v[16:17] op_sel_hi:[1,0]
	v_pk_mul_f32 v[16:17], v[66:67], v[16:17] op_sel_hi:[1,0]
	v_ashrrev_i32_e32 v53, 31, v52
	v_pk_fma_f32 v[54:55], v[10:11], v[16:17], v[2:3]
	v_cvt_pk_bf16_f32 v20, v20, v21
	v_cvt_pk_bf16_f32 v21, v22, v23
	v_cvt_pk_bf16_f32 v23, v54, v55
	v_lshlrev_b64 v[54:55], 12, v[52:53]
	v_pk_fma_f32 v[60:61], v[8:9], v[18:19], v[0:1]
	v_cvt_pk_bf16_f32 v16, v72, v73
	v_cvt_pk_bf16_f32 v17, v74, v75
	v_cvt_pk_bf16_f32 v18, v64, v65
	v_cvt_pk_bf16_f32 v19, v66, v67
	v_lshl_add_u64 v[54:55], v[200:201], 0, v[54:55]
	global_store_dwordx4 v[54:55], v[16:19], off
	v_cvt_pk_bf16_f32 v22, v60, v61
	s_and_b64 vcc, exec, s[12:13]
	v_lshlrev_b64 v[16:17], 11, v[52:53]
	v_lshl_add_u64 v[16:17], v[202:203], 0, v[16:17]
	global_store_dwordx4 v[16:17], v[20:23], off
	v_mov_b32_e32 v16, 0x7fc00000
	v_mov_b32_e32 v18, 0x7fc00000
	s_cbranch_vccnz .LBB0_470
	ds_read_b32 v18, v226
; __device__ __forceinline__ unsigned cvt_pk_bf16(float lo, float hi) { const f32x2 v = {lo, hi}; const bf16x2_t b = __builtin_convertvector(v, bf16x2_t); return __builtin_bit_cast(unsigned, b); }
;     __device__ __forceinline__ void epi(AccT& acc, const Unit& u, LAS unsigned char* lds, int wr, int wc, int fr, int fq) const {
;     ...
;         for (int ai = 0; ai < 2; ++ai)
; #pragma unroll
;             for (int m = 0; m < 4; ++m) { const int r = ai * 128 + wr * 64 + m * 16 + fr; const float rs = bad ? qnan : Sl[r]; const size_t grow = (size_t)(u.pm * 256 + r);
;                 const f32x4 x0 = acc[ai][0][m][0], x1 = acc[ai][0][m][1]; const f32x4 h0 = x0 * rs * sv[0] + tv[0], h1 = x1 * rs * sv[1] + tv[1]; u32x4 q, p;
;                 q.x = cvt_pk_bf16(x0[0], x0[1]); q.y = cvt_pk_bf16(x0[2], x0[3]); q.z = cvt_pk_bf16(x1[0], x1[1]); q.w = cvt_pk_bf16(x1[2], x1[3]);
;                 p.x = cvt_pk_bf16(h0[0], h0[1]); p.y = cvt_pk_bf16(h0[2], h0[3]); p.z = cvt_pk_bf16(h1[0], h1[1]); p.w = cvt_pk_bf16(h1[2], h1[3]);
;                 *(u32x4*)(XH + grow * (2 * D) + col0) = q; *(u32x4*)(H + grow * D + col0) = p; }
.LBB0_470:
	v_add_u32_e32 v22, s20, v225
	s_waitcnt lgkmcnt(0)
	v_pk_mul_f32 v[20:21], v[56:57], v[18:19] op_sel_hi:[1,0]
	v_pk_mul_f32 v[52:53], v[58:59], v[18:19] op_sel_hi:[1,0]
	v_ashrrev_i32_e32 v23, 31, v22
	v_pk_fma_f32 v[52:53], v[14:15], v[52:53], v[6:7]
	v_pk_fma_f32 v[54:55], v[12:13], v[20:21], v[4:5]
	v_pk_mul_f32 v[20:21], v[48:49], v[18:19] op_sel_hi:[1,0]
	v_pk_mul_f32 v[18:19], v[50:51], v[18:19] op_sel_hi:[1,0]
	v_pk_fma_f32 v[62:63], v[8:9], v[20:21], v[0:1]
	v_cvt_pk_bf16_f32 v20, v48, v49
	v_cvt_pk_bf16_f32 v49, v52, v53
	v_lshlrev_b64 v[52:53], 12, v[22:23]
	v_pk_fma_f32 v[60:61], v[10:11], v[18:19], v[2:3]
	v_cvt_pk_bf16_f32 v18, v56, v57
	v_cvt_pk_bf16_f32 v19, v58, v59
	v_cvt_pk_bf16_f32 v21, v50, v51
	v_lshl_add_u64 v[52:53], v[200:201], 0, v[52:53]
	global_store_dwordx4 v[52:53], v[18:21], off
	v_cvt_pk_bf16_f32 v48, v54, v55
	v_cvt_pk_bf16_f32 v50, v62, v63
	v_lshlrev_b64 v[18:19], 11, v[22:23]
	v_cvt_pk_bf16_f32 v51, v60, v61
	v_lshl_add_u64 v[18:19], v[202:203], 0, v[18:19]
	s_and_b64 vcc, exec, s[12:13]
	global_store_dwordx4 v[18:19], v[48:51], off
	s_cbranch_vccnz .LBB0_472
	ds_read_b32 v16, v228
.LBB0_472:
	s_nop 0
	v_add_u32_e32 v48, s20, v227
	s_waitcnt lgkmcnt(0)
	v_pk_mul_f32 v[18:19], v[40:41], v[16:17] op_sel_hi:[1,0]
	v_pk_mul_f32 v[20:21], v[42:43], v[16:17] op_sel_hi:[1,0]
	v_ashrrev_i32_e32 v49, 31, v48
	v_pk_fma_f32 v[22:23], v[14:15], v[20:21], v[6:7]
	v_pk_fma_f32 v[20:21], v[12:13], v[18:19], v[4:5]
	v_pk_mul_f32 v[18:19], v[32:33], v[16:17] op_sel_hi:[1,0]
	v_pk_mul_f32 v[16:17], v[34:35], v[16:17] op_sel_hi:[1,0]
	v_pk_fma_f32 v[52:53], v[8:9], v[18:19], v[0:1]
	v_cvt_pk_bf16_f32 v18, v32, v33
	v_lshlrev_b64 v[32:33], 12, v[48:49]
	v_pk_fma_f32 v[50:51], v[10:11], v[16:17], v[2:3]
	v_cvt_pk_bf16_f32 v16, v40, v41
	v_cvt_pk_bf16_f32 v17, v42, v43
	v_cvt_pk_bf16_f32 v19, v34, v35
	v_lshl_add_u64 v[32:33], v[200:201], 0, v[32:33]
	global_store_dwordx4 v[32:33], v[16:19], off
	v_cvt_pk_bf16_f32 v20, v20, v21
	v_cvt_pk_bf16_f32 v21, v22, v23
	v_lshlrev_b64 v[16:17], 11, v[48:49]
	v_cvt_pk_bf16_f32 v22, v52, v53
	v_cvt_pk_bf16_f32 v23, v50, v51
	v_lshl_add_u64 v[16:17], v[202:203], 0, v[16:17]
	global_store_dwordx4 v[16:17], v[20:23], off
	v_mov_b32_e32 v16, 0x7fc00000
	s_and_b64 vcc, exec, s[12:13]
	v_mov_b32_e32 v18, 0x7fc00000
	s_cbranch_vccnz .LBB0_474
	ds_read_b32 v18, v230
.LBB0_474:
	v_add_u32_e32 v32, s20, v229
	s_waitcnt lgkmcnt(0)
	v_pk_mul_f32 v[20:21], v[24:25], v[18:19] op_sel_hi:[1,0]
	v_pk_mul_f32 v[22:23], v[26:27], v[18:19] op_sel_hi:[1,0]
	v_ashrrev_i32_e32 v33, 31, v32
	v_pk_fma_f32 v[34:35], v[14:15], v[22:23], v[6:7]
	v_pk_fma_f32 v[22:23], v[12:13], v[20:21], v[4:5]
	v_pk_mul_f32 v[20:21], v[28:29], v[18:19] op_sel_hi:[1,0]
	v_pk_mul_f32 v[18:19], v[30:31], v[18:19] op_sel_hi:[1,0]
	v_pk_fma_f32 v[42:43], v[8:9], v[20:21], v[0:1]
	v_pk_fma_f32 v[40:41], v[10:11], v[18:19], v[2:3]
	v_cvt_pk_bf16_f32 v19, v26, v27
	v_lshlrev_b64 v[26:27], 12, v[32:33]
	v_cvt_pk_bf16_f32 v18, v24, v25
	v_cvt_pk_bf16_f32 v20, v28, v29
	v_cvt_pk_bf16_f32 v21, v30, v31
	v_lshl_add_u64 v[26:27], v[200:201], 0, v[26:27]
	global_store_dwordx4 v[26:27], v[18:21], off
	v_cvt_pk_bf16_f32 v22, v22, v23
	v_cvt_pk_bf16_f32 v23, v34, v35
	v_lshlrev_b64 v[18:19], 11, v[32:33]
	v_cvt_pk_bf16_f32 v24, v42, v43
	v_cvt_pk_bf16_f32 v25, v40, v41
	v_lshl_add_u64 v[18:19], v[202:203], 0, v[18:19]
	s_and_b64 vcc, exec, s[12:13]
	global_store_dwordx4 v[18:19], v[22:25], off
	s_cbranch_vccnz .LBB0_476
	ds_read_b32 v16, v232
.LBB0_476:
	s_waitcnt lgkmcnt(0)
	v_pk_mul_f32 v[20:21], v[36:37], v[16:17] op_sel_hi:[1,0]
	v_add_u32_e32 v18, s20, v231
	v_pk_mul_f32 v[22:23], v[38:39], v[16:17] op_sel_hi:[1,0]
	v_pk_fma_f32 v[4:5], v[12:13], v[20:21], v[4:5]
	v_pk_mul_f32 v[12:13], v[44:45], v[16:17] op_sel_hi:[1,0]
	v_ashrrev_i32_e32 v19, 31, v18
	v_pk_fma_f32 v[6:7], v[14:15], v[22:23], v[6:7]
	v_pk_fma_f32 v[8:9], v[8:9], v[12:13], v[0:1]
	v_pk_mul_f32 v[14:15], v[46:47], v[16:17] op_sel_hi:[1,0]
	v_cvt_pk_bf16_f32 v4, v4, v5
	v_cvt_pk_bf16_f32 v5, v6, v7
	v_cvt_pk_bf16_f32 v6, v8, v9
	v_lshlrev_b64 v[8:9], 12, v[18:19]
	v_pk_fma_f32 v[10:11], v[10:11], v[14:15], v[2:3]
	v_cvt_pk_bf16_f32 v0, v36, v37
	v_cvt_pk_bf16_f32 v1, v38, v39
	v_cvt_pk_bf16_f32 v2, v44, v45
	v_cvt_pk_bf16_f32 v3, v46, v47
	v_lshl_add_u64 v[8:9], v[200:201], 0, v[8:9]
	global_store_dwordx4 v[8:9], v[0:3], off
	v_cvt_pk_bf16_f32 v7, v10, v11
	s_andn2_b64 vcc, exec, s[60:61]
	v_lshlrev_b64 v[0:1], 11, v[18:19]
	v_lshl_add_u64 v[0:1], v[202:203], 0, v[0:1]
	global_store_dwordx4 v[0:1], v[4:7], off
	s_waitcnt lgkmcnt(0)
	s_barrier
	s_mov_b64 s[12:13], -1
	s_cbranch_vccnz .LBB0_415
	s_andn2_b64 vcc, exec, s[44:45]
	s_cbranch_vccnz .LBB0_414
	s_barrier
	s_branch .LBB0_414

; __device__ __forceinline__ unsigned xb_add(unsigned* p, unsigned v) { return __hip_atomic_fetch_add(p, v, __ATOMIC_RELAXED, __HIP_MEMORY_SCOPE_AGENT); }
;     ...
;             unsigned nloc = b.st[0], nx = b.st[1];
;             if (nloc == 0u) { xcd_barrier_complete(bar, b.x, nloc, nx); b.st[0] = nloc; b.st[1] = nx; }
;             const unsigned old = xb_add(&bar[XB_XSUB(b.x)], 1u);
;             gen_ = old / nloc;
;             if (old + 1u == (gen_ + 1u) * nloc) {
;                 if (!wt_only) __builtin_amdgcn_fence(__ATOMIC_RELEASE, "agent");
;                 asm volatile("s_waitcnt vmcnt(0)" ::: "memory");
;                 __hip_atomic_store(&bar[XB_XGEN(b.x)], gen_ + 1u, __ATOMIC_RELAXED, __HIP_MEMORY_SCOPE_AGENT);
.LBB0_515:
	s_or_b64 exec, exec, s[16:17]
	v_cvt_f32_u32_e32 v4, v1
	s_waitcnt vmcnt(0)
	v_readfirstlane_b32 s4, v3
	v_sub_u32_e32 v3, 0, v1
	v_rcp_iflag_f32_e32 v4, v4
	v_add_u32_e32 v5, s4, v2
	v_mul_f32_e32 v4, 0x4f7ffffe, v4
	v_cvt_u32_f32_e32 v4, v4
	v_mul_lo_u32 v2, v3, v4
	v_mul_hi_u32 v2, v4, v2
	v_add_u32_e32 v2, v4, v2
	v_mul_hi_u32 v2, v5, v2
	v_mul_lo_u32 v3, v2, v1
	v_sub_u32_e32 v3, v5, v3
	v_add_u32_e32 v4, 1, v2
	v_cmp_ge_u32_e32 vcc, v3, v1
	s_nop 1
	v_cndmask_b32_e32 v2, v2, v4, vcc
	v_sub_u32_e32 v4, v3, v1
	v_cndmask_b32_e32 v3, v3, v4, vcc
	v_add_u32_e32 v4, 1, v2
	v_cmp_ge_u32_e32 vcc, v3, v1
	s_nop 1
	v_cndmask_b32_e32 v2, v2, v4, vcc
	v_add_u32_e32 v3, 1, v2
	v_add_u32_e32 v4, 1, v5
	v_mul_lo_u32 v1, v3, v1
	v_cmp_eq_u32_e32 vcc, v4, v1
	s_and_saveexec_b64 s[14:15], vcc
	s_cbranch_execz .LBB0_517
	buffer_wbl2 sc1
	s_waitcnt vmcnt(0)
	v_mov_b32_e32 v1, 0x2000
	global_store_dword v1, v3, s[12:13] offset:1024 sc1

; __device__ __forceinline__ unsigned cvt_pk_bf16(float lo, float hi) { const f32x2 v = {lo, hi}; const bf16x2_t b = __builtin_convertvector(v, bf16x2_t); return __builtin_bit_cast(unsigned, b); }
; __device__ __forceinline__ void store16_wt(void* p, u32x4 v) { asm volatile("global_store_dwordx4 %0, %1, off sc1\n\ts_nop 1" :: "v"(p), "v"(v) : "memory"); }
; __device__ __forceinline__ u32x4 ror8_u4(u32x4 v) { const unsigned a = ror8_u(v.x), b = ror8_u(v.y), c = ror8_u(v.z), d = ror8_u(v.w); return (u32x4){a, b, c, d}; }
; #define PG8_STAGE(bufoff, gbase, voff, aux) do { _Pragma("unroll") for (int _i = 0; _i < 2; ++_i) \
;         __builtin_amdgcn_raw_ptr_buffer_load_lds(rs, (LAS void*)(lds + (bufoff) + ldsw + _i * 8192), 16, (voff)[_i], (unsigned)((const char*)(gbase) - wsb), 0, (aux)); } while (0)
; template <class Prob, bool ALIGN_EPI, bool SP2>
; __device__ __forceinline__ void gemm_phase(LAS unsigned char* lds, const Prob& Pb, int wave, const char* wsb) {
;     ...
;         if constexpr (SP2 && Prob::EPI_VM > 0) { static_assert(ALIGN_EPI, "early stage needs the aligned epilogue"); const char* e1 = nA + kstepA + hstepA; asm volatile("" : "+s"(e1)); PG8_STAGE(PG8_SA(1, 1), e1, voffA, Prob::A_AUX); }
;     __device__ __forceinline__ void epi(AccT& acc, const Unit& u, LAS unsigned char* lds, int wr, int wc, int fr, int fq) const {
;     ...
;         for (int ai = 0; ai < 2; ++ai)
; #pragma unroll
;             for (int m = 0; m < 4; ++m) { const bool lo = fr < 8; bf16_t* rp = O + (size_t)(u.pm * 256 + ai * 128 + wr * 64 + m * 16 + (fr & 7)) * ldc + u.pn * 256 + wc * 64 + (lo ? 0 : 32) + 8 * fq; u32x4 w[2];
; #pragma unroll
;                 for (int bj = 0; bj < 2; ++bj) { f32x4 v0 = acc[ai][bj][m][0], v1 = acc[ai][bj][m][1];
;                     if (ACT == 1) { v0 = __builtin_elementwise_max(v0, (f32x4){0.f, 0.f, 0.f, 0.f}); v1 = __builtin_elementwise_max(v1, (f32x4){0.f, 0.f, 0.f, 0.f}); v0 = v0 * v0; v1 = v1 * v1; }
;                     w[bj].x = cvt_pk_bf16(v0[0], v0[1]); w[bj].y = cvt_pk_bf16(v0[2], v0[3]); w[bj].z = cvt_pk_bf16(v1[0], v1[1]); w[bj].w = cvt_pk_bf16(v1[2], v1[3]); }
;                 const u32x4 r0 = ror8_u4(w[0]), r1 = ror8_u4(w[1]); store16_wt(rp, lo ? w[0] : r1); store16_wt(rp + (size_t)8 * ldc, lo ? r0 : w[1]); }
.LBB0_558:
	s_add_u32 s60, s64, 0x40080
	s_addc_u32 s61, s53, 0
	s_mov_b32 m0, s49
	s_sub_i32 s47, s60, s34
	s_mov_b32 s12, s34
	buffer_load_dwordx4 v138, s[12:15], s47 offen lds
	s_mov_b32 m0, s50
	v_lshl_add_u32 v136, s58, 8, v142
	buffer_load_dwordx4 v140, s[12:15], s47 offen lds
	s_lshl_b32 s58, s59, 8
	v_ashrrev_i32_e32 v137, 31, v136
	s_ashr_i32 s59, s58, 31
	v_lshlrev_b64 v[148:149], 13, v[136:137]
	v_max_f32_e32 v121, 0, v121
	v_max_f32_e32 v120, 0, v120
	v_max_f32_e32 v123, 0, v123
	v_max_f32_e32 v122, 0, v122
	v_max_f32_e32 v117, 0, v117
	v_max_f32_e32 v116, 0, v116
	v_lshl_add_u64 v[148:149], s[22:23], 0, v[148:149]
	s_lshl_b64 s[58:59], s[58:59], 1
	v_max_f32_e32 v125, 0, v125
	v_max_f32_e32 v124, 0, v124
	v_pk_mul_f32 v[122:123], v[122:123], v[122:123]
	v_pk_mul_f32 v[120:121], v[120:121], v[120:121]
	v_max_f32_e32 v119, 0, v119
	v_max_f32_e32 v118, 0, v118
	v_max_f32_e32 v113, 0, v113
	v_max_f32_e32 v112, 0, v112
	v_max_f32_e32 v115, 0, v115
	v_max_f32_e32 v114, 0, v114
	v_pk_mul_f32 v[116:117], v[116:117], v[116:117]
	v_lshl_add_u64 v[148:149], v[148:149], 0, s[58:59]
	v_max_f32_e32 v127, 0, v127
	v_max_f32_e32 v126, 0, v126
	v_pk_mul_f32 v[124:125], v[124:125], v[124:125]
	v_cvt_pk_bf16_f32 v120, v120, v121
	v_cvt_pk_bf16_f32 v121, v122, v123
	v_pk_mul_f32 v[118:119], v[118:119], v[118:119]
	v_pk_mul_f32 v[114:115], v[114:115], v[114:115]
	v_pk_mul_f32 v[112:113], v[112:113], v[112:113]
	v_cvt_pk_bf16_f32 v122, v116, v117
	v_lshl_add_u64 v[148:149], v[148:149], 0, s[20:21]
	v_pk_mul_f32 v[126:127], v[126:127], v[126:127]
	v_cvt_pk_bf16_f32 v124, v124, v125
	v_cvt_pk_bf16_f32 v118, v118, v119
	v_cvt_pk_bf16_f32 v119, v112, v113
	v_cvt_pk_bf16_f32 v123, v114, v115
	v_mov_b32_dpp v112, v122 row_ror:8 row_mask:0xf bank_mask:0xf bound_ctrl:1
	v_lshl_add_u64 v[148:149], v[148:149], 0, v[128:129]
	v_cvt_pk_bf16_f32 v125, v126, v127
	v_mov_b32_dpp v126, v124 row_ror:8 row_mask:0xf bank_mask:0xf bound_ctrl:1
	v_mov_b32_dpp v113, v118 row_ror:8 row_mask:0xf bank_mask:0xf bound_ctrl:1
	v_mov_b32_dpp v114, v119 row_ror:8 row_mask:0xf bank_mask:0xf bound_ctrl:1
	v_mov_b32_dpp v115, v123 row_ror:8 row_mask:0xf bank_mask:0xf bound_ctrl:1
	v_cndmask_b32_e64 v112, v112, v124, s[8:9]
	v_lshl_add_u64 v[116:117], v[148:149], 0, v[134:135]
	v_mov_b32_dpp v127, v125 row_ror:8 row_mask:0xf bank_mask:0xf bound_ctrl:1
	v_mov_b32_dpp v137, v120 row_ror:8 row_mask:0xf bank_mask:0xf bound_ctrl:1
	v_mov_b32_dpp v148, v121 row_ror:8 row_mask:0xf bank_mask:0xf bound_ctrl:1
	v_cndmask_b32_e64 v115, v115, v121, s[8:9]
	v_cndmask_b32_e64 v114, v114, v120, s[8:9]
	v_cndmask_b32_e64 v113, v113, v125, s[8:9]
	global_store_dwordx4 v[116:117], v[112:115], off sc1
	s_nop 1
	v_cndmask_b32_e64 v112, v122, v126, s[8:9]
	v_lshl_add_u64 v[116:117], v[116:117], 0, s[44:45]
	v_cndmask_b32_e64 v115, v123, v148, s[8:9]
	v_cndmask_b32_e64 v114, v119, v137, s[8:9]
	v_cndmask_b32_e64 v113, v118, v127, s[8:9]
	global_store_dwordx4 v[116:117], v[112:115], off sc1
	s_nop 1
	v_or_b32_e32 v112, 16, v136
	v_ashrrev_i32_e32 v113, 31, v112
	v_lshlrev_b64 v[112:113], 13, v[112:113]
	v_max_f32_e32 v105, 0, v105
	v_max_f32_e32 v104, 0, v104
	v_max_f32_e32 v107, 0, v107
	v_max_f32_e32 v106, 0, v106
	v_max_f32_e32 v101, 0, v101
	v_max_f32_e32 v100, 0, v100
	v_lshl_add_u64 v[112:113], s[22:23], 0, v[112:113]
	v_max_f32_e32 v109, 0, v109
	v_max_f32_e32 v108, 0, v108
	v_pk_mul_f32 v[106:107], v[106:107], v[106:107]
	v_pk_mul_f32 v[104:105], v[104:105], v[104:105]
	v_max_f32_e32 v103, 0, v103
	v_max_f32_e32 v102, 0, v102
	v_max_f32_e32 v97, 0, v97
	v_max_f32_e32 v96, 0, v96
	v_max_f32_e32 v99, 0, v99
	v_max_f32_e32 v98, 0, v98
	v_pk_mul_f32 v[100:101], v[100:101], v[100:101]
	v_lshl_add_u64 v[112:113], v[112:113], 0, s[58:59]
	v_max_f32_e32 v111, 0, v111
	v_max_f32_e32 v110, 0, v110
	v_pk_mul_f32 v[108:109], v[108:109], v[108:109]
	v_cvt_pk_bf16_f32 v104, v104, v105
	v_cvt_pk_bf16_f32 v105, v106, v107
	v_pk_mul_f32 v[102:103], v[102:103], v[102:103]
	v_pk_mul_f32 v[98:99], v[98:99], v[98:99]
	v_pk_mul_f32 v[96:97], v[96:97], v[96:97]
	v_cvt_pk_bf16_f32 v106, v100, v101
	v_lshl_add_u64 v[112:113], v[112:113], 0, s[20:21]
	v_pk_mul_f32 v[110:111], v[110:111], v[110:111]
	v_cvt_pk_bf16_f32 v108, v108, v109
	v_cvt_pk_bf16_f32 v102, v102, v103
	v_cvt_pk_bf16_f32 v103, v96, v97
	v_cvt_pk_bf16_f32 v107, v98, v99
	v_mov_b32_dpp v96, v106 row_ror:8 row_mask:0xf bank_mask:0xf bound_ctrl:1
	v_lshl_add_u64 v[112:113], v[112:113], 0, v[128:129]
	v_cvt_pk_bf16_f32 v109, v110, v111
	v_mov_b32_dpp v110, v108 row_ror:8 row_mask:0xf bank_mask:0xf bound_ctrl:1
	v_mov_b32_dpp v97, v102 row_ror:8 row_mask:0xf bank_mask:0xf bound_ctrl:1
	v_mov_b32_dpp v98, v103 row_ror:8 row_mask:0xf bank_mask:0xf bound_ctrl:1
	v_mov_b32_dpp v99, v107 row_ror:8 row_mask:0xf bank_mask:0xf bound_ctrl:1
	v_cndmask_b32_e64 v96, v96, v108, s[8:9]
	v_lshl_add_u64 v[100:101], v[112:113], 0, v[134:135]
	v_mov_b32_dpp v111, v109 row_ror:8 row_mask:0xf bank_mask:0xf bound_ctrl:1
	v_mov_b32_dpp v112, v104 row_ror:8 row_mask:0xf bank_mask:0xf bound_ctrl:1
	v_mov_b32_dpp v113, v105 row_ror:8 row_mask:0xf bank_mask:0xf bound_ctrl:1
	v_cndmask_b32_e64 v99, v99, v105, s[8:9]
	v_cndmask_b32_e64 v98, v98, v104, s[8:9]
	v_cndmask_b32_e64 v97, v97, v109, s[8:9]
	global_store_dwordx4 v[100:101], v[96:99], off sc1
	s_nop 1
	v_cndmask_b32_e64 v96, v106, v110, s[8:9]
	v_lshl_add_u64 v[100:101], v[100:101], 0, s[44:45]
	v_cndmask_b32_e64 v99, v107, v113, s[8:9]
	v_cndmask_b32_e64 v98, v103, v112, s[8:9]
	v_cndmask_b32_e64 v97, v102, v111, s[8:9]
	global_store_dwordx4 v[100:101], v[96:99], off sc1
	s_nop 1
	v_or_b32_e32 v96, 32, v136
; __device__ __forceinline__ unsigned cvt_pk_bf16(float lo, float hi) { const f32x2 v = {lo, hi}; const bf16x2_t b = __builtin_convertvector(v, bf16x2_t); return __builtin_bit_cast(unsigned, b); }
; __device__ __forceinline__ void store16_wt(void* p, u32x4 v) { asm volatile("global_store_dwordx4 %0, %1, off sc1\n\ts_nop 1" :: "v"(p), "v"(v) : "memory"); }
; __device__ __forceinline__ u32x4 ror8_u4(u32x4 v) { const unsigned a = ror8_u(v.x), b = ror8_u(v.y), c = ror8_u(v.z), d = ror8_u(v.w); return (u32x4){a, b, c, d}; }
;     __device__ __forceinline__ void epi(AccT& acc, const Unit& u, LAS unsigned char* lds, int wr, int wc, int fr, int fq) const {
;     ...
;         for (int ai = 0; ai < 2; ++ai)
; #pragma unroll
;             for (int m = 0; m < 4; ++m) { const bool lo = fr < 8; bf16_t* rp = O + (size_t)(u.pm * 256 + ai * 128 + wr * 64 + m * 16 + (fr & 7)) * ldc + u.pn * 256 + wc * 64 + (lo ? 0 : 32) + 8 * fq; u32x4 w[2];
; #pragma unroll
;                 for (int bj = 0; bj < 2; ++bj) { f32x4 v0 = acc[ai][bj][m][0], v1 = acc[ai][bj][m][1];
;                     if (ACT == 1) { v0 = __builtin_elementwise_max(v0, (f32x4){0.f, 0.f, 0.f, 0.f}); v1 = __builtin_elementwise_max(v1, (f32x4){0.f, 0.f, 0.f, 0.f}); v0 = v0 * v0; v1 = v1 * v1; }
;                     w[bj].x = cvt_pk_bf16(v0[0], v0[1]); w[bj].y = cvt_pk_bf16(v0[2], v0[3]); w[bj].z = cvt_pk_bf16(v1[0], v1[1]); w[bj].w = cvt_pk_bf16(v1[2], v1[3]); }
;                 const u32x4 r0 = ror8_u4(w[0]), r1 = ror8_u4(w[1]); store16_wt(rp, lo ? w[0] : r1); store16_wt(rp + (size_t)8 * ldc, lo ? r0 : w[1]); }
	v_ashrrev_i32_e32 v97, 31, v96
	v_lshlrev_b64 v[96:97], 13, v[96:97]
	v_max_f32_e32 v89, 0, v89
	v_max_f32_e32 v88, 0, v88
	v_max_f32_e32 v91, 0, v91
	v_max_f32_e32 v90, 0, v90
	v_max_f32_e32 v85, 0, v85
	v_max_f32_e32 v84, 0, v84
	v_lshl_add_u64 v[96:97], s[22:23], 0, v[96:97]
	v_max_f32_e32 v93, 0, v93
	v_max_f32_e32 v92, 0, v92
	v_pk_mul_f32 v[90:91], v[90:91], v[90:91]
	v_pk_mul_f32 v[88:89], v[88:89], v[88:89]
	v_max_f32_e32 v87, 0, v87
	v_max_f32_e32 v86, 0, v86
	v_max_f32_e32 v81, 0, v81
	v_max_f32_e32 v80, 0, v80
	v_max_f32_e32 v83, 0, v83
	v_max_f32_e32 v82, 0, v82
	v_pk_mul_f32 v[84:85], v[84:85], v[84:85]
	v_lshl_add_u64 v[96:97], v[96:97], 0, s[58:59]
	v_max_f32_e32 v95, 0, v95
	v_max_f32_e32 v94, 0, v94
	v_pk_mul_f32 v[92:93], v[92:93], v[92:93]
	v_cvt_pk_bf16_f32 v88, v88, v89
	v_cvt_pk_bf16_f32 v89, v90, v91
	v_pk_mul_f32 v[86:87], v[86:87], v[86:87]
	v_pk_mul_f32 v[82:83], v[82:83], v[82:83]
	v_pk_mul_f32 v[80:81], v[80:81], v[80:81]
	v_cvt_pk_bf16_f32 v90, v84, v85
	v_lshl_add_u64 v[96:97], v[96:97], 0, s[20:21]
	v_pk_mul_f32 v[94:95], v[94:95], v[94:95]
	v_cvt_pk_bf16_f32 v92, v92, v93
	v_cvt_pk_bf16_f32 v86, v86, v87
	v_cvt_pk_bf16_f32 v87, v80, v81
	v_cvt_pk_bf16_f32 v91, v82, v83
	v_mov_b32_dpp v80, v90 row_ror:8 row_mask:0xf bank_mask:0xf bound_ctrl:1
	v_lshl_add_u64 v[96:97], v[96:97], 0, v[128:129]
	v_cvt_pk_bf16_f32 v93, v94, v95
	v_mov_b32_dpp v94, v92 row_ror:8 row_mask:0xf bank_mask:0xf bound_ctrl:1
	v_mov_b32_dpp v81, v86 row_ror:8 row_mask:0xf bank_mask:0xf bound_ctrl:1
	v_mov_b32_dpp v82, v87 row_ror:8 row_mask:0xf bank_mask:0xf bound_ctrl:1
	v_mov_b32_dpp v83, v91 row_ror:8 row_mask:0xf bank_mask:0xf bound_ctrl:1
	v_cndmask_b32_e64 v80, v80, v92, s[8:9]
	v_lshl_add_u64 v[84:85], v[96:97], 0, v[134:135]
	v_mov_b32_dpp v95, v93 row_ror:8 row_mask:0xf bank_mask:0xf bound_ctrl:1
	v_mov_b32_dpp v96, v88 row_ror:8 row_mask:0xf bank_mask:0xf bound_ctrl:1
	v_mov_b32_dpp v97, v89 row_ror:8 row_mask:0xf bank_mask:0xf bound_ctrl:1
	v_cndmask_b32_e64 v83, v83, v89, s[8:9]
	v_cndmask_b32_e64 v82, v82, v88, s[8:9]
	v_cndmask_b32_e64 v81, v81, v93, s[8:9]
	global_store_dwordx4 v[84:85], v[80:83], off sc1
	s_nop 1
	v_cndmask_b32_e64 v80, v90, v94, s[8:9]
	v_lshl_add_u64 v[84:85], v[84:85], 0, s[44:45]
	v_cndmask_b32_e64 v83, v91, v97, s[8:9]
	v_cndmask_b32_e64 v82, v87, v96, s[8:9]
	v_cndmask_b32_e64 v81, v86, v95, s[8:9]
	global_store_dwordx4 v[84:85], v[80:83], off sc1
	s_nop 1
	v_or_b32_e32 v80, 48, v136
	v_ashrrev_i32_e32 v81, 31, v80
	v_lshlrev_b64 v[80:81], 13, v[80:81]
	v_max_f32_e32 v73, 0, v73
	v_max_f32_e32 v72, 0, v72
	v_max_f32_e32 v75, 0, v75
	v_max_f32_e32 v74, 0, v74
	v_max_f32_e32 v69, 0, v69
	v_max_f32_e32 v68, 0, v68
	v_lshl_add_u64 v[80:81], s[22:23], 0, v[80:81]
	v_max_f32_e32 v77, 0, v77
	v_max_f32_e32 v76, 0, v76
	v_pk_mul_f32 v[74:75], v[74:75], v[74:75]
	v_pk_mul_f32 v[72:73], v[72:73], v[72:73]
	v_max_f32_e32 v71, 0, v71
	v_max_f32_e32 v70, 0, v70
	v_max_f32_e32 v65, 0, v65
	v_max_f32_e32 v64, 0, v64
	v_max_f32_e32 v67, 0, v67
	v_max_f32_e32 v66, 0, v66
	v_pk_mul_f32 v[68:69], v[68:69], v[68:69]
	v_lshl_add_u64 v[80:81], v[80:81], 0, s[58:59]
	v_max_f32_e32 v79, 0, v79
	v_max_f32_e32 v78, 0, v78
	v_pk_mul_f32 v[76:77], v[76:77], v[76:77]
	v_cvt_pk_bf16_f32 v72, v72, v73
	v_cvt_pk_bf16_f32 v73, v74, v75
	v_pk_mul_f32 v[70:71], v[70:71], v[70:71]
	v_pk_mul_f32 v[66:67], v[66:67], v[66:67]
	v_pk_mul_f32 v[64:65], v[64:65], v[64:65]
	v_cvt_pk_bf16_f32 v74, v68, v69
	v_lshl_add_u64 v[80:81], v[80:81], 0, s[20:21]
	v_pk_mul_f32 v[78:79], v[78:79], v[78:79]
	v_cvt_pk_bf16_f32 v76, v76, v77
	v_cvt_pk_bf16_f32 v70, v70, v71
	v_cvt_pk_bf16_f32 v71, v64, v65
	v_cvt_pk_bf16_f32 v75, v66, v67
	v_mov_b32_dpp v64, v74 row_ror:8 row_mask:0xf bank_mask:0xf bound_ctrl:1
	v_lshl_add_u64 v[80:81], v[80:81], 0, v[128:129]
	v_cvt_pk_bf16_f32 v77, v78, v79
	v_mov_b32_dpp v78, v76 row_ror:8 row_mask:0xf bank_mask:0xf bound_ctrl:1
	v_mov_b32_dpp v65, v70 row_ror:8 row_mask:0xf bank_mask:0xf bound_ctrl:1
	v_mov_b32_dpp v66, v71 row_ror:8 row_mask:0xf bank_mask:0xf bound_ctrl:1
	v_mov_b32_dpp v67, v75 row_ror:8 row_mask:0xf bank_mask:0xf bound_ctrl:1
	v_cndmask_b32_e64 v64, v64, v76, s[8:9]
	v_lshl_add_u64 v[68:69], v[80:81], 0, v[134:135]
	v_mov_b32_dpp v79, v77 row_ror:8 row_mask:0xf bank_mask:0xf bound_ctrl:1
	v_mov_b32_dpp v80, v72 row_ror:8 row_mask:0xf bank_mask:0xf bound_ctrl:1
	v_mov_b32_dpp v81, v73 row_ror:8 row_mask:0xf bank_mask:0xf bound_ctrl:1
	v_cndmask_b32_e64 v67, v67, v73, s[8:9]
	v_cndmask_b32_e64 v66, v66, v72, s[8:9]
	v_cndmask_b32_e64 v65, v65, v77, s[8:9]
	global_store_dwordx4 v[68:69], v[64:67], off sc1
	s_nop 1
	v_cndmask_b32_e64 v64, v74, v78, s[8:9]
	v_lshl_add_u64 v[68:69], v[68:69], 0, s[44:45]
	v_cndmask_b32_e64 v67, v75, v81, s[8:9]
	v_cndmask_b32_e64 v66, v71, v80, s[8:9]
	v_cndmask_b32_e64 v65, v70, v79, s[8:9]
	global_store_dwordx4 v[68:69], v[64:67], off sc1
	s_nop 1
	v_add_u32_e32 v64, 0x80, v136
	v_ashrrev_i32_e32 v65, 31, v64
	v_lshlrev_b64 v[64:65], 13, v[64:65]
	v_max_f32_e32 v57, 0, v57
	v_max_f32_e32 v56, 0, v56
	v_max_f32_e32 v59, 0, v59
	v_max_f32_e32 v58, 0, v58
	v_max_f32_e32 v53, 0, v53
	v_max_f32_e32 v52, 0, v52
	v_lshl_add_u64 v[64:65], s[22:23], 0, v[64:65]
	v_max_f32_e32 v61, 0, v61
	v_max_f32_e32 v60, 0, v60
	v_pk_mul_f32 v[58:59], v[58:59], v[58:59]
	v_pk_mul_f32 v[56:57], v[56:57], v[56:57]
	v_max_f32_e32 v55, 0, v55
	v_max_f32_e32 v54, 0, v54
	v_max_f32_e32 v49, 0, v49
	v_max_f32_e32 v48, 0, v48
	v_max_f32_e32 v51, 0, v51
	v_max_f32_e32 v50, 0, v50
	v_pk_mul_f32 v[52:53], v[52:53], v[52:53]
	v_lshl_add_u64 v[64:65], v[64:65], 0, s[58:59]
	v_max_f32_e32 v63, 0, v63
; __device__ __forceinline__ unsigned cvt_pk_bf16(float lo, float hi) { const f32x2 v = {lo, hi}; const bf16x2_t b = __builtin_convertvector(v, bf16x2_t); return __builtin_bit_cast(unsigned, b); }
; __device__ __forceinline__ void store16_wt(void* p, u32x4 v) { asm volatile("global_store_dwordx4 %0, %1, off sc1\n\ts_nop 1" :: "v"(p), "v"(v) : "memory"); }
; __device__ __forceinline__ u32x4 ror8_u4(u32x4 v) { const unsigned a = ror8_u(v.x), b = ror8_u(v.y), c = ror8_u(v.z), d = ror8_u(v.w); return (u32x4){a, b, c, d}; }
;     __device__ __forceinline__ void epi(AccT& acc, const Unit& u, LAS unsigned char* lds, int wr, int wc, int fr, int fq) const {
;     ...
;         for (int ai = 0; ai < 2; ++ai)
; #pragma unroll
;             for (int m = 0; m < 4; ++m) { const bool lo = fr < 8; bf16_t* rp = O + (size_t)(u.pm * 256 + ai * 128 + wr * 64 + m * 16 + (fr & 7)) * ldc + u.pn * 256 + wc * 64 + (lo ? 0 : 32) + 8 * fq; u32x4 w[2];
; #pragma unroll
;                 for (int bj = 0; bj < 2; ++bj) { f32x4 v0 = acc[ai][bj][m][0], v1 = acc[ai][bj][m][1];
;                     if (ACT == 1) { v0 = __builtin_elementwise_max(v0, (f32x4){0.f, 0.f, 0.f, 0.f}); v1 = __builtin_elementwise_max(v1, (f32x4){0.f, 0.f, 0.f, 0.f}); v0 = v0 * v0; v1 = v1 * v1; }
;                     w[bj].x = cvt_pk_bf16(v0[0], v0[1]); w[bj].y = cvt_pk_bf16(v0[2], v0[3]); w[bj].z = cvt_pk_bf16(v1[0], v1[1]); w[bj].w = cvt_pk_bf16(v1[2], v1[3]); }
;                 const u32x4 r0 = ror8_u4(w[0]), r1 = ror8_u4(w[1]); store16_wt(rp, lo ? w[0] : r1); store16_wt(rp + (size_t)8 * ldc, lo ? r0 : w[1]); }
	v_max_f32_e32 v62, 0, v62
	v_pk_mul_f32 v[60:61], v[60:61], v[60:61]
	v_cvt_pk_bf16_f32 v56, v56, v57
	v_cvt_pk_bf16_f32 v57, v58, v59
	v_pk_mul_f32 v[54:55], v[54:55], v[54:55]
	v_pk_mul_f32 v[50:51], v[50:51], v[50:51]
	v_pk_mul_f32 v[48:49], v[48:49], v[48:49]
	v_cvt_pk_bf16_f32 v58, v52, v53
	v_lshl_add_u64 v[64:65], v[64:65], 0, s[20:21]
	v_pk_mul_f32 v[62:63], v[62:63], v[62:63]
	v_cvt_pk_bf16_f32 v60, v60, v61
	v_cvt_pk_bf16_f32 v54, v54, v55
	v_cvt_pk_bf16_f32 v55, v48, v49
	v_cvt_pk_bf16_f32 v59, v50, v51
	v_mov_b32_dpp v48, v58 row_ror:8 row_mask:0xf bank_mask:0xf bound_ctrl:1
	v_lshl_add_u64 v[64:65], v[64:65], 0, v[128:129]
	v_cvt_pk_bf16_f32 v61, v62, v63
	v_mov_b32_dpp v62, v60 row_ror:8 row_mask:0xf bank_mask:0xf bound_ctrl:1
	v_mov_b32_dpp v49, v54 row_ror:8 row_mask:0xf bank_mask:0xf bound_ctrl:1
	v_mov_b32_dpp v50, v55 row_ror:8 row_mask:0xf bank_mask:0xf bound_ctrl:1
	v_mov_b32_dpp v51, v59 row_ror:8 row_mask:0xf bank_mask:0xf bound_ctrl:1
	v_cndmask_b32_e64 v48, v48, v60, s[8:9]
	v_lshl_add_u64 v[52:53], v[64:65], 0, v[134:135]
	v_mov_b32_dpp v63, v61 row_ror:8 row_mask:0xf bank_mask:0xf bound_ctrl:1
	v_mov_b32_dpp v64, v56 row_ror:8 row_mask:0xf bank_mask:0xf bound_ctrl:1
	v_mov_b32_dpp v65, v57 row_ror:8 row_mask:0xf bank_mask:0xf bound_ctrl:1
	v_cndmask_b32_e64 v51, v51, v57, s[8:9]
	v_cndmask_b32_e64 v50, v50, v56, s[8:9]
	v_cndmask_b32_e64 v49, v49, v61, s[8:9]
	global_store_dwordx4 v[52:53], v[48:51], off sc1
	s_nop 1
	v_cndmask_b32_e64 v48, v58, v62, s[8:9]
	v_lshl_add_u64 v[52:53], v[52:53], 0, s[44:45]
	v_cndmask_b32_e64 v51, v59, v65, s[8:9]
	v_cndmask_b32_e64 v50, v55, v64, s[8:9]
	v_cndmask_b32_e64 v49, v54, v63, s[8:9]
	global_store_dwordx4 v[52:53], v[48:51], off sc1
	s_nop 1
	v_add_u32_e32 v48, 0x90, v136
	v_ashrrev_i32_e32 v49, 31, v48
	v_lshlrev_b64 v[48:49], 13, v[48:49]
	v_max_f32_e32 v41, 0, v41
	v_max_f32_e32 v40, 0, v40
	v_max_f32_e32 v43, 0, v43
	v_max_f32_e32 v42, 0, v42
	v_max_f32_e32 v37, 0, v37
	v_max_f32_e32 v36, 0, v36
	v_lshl_add_u64 v[48:49], s[22:23], 0, v[48:49]
	v_max_f32_e32 v45, 0, v45
	v_max_f32_e32 v44, 0, v44
	v_pk_mul_f32 v[42:43], v[42:43], v[42:43]
	v_pk_mul_f32 v[40:41], v[40:41], v[40:41]
	v_max_f32_e32 v39, 0, v39
	v_max_f32_e32 v38, 0, v38
	v_max_f32_e32 v33, 0, v33
	v_max_f32_e32 v32, 0, v32
	v_max_f32_e32 v35, 0, v35
	v_max_f32_e32 v34, 0, v34
	v_pk_mul_f32 v[36:37], v[36:37], v[36:37]
	v_lshl_add_u64 v[48:49], v[48:49], 0, s[58:59]
	v_max_f32_e32 v47, 0, v47
	v_max_f32_e32 v46, 0, v46
	v_pk_mul_f32 v[44:45], v[44:45], v[44:45]
	v_cvt_pk_bf16_f32 v40, v40, v41
	v_cvt_pk_bf16_f32 v41, v42, v43
	v_pk_mul_f32 v[38:39], v[38:39], v[38:39]
	v_pk_mul_f32 v[34:35], v[34:35], v[34:35]
	v_pk_mul_f32 v[32:33], v[32:33], v[32:33]
	v_cvt_pk_bf16_f32 v42, v36, v37
	v_lshl_add_u64 v[48:49], v[48:49], 0, s[20:21]
	v_pk_mul_f32 v[46:47], v[46:47], v[46:47]
	v_cvt_pk_bf16_f32 v44, v44, v45
	v_cvt_pk_bf16_f32 v38, v38, v39
	v_cvt_pk_bf16_f32 v39, v32, v33
	v_cvt_pk_bf16_f32 v43, v34, v35
	v_mov_b32_dpp v32, v42 row_ror:8 row_mask:0xf bank_mask:0xf bound_ctrl:1
	v_lshl_add_u64 v[48:49], v[48:49], 0, v[128:129]
	v_cvt_pk_bf16_f32 v45, v46, v47
	v_mov_b32_dpp v46, v44 row_ror:8 row_mask:0xf bank_mask:0xf bound_ctrl:1
	v_mov_b32_dpp v33, v38 row_ror:8 row_mask:0xf bank_mask:0xf bound_ctrl:1
	v_mov_b32_dpp v34, v39 row_ror:8 row_mask:0xf bank_mask:0xf bound_ctrl:1
	v_mov_b32_dpp v35, v43 row_ror:8 row_mask:0xf bank_mask:0xf bound_ctrl:1
	v_cndmask_b32_e64 v32, v32, v44, s[8:9]
	v_lshl_add_u64 v[36:37], v[48:49], 0, v[134:135]
	v_mov_b32_dpp v47, v45 row_ror:8 row_mask:0xf bank_mask:0xf bound_ctrl:1
	v_mov_b32_dpp v48, v40 row_ror:8 row_mask:0xf bank_mask:0xf bound_ctrl:1
	v_mov_b32_dpp v49, v41 row_ror:8 row_mask:0xf bank_mask:0xf bound_ctrl:1
	v_cndmask_b32_e64 v35, v35, v41, s[8:9]
	v_cndmask_b32_e64 v34, v34, v40, s[8:9]
	v_cndmask_b32_e64 v33, v33, v45, s[8:9]
	global_store_dwordx4 v[36:37], v[32:35], off sc1
	s_nop 1
	v_cndmask_b32_e64 v32, v42, v46, s[8:9]
	v_lshl_add_u64 v[36:37], v[36:37], 0, s[44:45]
	v_cndmask_b32_e64 v35, v43, v49, s[8:9]
	v_cndmask_b32_e64 v34, v39, v48, s[8:9]
	v_cndmask_b32_e64 v33, v38, v47, s[8:9]
	global_store_dwordx4 v[36:37], v[32:35], off sc1
	s_nop 1
	v_add_u32_e32 v32, 0xa0, v136
	v_ashrrev_i32_e32 v33, 31, v32
	v_lshlrev_b64 v[32:33], 13, v[32:33]
	v_max_f32_e32 v25, 0, v25
	v_max_f32_e32 v24, 0, v24
	v_max_f32_e32 v27, 0, v27
	v_max_f32_e32 v26, 0, v26
	v_max_f32_e32 v21, 0, v21
	v_max_f32_e32 v20, 0, v20
	v_lshl_add_u64 v[32:33], s[22:23], 0, v[32:33]
	v_max_f32_e32 v29, 0, v29
	v_max_f32_e32 v28, 0, v28
	v_pk_mul_f32 v[26:27], v[26:27], v[26:27]
; __device__ __forceinline__ unsigned cvt_pk_bf16(float lo, float hi) { const f32x2 v = {lo, hi}; const bf16x2_t b = __builtin_convertvector(v, bf16x2_t); return __builtin_bit_cast(unsigned, b); }
; __device__ __forceinline__ void store16_wt(void* p, u32x4 v) { asm volatile("global_store_dwordx4 %0, %1, off sc1\n\ts_nop 1" :: "v"(p), "v"(v) : "memory"); }
; __device__ __forceinline__ u32x4 ror8_u4(u32x4 v) { const unsigned a = ror8_u(v.x), b = ror8_u(v.y), c = ror8_u(v.z), d = ror8_u(v.w); return (u32x4){a, b, c, d}; }
;     __device__ __forceinline__ void epi(AccT& acc, const Unit& u, LAS unsigned char* lds, int wr, int wc, int fr, int fq) const {
;     ...
;         for (int ai = 0; ai < 2; ++ai)
; #pragma unroll
;             for (int m = 0; m < 4; ++m) { const bool lo = fr < 8; bf16_t* rp = O + (size_t)(u.pm * 256 + ai * 128 + wr * 64 + m * 16 + (fr & 7)) * ldc + u.pn * 256 + wc * 64 + (lo ? 0 : 32) + 8 * fq; u32x4 w[2];
; #pragma unroll
;                 for (int bj = 0; bj < 2; ++bj) { f32x4 v0 = acc[ai][bj][m][0], v1 = acc[ai][bj][m][1];
;                     if (ACT == 1) { v0 = __builtin_elementwise_max(v0, (f32x4){0.f, 0.f, 0.f, 0.f}); v1 = __builtin_elementwise_max(v1, (f32x4){0.f, 0.f, 0.f, 0.f}); v0 = v0 * v0; v1 = v1 * v1; }
;                     w[bj].x = cvt_pk_bf16(v0[0], v0[1]); w[bj].y = cvt_pk_bf16(v0[2], v0[3]); w[bj].z = cvt_pk_bf16(v1[0], v1[1]); w[bj].w = cvt_pk_bf16(v1[2], v1[3]); }
;                 const u32x4 r0 = ror8_u4(w[0]), r1 = ror8_u4(w[1]); store16_wt(rp, lo ? w[0] : r1); store16_wt(rp + (size_t)8 * ldc, lo ? r0 : w[1]); }
	v_pk_mul_f32 v[24:25], v[24:25], v[24:25]
	v_max_f32_e32 v23, 0, v23
	v_max_f32_e32 v22, 0, v22
	v_max_f32_e32 v17, 0, v17
	v_max_f32_e32 v16, 0, v16
	v_max_f32_e32 v19, 0, v19
	v_max_f32_e32 v18, 0, v18
	v_pk_mul_f32 v[20:21], v[20:21], v[20:21]
	v_lshl_add_u64 v[32:33], v[32:33], 0, s[58:59]
	v_max_f32_e32 v31, 0, v31
	v_max_f32_e32 v30, 0, v30
	v_pk_mul_f32 v[28:29], v[28:29], v[28:29]
	v_cvt_pk_bf16_f32 v24, v24, v25
	v_cvt_pk_bf16_f32 v25, v26, v27
	v_pk_mul_f32 v[22:23], v[22:23], v[22:23]
	v_pk_mul_f32 v[18:19], v[18:19], v[18:19]
	v_pk_mul_f32 v[16:17], v[16:17], v[16:17]
	v_cvt_pk_bf16_f32 v26, v20, v21
	v_lshl_add_u64 v[32:33], v[32:33], 0, s[20:21]
	v_pk_mul_f32 v[30:31], v[30:31], v[30:31]
	v_cvt_pk_bf16_f32 v28, v28, v29
	v_cvt_pk_bf16_f32 v22, v22, v23
	v_cvt_pk_bf16_f32 v23, v16, v17
	v_cvt_pk_bf16_f32 v27, v18, v19
	v_mov_b32_dpp v16, v26 row_ror:8 row_mask:0xf bank_mask:0xf bound_ctrl:1
	v_lshl_add_u64 v[32:33], v[32:33], 0, v[128:129]
	v_cvt_pk_bf16_f32 v29, v30, v31
	v_mov_b32_dpp v30, v28 row_ror:8 row_mask:0xf bank_mask:0xf bound_ctrl:1
	v_mov_b32_dpp v17, v22 row_ror:8 row_mask:0xf bank_mask:0xf bound_ctrl:1
	v_mov_b32_dpp v18, v23 row_ror:8 row_mask:0xf bank_mask:0xf bound_ctrl:1
	v_mov_b32_dpp v19, v27 row_ror:8 row_mask:0xf bank_mask:0xf bound_ctrl:1
	v_cndmask_b32_e64 v16, v16, v28, s[8:9]
	v_lshl_add_u64 v[20:21], v[32:33], 0, v[134:135]
	v_mov_b32_dpp v31, v29 row_ror:8 row_mask:0xf bank_mask:0xf bound_ctrl:1
	v_mov_b32_dpp v32, v24 row_ror:8 row_mask:0xf bank_mask:0xf bound_ctrl:1
	v_mov_b32_dpp v33, v25 row_ror:8 row_mask:0xf bank_mask:0xf bound_ctrl:1
	v_cndmask_b32_e64 v19, v19, v25, s[8:9]
	v_cndmask_b32_e64 v18, v18, v24, s[8:9]
	v_cndmask_b32_e64 v17, v17, v29, s[8:9]
	global_store_dwordx4 v[20:21], v[16:19], off sc1
	s_nop 1
	v_cndmask_b32_e64 v16, v26, v30, s[8:9]
	v_lshl_add_u64 v[20:21], v[20:21], 0, s[44:45]
	v_cndmask_b32_e64 v19, v27, v33, s[8:9]
	v_cndmask_b32_e64 v18, v23, v32, s[8:9]
	v_cndmask_b32_e64 v17, v22, v31, s[8:9]
	global_store_dwordx4 v[20:21], v[16:19], off sc1
	s_nop 1
	v_add_u32_e32 v16, 0xb0, v136
	v_ashrrev_i32_e32 v17, 31, v16
	v_lshlrev_b64 v[16:17], 13, v[16:17]
	v_lshl_add_u64 v[16:17], s[22:23], 0, v[16:17]
	v_max_f32_e32 v9, 0, v9
	v_max_f32_e32 v8, 0, v8
	v_max_f32_e32 v11, 0, v11
	v_max_f32_e32 v10, 0, v10
	v_max_f32_e32 v5, 0, v5
	v_max_f32_e32 v4, 0, v4
	v_max_f32_e32 v7, 0, v7
	v_max_f32_e32 v6, 0, v6
	v_max_f32_e32 v1, 0, v1
	v_max_f32_e32 v0, 0, v0
	v_max_f32_e32 v3, 0, v3
	v_max_f32_e32 v2, 0, v2
	v_lshl_add_u64 v[16:17], v[16:17], 0, s[58:59]
	v_max_f32_e32 v13, 0, v13
	v_max_f32_e32 v12, 0, v12
	v_max_f32_e32 v15, 0, v15
	v_max_f32_e32 v14, 0, v14
	v_pk_mul_f32 v[10:11], v[10:11], v[10:11]
	v_pk_mul_f32 v[8:9], v[8:9], v[8:9]
	v_pk_mul_f32 v[6:7], v[6:7], v[6:7]
	v_pk_mul_f32 v[4:5], v[4:5], v[4:5]
	v_pk_mul_f32 v[2:3], v[2:3], v[2:3]
	v_pk_mul_f32 v[0:1], v[0:1], v[0:1]
	v_lshl_add_u64 v[16:17], v[16:17], 0, s[20:21]
	v_pk_mul_f32 v[14:15], v[14:15], v[14:15]
	v_pk_mul_f32 v[12:13], v[12:13], v[12:13]
	v_cvt_pk_bf16_f32 v8, v8, v9
	v_cvt_pk_bf16_f32 v9, v10, v11
	v_cvt_pk_bf16_f32 v10, v4, v5
	v_cvt_pk_bf16_f32 v6, v6, v7
	v_cvt_pk_bf16_f32 v7, v0, v1
	v_cvt_pk_bf16_f32 v11, v2, v3
	v_lshl_add_u64 v[16:17], v[16:17], 0, v[128:129]
	v_cvt_pk_bf16_f32 v12, v12, v13
	v_cvt_pk_bf16_f32 v13, v14, v15
	v_mov_b32_dpp v0, v10 row_ror:8 row_mask:0xf bank_mask:0xf bound_ctrl:1
	v_mov_b32_dpp v1, v6 row_ror:8 row_mask:0xf bank_mask:0xf bound_ctrl:1
	v_mov_b32_dpp v2, v7 row_ror:8 row_mask:0xf bank_mask:0xf bound_ctrl:1
	v_mov_b32_dpp v3, v11 row_ror:8 row_mask:0xf bank_mask:0xf bound_ctrl:1
	v_lshl_add_u64 v[4:5], v[16:17], 0, v[134:135]
	v_mov_b32_dpp v14, v12 row_ror:8 row_mask:0xf bank_mask:0xf bound_ctrl:1
	v_mov_b32_dpp v15, v13 row_ror:8 row_mask:0xf bank_mask:0xf bound_ctrl:1
	v_mov_b32_dpp v16, v8 row_ror:8 row_mask:0xf bank_mask:0xf bound_ctrl:1
	v_mov_b32_dpp v17, v9 row_ror:8 row_mask:0xf bank_mask:0xf bound_ctrl:1
	v_cndmask_b32_e64 v3, v3, v9, s[8:9]
	v_cndmask_b32_e64 v2, v2, v8, s[8:9]
	v_cndmask_b32_e64 v1, v1, v13, s[8:9]
	v_cndmask_b32_e64 v0, v0, v12, s[8:9]
	global_store_dwordx4 v[4:5], v[0:3], off sc1
	s_nop 1
	v_lshl_add_u64 v[4:5], v[4:5], 0, s[44:45]
	v_cndmask_b32_e64 v3, v11, v17, s[8:9]
	v_cndmask_b32_e64 v2, v7, v16, s[8:9]
	v_cndmask_b32_e64 v1, v6, v15, s[8:9]
	v_cndmask_b32_e64 v0, v10, v14, s[8:9]
	global_store_dwordx4 v[4:5], v[0:3], off sc1
	s_nop 1
	s_andn2_b64 vcc, exec, s[10:11]
	s_mov_b64 s[10:11], -1
	s_cbranch_vccnz .LBB0_544
	s_andn2_b64 vcc, exec, s[18:19]
	s_cbranch_vccnz .LBB0_543
	s_barrier
	s_branch .LBB0_543

;     __device__ __forceinline__ void epi(AccT& acc, const Unit& u, LAS unsigned char* lds, int wr, int wc, int fr, int fq) const {
;     ...
;             __builtin_amdgcn_fence(__ATOMIC_ACQUIRE, "agent");
;             if (lane == 0) flag[0] = dead ? 1u : 0u;
.LBB0_675:
	v_readlane_b32 s90, v252, 39
	s_and_saveexec_b64 s[88:89], s[22:23]
	s_cbranch_execz .LBB0_678
	s_waitcnt vmcnt(0)
	s_and_b64 exec, exec, s[12:13]
	v_cndmask_b32_e64 v66, 0, 1, s[82:83]
	v_mov_b32_e32 v67, s40
	ds_write_b32 v67, v66

; #define LAS __attribute__((address_space(3)))
; #define GAS __attribute__((address_space(1)))
; __device__ __forceinline__ void phase_gla_kdec(Frame& F) {
;     ...
;     for (int unit = F.bid; unit < NB * (SEQ / CH); unit += F.G) {
;         const size_t m0 = (size_t)unit * CH;
;         __syncthreads();
;         {
;             f32x4 ga[4];
; #pragma unroll
;             for (int mb = 0; mb < 4; ++mb) ga[mb] = (f32x4){0.f, 0.f, 0.f, 0.f};
; #pragma unroll
;             for (int ks = 0; ks < 4; ++ks) { const int k0 = 128 * w + 32 * ks + 8 * g; const bf16x8 bfr = *(const GAS bf16x8*)(WGT + li * D + k0);
; #pragma unroll
;                 for (int mb = 0; mb < 4; ++mb) { const bf16x8 afr = *(const GAS bf16x8*)(H2 + (m0 + 16 * mb + li) * D + k0); ga[mb] = __builtin_amdgcn_mfma_f32_16x16x32_bf16(afr, bfr, ga[mb], 0, 0, 0); } }
; #pragma unroll
;             for (int mb = 0; mb < 4; ++mb)
; #pragma unroll
;                 for (int i = 0; i < 4; ++i) gpart[(w * 64 + 16 * mb + 4 * g + i) * 16 + li] = ga[mb][i];
;         }
; #pragma unroll
;         for (int i = 0; i < 8; ++i) { const int idx = F.tid + NTHR * i, row = idx >> 6, ch = idx & 63;
;             *(LAS u32x4*)(kt + row * KP + ch * 8) = *(const GAS u32x4*)(QKVR + (m0 + row) * NQKVR + QKW + ch * 8); }
;         u32x4 rv[4];
; #pragma unroll
;         for (int i = 0; i < 4; ++i) { const int idx = F.tid + NTHR * i, row = idx >> 5, ch = idx & 31; rv[i] = *(const GAS u32x4*)(QKVR + (m0 + row) * NQKVR + 2 * QKW + ch * 8); }
.LBB0_817:
	s_ashr_i32 s15, s14, 31
	s_lshl_b64 s[16:17], s[14:15], 6
	s_waitcnt vmcnt(11)
	v_mov_b32_e32 v1, s17
	v_or_b32_e32 v0, s16, v30
	s_waitcnt vmcnt(9)
	v_mov_b32_e32 v9, s17
	v_or_b32_e32 v8, s16, v40
	s_waitcnt vmcnt(8)
	v_mov_b32_e32 v13, s17
	v_or_b32_e32 v12, s16, v42
	v_mov_b32_e32 v89, s17
	v_or_b32_e32 v88, s16, v44
	v_lshlrev_b64 v[154:155], 11, v[0:1]
	v_lshlrev_b64 v[162:163], 11, v[8:9]
	v_lshlrev_b64 v[166:167], 11, v[12:13]
	v_lshlrev_b64 v[168:169], 11, v[88:89]
	v_lshl_add_u64 v[4:5], v[38:39], 0, v[154:155]
	v_lshl_add_u64 v[8:9], v[38:39], 0, v[162:163]
	v_lshl_add_u64 v[12:13], v[38:39], 0, v[166:167]
	v_lshl_add_u64 v[88:89], v[38:39], 0, v[168:169]
	s_barrier
	global_load_dwordx4 v[0:3], v[36:37], off
	v_lshl_add_u64 v[92:93], v[46:47], 0, v[154:155]
	global_load_dwordx4 v[4:7], v[4:5], off
	v_lshl_add_u64 v[122:123], v[46:47], 0, v[162:163]
	global_load_dwordx4 v[8:11], v[8:9], off
	v_lshl_add_u64 v[126:127], v[46:47], 0, v[166:167]
	global_load_dwordx4 v[12:15], v[12:13], off
	v_lshl_add_u64 v[130:131], v[46:47], 0, v[168:169]
	global_load_dwordx4 v[88:91], v[88:89], off
	s_nop 0
	global_load_dwordx4 v[92:95], v[92:93], off
	s_nop 0
	global_load_dwordx4 v[118:121], v[36:37], off offset:64
	v_lshl_add_u64 v[134:135], v[48:49], 0, v[154:155]
	global_load_dwordx4 v[122:125], v[122:123], off
	v_lshl_add_u64 v[142:143], v[48:49], 0, v[162:163]
	global_load_dwordx4 v[126:129], v[126:127], off
	v_lshl_add_u64 v[146:147], v[48:49], 0, v[166:167]
	global_load_dwordx4 v[130:133], v[130:131], off
	s_nop 0
	global_load_dwordx4 v[134:137], v[134:135], off
	s_nop 0
	global_load_dwordx4 v[138:141], v[36:37], off offset:128
	v_lshl_add_u64 v[150:151], v[48:49], 0, v[168:169]
	global_load_dwordx4 v[142:145], v[142:143], off
	v_lshl_add_u64 v[154:155], v[50:51], 0, v[154:155]
	global_load_dwordx4 v[146:149], v[146:147], off
	v_lshl_add_u64 v[166:167], v[50:51], 0, v[166:167]
	global_load_dwordx4 v[150:153], v[150:151], off
	s_nop 0
	global_load_dwordx4 v[154:157], v[154:155], off
	s_nop 0
	global_load_dwordx4 v[158:161], v[36:37], off offset:192
	v_lshl_add_u64 v[162:163], v[50:51], 0, v[162:163]
	global_load_dwordx4 v[162:165], v[162:163], off
	v_lshl_add_u64 v[170:171], s[16:17], 0, v[54:55]
	v_lshl_add_u64 v[172:173], s[16:17], 0, v[56:57]
	v_lshl_add_u64 v[174:175], s[16:17], 0, v[58:59]
	v_lshl_add_u64 v[176:177], s[16:17], 0, v[64:65]
	s_waitcnt vmcnt(16)
	v_mfma_f32_16x16x32_bf16 v[4:7], v[4:7], v[0:3], 0
	s_waitcnt vmcnt(15)
	v_mfma_f32_16x16x32_bf16 v[8:11], v[8:11], v[0:3], 0
	s_waitcnt vmcnt(14)
	v_mfma_f32_16x16x32_bf16 v[12:15], v[12:15], v[0:3], 0
	s_waitcnt vmcnt(13)
	v_mfma_f32_16x16x32_bf16 v[0:3], v[88:91], v[0:3], 0
	global_load_dwordx4 v[88:91], v[166:167], off
	v_lshl_add_u64 v[166:167], s[16:17], 0, v[52:53]
	s_waitcnt vmcnt(10)
	v_mfma_f32_16x16x32_bf16 v[12:15], v[126:129], v[118:121], v[12:15]
	v_mad_u64_u32 v[126:127], s[0:1], v166, s21, v[76:77]
	v_mad_u64_u32 v[128:129], s[0:1], v170, s21, v[76:77]
	v_mfma_f32_16x16x32_bf16 v[4:7], v[92:95], v[118:121], v[4:7]
	v_lshl_add_u64 v[92:93], v[50:51], 0, v[168:169]
	global_load_dwordx4 v[92:95], v[92:93], off
	v_mad_i32_i24 v127, v167, s21, v127
	s_waitcnt vmcnt(6)
	v_mfma_f32_16x16x32_bf16 v[12:15], v[146:149], v[138:141], v[12:15]
	v_mad_i32_i24 v129, v171, s21, v129
	v_mfma_f32_16x16x32_bf16 v[8:11], v[122:125], v[118:121], v[8:11]
	v_lshl_add_u64 v[122:123], s[16:17], 0, v[60:61]
	v_lshl_add_u64 v[124:125], s[16:17], 0, v[62:63]
	v_mad_u64_u32 v[178:179], s[0:1], v124, s21, v[76:77]
	v_mfma_f32_16x16x32_bf16 v[0:3], v[130:133], v[118:121], v[0:3]
	v_mad_u64_u32 v[130:131], s[0:1], v172, s21, v[76:77]
	v_mad_u64_u32 v[132:133], s[0:1], v174, s21, v[76:77]
	v_mfma_f32_16x16x32_bf16 v[4:7], v[134:137], v[138:141], v[4:7]
	v_mad_u64_u32 v[134:135], s[0:1], v122, s21, v[76:77]
	v_mad_i32_i24 v131, v173, s21, v131
	v_mfma_f32_16x16x32_bf16 v[8:11], v[142:145], v[138:141], v[8:11]
	v_mad_u64_u32 v[142:143], s[0:1], v176, s21, v[76:77]
	v_mad_i32_i24 v133, v175, s21, v133
	v_mad_i32_i24 v135, v123, s21, v135
	v_mad_i32_i24 v143, v177, s21, v143
	s_waitcnt vmcnt(5)
	v_mfma_f32_16x16x32_bf16 v[0:3], v[150:153], v[138:141], v[0:3]
	v_mad_i32_i24 v179, v125, s21, v179
	global_load_dwordx4 v[118:121], v[126:127], off offset:1024
	global_load_dwordx4 v[122:125], v[128:129], off offset:1024
	s_nop 0
	global_load_dwordx4 v[126:129], v[130:131], off offset:1024
	s_nop 0
	global_load_dwordx4 v[130:133], v[132:133], off offset:1024
	s_nop 0
	global_load_dwordx4 v[134:137], v[134:135], off offset:1024
	s_nop 0
	global_load_dwordx4 v[138:141], v[178:179], off offset:1024
	s_waitcnt vmcnt(9)
	v_mfma_f32_16x16x32_bf16 v[4:7], v[154:157], v[158:161], v[4:7]
	s_waitcnt vmcnt(8)
	v_mfma_f32_16x16x32_bf16 v[8:11], v[162:165], v[158:161], v[8:11]
	s_waitcnt vmcnt(7)
	v_mfma_f32_16x16x32_bf16 v[12:15], v[88:91], v[158:161], v[12:15]
	v_lshl_add_u64 v[88:89], s[16:17], 0, v[66:67]
	v_mad_u64_u32 v[144:145], s[0:1], v88, s21, v[76:77]
	v_mad_i32_i24 v145, v89, s21, v145
	global_load_dwordx4 v[88:91], v[142:143], off offset:1024
	s_nop 0
	global_load_dwordx4 v[142:145], v[144:145], off offset:1024
	s_waitcnt vmcnt(8)
	v_mfma_f32_16x16x32_bf16 v[0:3], v[92:95], v[158:161], v[0:3]
	ds_write2_b32 v116, v4, v5 offset1:16
	ds_write2_b32 v116, v6, v7 offset0:32 offset1:48
	v_add_u32_e32 v4, 0x400, v116
	ds_write2_b32 v4, v8, v9 offset1:16
	ds_write2_b32 v4, v10, v11 offset0:32 offset1:48
	v_add_u32_e32 v4, 0x800, v116
	ds_write2_b32 v4, v12, v13 offset1:16
	ds_write2_b32 v4, v14, v15 offset0:32 offset1:48
	v_add_u32_e32 v4, 0xc00, v116
	v_lshl_add_u64 v[8:9], s[16:17], 0, v[72:73]
	ds_write2_b32 v4, v0, v1 offset1:16
	ds_write2_b32 v4, v2, v3 offset0:32 offset1:48
	s_waitcnt vmcnt(7)
	ds_write_b128 v101, v[118:121] offset:4096
	s_waitcnt vmcnt(6)
	ds_write_b128 v102, v[122:125] offset:4096
	s_waitcnt vmcnt(5)
	ds_write_b128 v103, v[126:129] offset:4096
	s_waitcnt vmcnt(4)
	ds_write_b128 v104, v[130:133] offset:4096
	s_waitcnt vmcnt(3)
	ds_write_b128 v105, v[134:137] offset:4096
	s_waitcnt vmcnt(2)
	ds_write_b128 v106, v[138:141] offset:4096
	s_waitcnt vmcnt(1)
	ds_write_b128 v107, v[88:91] offset:4096
	s_waitcnt vmcnt(0)
	ds_write_b128 v108, v[142:145] offset:4096
	v_lshl_add_u64 v[0:1], s[16:17], 0, v[68:69]
	v_mad_u64_u32 v[2:3], s[0:1], v0, s21, v[78:79]
	v_mad_u64_u32 v[88:89], s[0:1], v8, s21, v[78:79]
	v_mad_i32_i24 v3, v1, s21, v3
	v_lshl_add_u64 v[0:1], s[16:17], 0, v[70:71]
	v_mad_i32_i24 v89, v9, s21, v89
	v_lshl_add_u64 v[8:9], s[16:17], 0, v[74:75]
	v_mad_u64_u32 v[4:5], s[0:1], v0, s21, v[78:79]
	v_mad_u64_u32 v[90:91], s[0:1], v8, s21, v[78:79]
	v_mad_i32_i24 v5, v1, s21, v5
	v_mad_i32_i24 v91, v9, s21, v91
	global_load_dwordx4 v[0:3], v[2:3], off offset:2048
	s_nop 0
	global_load_dwordx4 v[4:7], v[4:5], off offset:2048
	s_nop 0
	global_load_dwordx4 v[8:11], v[88:89], off offset:2048
	global_load_dwordx4 v[12:15], v[90:91], off offset:2048
	s_waitcnt lgkmcnt(0)
	s_barrier
; #define LAS __attribute__((address_space(3)))
; __device__ __forceinline__ void phase_gla_kdec(Frame& F) {
;     ...
;         { const int sIdx = F.tid >> 3, r2 = (F.tid & 7) * 2; float s0 = 0.f, s1 = 0.f;
; #pragma unroll
;             for (int v = 0; v < 8; ++v) { s0 += gpart[(v * 64 + sIdx) * 16 + r2]; s1 += gpart[(v * 64 + sIdx) * 16 + r2 + 1]; }
;             glr[sIdx * 16 + r2] = s0; glr[sIdx * 16 + r2 + 1] = s1; }
;         __syncthreads();
;         { float gc[CH]; float run = 0.f;
; #pragma unroll
;             for (int s = 0; s < CH; ++s) { float a = bgc;
; #pragma unroll
;                 for (int r4 = 0; r4 < 4; ++r4) { const f32x4 gv = *(const LAS f32x4*)(glr + s * 16 + r4 * 4); a += (gv.x * w2c[4 * r4] + gv.y * w2c[4 * r4 + 1]) + (gv.z * w2c[4 * r4 + 2] + gv.w * w2c[4 * r4 + 3]); }
;                 run += fast_logsigmoid(a) * (1.f / 16.f); gc[s] = run; }
	ds_read2st64_b64 v[88:91], v109 offset1:8
	ds_read2st64_b64 v[92:95], v109 offset0:16 offset1:24
	ds_read2st64_b64 v[118:121], v109 offset0:32 offset1:40
	s_lshl_b64 s[0:1], s[14:15], 11
	s_mov_b32 s16, s19
	s_waitcnt lgkmcnt(2)
	v_pk_add_f32 v[88:89], v[88:89], 0 op_sel_hi:[1,0]
	s_nop 0
	v_pk_add_f32 v[122:123], v[88:89], v[90:91]
	ds_read2st64_b64 v[88:91], v109 offset0:48 offset1:56
	s_waitcnt lgkmcnt(2)
	v_pk_add_f32 v[92:93], v[122:123], v[92:93]
	s_nop 0
	v_pk_add_f32 v[92:93], v[92:93], v[94:95]
	s_waitcnt lgkmcnt(1)
	v_pk_add_f32 v[92:93], v[92:93], v[118:119]
	s_nop 0
	v_pk_add_f32 v[92:93], v[92:93], v[120:121]
	s_waitcnt lgkmcnt(0)
	v_pk_add_f32 v[88:89], v[92:93], v[88:89]
	s_nop 0
	v_pk_add_f32 v[88:89], v[88:89], v[90:91]
	ds_write_b64 v110, v[88:89]
	s_waitcnt lgkmcnt(0)
	s_barrier
	ds_read_b128 v[88:91], v33
	ds_read_b128 v[92:95], v33 offset:16
	ds_read_b128 v[118:121], v33 offset:32
	ds_read_b128 v[122:125], v33 offset:48
	ds_read_b128 v[144:147], v33 offset:1680
	s_waitcnt lgkmcnt(4)
	v_mul_f32_e32 v89, v18, v89
	v_fmac_f32_e32 v89, v16, v88
	v_mul_f32_e32 v88, v17, v91
	v_fmac_f32_e32 v88, v19, v90
	v_add_f32_e32 v88, v89, v88
	s_waitcnt lgkmcnt(3)
	v_mul_f32_e32 v89, v22, v93
	v_mul_f32_e32 v90, v21, v95
	v_fmac_f32_e32 v89, v20, v92
	v_fmac_f32_e32 v90, v23, v94
	v_add_f32_e32 v88, v96, v88
	v_add_f32_e32 v89, v89, v90
	v_add_f32_e32 v88, v88, v89
	s_waitcnt lgkmcnt(2)
	v_mul_f32_e32 v89, v25, v119
	v_mul_f32_e32 v90, v27, v121
	v_fmac_f32_e32 v89, v24, v118
	v_fmac_f32_e32 v90, v26, v120
	v_add_f32_e32 v89, v89, v90
	v_add_f32_e32 v88, v88, v89
	s_waitcnt lgkmcnt(1)
	v_mul_f32_e32 v89, v41, v123
	v_mul_f32_e32 v90, v45, v125
	v_fmac_f32_e32 v89, v31, v122
	v_fmac_f32_e32 v90, v43, v124
	v_add_f32_e32 v89, v89, v90
	v_add_f32_e32 v117, v88, v89
	v_mul_f32_e64 v88, |v117|, s22
	v_exp_f32_e32 v92, v88
	ds_read_b128 v[88:91], v33 offset:64
	v_add_f32_e32 v92, 1.0, v92
	v_log_f32_e32 v118, v92
	ds_read_b128 v[92:95], v33 offset:80
	s_waitcnt lgkmcnt(1)
	v_mul_f32_e32 v89, v18, v89
	v_fmac_f32_e32 v89, v16, v88
	v_mul_f32_e32 v88, v17, v91
	v_fmac_f32_e32 v88, v19, v90
	v_add_f32_e32 v88, v89, v88
	s_waitcnt lgkmcnt(0)
	v_mul_f32_e32 v93, v22, v93
	v_add_f32_e32 v119, v96, v88
	v_fmac_f32_e32 v93, v20, v92
	v_mul_f32_e32 v92, v21, v95
	ds_read_b128 v[88:91], v33 offset:96
	v_fmac_f32_e32 v92, v23, v94
	v_add_f32_e32 v92, v93, v92
	v_add_f32_e32 v119, v119, v92
	ds_read_b128 v[92:95], v33 offset:112
	s_waitcnt lgkmcnt(1)
	v_mul_f32_e32 v89, v25, v89
	v_fmac_f32_e32 v89, v24, v88
	v_mul_f32_e32 v88, v27, v91
	v_fmac_f32_e32 v88, v26, v90
	v_add_f32_e32 v88, v89, v88
	s_waitcnt lgkmcnt(0)
	v_mul_f32_e32 v89, v41, v93
	v_mul_f32_e32 v90, v45, v95
	v_fmac_f32_e32 v89, v31, v92
	v_fmac_f32_e32 v90, v43, v94
	v_add_f32_e32 v88, v119, v88
	v_add_f32_e32 v89, v89, v90
	v_add_f32_e32 v88, v88, v89
	ds_read_b128 v[90:93], v33 offset:128
	v_mul_f32_e64 v89, |v88|, s22
	v_exp_f32_e32 v89, v89
	v_min_f32_e32 v94, 0, v117
	v_fmac_f32_e32 v94, 0xbf317218, v118
	ds_read_b128 v[118:121], v33 offset:144
	s_waitcnt lgkmcnt(1)
	v_mul_f32_e32 v91, v18, v91
	v_add_f32_e32 v89, 1.0, v89
	v_fmac_f32_e32 v91, v16, v90
	v_mul_f32_e32 v90, v17, v93
	v_log_f32_e32 v95, v89
	v_fmac_f32_e32 v90, v19, v92
	v_add_f32_e32 v90, v91, v90
	v_fma_f32 v89, v94, s23, 0
	v_add_f32_e32 v94, v96, v90
	ds_read_b128 v[90:93], v33 offset:160
	v_min_f32_e32 v88, 0, v88
	v_fmac_f32_e32 v88, 0xbf317218, v95
	s_waitcnt lgkmcnt(1)
	v_mul_f32_e32 v95, v22, v119
	v_mul_f32_e32 v117, v21, v121
	v_fmac_f32_e32 v95, v20, v118
	v_fmac_f32_e32 v117, v23, v120
	ds_read_b128 v[118:121], v33 offset:176
	s_waitcnt lgkmcnt(1)
	v_mul_f32_e32 v91, v25, v91
	v_fmac_f32_e32 v91, v24, v90
	v_mul_f32_e32 v90, v27, v93
	v_fmac_f32_e32 v90, v26, v92
	v_add_f32_e32 v95, v95, v117
	v_add_f32_e32 v90, v91, v90
	s_waitcnt lgkmcnt(0)
	v_mul_f32_e32 v91, v41, v119
	v_mul_f32_e32 v92, v45, v121
	v_add_f32_e32 v94, v94, v95
	v_fmac_f32_e32 v91, v31, v118
	v_fmac_f32_e32 v92, v43, v120
	v_add_f32_e32 v90, v94, v90
	v_add_f32_e32 v91, v91, v92
	v_add_f32_e32 v94, v90, v91
	v_mul_f32_e64 v90, |v94|, s22
	v_exp_f32_e32 v95, v90
	ds_read_b128 v[90:93], v33 offset:192
	ds_read_b128 v[118:121], v33 offset:208
	v_min_f32_e32 v117, 0, v94
	v_add_f32_e32 v94, 1.0, v95
	v_log_f32_e32 v94, v94
	s_waitcnt lgkmcnt(1)
	v_mul_f32_e32 v91, v18, v91
	v_fmac_f32_e32 v91, v16, v90
	v_mul_f32_e32 v90, v17, v93
	v_fmac_f32_e32 v90, v19, v92
	v_add_f32_e32 v90, v91, v90
	s_waitcnt lgkmcnt(0)
	v_mul_f32_e32 v119, v22, v119
	v_add_f32_e32 v95, v96, v90
	v_fmac_f32_e32 v119, v20, v118
	v_mul_f32_e32 v118, v21, v121
	ds_read_b128 v[90:93], v33 offset:224
	v_fmac_f32_e32 v118, v23, v120
	v_add_f32_e32 v118, v119, v118
	v_add_f32_e32 v95, v95, v118
	ds_read_b128 v[118:121], v33 offset:240
	s_waitcnt lgkmcnt(1)
	v_mul_f32_e32 v91, v25, v91
	v_fmac_f32_e32 v91, v24, v90
	v_mul_f32_e32 v90, v27, v93
	v_fmac_f32_e32 v90, v26, v92
	v_add_f32_e32 v90, v91, v90
	s_waitcnt lgkmcnt(0)
	v_mul_f32_e32 v91, v41, v119
	v_mul_f32_e32 v92, v45, v121
	v_fmac_f32_e32 v91, v31, v118
	v_fmac_f32_e32 v92, v43, v120
	v_add_f32_e32 v90, v95, v90
	v_add_f32_e32 v91, v91, v92
	v_add_f32_e32 v91, v90, v91
	v_mul_f32_e64 v90, |v91|, s22
	v_exp_f32_e32 v118, v90
	v_fmac_f32_e32 v117, 0xbf317218, v94
	ds_read_b128 v[92:95], v33 offset:256
	v_fmamk_f32 v88, v88, 0x3d800000, v89
	v_fmamk_f32 v90, v117, 0x3d800000, v88
	v_add_f32_e32 v117, 1.0, v118
	ds_read_b128 v[118:121], v33 offset:272
	s_waitcnt lgkmcnt(1)
	v_mul_f32_e32 v93, v18, v93
	v_fmac_f32_e32 v93, v16, v92
	v_mul_f32_e32 v92, v17, v95
	v_fmac_f32_e32 v92, v19, v94
	v_add_f32_e32 v92, v93, v92
	s_waitcnt lgkmcnt(0)
; #define LAS __attribute__((address_space(3)))
; __device__ __forceinline__ void phase_gla_kdec(Frame& F) {
;     ...
;             for (int s = 0; s < CH; ++s) { float a = bgc;
; #pragma unroll
;                 for (int r4 = 0; r4 < 4; ++r4) { const f32x4 gv = *(const LAS f32x4*)(glr + s * 16 + r4 * 4); a += (gv.x * w2c[4 * r4] + gv.y * w2c[4 * r4 + 1]) + (gv.z * w2c[4 * r4 + 2] + gv.w * w2c[4 * r4 + 3]); }
;                 run += fast_logsigmoid(a) * (1.f / 16.f); gc[s] = run; }
	v_mul_f32_e32 v119, v22, v119
	v_add_f32_e32 v122, v96, v92
	v_fmac_f32_e32 v119, v20, v118
	v_mul_f32_e32 v118, v21, v121
	ds_read_b128 v[92:95], v33 offset:288
	v_fmac_f32_e32 v118, v23, v120
	v_add_f32_e32 v118, v119, v118
	v_add_f32_e32 v122, v122, v118
	ds_read_b128 v[118:121], v33 offset:304
	s_waitcnt lgkmcnt(1)
	v_mul_f32_e32 v93, v25, v93
	v_fmac_f32_e32 v93, v24, v92
	v_mul_f32_e32 v92, v27, v95
	v_fmac_f32_e32 v92, v26, v94
	v_add_f32_e32 v92, v93, v92
	s_waitcnt lgkmcnt(0)
	v_mul_f32_e32 v93, v41, v119
	v_mul_f32_e32 v94, v45, v121
	v_fmac_f32_e32 v93, v31, v118
	v_fmac_f32_e32 v94, v43, v120
	v_add_f32_e32 v92, v122, v92
	v_add_f32_e32 v93, v93, v94
	v_add_f32_e32 v122, v92, v93
	v_mul_f32_e64 v92, |v122|, s22
	v_log_f32_e32 v117, v117
	v_exp_f32_e32 v118, v92
	ds_read_b128 v[92:95], v33 offset:320
	v_min_f32_e32 v91, 0, v91
	v_fmac_f32_e32 v91, 0xbf317218, v117
	v_add_f32_e32 v117, 1.0, v118
	ds_read_b128 v[118:121], v33 offset:336
	s_waitcnt lgkmcnt(1)
	v_mul_f32_e32 v93, v18, v93
	v_fmac_f32_e32 v93, v16, v92
	v_mul_f32_e32 v92, v17, v95
	v_fmac_f32_e32 v92, v19, v94
	v_add_f32_e32 v92, v93, v92
	s_waitcnt lgkmcnt(0)
	v_mul_f32_e32 v119, v22, v119
	v_add_f32_e32 v123, v96, v92
	v_fmac_f32_e32 v119, v20, v118
	v_mul_f32_e32 v118, v21, v121
	ds_read_b128 v[92:95], v33 offset:352
	v_fmac_f32_e32 v118, v23, v120
	v_add_f32_e32 v118, v119, v118
	v_add_f32_e32 v123, v123, v118
	ds_read_b128 v[118:121], v33 offset:368
	s_waitcnt lgkmcnt(1)
	v_mul_f32_e32 v93, v25, v93
	v_fmac_f32_e32 v93, v24, v92
	v_mul_f32_e32 v92, v27, v95
	v_fmac_f32_e32 v92, v26, v94
	v_add_f32_e32 v92, v93, v92
	s_waitcnt lgkmcnt(0)
	v_mul_f32_e32 v93, v41, v119
	v_mul_f32_e32 v94, v45, v121
	v_fmac_f32_e32 v93, v31, v118
	v_fmac_f32_e32 v94, v43, v120
	v_add_f32_e32 v92, v123, v92
	v_add_f32_e32 v93, v93, v94
	v_add_f32_e32 v93, v92, v93
	v_mul_f32_e64 v92, |v93|, s22
	v_exp_f32_e32 v92, v92
	v_log_f32_e32 v117, v117
	ds_read_b128 v[118:121], v33 offset:384
	v_min_f32_e32 v94, 0, v122
	v_add_f32_e32 v92, 1.0, v92
	v_log_f32_e32 v95, v92
	ds_read_b128 v[122:125], v33 offset:400
	v_fmamk_f32 v91, v91, 0x3d800000, v90
	v_fmac_f32_e32 v94, 0xbf317218, v117
	v_min_f32_e32 v93, 0, v93
	v_fmamk_f32 v92, v94, 0x3d800000, v91
	v_fmac_f32_e32 v93, 0xbf317218, v95
	s_waitcnt lgkmcnt(1)
	v_mul_f32_e32 v94, v18, v119
	v_mul_f32_e32 v95, v17, v121
	v_fmac_f32_e32 v94, v16, v118
	v_fmac_f32_e32 v95, v19, v120
	ds_read_b128 v[118:121], v33 offset:416
	v_add_f32_e32 v94, v94, v95
	s_waitcnt lgkmcnt(1)
	v_mul_f32_e32 v95, v22, v123
	v_mul_f32_e32 v117, v21, v125
	v_fmac_f32_e32 v95, v20, v122
	v_fmac_f32_e32 v117, v23, v124
	ds_read_b128 v[122:125], v33 offset:432
	v_add_f32_e32 v94, v96, v94
	v_add_f32_e32 v95, v95, v117
	v_add_f32_e32 v94, v94, v95
	s_waitcnt lgkmcnt(1)
	v_mul_f32_e32 v95, v25, v119
	v_mul_f32_e32 v117, v27, v121
	v_fmac_f32_e32 v95, v24, v118
	v_fmac_f32_e32 v117, v26, v120
	ds_read_b128 v[118:121], v33 offset:448
	v_add_f32_e32 v95, v95, v117
	v_add_f32_e32 v94, v94, v95
	s_waitcnt lgkmcnt(1)
	v_mul_f32_e32 v95, v41, v123
	v_mul_f32_e32 v117, v45, v125
	v_fmac_f32_e32 v95, v31, v122
	v_fmac_f32_e32 v117, v43, v124
	ds_read_b128 v[122:125], v33 offset:464
	v_add_f32_e32 v95, v95, v117
	s_waitcnt lgkmcnt(1)
	v_mul_f32_e32 v117, v18, v119
	v_fmac_f32_e32 v117, v16, v118
	v_mul_f32_e32 v118, v17, v121
	v_fmac_f32_e32 v118, v19, v120
	v_add_f32_e32 v117, v117, v118
	s_waitcnt lgkmcnt(0)
	v_mul_f32_e32 v123, v22, v123
	ds_read_b128 v[118:121], v33 offset:480
	v_fmac_f32_e32 v123, v20, v122
	v_mul_f32_e32 v122, v21, v125
	v_fmac_f32_e32 v122, v23, v124
	v_add_f32_e32 v117, v96, v117
	v_add_f32_e32 v122, v123, v122
	v_add_f32_e32 v117, v117, v122
	ds_read_b128 v[122:125], v33 offset:496
	s_waitcnt lgkmcnt(1)
	v_mul_f32_e32 v119, v25, v119
	v_fmac_f32_e32 v119, v24, v118
	v_mul_f32_e32 v118, v27, v121
	v_add_f32_e32 v94, v94, v95
	v_fmac_f32_e32 v118, v26, v120
	v_mul_f32_e64 v95, |v94|, s22
	v_add_f32_e32 v118, v119, v118
	v_exp_f32_e32 v95, v95
	v_add_f32_e32 v117, v117, v118
	s_waitcnt lgkmcnt(0)
	v_mul_f32_e32 v118, v41, v123
	v_mul_f32_e32 v119, v45, v125
	v_fmac_f32_e32 v118, v31, v122
	v_fmac_f32_e32 v119, v43, v124
	v_add_f32_e32 v118, v118, v119
	v_add_f32_e32 v117, v117, v118
	v_add_f32_e32 v95, 1.0, v95
	v_mul_f32_e64 v118, |v117|, s22
	v_log_f32_e32 v95, v95
	v_exp_f32_e32 v122, v118
	ds_read_b128 v[118:121], v33 offset:512
	v_min_f32_e32 v94, 0, v94
	v_fmac_f32_e32 v94, 0xbf317218, v95
	v_add_f32_e32 v95, 1.0, v122
	ds_read_b128 v[122:125], v33 offset:528
	s_waitcnt lgkmcnt(1)
	v_mul_f32_e32 v119, v18, v119
	v_fmac_f32_e32 v119, v16, v118
	v_mul_f32_e32 v118, v17, v121
	v_fmac_f32_e32 v118, v19, v120
	v_add_f32_e32 v118, v119, v118
	s_waitcnt lgkmcnt(0)
	v_mul_f32_e32 v123, v22, v123
	v_add_f32_e32 v126, v96, v118
	v_fmac_f32_e32 v123, v20, v122
	v_mul_f32_e32 v122, v21, v125
	ds_read_b128 v[118:121], v33 offset:544
	v_fmac_f32_e32 v122, v23, v124
	v_add_f32_e32 v122, v123, v122
	v_add_f32_e32 v126, v126, v122
	ds_read_b128 v[122:125], v33 offset:560
	s_waitcnt lgkmcnt(1)
	v_mul_f32_e32 v119, v25, v119
	v_fmac_f32_e32 v119, v24, v118
	v_mul_f32_e32 v118, v27, v121
	v_fmac_f32_e32 v118, v26, v120
	v_add_f32_e32 v118, v119, v118
	s_waitcnt lgkmcnt(0)
	v_mul_f32_e32 v119, v41, v123
	v_mul_f32_e32 v120, v45, v125
	v_fmac_f32_e32 v119, v31, v122
	v_fmac_f32_e32 v120, v43, v124
	v_add_f32_e32 v118, v126, v118
	v_add_f32_e32 v119, v119, v120
	v_add_f32_e32 v126, v118, v119
	v_mul_f32_e64 v118, |v126|, s22
	v_log_f32_e32 v95, v95
	v_exp_f32_e32 v122, v118
	ds_read_b128 v[118:121], v33 offset:576
	v_min_f32_e32 v117, 0, v117
	v_fmac_f32_e32 v117, 0xbf317218, v95
	v_add_f32_e32 v95, 1.0, v122
	ds_read_b128 v[122:125], v33 offset:592
	s_waitcnt lgkmcnt(1)
; #define LAS __attribute__((address_space(3)))
; __device__ __forceinline__ void phase_gla_kdec(Frame& F) {
;     ...
;             for (int s = 0; s < CH; ++s) { float a = bgc;
; #pragma unroll
;                 for (int r4 = 0; r4 < 4; ++r4) { const f32x4 gv = *(const LAS f32x4*)(glr + s * 16 + r4 * 4); a += (gv.x * w2c[4 * r4] + gv.y * w2c[4 * r4 + 1]) + (gv.z * w2c[4 * r4 + 2] + gv.w * w2c[4 * r4 + 3]); }
;                 run += fast_logsigmoid(a) * (1.f / 16.f); gc[s] = run; }
	v_mul_f32_e32 v119, v18, v119
	v_fmac_f32_e32 v119, v16, v118
	v_mul_f32_e32 v118, v17, v121
	v_fmac_f32_e32 v118, v19, v120
	v_add_f32_e32 v118, v119, v118
	s_waitcnt lgkmcnt(0)
	v_mul_f32_e32 v123, v22, v123
	v_add_f32_e32 v127, v96, v118
	v_fmac_f32_e32 v123, v20, v122
	v_mul_f32_e32 v122, v21, v125
	ds_read_b128 v[118:121], v33 offset:608
	v_fmac_f32_e32 v122, v23, v124
	v_add_f32_e32 v122, v123, v122
	v_add_f32_e32 v127, v127, v122
	ds_read_b128 v[122:125], v33 offset:624
	s_waitcnt lgkmcnt(1)
	v_mul_f32_e32 v119, v25, v119
	v_fmac_f32_e32 v119, v24, v118
	v_mul_f32_e32 v118, v27, v121
	v_fmac_f32_e32 v118, v26, v120
	v_add_f32_e32 v118, v119, v118
	s_waitcnt lgkmcnt(0)
	v_mul_f32_e32 v119, v41, v123
	v_mul_f32_e32 v120, v45, v125
	v_fmac_f32_e32 v119, v31, v122
	v_fmac_f32_e32 v120, v43, v124
	v_add_f32_e32 v118, v127, v118
	v_add_f32_e32 v119, v119, v120
	v_add_f32_e32 v119, v118, v119
	v_mul_f32_e64 v118, |v119|, s22
	v_log_f32_e32 v95, v95
	v_exp_f32_e32 v120, v118
	v_fmamk_f32 v93, v93, 0x3d800000, v92
	v_fmamk_f32 v94, v94, 0x3d800000, v93
	v_fmamk_f32 v118, v117, 0x3d800000, v94
	v_min_f32_e32 v117, 0, v126
	v_fmac_f32_e32 v117, 0xbf317218, v95
	v_add_f32_e32 v95, 1.0, v120
	ds_read_b128 v[120:123], v33 offset:640
	ds_read_b128 v[124:127], v33 offset:656
	v_log_f32_e32 v95, v95
	v_min_f32_e32 v119, 0, v119
	v_fmamk_f32 v117, v117, 0x3d800000, v118
	v_fmac_f32_e32 v119, 0xbf317218, v95
	s_waitcnt lgkmcnt(1)
	v_mul_f32_e32 v95, v18, v121
	v_fmac_f32_e32 v95, v16, v120
	v_mul_f32_e32 v120, v17, v123
	v_fmac_f32_e32 v120, v19, v122
	v_add_f32_e32 v95, v95, v120
	s_waitcnt lgkmcnt(0)
	v_mul_f32_e32 v125, v22, v125
	ds_read_b128 v[120:123], v33 offset:672
	v_fmac_f32_e32 v125, v20, v124
	v_mul_f32_e32 v124, v21, v127
	v_fmac_f32_e32 v124, v23, v126
	v_add_f32_e32 v95, v96, v95
	v_add_f32_e32 v124, v125, v124
	v_add_f32_e32 v95, v95, v124
	ds_read_b128 v[124:127], v33 offset:688
	s_waitcnt lgkmcnt(1)
	v_mul_f32_e32 v121, v25, v121
	v_fmac_f32_e32 v121, v24, v120
	v_mul_f32_e32 v120, v27, v123
	v_fmac_f32_e32 v120, v26, v122
	v_add_f32_e32 v120, v121, v120
	v_add_f32_e32 v95, v95, v120
	s_waitcnt lgkmcnt(0)
	v_mul_f32_e32 v120, v41, v125
	v_mul_f32_e32 v121, v45, v127
	v_fmac_f32_e32 v120, v31, v124
	v_fmac_f32_e32 v121, v43, v126
	v_add_f32_e32 v120, v120, v121
	v_add_f32_e32 v124, v95, v120
	v_mul_f32_e64 v95, |v124|, s22
	v_exp_f32_e32 v125, v95
	ds_read_b128 v[120:123], v33 offset:704
	v_fmamk_f32 v95, v119, 0x3d800000, v117
	v_min_f32_e32 v119, 0, v124
	v_add_f32_e32 v124, 1.0, v125
	v_log_f32_e32 v128, v124
	ds_read_b128 v[124:127], v33 offset:720
	s_waitcnt lgkmcnt(1)
	v_mul_f32_e32 v121, v18, v121
	v_fmac_f32_e32 v121, v16, v120
	v_mul_f32_e32 v120, v17, v123
	v_fmac_f32_e32 v120, v19, v122
	v_add_f32_e32 v120, v121, v120
	s_waitcnt lgkmcnt(0)
	v_mul_f32_e32 v125, v22, v125
	v_add_f32_e32 v129, v96, v120
	v_fmac_f32_e32 v125, v20, v124
	v_mul_f32_e32 v124, v21, v127
	ds_read_b128 v[120:123], v33 offset:736
	v_fmac_f32_e32 v124, v23, v126
	v_add_f32_e32 v124, v125, v124
	v_add_f32_e32 v129, v129, v124
	ds_read_b128 v[124:127], v33 offset:752
	s_waitcnt lgkmcnt(1)
	v_mul_f32_e32 v121, v25, v121
	v_fmac_f32_e32 v121, v24, v120
	v_mul_f32_e32 v120, v27, v123
	v_fmac_f32_e32 v120, v26, v122
	v_add_f32_e32 v120, v121, v120
	s_waitcnt lgkmcnt(0)
	v_mul_f32_e32 v121, v41, v125
	v_mul_f32_e32 v122, v45, v127
	v_fmac_f32_e32 v121, v31, v124
	v_fmac_f32_e32 v122, v43, v126
	v_add_f32_e32 v120, v129, v120
	v_add_f32_e32 v121, v121, v122
	v_add_f32_e32 v129, v120, v121
	v_mul_f32_e64 v120, |v129|, s22
	v_exp_f32_e32 v124, v120
	ds_read_b128 v[120:123], v33 offset:768
	v_fmac_f32_e32 v119, 0xbf317218, v128
	v_min_f32_e32 v129, 0, v129
	v_add_f32_e32 v124, 1.0, v124
	v_log_f32_e32 v128, v124
	ds_read_b128 v[124:127], v33 offset:784
	s_waitcnt lgkmcnt(1)
	v_mul_f32_e32 v121, v18, v121
	v_fmac_f32_e32 v121, v16, v120
	v_mul_f32_e32 v120, v17, v123
	v_fmac_f32_e32 v120, v19, v122
	v_add_f32_e32 v120, v121, v120
	s_waitcnt lgkmcnt(0)
	v_mul_f32_e32 v125, v22, v125
	v_add_f32_e32 v130, v96, v120
	v_fmac_f32_e32 v125, v20, v124
	v_mul_f32_e32 v124, v21, v127
	ds_read_b128 v[120:123], v33 offset:800
	v_fmac_f32_e32 v124, v23, v126
	v_add_f32_e32 v124, v125, v124
	v_add_f32_e32 v130, v130, v124
	ds_read_b128 v[124:127], v33 offset:816
	s_waitcnt lgkmcnt(1)
	v_mul_f32_e32 v121, v25, v121
	v_fmac_f32_e32 v121, v24, v120
	v_mul_f32_e32 v120, v27, v123
	v_fmac_f32_e32 v120, v26, v122
	v_add_f32_e32 v120, v121, v120
	s_waitcnt lgkmcnt(0)
	v_mul_f32_e32 v121, v41, v125
	v_mul_f32_e32 v122, v45, v127
	v_fmac_f32_e32 v121, v31, v124
	v_fmac_f32_e32 v122, v43, v126
	v_add_f32_e32 v120, v130, v120
	v_add_f32_e32 v121, v121, v122
	v_add_f32_e32 v130, v120, v121
	v_mul_f32_e64 v120, |v130|, s22
	v_exp_f32_e32 v124, v120
	ds_read_b128 v[120:123], v33 offset:832
	v_fmac_f32_e32 v129, 0xbf317218, v128
	v_fmamk_f32 v119, v119, 0x3d800000, v95
	v_add_f32_e32 v124, 1.0, v124
	v_log_f32_e32 v128, v124
	ds_read_b128 v[124:127], v33 offset:848
	s_waitcnt lgkmcnt(1)
	v_mul_f32_e32 v121, v18, v121
	v_fmac_f32_e32 v121, v16, v120
	v_mul_f32_e32 v120, v17, v123
	v_fmac_f32_e32 v120, v19, v122
	v_add_f32_e32 v120, v121, v120
	s_waitcnt lgkmcnt(0)
	v_mul_f32_e32 v125, v22, v125
	v_add_f32_e32 v131, v96, v120
	v_fmac_f32_e32 v125, v20, v124
	v_mul_f32_e32 v124, v21, v127
	ds_read_b128 v[120:123], v33 offset:864
	v_fmac_f32_e32 v124, v23, v126
	v_add_f32_e32 v124, v125, v124
	v_add_f32_e32 v131, v131, v124
	ds_read_b128 v[124:127], v33 offset:880
	s_waitcnt lgkmcnt(1)
	v_mul_f32_e32 v121, v25, v121
	v_fmac_f32_e32 v121, v24, v120
	v_mul_f32_e32 v120, v27, v123
	v_fmac_f32_e32 v120, v26, v122
	v_add_f32_e32 v120, v121, v120
	s_waitcnt lgkmcnt(0)
; #define LAS __attribute__((address_space(3)))
; __device__ __forceinline__ void phase_gla_kdec(Frame& F) {
;     ...
;             for (int s = 0; s < CH; ++s) { float a = bgc;
; #pragma unroll
;                 for (int r4 = 0; r4 < 4; ++r4) { const f32x4 gv = *(const LAS f32x4*)(glr + s * 16 + r4 * 4); a += (gv.x * w2c[4 * r4] + gv.y * w2c[4 * r4 + 1]) + (gv.z * w2c[4 * r4 + 2] + gv.w * w2c[4 * r4 + 3]); }
;                 run += fast_logsigmoid(a) * (1.f / 16.f); gc[s] = run; }
	v_mul_f32_e32 v121, v41, v125
	v_mul_f32_e32 v122, v45, v127
	v_fmac_f32_e32 v121, v31, v124
	v_fmac_f32_e32 v122, v43, v126
	v_add_f32_e32 v120, v131, v120
	v_add_f32_e32 v121, v121, v122
	v_add_f32_e32 v126, v120, v121
	v_mul_f32_e64 v120, |v126|, s22
	v_exp_f32_e32 v121, v120
	v_min_f32_e32 v127, 0, v130
	v_fmac_f32_e32 v127, 0xbf317218, v128
	ds_read_b128 v[122:125], v33 offset:896
	v_add_f32_e32 v121, 1.0, v121
	v_log_f32_e32 v128, v121
	v_fmamk_f32 v120, v129, 0x3d800000, v119
	v_min_f32_e32 v130, 0, v126
	v_fmamk_f32 v121, v127, 0x3d800000, v120
	v_fmac_f32_e32 v130, 0xbf317218, v128
	ds_read_b128 v[126:129], v33 offset:912
	s_waitcnt lgkmcnt(1)
	v_mul_f32_e32 v123, v18, v123
	v_fmac_f32_e32 v123, v16, v122
	v_mul_f32_e32 v122, v17, v125
	v_fmac_f32_e32 v122, v19, v124
	v_add_f32_e32 v122, v123, v122
	s_waitcnt lgkmcnt(0)
	v_mul_f32_e32 v127, v22, v127
	v_add_f32_e32 v131, v96, v122
	v_fmac_f32_e32 v127, v20, v126
	v_mul_f32_e32 v126, v21, v129
	ds_read_b128 v[122:125], v33 offset:928
	v_fmac_f32_e32 v126, v23, v128
	v_add_f32_e32 v126, v127, v126
	v_add_f32_e32 v131, v131, v126
	ds_read_b128 v[126:129], v33 offset:944
	s_waitcnt lgkmcnt(1)
	v_mul_f32_e32 v123, v25, v123
	v_fmac_f32_e32 v123, v24, v122
	v_mul_f32_e32 v122, v27, v125
	v_fmac_f32_e32 v122, v26, v124
	v_add_f32_e32 v122, v123, v122
	s_waitcnt lgkmcnt(0)
	v_mul_f32_e32 v123, v41, v127
	v_mul_f32_e32 v124, v45, v129
	v_fmac_f32_e32 v123, v31, v126
	v_fmac_f32_e32 v124, v43, v128
	v_add_f32_e32 v122, v131, v122
	v_add_f32_e32 v123, v123, v124
	v_add_f32_e32 v123, v122, v123
	v_mul_f32_e64 v122, |v123|, s22
	v_exp_f32_e32 v128, v122
	ds_read_b128 v[124:127], v33 offset:960
	v_fmamk_f32 v122, v130, 0x3d800000, v121
	v_min_f32_e32 v123, 0, v123
	v_add_f32_e32 v128, 1.0, v128
	v_log_f32_e32 v132, v128
	ds_read_b128 v[128:131], v33 offset:976
	s_waitcnt lgkmcnt(1)
	v_mul_f32_e32 v125, v18, v125
	v_fmac_f32_e32 v125, v16, v124
	v_mul_f32_e32 v124, v17, v127
	v_fmac_f32_e32 v124, v19, v126
	v_add_f32_e32 v124, v125, v124
	s_waitcnt lgkmcnt(0)
	v_mul_f32_e32 v129, v22, v129
	v_add_f32_e32 v133, v96, v124
	v_fmac_f32_e32 v129, v20, v128
	v_mul_f32_e32 v128, v21, v131
	ds_read_b128 v[124:127], v33 offset:992
	v_fmac_f32_e32 v128, v23, v130
	v_add_f32_e32 v128, v129, v128
	v_add_f32_e32 v133, v133, v128
	ds_read_b128 v[128:131], v33 offset:1008
	s_waitcnt lgkmcnt(1)
	v_mul_f32_e32 v125, v25, v125
	v_fmac_f32_e32 v125, v24, v124
	v_mul_f32_e32 v124, v27, v127
	v_fmac_f32_e32 v124, v26, v126
	v_add_f32_e32 v124, v125, v124
	s_waitcnt lgkmcnt(0)
	v_mul_f32_e32 v125, v41, v129
	v_mul_f32_e32 v126, v45, v131
	v_fmac_f32_e32 v125, v31, v128
	v_fmac_f32_e32 v126, v43, v130
	v_add_f32_e32 v124, v133, v124
	v_add_f32_e32 v125, v125, v126
	v_add_f32_e32 v133, v124, v125
	v_mul_f32_e64 v124, |v133|, s22
	v_exp_f32_e32 v128, v124
	ds_read_b128 v[124:127], v33 offset:1024
	v_fmac_f32_e32 v123, 0xbf317218, v132
	v_min_f32_e32 v133, 0, v133
	v_add_f32_e32 v128, 1.0, v128
	v_log_f32_e32 v132, v128
	ds_read_b128 v[128:131], v33 offset:1040
	s_waitcnt lgkmcnt(1)
	v_mul_f32_e32 v125, v18, v125
	v_fmac_f32_e32 v125, v16, v124
	v_mul_f32_e32 v124, v17, v127
	v_fmac_f32_e32 v124, v19, v126
	v_add_f32_e32 v124, v125, v124
	s_waitcnt lgkmcnt(0)
	v_mul_f32_e32 v129, v22, v129
	v_add_f32_e32 v134, v96, v124
	v_fmac_f32_e32 v129, v20, v128
	v_mul_f32_e32 v128, v21, v131
	ds_read_b128 v[124:127], v33 offset:1056
	v_fmac_f32_e32 v128, v23, v130
	v_add_f32_e32 v128, v129, v128
	v_add_f32_e32 v134, v134, v128
	ds_read_b128 v[128:131], v33 offset:1072
	s_waitcnt lgkmcnt(1)
	v_mul_f32_e32 v125, v25, v125
	v_fmac_f32_e32 v125, v24, v124
	v_mul_f32_e32 v124, v27, v127
	v_fmac_f32_e32 v124, v26, v126
	v_add_f32_e32 v124, v125, v124
	s_waitcnt lgkmcnt(0)
	v_mul_f32_e32 v125, v41, v129
	v_mul_f32_e32 v126, v45, v131
	v_fmac_f32_e32 v125, v31, v128
	v_fmac_f32_e32 v126, v43, v130
	v_add_f32_e32 v124, v134, v124
	v_add_f32_e32 v125, v125, v126
	v_add_f32_e32 v134, v124, v125
	v_mul_f32_e64 v124, |v134|, s22
	v_exp_f32_e32 v128, v124
	ds_read_b128 v[124:127], v33 offset:1088
	v_fmac_f32_e32 v133, 0xbf317218, v132
	v_fmamk_f32 v123, v123, 0x3d800000, v122
	v_add_f32_e32 v128, 1.0, v128
	v_log_f32_e32 v132, v128
	ds_read_b128 v[128:131], v33 offset:1104
	s_waitcnt lgkmcnt(1)
	v_mul_f32_e32 v125, v18, v125
	v_fmac_f32_e32 v125, v16, v124
	v_mul_f32_e32 v124, v17, v127
	v_fmac_f32_e32 v124, v19, v126
	v_add_f32_e32 v124, v125, v124
	s_waitcnt lgkmcnt(0)
	v_mul_f32_e32 v129, v22, v129
	v_add_f32_e32 v135, v96, v124
	v_fmac_f32_e32 v129, v20, v128
	v_mul_f32_e32 v128, v21, v131
	ds_read_b128 v[124:127], v33 offset:1120
	v_fmac_f32_e32 v128, v23, v130
	v_add_f32_e32 v128, v129, v128
	v_add_f32_e32 v135, v135, v128
	ds_read_b128 v[128:131], v33 offset:1136
	s_waitcnt lgkmcnt(1)
	v_mul_f32_e32 v125, v25, v125
	v_fmac_f32_e32 v125, v24, v124
	v_mul_f32_e32 v124, v27, v127
	v_fmac_f32_e32 v124, v26, v126
	v_add_f32_e32 v124, v125, v124
	s_waitcnt lgkmcnt(0)
	v_mul_f32_e32 v125, v41, v129
	v_mul_f32_e32 v126, v45, v131
	v_fmac_f32_e32 v125, v31, v128
	v_fmac_f32_e32 v126, v43, v130
	v_add_f32_e32 v124, v135, v124
	v_add_f32_e32 v125, v125, v126
	v_add_f32_e32 v124, v124, v125
	v_mul_f32_e64 v125, |v124|, s22
	v_exp_f32_e32 v125, v125
	v_min_f32_e32 v127, 0, v134
	v_fmac_f32_e32 v127, 0xbf317218, v132
	ds_read_b128 v[128:131], v33 offset:1152
	v_add_f32_e32 v125, 1.0, v125
	v_log_f32_e32 v132, v125
	v_min_f32_e32 v124, 0, v124
	v_fmamk_f32 v126, v133, 0x3d800000, v123
	v_fmamk_f32 v125, v127, 0x3d800000, v126
	v_fmac_f32_e32 v124, 0xbf317218, v132
	ds_read_b128 v[132:135], v33 offset:1168
	s_waitcnt lgkmcnt(1)
; #define LAS __attribute__((address_space(3)))
; __device__ __forceinline__ void phase_gla_kdec(Frame& F) {
;     ...
;             for (int s = 0; s < CH; ++s) { float a = bgc;
; #pragma unroll
;                 for (int r4 = 0; r4 < 4; ++r4) { const f32x4 gv = *(const LAS f32x4*)(glr + s * 16 + r4 * 4); a += (gv.x * w2c[4 * r4] + gv.y * w2c[4 * r4 + 1]) + (gv.z * w2c[4 * r4 + 2] + gv.w * w2c[4 * r4 + 3]); }
;                 run += fast_logsigmoid(a) * (1.f / 16.f); gc[s] = run; }
	v_mul_f32_e32 v127, v18, v129
	v_fmac_f32_e32 v127, v16, v128
	v_mul_f32_e32 v128, v17, v131
	v_fmac_f32_e32 v128, v19, v130
	v_add_f32_e32 v127, v127, v128
	s_waitcnt lgkmcnt(0)
	v_mul_f32_e32 v133, v22, v133
	ds_read_b128 v[128:131], v33 offset:1184
	v_fmac_f32_e32 v133, v20, v132
	v_mul_f32_e32 v132, v21, v135
	v_fmac_f32_e32 v132, v23, v134
	v_add_f32_e32 v127, v96, v127
	v_add_f32_e32 v132, v133, v132
	v_add_f32_e32 v127, v127, v132
	ds_read_b128 v[132:135], v33 offset:1200
	s_waitcnt lgkmcnt(1)
	v_mul_f32_e32 v129, v25, v129
	v_fmac_f32_e32 v129, v24, v128
	v_mul_f32_e32 v128, v27, v131
	v_fmac_f32_e32 v128, v26, v130
	v_add_f32_e32 v128, v129, v128
	v_add_f32_e32 v127, v127, v128
	s_waitcnt lgkmcnt(0)
	v_mul_f32_e32 v128, v41, v133
	v_mul_f32_e32 v129, v45, v135
	v_fmac_f32_e32 v128, v31, v132
	v_fmac_f32_e32 v129, v43, v134
	v_add_f32_e32 v128, v128, v129
	v_add_f32_e32 v127, v127, v128
	v_mul_f32_e64 v128, |v127|, s22
	v_exp_f32_e32 v132, v128
	ds_read_b128 v[128:131], v33 offset:1216
	v_min_f32_e32 v127, 0, v127
	v_fmamk_f32 v124, v124, 0x3d800000, v125
	v_add_f32_e32 v132, 1.0, v132
	v_log_f32_e32 v136, v132
	ds_read_b128 v[132:135], v33 offset:1232
	s_waitcnt lgkmcnt(1)
	v_mul_f32_e32 v129, v18, v129
	v_fmac_f32_e32 v129, v16, v128
	v_mul_f32_e32 v128, v17, v131
	v_fmac_f32_e32 v128, v19, v130
	v_add_f32_e32 v128, v129, v128
	s_waitcnt lgkmcnt(0)
	v_mul_f32_e32 v133, v22, v133
	v_add_f32_e32 v137, v96, v128
	v_fmac_f32_e32 v133, v20, v132
	v_mul_f32_e32 v132, v21, v135
	ds_read_b128 v[128:131], v33 offset:1248
	v_fmac_f32_e32 v132, v23, v134
	v_add_f32_e32 v132, v133, v132
	v_add_f32_e32 v137, v137, v132
	ds_read_b128 v[132:135], v33 offset:1264
	s_waitcnt lgkmcnt(1)
	v_mul_f32_e32 v129, v25, v129
	v_fmac_f32_e32 v129, v24, v128
	v_mul_f32_e32 v128, v27, v131
	v_fmac_f32_e32 v128, v26, v130
	v_add_f32_e32 v128, v129, v128
	s_waitcnt lgkmcnt(0)
	v_mul_f32_e32 v129, v41, v133
	v_mul_f32_e32 v130, v45, v135
	v_fmac_f32_e32 v129, v31, v132
	v_fmac_f32_e32 v130, v43, v134
	v_add_f32_e32 v128, v137, v128
	v_add_f32_e32 v129, v129, v130
	v_add_f32_e32 v137, v128, v129
	v_mul_f32_e64 v128, |v137|, s22
	v_exp_f32_e32 v132, v128
	ds_read_b128 v[128:131], v33 offset:1280
	v_fmac_f32_e32 v127, 0xbf317218, v136
	v_min_f32_e32 v137, 0, v137
	v_add_f32_e32 v132, 1.0, v132
	v_log_f32_e32 v136, v132
	ds_read_b128 v[132:135], v33 offset:1296
	s_waitcnt lgkmcnt(1)
	v_mul_f32_e32 v129, v18, v129
	v_fmac_f32_e32 v129, v16, v128
	v_mul_f32_e32 v128, v17, v131
	v_fmac_f32_e32 v128, v19, v130
	v_add_f32_e32 v128, v129, v128
	s_waitcnt lgkmcnt(0)
	v_mul_f32_e32 v133, v22, v133
	v_add_f32_e32 v138, v96, v128
	v_fmac_f32_e32 v133, v20, v132
	v_mul_f32_e32 v132, v21, v135
	ds_read_b128 v[128:131], v33 offset:1312
	v_fmac_f32_e32 v132, v23, v134
	v_add_f32_e32 v132, v133, v132
	v_add_f32_e32 v138, v138, v132
	ds_read_b128 v[132:135], v33 offset:1328
	s_waitcnt lgkmcnt(1)
	v_mul_f32_e32 v129, v25, v129
	v_fmac_f32_e32 v129, v24, v128
	v_mul_f32_e32 v128, v27, v131
	v_fmac_f32_e32 v128, v26, v130
	v_add_f32_e32 v128, v129, v128
	s_waitcnt lgkmcnt(0)
	v_mul_f32_e32 v129, v41, v133
	v_mul_f32_e32 v130, v45, v135
	v_fmac_f32_e32 v129, v31, v132
	v_fmac_f32_e32 v130, v43, v134
	v_add_f32_e32 v128, v138, v128
	v_add_f32_e32 v129, v129, v130
	v_add_f32_e32 v138, v128, v129
	v_mul_f32_e64 v128, |v138|, s22
	v_exp_f32_e32 v132, v128
	ds_read_b128 v[128:131], v33 offset:1344
	v_fmac_f32_e32 v137, 0xbf317218, v136
	v_fmamk_f32 v127, v127, 0x3d800000, v124
	v_add_f32_e32 v132, 1.0, v132
	v_log_f32_e32 v136, v132
	ds_read_b128 v[132:135], v33 offset:1360
	s_waitcnt lgkmcnt(1)
	v_mul_f32_e32 v129, v18, v129
	v_fmac_f32_e32 v129, v16, v128
	v_mul_f32_e32 v128, v17, v131
	v_fmac_f32_e32 v128, v19, v130
	v_add_f32_e32 v128, v129, v128
	s_waitcnt lgkmcnt(0)
	v_mul_f32_e32 v133, v22, v133
	v_add_f32_e32 v139, v96, v128
	v_fmac_f32_e32 v133, v20, v132
	v_mul_f32_e32 v132, v21, v135
	ds_read_b128 v[128:131], v33 offset:1376
	v_fmac_f32_e32 v132, v23, v134
	v_add_f32_e32 v132, v133, v132
	v_add_f32_e32 v139, v139, v132
	ds_read_b128 v[132:135], v33 offset:1392
	s_waitcnt lgkmcnt(1)
	v_mul_f32_e32 v129, v25, v129
	v_fmac_f32_e32 v129, v24, v128
	v_mul_f32_e32 v128, v27, v131
	v_fmac_f32_e32 v128, v26, v130
	v_add_f32_e32 v128, v129, v128
	s_waitcnt lgkmcnt(0)
	v_mul_f32_e32 v129, v41, v133
	v_mul_f32_e32 v130, v45, v135
	v_fmac_f32_e32 v129, v31, v132
	v_fmac_f32_e32 v130, v43, v134
	v_add_f32_e32 v128, v139, v128
	v_add_f32_e32 v129, v129, v130
	v_add_f32_e32 v128, v128, v129
	v_mul_f32_e64 v129, |v128|, s22
	v_exp_f32_e32 v129, v129
	ds_read_b128 v[132:135], v33 offset:1408
	v_min_f32_e32 v131, 0, v138
	v_fmamk_f32 v130, v137, 0x3d800000, v127
	v_add_f32_e32 v129, 1.0, v129
	v_log_f32_e32 v129, v129
	v_fmac_f32_e32 v131, 0xbf317218, v136
	ds_read_b128 v[136:139], v33 offset:1424
	v_min_f32_e32 v128, 0, v128
	v_fmac_f32_e32 v128, 0xbf317218, v129
	s_waitcnt lgkmcnt(1)
	v_mul_f32_e32 v129, v18, v133
	v_fmac_f32_e32 v129, v16, v132
	v_mul_f32_e32 v132, v17, v135
	v_fmac_f32_e32 v132, v19, v134
	v_add_f32_e32 v129, v129, v132
	s_waitcnt lgkmcnt(0)
	v_mul_f32_e32 v137, v22, v137
	ds_read_b128 v[132:135], v33 offset:1440
	v_fmac_f32_e32 v137, v20, v136
	v_mul_f32_e32 v136, v21, v139
	v_fmac_f32_e32 v136, v23, v138
	v_add_f32_e32 v129, v96, v129
	v_add_f32_e32 v136, v137, v136
	v_add_f32_e32 v129, v129, v136
	ds_read_b128 v[136:139], v33 offset:1456
	s_waitcnt lgkmcnt(1)
	v_mul_f32_e32 v133, v25, v133
	v_fmac_f32_e32 v133, v24, v132
	v_mul_f32_e32 v132, v27, v135
	v_fmac_f32_e32 v132, v26, v134
	v_add_f32_e32 v132, v133, v132
	v_add_f32_e32 v129, v129, v132
	s_waitcnt lgkmcnt(0)
; #define LAS __attribute__((address_space(3)))
; __device__ __forceinline__ void phase_gla_kdec(Frame& F) {
;     ...
;             for (int s = 0; s < CH; ++s) { float a = bgc;
; #pragma unroll
;                 for (int r4 = 0; r4 < 4; ++r4) { const f32x4 gv = *(const LAS f32x4*)(glr + s * 16 + r4 * 4); a += (gv.x * w2c[4 * r4] + gv.y * w2c[4 * r4 + 1]) + (gv.z * w2c[4 * r4 + 2] + gv.w * w2c[4 * r4 + 3]); }
;                 run += fast_logsigmoid(a) * (1.f / 16.f); gc[s] = run; }
	v_mul_f32_e32 v132, v41, v137
	v_mul_f32_e32 v133, v45, v139
	v_fmac_f32_e32 v132, v31, v136
	v_fmac_f32_e32 v133, v43, v138
	v_add_f32_e32 v132, v132, v133
	v_add_f32_e32 v129, v129, v132
	v_mul_f32_e64 v132, |v129|, s22
	ds_read_b128 v[134:137], v33 offset:1472
	ds_read_b128 v[138:141], v33 offset:1488
	v_exp_f32_e32 v133, v132
	v_fmamk_f32 v131, v131, 0x3d800000, v130
	v_fmamk_f32 v132, v128, 0x3d800000, v131
	v_min_f32_e32 v128, 0, v129
	v_add_f32_e32 v129, 1.0, v133
	s_waitcnt lgkmcnt(1)
	v_mul_f32_e32 v133, v18, v135
	v_fmac_f32_e32 v133, v16, v134
	v_mul_f32_e32 v134, v17, v137
	v_fmac_f32_e32 v134, v19, v136
	v_add_f32_e32 v133, v133, v134
	s_waitcnt lgkmcnt(0)
	v_mul_f32_e32 v139, v22, v139
	ds_read_b128 v[134:137], v33 offset:1504
	v_fmac_f32_e32 v139, v20, v138
	v_mul_f32_e32 v138, v21, v141
	v_fmac_f32_e32 v138, v23, v140
	v_add_f32_e32 v133, v96, v133
	v_add_f32_e32 v138, v139, v138
	v_add_f32_e32 v133, v133, v138
	ds_read_b128 v[138:141], v33 offset:1520
	s_waitcnt lgkmcnt(1)
	v_mul_f32_e32 v135, v25, v135
	v_fmac_f32_e32 v135, v24, v134
	v_mul_f32_e32 v134, v27, v137
	v_fmac_f32_e32 v134, v26, v136
	v_add_f32_e32 v134, v135, v134
	v_add_f32_e32 v133, v133, v134
	s_waitcnt lgkmcnt(0)
	v_mul_f32_e32 v134, v41, v139
	v_mul_f32_e32 v135, v45, v141
	v_fmac_f32_e32 v134, v31, v138
	v_fmac_f32_e32 v135, v43, v140
	v_add_f32_e32 v134, v134, v135
	v_add_f32_e32 v133, v133, v134
	v_log_f32_e32 v129, v129
	v_mul_f32_e64 v134, |v133|, s22
	ds_read_b128 v[136:139], v33 offset:1536
	ds_read_b128 v[140:143], v33 offset:1552
	v_exp_f32_e32 v134, v134
	v_fmac_f32_e32 v128, 0xbf317218, v129
	v_fmamk_f32 v135, v128, 0x3d800000, v132
	s_waitcnt lgkmcnt(1)
	v_mul_f32_e32 v129, v18, v137
	v_add_f32_e32 v128, 1.0, v134
	v_mul_f32_e32 v134, v17, v139
	v_fmac_f32_e32 v129, v16, v136
	v_fmac_f32_e32 v134, v19, v138
	ds_read_b128 v[136:139], v33 offset:1568
	v_add_f32_e32 v129, v129, v134
	s_waitcnt lgkmcnt(1)
	v_mul_f32_e32 v134, v22, v141
	v_fmac_f32_e32 v134, v20, v140
	v_mul_f32_e32 v140, v21, v143
	v_fmac_f32_e32 v140, v23, v142
	v_add_f32_e32 v129, v96, v129
	v_add_f32_e32 v134, v134, v140
	ds_read_b128 v[140:143], v33 offset:1584
	v_add_f32_e32 v129, v129, v134
	s_waitcnt lgkmcnt(1)
	v_mul_f32_e32 v134, v25, v137
	v_fmac_f32_e32 v134, v24, v136
	v_mul_f32_e32 v136, v27, v139
	v_fmac_f32_e32 v136, v26, v138
	v_add_f32_e32 v134, v134, v136
	v_add_f32_e32 v129, v129, v134
	s_waitcnt lgkmcnt(0)
	v_mul_f32_e32 v134, v41, v141
	v_mul_f32_e32 v136, v45, v143
	v_fmac_f32_e32 v134, v31, v140
	v_fmac_f32_e32 v136, v43, v142
	v_add_f32_e32 v134, v134, v136
	v_add_f32_e32 v129, v129, v134
	v_mul_f32_e64 v134, |v129|, s22
	ds_read_b128 v[136:139], v33 offset:1600
	ds_read_b128 v[140:143], v33 offset:1616
	v_log_f32_e32 v128, v128
	v_exp_f32_e32 v134, v134
	v_min_f32_e32 v133, 0, v133
	v_min_f32_e32 v129, 0, v129
	v_fmac_f32_e32 v133, 0xbf317218, v128
	v_add_f32_e32 v128, 1.0, v134
	s_waitcnt lgkmcnt(1)
	v_mul_f32_e32 v134, v18, v137
	v_fmac_f32_e32 v134, v16, v136
	v_mul_f32_e32 v136, v17, v139
	v_fmac_f32_e32 v136, v19, v138
	v_add_f32_e32 v134, v134, v136
	s_waitcnt lgkmcnt(0)
	v_mul_f32_e32 v141, v22, v141
	ds_read_b128 v[136:139], v33 offset:1632
	v_fmac_f32_e32 v141, v20, v140
	v_mul_f32_e32 v140, v21, v143
	v_fmac_f32_e32 v140, v23, v142
	v_add_f32_e32 v134, v96, v134
	v_add_f32_e32 v140, v141, v140
	v_add_f32_e32 v134, v134, v140
	ds_read_b128 v[140:143], v33 offset:1648
	s_waitcnt lgkmcnt(1)
	v_mul_f32_e32 v137, v25, v137
	v_fmac_f32_e32 v137, v24, v136
	v_mul_f32_e32 v136, v27, v139
	v_fmac_f32_e32 v136, v26, v138
	v_add_f32_e32 v136, v137, v136
	v_add_f32_e32 v134, v134, v136
	s_waitcnt lgkmcnt(0)
	v_mul_f32_e32 v136, v41, v141
	v_mul_f32_e32 v137, v45, v143
	v_fmac_f32_e32 v136, v31, v140
	v_fmac_f32_e32 v137, v43, v142
	v_add_f32_e32 v136, v136, v137
	v_add_f32_e32 v134, v134, v136
	v_mul_f32_e64 v136, |v134|, s22
	v_log_f32_e32 v128, v128
	v_exp_f32_e32 v136, v136
	ds_read_b128 v[140:143], v33 offset:1664
	v_fmamk_f32 v139, v133, 0x3d800000, v135
	v_fmac_f32_e32 v129, 0xbf317218, v128
	v_add_f32_e32 v128, 1.0, v136
	v_log_f32_e32 v128, v128
	v_fmamk_f32 v138, v129, 0x3d800000, v139
	v_min_f32_e32 v129, 0, v134
	s_waitcnt lgkmcnt(0)
	v_mul_f32_e32 v133, v17, v143
	v_fmac_f32_e32 v129, 0xbf317218, v128
	v_mul_f32_e32 v128, v18, v141
	v_fmac_f32_e32 v128, v16, v140
	v_fmac_f32_e32 v133, v19, v142
	ds_read_b128 v[140:143], v33 offset:1696
	v_add_f32_e32 v128, v128, v133
	v_mul_f32_e32 v133, v22, v145
	v_mul_f32_e32 v134, v21, v147
	v_fmac_f32_e32 v133, v20, v144
	v_fmac_f32_e32 v134, v23, v146
	ds_read_b128 v[144:147], v33 offset:1712
	v_add_f32_e32 v128, v96, v128
	v_add_f32_e32 v133, v133, v134
	v_add_f32_e32 v128, v128, v133
	s_waitcnt lgkmcnt(1)
	v_mul_f32_e32 v133, v25, v141
	v_mul_f32_e32 v134, v27, v143
	v_fmac_f32_e32 v133, v24, v140
	v_fmac_f32_e32 v134, v26, v142
	v_add_f32_e32 v133, v133, v134
	v_add_f32_e32 v128, v128, v133
	s_waitcnt lgkmcnt(0)
	v_mul_f32_e32 v133, v41, v145
	v_mul_f32_e32 v134, v45, v147
	v_fmac_f32_e32 v133, v31, v144
	v_fmac_f32_e32 v134, v43, v146
	v_add_f32_e32 v133, v133, v134
	v_add_f32_e32 v133, v128, v133
	v_mul_f32_e64 v128, |v133|, s22
	ds_read_b128 v[140:143], v33 offset:1728
	ds_read_b128 v[144:147], v33 offset:1744
	v_exp_f32_e32 v134, v128
	v_fmamk_f32 v128, v129, 0x3d800000, v138
	v_min_f32_e32 v129, 0, v133
	s_waitcnt lgkmcnt(1)
	v_mul_f32_e32 v136, v17, v143
	v_add_f32_e32 v133, 1.0, v134
	v_mul_f32_e32 v134, v18, v141
	v_fmac_f32_e32 v134, v16, v140
	v_fmac_f32_e32 v136, v19, v142
	ds_read_b128 v[140:143], v33 offset:1760
	v_add_f32_e32 v134, v134, v136
	s_waitcnt lgkmcnt(1)
; #define LAS __attribute__((address_space(3)))
; __device__ __forceinline__ void phase_gla_kdec(Frame& F) {
;     ...
;             for (int s = 0; s < CH; ++s) { float a = bgc;
; #pragma unroll
;                 for (int r4 = 0; r4 < 4; ++r4) { const f32x4 gv = *(const LAS f32x4*)(glr + s * 16 + r4 * 4); a += (gv.x * w2c[4 * r4] + gv.y * w2c[4 * r4 + 1]) + (gv.z * w2c[4 * r4 + 2] + gv.w * w2c[4 * r4 + 3]); }
;                 run += fast_logsigmoid(a) * (1.f / 16.f); gc[s] = run; }
	v_mul_f32_e32 v136, v22, v145
	v_mul_f32_e32 v137, v21, v147
	v_fmac_f32_e32 v136, v20, v144
	v_fmac_f32_e32 v137, v23, v146
	ds_read_b128 v[144:147], v33 offset:1776
	v_add_f32_e32 v134, v96, v134
	v_add_f32_e32 v136, v136, v137
	v_add_f32_e32 v134, v134, v136
	s_waitcnt lgkmcnt(1)
	v_mul_f32_e32 v136, v25, v141
	v_mul_f32_e32 v137, v27, v143
	v_fmac_f32_e32 v136, v24, v140
	v_fmac_f32_e32 v137, v26, v142
	v_add_f32_e32 v136, v136, v137
	v_add_f32_e32 v134, v134, v136
	s_waitcnt lgkmcnt(0)
	v_mul_f32_e32 v136, v41, v145
	v_mul_f32_e32 v137, v45, v147
	v_fmac_f32_e32 v136, v31, v144
	v_fmac_f32_e32 v137, v43, v146
	v_add_f32_e32 v136, v136, v137
	v_add_f32_e32 v134, v134, v136
	v_mul_f32_e64 v136, |v134|, s22
	ds_read_b128 v[140:143], v33 offset:1792
	ds_read_b128 v[144:147], v33 offset:1808
	v_log_f32_e32 v133, v133
	v_exp_f32_e32 v136, v136
	v_min_f32_e32 v134, 0, v134
	s_waitcnt lgkmcnt(1)
	v_mul_f32_e32 v137, v17, v143
	v_fmac_f32_e32 v129, 0xbf317218, v133
	v_add_f32_e32 v133, 1.0, v136
	v_mul_f32_e32 v136, v18, v141
	v_fmac_f32_e32 v136, v16, v140
	v_fmac_f32_e32 v137, v19, v142
	ds_read_b128 v[140:143], v33 offset:1824
	v_add_f32_e32 v136, v136, v137
	s_waitcnt lgkmcnt(1)
	v_mul_f32_e32 v137, v22, v145
	v_fmac_f32_e32 v137, v20, v144
	v_mul_f32_e32 v144, v21, v147
	v_fmac_f32_e32 v144, v23, v146
	v_add_f32_e32 v136, v96, v136
	v_add_f32_e32 v137, v137, v144
	ds_read_b128 v[144:147], v33 offset:1840
	v_add_f32_e32 v136, v136, v137
	s_waitcnt lgkmcnt(1)
	v_mul_f32_e32 v137, v25, v141
	v_fmac_f32_e32 v137, v24, v140
	v_mul_f32_e32 v140, v27, v143
	v_fmac_f32_e32 v140, v26, v142
	v_add_f32_e32 v137, v137, v140
	v_add_f32_e32 v136, v136, v137
	s_waitcnt lgkmcnt(0)
	v_mul_f32_e32 v137, v41, v145
	v_mul_f32_e32 v140, v45, v147
	v_fmac_f32_e32 v137, v31, v144
	v_fmac_f32_e32 v140, v43, v146
	v_add_f32_e32 v137, v137, v140
	v_add_f32_e32 v136, v136, v137
	v_mul_f32_e64 v137, |v136|, s22
	v_log_f32_e32 v133, v133
	v_exp_f32_e32 v137, v137
	ds_read_b128 v[140:143], v33 offset:1856
	ds_read_b128 v[144:147], v33 offset:1872
	v_fmac_f32_e32 v134, 0xbf317218, v133
	v_add_f32_e32 v133, 1.0, v137
	v_log_f32_e32 v137, v133
	s_waitcnt lgkmcnt(1)
	v_mul_f32_e32 v133, v18, v141
	v_fmac_f32_e32 v133, v16, v140
	v_mul_f32_e32 v140, v17, v143
	v_fmac_f32_e32 v140, v19, v142
	v_add_f32_e32 v133, v133, v140
	s_waitcnt lgkmcnt(0)
	v_mul_f32_e32 v145, v22, v145
	ds_read_b128 v[140:143], v33 offset:1888
	v_fmac_f32_e32 v145, v20, v144
	v_mul_f32_e32 v144, v21, v147
	v_fmac_f32_e32 v144, v23, v146
	v_add_f32_e32 v133, v96, v133
	v_add_f32_e32 v144, v145, v144
	v_add_f32_e32 v133, v133, v144
	ds_read_b128 v[144:147], v33 offset:1904
	s_waitcnt lgkmcnt(1)
	v_mul_f32_e32 v141, v25, v141
	v_fmac_f32_e32 v141, v24, v140
	v_mul_f32_e32 v140, v27, v143
	v_fmac_f32_e32 v140, v26, v142
	v_add_f32_e32 v140, v141, v140
	v_add_f32_e32 v133, v133, v140
	s_waitcnt lgkmcnt(0)
	v_mul_f32_e32 v140, v41, v145
	v_mul_f32_e32 v141, v45, v147
	v_fmac_f32_e32 v140, v31, v144
	v_fmac_f32_e32 v141, v43, v146
	v_add_f32_e32 v140, v140, v141
	v_add_f32_e32 v144, v133, v140
	v_mul_f32_e64 v133, |v144|, s22
	v_exp_f32_e32 v140, v133
	v_fmamk_f32 v129, v129, 0x3d800000, v128
	v_fmamk_f32 v133, v134, 0x3d800000, v129
	v_min_f32_e32 v134, 0, v136
	v_add_f32_e32 v136, 1.0, v140
	ds_read_b128 v[140:143], v33 offset:1920
	v_log_f32_e32 v136, v136
	v_fmac_f32_e32 v134, 0xbf317218, v137
	v_min_f32_e32 v137, 0, v144
	ds_read_b128 v[144:147], v33 offset:1936
	v_fmac_f32_e32 v137, 0xbf317218, v136
	s_waitcnt lgkmcnt(1)
	v_mul_f32_e32 v136, v18, v141
	v_fmac_f32_e32 v136, v16, v140
	v_mul_f32_e32 v140, v17, v143
	v_fmac_f32_e32 v140, v19, v142
	v_add_f32_e32 v136, v136, v140
	s_waitcnt lgkmcnt(0)
	v_mul_f32_e32 v145, v22, v145
	ds_read_b128 v[140:143], v33 offset:1952
	v_fmac_f32_e32 v145, v20, v144
	v_mul_f32_e32 v144, v21, v147
	v_fmac_f32_e32 v144, v23, v146
	v_add_f32_e32 v136, v96, v136
	v_add_f32_e32 v144, v145, v144
	v_add_f32_e32 v136, v136, v144
	ds_read_b128 v[144:147], v33 offset:1968
	s_waitcnt lgkmcnt(1)
	v_mul_f32_e32 v141, v25, v141
	v_fmac_f32_e32 v141, v24, v140
	v_mul_f32_e32 v140, v27, v143
	v_fmac_f32_e32 v140, v26, v142
	v_add_f32_e32 v140, v141, v140
	v_add_f32_e32 v136, v136, v140
	s_waitcnt lgkmcnt(0)
	v_mul_f32_e32 v140, v41, v145
	v_mul_f32_e32 v141, v45, v147
	v_fmac_f32_e32 v140, v31, v144
	v_fmac_f32_e32 v141, v43, v146
	v_add_f32_e32 v140, v140, v141
	v_add_f32_e32 v144, v136, v140
	v_mul_f32_e64 v136, |v144|, s22
	v_exp_f32_e32 v145, v136
	ds_read_b128 v[140:143], v33 offset:1984
	v_fmamk_f32 v134, v134, 0x3d800000, v133
	v_fmamk_f32 v136, v137, 0x3d800000, v134
	v_min_f32_e32 v137, 0, v144
	v_add_f32_e32 v144, 1.0, v145
	v_log_f32_e32 v148, v144
	ds_read_b128 v[144:147], v33 offset:2000
	s_waitcnt lgkmcnt(1)
	v_mul_f32_e32 v141, v18, v141
	v_fmac_f32_e32 v141, v16, v140
	v_mul_f32_e32 v140, v17, v143
	v_fmac_f32_e32 v140, v19, v142
	v_add_f32_e32 v140, v141, v140
	s_waitcnt lgkmcnt(0)
	v_mul_f32_e32 v145, v22, v145
	v_add_f32_e32 v149, v96, v140
	v_fmac_f32_e32 v145, v20, v144
	v_mul_f32_e32 v144, v21, v147
	ds_read_b128 v[140:143], v33 offset:2016
	v_fmac_f32_e32 v144, v23, v146
	v_add_f32_e32 v144, v145, v144
	v_add_f32_e32 v149, v149, v144
	ds_read_b128 v[144:147], v33 offset:2032
	s_waitcnt lgkmcnt(1)
	v_mul_f32_e32 v141, v25, v141
	v_fmac_f32_e32 v141, v24, v140
	v_mul_f32_e32 v140, v27, v143
	v_fmac_f32_e32 v140, v26, v142
	v_add_f32_e32 v140, v141, v140
	s_waitcnt lgkmcnt(0)
; #define LAS __attribute__((address_space(3)))
; __device__ __forceinline__ void phase_gla_kdec(Frame& F) {
;     ...
;             for (int s = 0; s < CH; ++s) { float a = bgc;
; #pragma unroll
;                 for (int r4 = 0; r4 < 4; ++r4) { const f32x4 gv = *(const LAS f32x4*)(glr + s * 16 + r4 * 4); a += (gv.x * w2c[4 * r4] + gv.y * w2c[4 * r4 + 1]) + (gv.z * w2c[4 * r4 + 2] + gv.w * w2c[4 * r4 + 3]); }
;                 run += fast_logsigmoid(a) * (1.f / 16.f); gc[s] = run; }
	v_mul_f32_e32 v141, v41, v145
	v_mul_f32_e32 v142, v45, v147
	v_fmac_f32_e32 v141, v31, v144
	v_fmac_f32_e32 v142, v43, v146
	v_add_f32_e32 v140, v149, v140
	v_add_f32_e32 v141, v141, v142
	v_add_f32_e32 v149, v140, v141
	v_mul_f32_e64 v140, |v149|, s22
	v_exp_f32_e32 v144, v140
	ds_read_b128 v[140:143], v33 offset:2048
	v_fmac_f32_e32 v137, 0xbf317218, v148
	v_min_f32_e32 v149, 0, v149
	v_add_f32_e32 v144, 1.0, v144
	v_log_f32_e32 v148, v144
	ds_read_b128 v[144:147], v33 offset:2064
	s_waitcnt lgkmcnt(1)
	v_mul_f32_e32 v141, v18, v141
	v_fmac_f32_e32 v141, v16, v140
	v_mul_f32_e32 v140, v17, v143
	v_fmac_f32_e32 v140, v19, v142
	v_add_f32_e32 v140, v141, v140
	s_waitcnt lgkmcnt(0)
	v_mul_f32_e32 v145, v22, v145
	v_add_f32_e32 v150, v96, v140
	v_fmac_f32_e32 v145, v20, v144
	v_mul_f32_e32 v144, v21, v147
	ds_read_b128 v[140:143], v33 offset:2080
	v_fmac_f32_e32 v144, v23, v146
	v_add_f32_e32 v144, v145, v144
	v_add_f32_e32 v150, v150, v144
	ds_read_b128 v[144:147], v33 offset:2096
	s_waitcnt lgkmcnt(1)
	v_mul_f32_e32 v141, v25, v141
	v_fmac_f32_e32 v141, v24, v140
	v_mul_f32_e32 v140, v27, v143
	v_fmac_f32_e32 v140, v26, v142
	v_add_f32_e32 v140, v141, v140
	s_waitcnt lgkmcnt(0)
	v_mul_f32_e32 v141, v41, v145
	v_mul_f32_e32 v142, v45, v147
	v_fmac_f32_e32 v141, v31, v144
	v_fmac_f32_e32 v142, v43, v146
	v_add_f32_e32 v140, v150, v140
	v_add_f32_e32 v141, v141, v142
	v_add_f32_e32 v150, v140, v141
	v_mul_f32_e64 v140, |v150|, s22
	v_exp_f32_e32 v144, v140
	ds_read_b128 v[140:143], v33 offset:2112
	v_fmac_f32_e32 v149, 0xbf317218, v148
	v_fmamk_f32 v137, v137, 0x3d800000, v136
	v_add_f32_e32 v144, 1.0, v144
	v_log_f32_e32 v148, v144
	ds_read_b128 v[144:147], v33 offset:2128
	s_waitcnt lgkmcnt(1)
	v_mul_f32_e32 v141, v18, v141
	v_fmac_f32_e32 v141, v16, v140
	v_mul_f32_e32 v140, v17, v143
	v_fmac_f32_e32 v140, v19, v142
	v_add_f32_e32 v140, v141, v140
	s_waitcnt lgkmcnt(0)
	v_mul_f32_e32 v145, v22, v145
	v_add_f32_e32 v151, v96, v140
	v_fmac_f32_e32 v145, v20, v144
	v_mul_f32_e32 v144, v21, v147
	ds_read_b128 v[140:143], v33 offset:2144
	v_fmac_f32_e32 v144, v23, v146
	v_add_f32_e32 v144, v145, v144
	v_add_f32_e32 v151, v151, v144
	ds_read_b128 v[144:147], v33 offset:2160
	s_waitcnt lgkmcnt(1)
	v_mul_f32_e32 v141, v25, v141
	v_fmac_f32_e32 v141, v24, v140
	v_mul_f32_e32 v140, v27, v143
	v_fmac_f32_e32 v140, v26, v142
	v_add_f32_e32 v140, v141, v140
	s_waitcnt lgkmcnt(0)
	v_mul_f32_e32 v141, v41, v145
	v_mul_f32_e32 v142, v45, v147
	v_fmac_f32_e32 v141, v31, v144
	v_fmac_f32_e32 v142, v43, v146
	v_add_f32_e32 v140, v151, v140
	v_add_f32_e32 v141, v141, v142
	v_add_f32_e32 v146, v140, v141
	v_mul_f32_e64 v140, |v146|, s22
	v_exp_f32_e32 v141, v140
	v_min_f32_e32 v147, 0, v150
	v_fmac_f32_e32 v147, 0xbf317218, v148
	ds_read_b128 v[142:145], v33 offset:2176
	v_add_f32_e32 v141, 1.0, v141
	v_log_f32_e32 v148, v141
	v_fmamk_f32 v140, v149, 0x3d800000, v137
	v_min_f32_e32 v150, 0, v146
	v_fmamk_f32 v141, v147, 0x3d800000, v140
	v_fmac_f32_e32 v150, 0xbf317218, v148
	ds_read_b128 v[146:149], v33 offset:2192
	s_waitcnt lgkmcnt(1)
	v_mul_f32_e32 v143, v18, v143
	v_fmac_f32_e32 v143, v16, v142
	v_mul_f32_e32 v142, v17, v145
	v_fmac_f32_e32 v142, v19, v144
	v_add_f32_e32 v142, v143, v142
	s_waitcnt lgkmcnt(0)
	v_mul_f32_e32 v147, v22, v147
	v_add_f32_e32 v151, v96, v142
	v_fmac_f32_e32 v147, v20, v146
	v_mul_f32_e32 v146, v21, v149
	ds_read_b128 v[142:145], v33 offset:2208
	v_fmac_f32_e32 v146, v23, v148
	v_add_f32_e32 v146, v147, v146
	v_add_f32_e32 v151, v151, v146
	ds_read_b128 v[146:149], v33 offset:2224
	s_waitcnt lgkmcnt(1)
	v_mul_f32_e32 v143, v25, v143
	v_fmac_f32_e32 v143, v24, v142
	v_mul_f32_e32 v142, v27, v145
	v_fmac_f32_e32 v142, v26, v144
	v_add_f32_e32 v142, v143, v142
	s_waitcnt lgkmcnt(0)
	v_mul_f32_e32 v143, v41, v147
	v_mul_f32_e32 v144, v45, v149
	v_fmac_f32_e32 v143, v31, v146
	v_fmac_f32_e32 v144, v43, v148
	v_add_f32_e32 v142, v151, v142
	v_add_f32_e32 v143, v143, v144
	v_add_f32_e32 v143, v142, v143
	v_mul_f32_e64 v142, |v143|, s22
	v_exp_f32_e32 v148, v142
	ds_read_b128 v[144:147], v33 offset:2240
	v_fmamk_f32 v142, v150, 0x3d800000, v141
	v_min_f32_e32 v143, 0, v143
	v_add_f32_e32 v148, 1.0, v148
	v_log_f32_e32 v152, v148
	ds_read_b128 v[148:151], v33 offset:2256
	s_waitcnt lgkmcnt(1)
	v_mul_f32_e32 v145, v18, v145
	v_fmac_f32_e32 v145, v16, v144
	v_mul_f32_e32 v144, v17, v147
	v_fmac_f32_e32 v144, v19, v146
	v_add_f32_e32 v144, v145, v144
	s_waitcnt lgkmcnt(0)
	v_mul_f32_e32 v149, v22, v149
	v_add_f32_e32 v153, v96, v144
	v_fmac_f32_e32 v149, v20, v148
	v_mul_f32_e32 v148, v21, v151
	ds_read_b128 v[144:147], v33 offset:2272
	v_fmac_f32_e32 v148, v23, v150
	v_add_f32_e32 v148, v149, v148
	v_add_f32_e32 v153, v153, v148
	ds_read_b128 v[148:151], v33 offset:2288
	s_waitcnt lgkmcnt(1)
	v_mul_f32_e32 v145, v25, v145
	v_fmac_f32_e32 v145, v24, v144
	v_mul_f32_e32 v144, v27, v147
	v_fmac_f32_e32 v144, v26, v146
	v_add_f32_e32 v144, v145, v144
	s_waitcnt lgkmcnt(0)
	v_mul_f32_e32 v145, v41, v149
	v_mul_f32_e32 v146, v45, v151
	v_fmac_f32_e32 v145, v31, v148
	v_fmac_f32_e32 v146, v43, v150
	v_add_f32_e32 v144, v153, v144
	v_add_f32_e32 v145, v145, v146
	v_add_f32_e32 v153, v144, v145
	v_mul_f32_e64 v144, |v153|, s22
	v_exp_f32_e32 v148, v144
	ds_read_b128 v[144:147], v33 offset:2304
	v_fmac_f32_e32 v143, 0xbf317218, v152
	v_min_f32_e32 v153, 0, v153
	v_add_f32_e32 v148, 1.0, v148
	v_log_f32_e32 v152, v148
	ds_read_b128 v[148:151], v33 offset:2320
	s_waitcnt lgkmcnt(1)
	v_mul_f32_e32 v145, v18, v145
	v_fmac_f32_e32 v145, v16, v144
	v_mul_f32_e32 v144, v17, v147
	v_fmac_f32_e32 v144, v19, v146
	v_add_f32_e32 v144, v145, v144
	s_waitcnt lgkmcnt(0)
; #define LAS __attribute__((address_space(3)))
; __device__ __forceinline__ void phase_gla_kdec(Frame& F) {
;     ...
;             for (int s = 0; s < CH; ++s) { float a = bgc;
; #pragma unroll
;                 for (int r4 = 0; r4 < 4; ++r4) { const f32x4 gv = *(const LAS f32x4*)(glr + s * 16 + r4 * 4); a += (gv.x * w2c[4 * r4] + gv.y * w2c[4 * r4 + 1]) + (gv.z * w2c[4 * r4 + 2] + gv.w * w2c[4 * r4 + 3]); }
;                 run += fast_logsigmoid(a) * (1.f / 16.f); gc[s] = run; }
	v_mul_f32_e32 v149, v22, v149
	v_add_f32_e32 v154, v96, v144
	v_fmac_f32_e32 v149, v20, v148
	v_mul_f32_e32 v148, v21, v151
	ds_read_b128 v[144:147], v33 offset:2336
	v_fmac_f32_e32 v148, v23, v150
	v_add_f32_e32 v148, v149, v148
	v_add_f32_e32 v154, v154, v148
	ds_read_b128 v[148:151], v33 offset:2352
	s_waitcnt lgkmcnt(1)
	v_mul_f32_e32 v145, v25, v145
	v_fmac_f32_e32 v145, v24, v144
	v_mul_f32_e32 v144, v27, v147
	v_fmac_f32_e32 v144, v26, v146
	v_add_f32_e32 v144, v145, v144
	s_waitcnt lgkmcnt(0)
	v_mul_f32_e32 v145, v41, v149
	v_mul_f32_e32 v146, v45, v151
	v_fmac_f32_e32 v145, v31, v148
	v_fmac_f32_e32 v146, v43, v150
	v_add_f32_e32 v144, v154, v144
	v_add_f32_e32 v145, v145, v146
	v_add_f32_e32 v154, v144, v145
	v_mul_f32_e64 v144, |v154|, s22
	v_exp_f32_e32 v148, v144
	ds_read_b128 v[144:147], v33 offset:2368
	v_fmac_f32_e32 v153, 0xbf317218, v152
	v_fmamk_f32 v143, v143, 0x3d800000, v142
	v_add_f32_e32 v148, 1.0, v148
	v_log_f32_e32 v152, v148
	ds_read_b128 v[148:151], v33 offset:2384
	s_waitcnt lgkmcnt(1)
	v_mul_f32_e32 v145, v18, v145
	v_fmac_f32_e32 v145, v16, v144
	v_mul_f32_e32 v144, v17, v147
	v_fmac_f32_e32 v144, v19, v146
	v_add_f32_e32 v144, v145, v144
	s_waitcnt lgkmcnt(0)
	v_mul_f32_e32 v149, v22, v149
	v_add_f32_e32 v155, v96, v144
	v_fmac_f32_e32 v149, v20, v148
	v_mul_f32_e32 v148, v21, v151
	ds_read_b128 v[144:147], v33 offset:2400
	v_fmac_f32_e32 v148, v23, v150
	v_add_f32_e32 v148, v149, v148
	v_add_f32_e32 v155, v155, v148
	ds_read_b128 v[148:151], v33 offset:2416
	s_waitcnt lgkmcnt(1)
	v_mul_f32_e32 v145, v25, v145
	v_fmac_f32_e32 v145, v24, v144
	v_mul_f32_e32 v144, v27, v147
	v_fmac_f32_e32 v144, v26, v146
	v_add_f32_e32 v144, v145, v144
	s_waitcnt lgkmcnt(0)
	v_mul_f32_e32 v145, v41, v149
	v_mul_f32_e32 v146, v45, v151
	v_fmac_f32_e32 v145, v31, v148
	v_fmac_f32_e32 v146, v43, v150
	v_add_f32_e32 v144, v155, v144
	v_add_f32_e32 v145, v145, v146
	v_add_f32_e32 v150, v144, v145
	v_mul_f32_e64 v144, |v150|, s22
	v_exp_f32_e32 v145, v144
	v_min_f32_e32 v151, 0, v154
	v_fmac_f32_e32 v151, 0xbf317218, v152
	ds_read_b128 v[146:149], v33 offset:2432
	v_add_f32_e32 v145, 1.0, v145
	v_log_f32_e32 v152, v145
	v_fmamk_f32 v144, v153, 0x3d800000, v143
	v_min_f32_e32 v154, 0, v150
	v_fmamk_f32 v145, v151, 0x3d800000, v144
	v_fmac_f32_e32 v154, 0xbf317218, v152
	ds_read_b128 v[150:153], v33 offset:2448
	s_waitcnt lgkmcnt(1)
	v_mul_f32_e32 v147, v18, v147
	v_fmac_f32_e32 v147, v16, v146
	v_mul_f32_e32 v146, v17, v149
	v_fmac_f32_e32 v146, v19, v148
	v_add_f32_e32 v146, v147, v146
	s_waitcnt lgkmcnt(0)
	v_mul_f32_e32 v151, v22, v151
	v_add_f32_e32 v155, v96, v146
	v_fmac_f32_e32 v151, v20, v150
	v_mul_f32_e32 v150, v21, v153
	ds_read_b128 v[146:149], v33 offset:2464
	v_fmac_f32_e32 v150, v23, v152
	v_add_f32_e32 v150, v151, v150
	v_add_f32_e32 v155, v155, v150
	ds_read_b128 v[150:153], v33 offset:2480
	s_waitcnt lgkmcnt(1)
	v_mul_f32_e32 v147, v25, v147
	v_fmac_f32_e32 v147, v24, v146
	v_mul_f32_e32 v146, v27, v149
	v_fmac_f32_e32 v146, v26, v148
	v_add_f32_e32 v146, v147, v146
	s_waitcnt lgkmcnt(0)
	v_mul_f32_e32 v147, v41, v151
	v_mul_f32_e32 v148, v45, v153
	v_fmac_f32_e32 v147, v31, v150
	v_fmac_f32_e32 v148, v43, v152
	v_add_f32_e32 v146, v155, v146
	v_add_f32_e32 v147, v147, v148
	v_add_f32_e32 v147, v146, v147
	v_mul_f32_e64 v146, |v147|, s22
	v_exp_f32_e32 v152, v146
	ds_read_b128 v[148:151], v33 offset:2496
	v_fmamk_f32 v146, v154, 0x3d800000, v145
	v_min_f32_e32 v147, 0, v147
	v_add_f32_e32 v152, 1.0, v152
	v_log_f32_e32 v156, v152
	ds_read_b128 v[152:155], v33 offset:2512
	s_waitcnt lgkmcnt(1)
	v_mul_f32_e32 v149, v18, v149
	v_fmac_f32_e32 v149, v16, v148
	v_mul_f32_e32 v148, v17, v151
	v_fmac_f32_e32 v148, v19, v150
	v_add_f32_e32 v148, v149, v148
	s_waitcnt lgkmcnt(0)
	v_mul_f32_e32 v153, v22, v153
	v_add_f32_e32 v157, v96, v148
	v_fmac_f32_e32 v153, v20, v152
	v_mul_f32_e32 v152, v21, v155
	ds_read_b128 v[148:151], v33 offset:2528
	v_fmac_f32_e32 v152, v23, v154
	v_add_f32_e32 v152, v153, v152
	v_add_f32_e32 v157, v157, v152
	ds_read_b128 v[152:155], v33 offset:2544
	s_waitcnt lgkmcnt(1)
	v_mul_f32_e32 v149, v25, v149
	v_fmac_f32_e32 v149, v24, v148
	v_mul_f32_e32 v148, v27, v151
	v_fmac_f32_e32 v148, v26, v150
	v_add_f32_e32 v148, v149, v148
	s_waitcnt lgkmcnt(0)
	v_mul_f32_e32 v149, v41, v153
	v_mul_f32_e32 v150, v45, v155
	v_fmac_f32_e32 v149, v31, v152
	v_fmac_f32_e32 v150, v43, v154
	v_add_f32_e32 v148, v157, v148
	v_add_f32_e32 v149, v149, v150
	v_add_f32_e32 v157, v148, v149
	v_mul_f32_e64 v148, |v157|, s22
	v_exp_f32_e32 v152, v148
	ds_read_b128 v[148:151], v33 offset:2560
	v_fmac_f32_e32 v147, 0xbf317218, v156
	v_min_f32_e32 v157, 0, v157
	v_add_f32_e32 v152, 1.0, v152
	v_log_f32_e32 v156, v152
	ds_read_b128 v[152:155], v33 offset:2576
	s_waitcnt lgkmcnt(1)
	v_mul_f32_e32 v149, v18, v149
	v_fmac_f32_e32 v149, v16, v148
	v_mul_f32_e32 v148, v17, v151
	v_fmac_f32_e32 v148, v19, v150
	v_add_f32_e32 v148, v149, v148
	s_waitcnt lgkmcnt(0)
	v_mul_f32_e32 v153, v22, v153
	v_add_f32_e32 v158, v96, v148
	v_fmac_f32_e32 v153, v20, v152
	v_mul_f32_e32 v152, v21, v155
	ds_read_b128 v[148:151], v33 offset:2592
	v_fmac_f32_e32 v152, v23, v154
	v_add_f32_e32 v152, v153, v152
	v_add_f32_e32 v158, v158, v152
	ds_read_b128 v[152:155], v33 offset:2608
	s_waitcnt lgkmcnt(1)
	v_mul_f32_e32 v149, v25, v149
	v_fmac_f32_e32 v149, v24, v148
	v_mul_f32_e32 v148, v27, v151
	v_fmac_f32_e32 v148, v26, v150
	v_add_f32_e32 v148, v149, v148
	s_waitcnt lgkmcnt(0)
; #define LAS __attribute__((address_space(3)))
; __device__ __forceinline__ void phase_gla_kdec(Frame& F) {
;     ...
;             for (int s = 0; s < CH; ++s) { float a = bgc;
; #pragma unroll
;                 for (int r4 = 0; r4 < 4; ++r4) { const f32x4 gv = *(const LAS f32x4*)(glr + s * 16 + r4 * 4); a += (gv.x * w2c[4 * r4] + gv.y * w2c[4 * r4 + 1]) + (gv.z * w2c[4 * r4 + 2] + gv.w * w2c[4 * r4 + 3]); }
;                 run += fast_logsigmoid(a) * (1.f / 16.f); gc[s] = run; }
	v_mul_f32_e32 v149, v41, v153
	v_mul_f32_e32 v150, v45, v155
	v_fmac_f32_e32 v149, v31, v152
	v_fmac_f32_e32 v150, v43, v154
	v_add_f32_e32 v148, v158, v148
	v_add_f32_e32 v149, v149, v150
	v_add_f32_e32 v158, v148, v149
	v_mul_f32_e64 v148, |v158|, s22
	v_exp_f32_e32 v152, v148
	ds_read_b128 v[148:151], v33 offset:2624
	v_fmac_f32_e32 v157, 0xbf317218, v156
	v_fmamk_f32 v147, v147, 0x3d800000, v146
	v_add_f32_e32 v152, 1.0, v152
	v_log_f32_e32 v156, v152
	ds_read_b128 v[152:155], v33 offset:2640
	s_waitcnt lgkmcnt(1)
	v_mul_f32_e32 v149, v18, v149
	v_fmac_f32_e32 v149, v16, v148
	v_mul_f32_e32 v148, v17, v151
	v_fmac_f32_e32 v148, v19, v150
	v_add_f32_e32 v148, v149, v148
	s_waitcnt lgkmcnt(0)
	v_mul_f32_e32 v153, v22, v153
	v_add_f32_e32 v159, v96, v148
	v_fmac_f32_e32 v153, v20, v152
	v_mul_f32_e32 v152, v21, v155
	ds_read_b128 v[148:151], v33 offset:2656
	v_fmac_f32_e32 v152, v23, v154
	v_add_f32_e32 v152, v153, v152
	v_add_f32_e32 v159, v159, v152
	ds_read_b128 v[152:155], v33 offset:2672
	s_waitcnt lgkmcnt(1)
	v_mul_f32_e32 v149, v25, v149
	v_fmac_f32_e32 v149, v24, v148
	v_mul_f32_e32 v148, v27, v151
	v_fmac_f32_e32 v148, v26, v150
	v_add_f32_e32 v148, v149, v148
	s_waitcnt lgkmcnt(0)
	v_mul_f32_e32 v149, v41, v153
	v_mul_f32_e32 v150, v45, v155
	v_fmac_f32_e32 v149, v31, v152
	v_fmac_f32_e32 v150, v43, v154
	v_add_f32_e32 v148, v159, v148
	v_add_f32_e32 v149, v149, v150
	v_add_f32_e32 v154, v148, v149
	v_mul_f32_e64 v148, |v154|, s22
	v_exp_f32_e32 v149, v148
	v_min_f32_e32 v155, 0, v158
	v_fmac_f32_e32 v155, 0xbf317218, v156
	ds_read_b128 v[150:153], v33 offset:2688
	v_add_f32_e32 v149, 1.0, v149
	v_log_f32_e32 v156, v149
	v_fmamk_f32 v148, v157, 0x3d800000, v147
	v_min_f32_e32 v158, 0, v154
	v_fmamk_f32 v149, v155, 0x3d800000, v148
	v_fmac_f32_e32 v158, 0xbf317218, v156
	ds_read_b128 v[154:157], v33 offset:2704
	s_waitcnt lgkmcnt(1)
	v_mul_f32_e32 v151, v18, v151
	v_fmac_f32_e32 v151, v16, v150
	v_mul_f32_e32 v150, v17, v153
	v_fmac_f32_e32 v150, v19, v152
	v_add_f32_e32 v150, v151, v150
	s_waitcnt lgkmcnt(0)
	v_mul_f32_e32 v155, v22, v155
	v_add_f32_e32 v159, v96, v150
	v_fmac_f32_e32 v155, v20, v154
	v_mul_f32_e32 v154, v21, v157
	ds_read_b128 v[150:153], v33 offset:2720
	v_fmac_f32_e32 v154, v23, v156
	v_add_f32_e32 v154, v155, v154
	v_add_f32_e32 v159, v159, v154
	ds_read_b128 v[154:157], v33 offset:2736
	s_waitcnt lgkmcnt(1)
	v_mul_f32_e32 v151, v25, v151
	v_fmac_f32_e32 v151, v24, v150
	v_mul_f32_e32 v150, v27, v153
	v_fmac_f32_e32 v150, v26, v152
	v_add_f32_e32 v150, v151, v150
	s_waitcnt lgkmcnt(0)
	v_mul_f32_e32 v151, v41, v155
	v_mul_f32_e32 v152, v45, v157
	v_fmac_f32_e32 v151, v31, v154
	v_fmac_f32_e32 v152, v43, v156
	v_add_f32_e32 v150, v159, v150
	v_add_f32_e32 v151, v151, v152
	v_add_f32_e32 v151, v150, v151
	v_mul_f32_e64 v150, |v151|, s22
	v_exp_f32_e32 v156, v150
	ds_read_b128 v[152:155], v33 offset:2752
	v_fmamk_f32 v150, v158, 0x3d800000, v149
	v_min_f32_e32 v151, 0, v151
	v_add_f32_e32 v156, 1.0, v156
	v_log_f32_e32 v160, v156
	ds_read_b128 v[156:159], v33 offset:2768
	s_waitcnt lgkmcnt(1)
	v_mul_f32_e32 v153, v18, v153
	v_fmac_f32_e32 v153, v16, v152
	v_mul_f32_e32 v152, v17, v155
	v_fmac_f32_e32 v152, v19, v154
	v_add_f32_e32 v152, v153, v152
	s_waitcnt lgkmcnt(0)
	v_mul_f32_e32 v157, v22, v157
	v_add_f32_e32 v161, v96, v152
	v_fmac_f32_e32 v157, v20, v156
	v_mul_f32_e32 v156, v21, v159
	ds_read_b128 v[152:155], v33 offset:2784
	v_fmac_f32_e32 v156, v23, v158
	v_add_f32_e32 v156, v157, v156
	v_add_f32_e32 v161, v161, v156
	ds_read_b128 v[156:159], v33 offset:2800
	s_waitcnt lgkmcnt(1)
	v_mul_f32_e32 v153, v25, v153
	v_fmac_f32_e32 v153, v24, v152
	v_mul_f32_e32 v152, v27, v155
	v_fmac_f32_e32 v152, v26, v154
	v_add_f32_e32 v152, v153, v152
	s_waitcnt lgkmcnt(0)
	v_mul_f32_e32 v153, v41, v157
	v_mul_f32_e32 v154, v45, v159
	v_fmac_f32_e32 v153, v31, v156
	v_fmac_f32_e32 v154, v43, v158
	v_add_f32_e32 v152, v161, v152
	v_add_f32_e32 v153, v153, v154
	v_add_f32_e32 v161, v152, v153
	v_mul_f32_e64 v152, |v161|, s22
	v_exp_f32_e32 v156, v152
	ds_read_b128 v[152:155], v33 offset:2816
	v_fmac_f32_e32 v151, 0xbf317218, v160
	v_min_f32_e32 v161, 0, v161
	v_add_f32_e32 v156, 1.0, v156
	v_log_f32_e32 v160, v156
	ds_read_b128 v[156:159], v33 offset:2832
	s_waitcnt lgkmcnt(1)
	v_mul_f32_e32 v153, v18, v153
	v_fmac_f32_e32 v153, v16, v152
	v_mul_f32_e32 v152, v17, v155
	v_fmac_f32_e32 v152, v19, v154
	v_add_f32_e32 v152, v153, v152
	s_waitcnt lgkmcnt(0)
	v_mul_f32_e32 v157, v22, v157
	v_add_f32_e32 v162, v96, v152
	v_fmac_f32_e32 v157, v20, v156
	v_mul_f32_e32 v156, v21, v159
	ds_read_b128 v[152:155], v33 offset:2848
	v_fmac_f32_e32 v156, v23, v158
	v_add_f32_e32 v156, v157, v156
	v_add_f32_e32 v162, v162, v156
	ds_read_b128 v[156:159], v33 offset:2864
	s_waitcnt lgkmcnt(1)
	v_mul_f32_e32 v153, v25, v153
	v_fmac_f32_e32 v153, v24, v152
	v_mul_f32_e32 v152, v27, v155
	v_fmac_f32_e32 v152, v26, v154
	v_add_f32_e32 v152, v153, v152
	s_waitcnt lgkmcnt(0)
	v_mul_f32_e32 v153, v41, v157
	v_mul_f32_e32 v154, v45, v159
	v_fmac_f32_e32 v153, v31, v156
	v_fmac_f32_e32 v154, v43, v158
	v_add_f32_e32 v152, v162, v152
	v_add_f32_e32 v153, v153, v154
	v_add_f32_e32 v162, v152, v153
	v_mul_f32_e64 v152, |v162|, s22
	v_exp_f32_e32 v156, v152
	ds_read_b128 v[152:155], v33 offset:2880
	v_fmac_f32_e32 v161, 0xbf317218, v160
	v_fmamk_f32 v151, v151, 0x3d800000, v150
	v_add_f32_e32 v156, 1.0, v156
	v_log_f32_e32 v160, v156
	ds_read_b128 v[156:159], v33 offset:2896
	s_waitcnt lgkmcnt(1)
	v_mul_f32_e32 v153, v18, v153
	v_fmac_f32_e32 v153, v16, v152
	v_mul_f32_e32 v152, v17, v155
	v_fmac_f32_e32 v152, v19, v154
	v_add_f32_e32 v152, v153, v152
	s_waitcnt lgkmcnt(0)
; #define LAS __attribute__((address_space(3)))
; __device__ __forceinline__ void phase_gla_kdec(Frame& F) {
;     ...
;             for (int s = 0; s < CH; ++s) { float a = bgc;
; #pragma unroll
;                 for (int r4 = 0; r4 < 4; ++r4) { const f32x4 gv = *(const LAS f32x4*)(glr + s * 16 + r4 * 4); a += (gv.x * w2c[4 * r4] + gv.y * w2c[4 * r4 + 1]) + (gv.z * w2c[4 * r4 + 2] + gv.w * w2c[4 * r4 + 3]); }
;                 run += fast_logsigmoid(a) * (1.f / 16.f); gc[s] = run; }
	v_mul_f32_e32 v157, v22, v157
	v_add_f32_e32 v163, v96, v152
	v_fmac_f32_e32 v157, v20, v156
	v_mul_f32_e32 v156, v21, v159
	ds_read_b128 v[152:155], v33 offset:2912
	v_fmac_f32_e32 v156, v23, v158
	v_add_f32_e32 v156, v157, v156
	v_add_f32_e32 v163, v163, v156
	ds_read_b128 v[156:159], v33 offset:2928
	s_waitcnt lgkmcnt(1)
	v_mul_f32_e32 v153, v25, v153
	v_fmac_f32_e32 v153, v24, v152
	v_mul_f32_e32 v152, v27, v155
	v_fmac_f32_e32 v152, v26, v154
	v_add_f32_e32 v152, v153, v152
	s_waitcnt lgkmcnt(0)
	v_mul_f32_e32 v153, v41, v157
	v_mul_f32_e32 v154, v45, v159
	v_fmac_f32_e32 v153, v31, v156
	v_fmac_f32_e32 v154, v43, v158
	v_add_f32_e32 v152, v163, v152
	v_add_f32_e32 v153, v153, v154
	v_add_f32_e32 v158, v152, v153
	v_mul_f32_e64 v152, |v158|, s22
	v_exp_f32_e32 v153, v152
	v_min_f32_e32 v159, 0, v162
	v_fmac_f32_e32 v159, 0xbf317218, v160
	ds_read_b128 v[154:157], v33 offset:2944
	v_add_f32_e32 v153, 1.0, v153
	v_log_f32_e32 v160, v153
	v_fmamk_f32 v152, v161, 0x3d800000, v151
	v_min_f32_e32 v162, 0, v158
	v_fmamk_f32 v153, v159, 0x3d800000, v152
	v_fmac_f32_e32 v162, 0xbf317218, v160
	ds_read_b128 v[158:161], v33 offset:2960
	s_waitcnt lgkmcnt(1)
	v_mul_f32_e32 v155, v18, v155
	v_fmac_f32_e32 v155, v16, v154
	v_mul_f32_e32 v154, v17, v157
	v_fmac_f32_e32 v154, v19, v156
	v_add_f32_e32 v154, v155, v154
	s_waitcnt lgkmcnt(0)
	v_mul_f32_e32 v159, v22, v159
	v_add_f32_e32 v163, v96, v154
	v_fmac_f32_e32 v159, v20, v158
	v_mul_f32_e32 v158, v21, v161
	ds_read_b128 v[154:157], v33 offset:2976
	v_fmac_f32_e32 v158, v23, v160
	v_add_f32_e32 v158, v159, v158
	v_add_f32_e32 v163, v163, v158
	ds_read_b128 v[158:161], v33 offset:2992
	s_waitcnt lgkmcnt(1)
	v_mul_f32_e32 v155, v25, v155
	v_fmac_f32_e32 v155, v24, v154
	v_mul_f32_e32 v154, v27, v157
	v_fmac_f32_e32 v154, v26, v156
	v_add_f32_e32 v154, v155, v154
	s_waitcnt lgkmcnt(0)
	v_mul_f32_e32 v155, v41, v159
	v_mul_f32_e32 v156, v45, v161
	v_fmac_f32_e32 v155, v31, v158
	v_fmac_f32_e32 v156, v43, v160
	v_add_f32_e32 v154, v163, v154
	v_add_f32_e32 v155, v155, v156
	v_add_f32_e32 v155, v154, v155
	v_mul_f32_e64 v154, |v155|, s22
	v_exp_f32_e32 v160, v154
	ds_read_b128 v[156:159], v33 offset:3008
	v_fmamk_f32 v154, v162, 0x3d800000, v153
	v_min_f32_e32 v155, 0, v155
	v_add_f32_e32 v160, 1.0, v160
	v_log_f32_e32 v164, v160
	ds_read_b128 v[160:163], v33 offset:3024
	s_waitcnt lgkmcnt(1)
	v_mul_f32_e32 v157, v18, v157
	v_fmac_f32_e32 v157, v16, v156
	v_mul_f32_e32 v156, v17, v159
	v_fmac_f32_e32 v156, v19, v158
	v_add_f32_e32 v156, v157, v156
	s_waitcnt lgkmcnt(0)
	v_mul_f32_e32 v161, v22, v161
	v_add_f32_e32 v165, v96, v156
	v_fmac_f32_e32 v161, v20, v160
	v_mul_f32_e32 v160, v21, v163
	ds_read_b128 v[156:159], v33 offset:3040
	v_fmac_f32_e32 v160, v23, v162
	v_add_f32_e32 v160, v161, v160
	v_add_f32_e32 v165, v165, v160
	ds_read_b128 v[160:163], v33 offset:3056
	s_waitcnt lgkmcnt(1)
	v_mul_f32_e32 v157, v25, v157
	v_fmac_f32_e32 v157, v24, v156
	v_mul_f32_e32 v156, v27, v159
	v_fmac_f32_e32 v156, v26, v158
	v_add_f32_e32 v156, v157, v156
	s_waitcnt lgkmcnt(0)
	v_mul_f32_e32 v157, v41, v161
	v_mul_f32_e32 v158, v45, v163
	v_fmac_f32_e32 v157, v31, v160
	v_fmac_f32_e32 v158, v43, v162
	v_add_f32_e32 v156, v165, v156
	v_add_f32_e32 v157, v157, v158
	v_add_f32_e32 v165, v156, v157
	v_mul_f32_e64 v156, |v165|, s22
	v_exp_f32_e32 v160, v156
	ds_read_b128 v[156:159], v33 offset:3072
	v_fmac_f32_e32 v155, 0xbf317218, v164
	v_min_f32_e32 v165, 0, v165
	v_add_f32_e32 v160, 1.0, v160
	v_log_f32_e32 v164, v160
	ds_read_b128 v[160:163], v33 offset:3088
	s_waitcnt lgkmcnt(1)
	v_mul_f32_e32 v157, v18, v157
	v_fmac_f32_e32 v157, v16, v156
	v_mul_f32_e32 v156, v17, v159
	v_fmac_f32_e32 v156, v19, v158
	v_add_f32_e32 v156, v157, v156
	s_waitcnt lgkmcnt(0)
	v_mul_f32_e32 v161, v22, v161
	v_add_f32_e32 v166, v96, v156
	v_fmac_f32_e32 v161, v20, v160
	v_mul_f32_e32 v160, v21, v163
	ds_read_b128 v[156:159], v33 offset:3104
	v_fmac_f32_e32 v160, v23, v162
	v_add_f32_e32 v160, v161, v160
	v_add_f32_e32 v166, v166, v160
	ds_read_b128 v[160:163], v33 offset:3120
	s_waitcnt lgkmcnt(1)
	v_mul_f32_e32 v157, v25, v157
	v_fmac_f32_e32 v157, v24, v156
	v_mul_f32_e32 v156, v27, v159
	v_fmac_f32_e32 v156, v26, v158
	v_add_f32_e32 v156, v157, v156
	s_waitcnt lgkmcnt(0)
	v_mul_f32_e32 v157, v41, v161
	v_mul_f32_e32 v158, v45, v163
	v_fmac_f32_e32 v157, v31, v160
	v_fmac_f32_e32 v158, v43, v162
	v_add_f32_e32 v156, v166, v156
	v_add_f32_e32 v157, v157, v158
	v_add_f32_e32 v166, v156, v157
	v_mul_f32_e64 v156, |v166|, s22
	v_exp_f32_e32 v160, v156
	ds_read_b128 v[156:159], v33 offset:3136
	v_fmac_f32_e32 v165, 0xbf317218, v164
	v_fmamk_f32 v155, v155, 0x3d800000, v154
	v_add_f32_e32 v160, 1.0, v160
	v_log_f32_e32 v164, v160
	ds_read_b128 v[160:163], v33 offset:3152
	s_waitcnt lgkmcnt(1)
	v_mul_f32_e32 v157, v18, v157
	v_fmac_f32_e32 v157, v16, v156
	v_mul_f32_e32 v156, v17, v159
	v_fmac_f32_e32 v156, v19, v158
	v_add_f32_e32 v156, v157, v156
	s_waitcnt lgkmcnt(0)
	v_mul_f32_e32 v161, v22, v161
	v_add_f32_e32 v167, v96, v156
	v_fmac_f32_e32 v161, v20, v160
	v_mul_f32_e32 v160, v21, v163
	ds_read_b128 v[156:159], v33 offset:3168
	v_fmac_f32_e32 v160, v23, v162
	v_add_f32_e32 v160, v161, v160
	v_add_f32_e32 v167, v167, v160
	ds_read_b128 v[160:163], v33 offset:3184
	s_waitcnt lgkmcnt(1)
	v_mul_f32_e32 v157, v25, v157
	v_fmac_f32_e32 v157, v24, v156
	v_mul_f32_e32 v156, v27, v159
	v_fmac_f32_e32 v156, v26, v158
	v_add_f32_e32 v156, v157, v156
	s_waitcnt lgkmcnt(0)
; #define LAS __attribute__((address_space(3)))
; __device__ __forceinline__ void phase_gla_kdec(Frame& F) {
;     ...
;             for (int s = 0; s < CH; ++s) { float a = bgc;
; #pragma unroll
;                 for (int r4 = 0; r4 < 4; ++r4) { const f32x4 gv = *(const LAS f32x4*)(glr + s * 16 + r4 * 4); a += (gv.x * w2c[4 * r4] + gv.y * w2c[4 * r4 + 1]) + (gv.z * w2c[4 * r4 + 2] + gv.w * w2c[4 * r4 + 3]); }
;                 run += fast_logsigmoid(a) * (1.f / 16.f); gc[s] = run; }
	v_mul_f32_e32 v157, v41, v161
	v_mul_f32_e32 v158, v45, v163
	v_fmac_f32_e32 v157, v31, v160
	v_fmac_f32_e32 v158, v43, v162
	v_add_f32_e32 v156, v167, v156
	v_add_f32_e32 v157, v157, v158
	v_add_f32_e32 v162, v156, v157
	v_mul_f32_e64 v156, |v162|, s22
	v_exp_f32_e32 v157, v156
	v_min_f32_e32 v163, 0, v166
	v_fmac_f32_e32 v163, 0xbf317218, v164
	ds_read_b128 v[158:161], v33 offset:3200
	v_add_f32_e32 v157, 1.0, v157
	v_log_f32_e32 v164, v157
	v_fmamk_f32 v156, v165, 0x3d800000, v155
	v_min_f32_e32 v166, 0, v162
	v_fmamk_f32 v157, v163, 0x3d800000, v156
	v_fmac_f32_e32 v166, 0xbf317218, v164
	ds_read_b128 v[162:165], v33 offset:3216
	s_waitcnt lgkmcnt(1)
	v_mul_f32_e32 v159, v18, v159
	v_fmac_f32_e32 v159, v16, v158
	v_mul_f32_e32 v158, v17, v161
	v_fmac_f32_e32 v158, v19, v160
	v_add_f32_e32 v158, v159, v158
	s_waitcnt lgkmcnt(0)
	v_mul_f32_e32 v163, v22, v163
	v_add_f32_e32 v167, v96, v158
	v_fmac_f32_e32 v163, v20, v162
	v_mul_f32_e32 v162, v21, v165
	ds_read_b128 v[158:161], v33 offset:3232
	v_fmac_f32_e32 v162, v23, v164
	v_add_f32_e32 v162, v163, v162
	v_add_f32_e32 v167, v167, v162
	ds_read_b128 v[162:165], v33 offset:3248
	s_waitcnt lgkmcnt(1)
	v_mul_f32_e32 v159, v25, v159
	v_fmac_f32_e32 v159, v24, v158
	v_mul_f32_e32 v158, v27, v161
	v_fmac_f32_e32 v158, v26, v160
	v_add_f32_e32 v158, v159, v158
	s_waitcnt lgkmcnt(0)
	v_mul_f32_e32 v159, v41, v163
	v_mul_f32_e32 v160, v45, v165
	v_fmac_f32_e32 v159, v31, v162
	v_fmac_f32_e32 v160, v43, v164
	v_add_f32_e32 v158, v167, v158
	v_add_f32_e32 v159, v159, v160
	v_add_f32_e32 v159, v158, v159
	v_mul_f32_e64 v158, |v159|, s22
	v_exp_f32_e32 v164, v158
	ds_read_b128 v[160:163], v33 offset:3264
	v_fmamk_f32 v158, v166, 0x3d800000, v157
	v_min_f32_e32 v159, 0, v159
	v_add_f32_e32 v164, 1.0, v164
	v_log_f32_e32 v168, v164
	ds_read_b128 v[164:167], v33 offset:3280
	s_waitcnt lgkmcnt(1)
	v_mul_f32_e32 v161, v18, v161
	v_fmac_f32_e32 v161, v16, v160
	v_mul_f32_e32 v160, v17, v163
	v_fmac_f32_e32 v160, v19, v162
	v_add_f32_e32 v160, v161, v160
	s_waitcnt lgkmcnt(0)
	v_mul_f32_e32 v165, v22, v165
	v_add_f32_e32 v169, v96, v160
	v_fmac_f32_e32 v165, v20, v164
	v_mul_f32_e32 v164, v21, v167
	ds_read_b128 v[160:163], v33 offset:3296
	v_fmac_f32_e32 v164, v23, v166
	v_add_f32_e32 v164, v165, v164
	v_add_f32_e32 v169, v169, v164
	ds_read_b128 v[164:167], v33 offset:3312
	s_waitcnt lgkmcnt(1)
	v_mul_f32_e32 v161, v25, v161
	v_fmac_f32_e32 v161, v24, v160
	v_mul_f32_e32 v160, v27, v163
	v_fmac_f32_e32 v160, v26, v162
	v_add_f32_e32 v160, v161, v160
	s_waitcnt lgkmcnt(0)
	v_mul_f32_e32 v161, v41, v165
	v_mul_f32_e32 v162, v45, v167
	v_fmac_f32_e32 v161, v31, v164
	v_fmac_f32_e32 v162, v43, v166
	v_add_f32_e32 v160, v169, v160
	v_add_f32_e32 v161, v161, v162
	v_add_f32_e32 v169, v160, v161
	v_mul_f32_e64 v160, |v169|, s22
	v_exp_f32_e32 v164, v160
	ds_read_b128 v[160:163], v33 offset:3328
	v_fmac_f32_e32 v159, 0xbf317218, v168
	v_min_f32_e32 v169, 0, v169
	v_add_f32_e32 v164, 1.0, v164
	v_log_f32_e32 v168, v164
	ds_read_b128 v[164:167], v33 offset:3344
	s_waitcnt lgkmcnt(1)
	v_mul_f32_e32 v161, v18, v161
	v_fmac_f32_e32 v161, v16, v160
	v_mul_f32_e32 v160, v17, v163
	v_fmac_f32_e32 v160, v19, v162
	v_add_f32_e32 v160, v161, v160
	s_waitcnt lgkmcnt(0)
	v_mul_f32_e32 v165, v22, v165
	v_add_f32_e32 v170, v96, v160
	v_fmac_f32_e32 v165, v20, v164
	v_mul_f32_e32 v164, v21, v167
	ds_read_b128 v[160:163], v33 offset:3360
	v_fmac_f32_e32 v164, v23, v166
	v_add_f32_e32 v164, v165, v164
	v_add_f32_e32 v170, v170, v164
	ds_read_b128 v[164:167], v33 offset:3376
	s_waitcnt lgkmcnt(1)
	v_mul_f32_e32 v161, v25, v161
	v_fmac_f32_e32 v161, v24, v160
	v_mul_f32_e32 v160, v27, v163
	v_fmac_f32_e32 v160, v26, v162
	v_add_f32_e32 v160, v161, v160
	s_waitcnt lgkmcnt(0)
	v_mul_f32_e32 v161, v41, v165
	v_mul_f32_e32 v162, v45, v167
	v_fmac_f32_e32 v161, v31, v164
	v_fmac_f32_e32 v162, v43, v166
	v_add_f32_e32 v160, v170, v160
	v_add_f32_e32 v161, v161, v162
	v_add_f32_e32 v170, v160, v161
	v_mul_f32_e64 v160, |v170|, s22
	v_exp_f32_e32 v164, v160
	ds_read_b128 v[160:163], v33 offset:3392
	v_fmac_f32_e32 v169, 0xbf317218, v168
	v_fmamk_f32 v159, v159, 0x3d800000, v158
	v_add_f32_e32 v164, 1.0, v164
	v_log_f32_e32 v168, v164
	ds_read_b128 v[164:167], v33 offset:3408
	s_waitcnt lgkmcnt(1)
	v_mul_f32_e32 v161, v18, v161
	v_fmac_f32_e32 v161, v16, v160
	v_mul_f32_e32 v160, v17, v163
	v_fmac_f32_e32 v160, v19, v162
	v_add_f32_e32 v160, v161, v160
	s_waitcnt lgkmcnt(0)
	v_mul_f32_e32 v165, v22, v165
	v_add_f32_e32 v171, v96, v160
	v_fmac_f32_e32 v165, v20, v164
	v_mul_f32_e32 v164, v21, v167
	ds_read_b128 v[160:163], v33 offset:3424
	v_fmac_f32_e32 v164, v23, v166
	v_add_f32_e32 v164, v165, v164
	v_add_f32_e32 v171, v171, v164
	ds_read_b128 v[164:167], v33 offset:3440
	s_waitcnt lgkmcnt(1)
	v_mul_f32_e32 v161, v25, v161
	v_fmac_f32_e32 v161, v24, v160
	v_mul_f32_e32 v160, v27, v163
	v_fmac_f32_e32 v160, v26, v162
	v_add_f32_e32 v160, v161, v160
	s_waitcnt lgkmcnt(0)
	v_mul_f32_e32 v161, v41, v165
	v_mul_f32_e32 v162, v45, v167
	v_fmac_f32_e32 v161, v31, v164
	v_fmac_f32_e32 v162, v43, v166
	v_add_f32_e32 v160, v171, v160
	v_add_f32_e32 v161, v161, v162
	v_add_f32_e32 v166, v160, v161
	v_mul_f32_e64 v160, |v166|, s22
	v_exp_f32_e32 v161, v160
	v_min_f32_e32 v167, 0, v170
	v_fmac_f32_e32 v167, 0xbf317218, v168
	ds_read_b128 v[162:165], v33 offset:3456
	v_add_f32_e32 v161, 1.0, v161
	v_log_f32_e32 v168, v161
	v_fmamk_f32 v160, v169, 0x3d800000, v159
	v_min_f32_e32 v170, 0, v166
	v_fmamk_f32 v161, v167, 0x3d800000, v160
	v_fmac_f32_e32 v170, 0xbf317218, v168
	ds_read_b128 v[166:169], v33 offset:3472
	s_waitcnt lgkmcnt(1)
; #define LAS __attribute__((address_space(3)))
; __device__ __forceinline__ void phase_gla_kdec(Frame& F) {
;     ...
;             for (int s = 0; s < CH; ++s) { float a = bgc;
; #pragma unroll
;                 for (int r4 = 0; r4 < 4; ++r4) { const f32x4 gv = *(const LAS f32x4*)(glr + s * 16 + r4 * 4); a += (gv.x * w2c[4 * r4] + gv.y * w2c[4 * r4 + 1]) + (gv.z * w2c[4 * r4 + 2] + gv.w * w2c[4 * r4 + 3]); }
;                 run += fast_logsigmoid(a) * (1.f / 16.f); gc[s] = run; }
	v_mul_f32_e32 v163, v18, v163
	v_fmac_f32_e32 v163, v16, v162
	v_mul_f32_e32 v162, v17, v165
	v_fmac_f32_e32 v162, v19, v164
	v_add_f32_e32 v162, v163, v162
	s_waitcnt lgkmcnt(0)
	v_mul_f32_e32 v167, v22, v167
	v_add_f32_e32 v171, v96, v162
	v_fmac_f32_e32 v167, v20, v166
	v_mul_f32_e32 v166, v21, v169
	ds_read_b128 v[162:165], v33 offset:3488
	v_fmac_f32_e32 v166, v23, v168
	v_add_f32_e32 v166, v167, v166
	v_add_f32_e32 v171, v171, v166
	ds_read_b128 v[166:169], v33 offset:3504
	s_waitcnt lgkmcnt(1)
	v_mul_f32_e32 v163, v25, v163
	v_fmac_f32_e32 v163, v24, v162
	v_mul_f32_e32 v162, v27, v165
	v_fmac_f32_e32 v162, v26, v164
	v_add_f32_e32 v162, v163, v162
	s_waitcnt lgkmcnt(0)
	v_mul_f32_e32 v163, v41, v167
	v_mul_f32_e32 v164, v45, v169
	v_fmac_f32_e32 v163, v31, v166
	v_fmac_f32_e32 v164, v43, v168
	v_add_f32_e32 v162, v171, v162
	v_add_f32_e32 v163, v163, v164
	v_add_f32_e32 v163, v162, v163
	v_mul_f32_e64 v162, |v163|, s22
	v_exp_f32_e32 v168, v162
	ds_read_b128 v[164:167], v33 offset:3520
	v_fmamk_f32 v162, v170, 0x3d800000, v161
	v_min_f32_e32 v163, 0, v163
	v_add_f32_e32 v168, 1.0, v168
	v_log_f32_e32 v172, v168
	ds_read_b128 v[168:171], v33 offset:3536
	s_waitcnt lgkmcnt(1)
	v_mul_f32_e32 v165, v18, v165
	v_fmac_f32_e32 v165, v16, v164
	v_mul_f32_e32 v164, v17, v167
	v_fmac_f32_e32 v164, v19, v166
	v_add_f32_e32 v164, v165, v164
	s_waitcnt lgkmcnt(0)
	v_mul_f32_e32 v169, v22, v169
	v_add_f32_e32 v173, v96, v164
	v_fmac_f32_e32 v169, v20, v168
	v_mul_f32_e32 v168, v21, v171
	ds_read_b128 v[164:167], v33 offset:3552
	v_fmac_f32_e32 v168, v23, v170
	v_add_f32_e32 v168, v169, v168
	v_add_f32_e32 v173, v173, v168
	ds_read_b128 v[168:171], v33 offset:3568
	s_waitcnt lgkmcnt(1)
	v_mul_f32_e32 v165, v25, v165
	v_fmac_f32_e32 v165, v24, v164
	v_mul_f32_e32 v164, v27, v167
	v_fmac_f32_e32 v164, v26, v166
	v_add_f32_e32 v164, v165, v164
	s_waitcnt lgkmcnt(0)
	v_mul_f32_e32 v165, v41, v169
	v_mul_f32_e32 v166, v45, v171
	v_fmac_f32_e32 v165, v31, v168
	v_fmac_f32_e32 v166, v43, v170
	v_add_f32_e32 v164, v173, v164
	v_add_f32_e32 v165, v165, v166
	v_add_f32_e32 v173, v164, v165
	v_mul_f32_e64 v164, |v173|, s22
	v_exp_f32_e32 v168, v164
	ds_read_b128 v[164:167], v33 offset:3584
	v_fmac_f32_e32 v163, 0xbf317218, v172
	v_min_f32_e32 v173, 0, v173
	v_add_f32_e32 v168, 1.0, v168
	v_log_f32_e32 v172, v168
	ds_read_b128 v[168:171], v33 offset:3600
	s_waitcnt lgkmcnt(1)
	v_mul_f32_e32 v165, v18, v165
	v_fmac_f32_e32 v165, v16, v164
	v_mul_f32_e32 v164, v17, v167
	v_fmac_f32_e32 v164, v19, v166
	v_add_f32_e32 v164, v165, v164
	s_waitcnt lgkmcnt(0)
	v_mul_f32_e32 v169, v22, v169
	v_add_f32_e32 v174, v96, v164
	v_fmac_f32_e32 v169, v20, v168
	v_mul_f32_e32 v168, v21, v171
	ds_read_b128 v[164:167], v33 offset:3616
	v_fmac_f32_e32 v168, v23, v170
	v_add_f32_e32 v168, v169, v168
	v_add_f32_e32 v174, v174, v168
	ds_read_b128 v[168:171], v33 offset:3632
	s_waitcnt lgkmcnt(1)
	v_mul_f32_e32 v165, v25, v165
	v_fmac_f32_e32 v165, v24, v164
	v_mul_f32_e32 v164, v27, v167
	v_fmac_f32_e32 v164, v26, v166
	v_add_f32_e32 v164, v165, v164
	s_waitcnt lgkmcnt(0)
	v_mul_f32_e32 v165, v41, v169
	v_mul_f32_e32 v166, v45, v171
	v_fmac_f32_e32 v165, v31, v168
	v_fmac_f32_e32 v166, v43, v170
	v_add_f32_e32 v164, v174, v164
	v_add_f32_e32 v165, v165, v166
	v_add_f32_e32 v174, v164, v165
	v_mul_f32_e64 v164, |v174|, s22
	v_exp_f32_e32 v168, v164
	ds_read_b128 v[164:167], v33 offset:3648
	v_fmac_f32_e32 v173, 0xbf317218, v172
	v_fmamk_f32 v163, v163, 0x3d800000, v162
	v_add_f32_e32 v168, 1.0, v168
	v_log_f32_e32 v172, v168
	ds_read_b128 v[168:171], v33 offset:3664
	s_waitcnt lgkmcnt(1)
	v_mul_f32_e32 v165, v18, v165
	v_fmac_f32_e32 v165, v16, v164
	v_mul_f32_e32 v164, v17, v167
	v_fmac_f32_e32 v164, v19, v166
	v_add_f32_e32 v164, v165, v164
	s_waitcnt lgkmcnt(0)
	v_mul_f32_e32 v169, v22, v169
	v_add_f32_e32 v175, v96, v164
	v_fmac_f32_e32 v169, v20, v168
	v_mul_f32_e32 v168, v21, v171
	ds_read_b128 v[164:167], v33 offset:3680
	v_fmac_f32_e32 v168, v23, v170
	v_add_f32_e32 v168, v169, v168
	v_add_f32_e32 v175, v175, v168
	ds_read_b128 v[168:171], v33 offset:3696
	s_waitcnt lgkmcnt(1)
	v_mul_f32_e32 v165, v25, v165
	v_fmac_f32_e32 v165, v24, v164
	v_mul_f32_e32 v164, v27, v167
	v_fmac_f32_e32 v164, v26, v166
	v_add_f32_e32 v164, v165, v164
	s_waitcnt lgkmcnt(0)
	v_mul_f32_e32 v165, v41, v169
	v_mul_f32_e32 v166, v45, v171
	v_fmac_f32_e32 v165, v31, v168
	v_fmac_f32_e32 v166, v43, v170
	v_add_f32_e32 v164, v175, v164
	v_add_f32_e32 v165, v165, v166
	v_add_f32_e32 v170, v164, v165
	v_mul_f32_e64 v164, |v170|, s22
	v_exp_f32_e32 v165, v164
	v_min_f32_e32 v171, 0, v174
	ds_read_b128 v[166:169], v33 offset:3712
	v_fmac_f32_e32 v171, 0xbf317218, v172
	v_add_f32_e32 v165, 1.0, v165
	v_log_f32_e32 v172, v165
	v_fmamk_f32 v164, v173, 0x3d800000, v163
	v_min_f32_e32 v182, 0, v170
	v_fmamk_f32 v165, v171, 0x3d800000, v164
	v_fmac_f32_e32 v182, 0xbf317218, v172
	ds_read_b128 v[170:173], v33 offset:3728
	s_waitcnt lgkmcnt(1)
	v_mov_b32_e32 v174, v167
	v_mov_b32_e32 v167, v169
	v_mov_b32_e32 v175, v168
	v_pk_mul_f32 v[166:167], v[16:17], v[166:167]
	s_waitcnt lgkmcnt(0)
	v_mov_b32_e32 v180, v171
	v_pk_fma_f32 v[166:167], v[18:19], v[174:175], v[166:167]
	v_mov_b32_e32 v171, v173
	v_add_f32_e32 v166, v166, v167
	v_add_f32_e32 v178, v96, v166
	ds_read_b128 v[166:169], v33 offset:3744
	ds_read_b128 v[174:177], v33 offset:3760
	v_mov_b32_e32 v181, v172
	v_pk_mul_f32 v[170:171], v[20:21], v[170:171]
	s_waitcnt lgkmcnt(0)
; #define LAS __attribute__((address_space(3)))
; __device__ __forceinline__ void phase_gla_kdec(Frame& F) {
;     ...
;             for (int s = 0; s < CH; ++s) { float a = bgc;
; #pragma unroll
;                 for (int r4 = 0; r4 < 4; ++r4) { const f32x4 gv = *(const LAS f32x4*)(glr + s * 16 + r4 * 4); a += (gv.x * w2c[4 * r4] + gv.y * w2c[4 * r4 + 1]) + (gv.z * w2c[4 * r4 + 2] + gv.w * w2c[4 * r4 + 3]); }
;                 run += fast_logsigmoid(a) * (1.f / 16.f); gc[s] = run; }
	v_mul_f32_e32 v172, v41, v175
	v_pk_fma_f32 v[170:171], v[22:23], v[180:181], v[170:171]
	v_mul_f32_e32 v173, v43, v176
	v_pk_add_f32 v[170:171], v[170:171], v[170:171] op_sel:[0,1] op_sel_hi:[1,0]
	v_mul_f32_e32 v179, v31, v174
	v_mov_b32_e32 v171, v172
	v_mul_f32_e32 v172, v25, v167
	v_pk_fma_f32 v[166:167], v[24:25], v[166:167], v[172:173] op_sel_hi:[1,1,0]
	v_mul_f32_e32 v172, v27, v169
	v_mul_f32_e32 v174, v45, v177
	v_pk_fma_f32 v[168:169], v[26:27], v[168:169], v[172:173] op_sel_hi:[1,1,0]
	v_mov_b32_e32 v167, v173
	v_mov_b32_e32 v169, v174
	v_pk_add_f32 v[170:171], v[178:179], v[170:171]
	v_pk_add_f32 v[166:167], v[166:167], v[168:169]
	s_nop 0
	v_pk_add_f32 v[166:167], v[170:171], v[166:167]
	ds_read_b128 v[168:171], v33 offset:3776
	v_add_f32_e32 v167, v166, v167
	v_mul_f32_e64 v166, |v167|, s22
	v_exp_f32_e32 v172, v166
	v_fmamk_f32 v166, v182, 0x3d800000, v165
	v_min_f32_e32 v167, 0, v167
	v_add_f32_e32 v172, 1.0, v172
	v_log_f32_e32 v184, v172
	ds_read_b128 v[172:175], v33 offset:3792
	s_waitcnt lgkmcnt(1)
	v_mov_b32_e32 v176, v169
	v_mov_b32_e32 v169, v171
	v_mov_b32_e32 v177, v170
	v_pk_mul_f32 v[168:169], v[16:17], v[168:169]
	s_waitcnt lgkmcnt(0)
	v_mov_b32_e32 v182, v173
	v_pk_fma_f32 v[168:169], v[18:19], v[176:177], v[168:169]
	v_mov_b32_e32 v173, v175
	v_add_f32_e32 v168, v168, v169
	v_add_f32_e32 v180, v96, v168
	ds_read_b128 v[168:171], v33 offset:3808
	ds_read_b128 v[176:179], v33 offset:3824
	v_mov_b32_e32 v183, v174
	v_pk_mul_f32 v[172:173], v[20:21], v[172:173]
	v_fmac_f32_e32 v167, 0xbf317218, v184
	v_pk_fma_f32 v[172:173], v[22:23], v[182:183], v[172:173]
	s_waitcnt lgkmcnt(0)
	v_mul_f32_e32 v174, v41, v177
	v_pk_add_f32 v[172:173], v[172:173], v[172:173] op_sel:[0,1] op_sel_hi:[1,0]
	v_mul_f32_e32 v175, v43, v178
	v_mov_b32_e32 v173, v174
	v_mul_f32_e32 v174, v25, v169
	v_pk_fma_f32 v[168:169], v[24:25], v[168:169], v[174:175] op_sel_hi:[1,1,0]
	v_mul_f32_e32 v174, v27, v171
	v_mul_f32_e32 v181, v31, v176
	v_mul_f32_e32 v176, v45, v179
	v_pk_fma_f32 v[170:171], v[26:27], v[170:171], v[174:175] op_sel_hi:[1,1,0]
	v_mov_b32_e32 v169, v175
	v_mov_b32_e32 v171, v176
	v_pk_add_f32 v[172:173], v[180:181], v[172:173]
	v_pk_add_f32 v[168:169], v[168:169], v[170:171]
	v_fmamk_f32 v167, v167, 0x3d800000, v166
	v_pk_add_f32 v[168:169], v[172:173], v[168:169]
	s_nop 0
	v_add_f32_e32 v185, v168, v169
	v_mul_f32_e64 v168, |v185|, s22
	v_exp_f32_e32 v172, v168
	ds_read_b128 v[168:171], v33 offset:3840
	v_min_f32_e32 v185, 0, v185
	v_add_f32_e32 v172, 1.0, v172
	v_log_f32_e32 v184, v172
	ds_read_b128 v[172:175], v33 offset:3856
	s_waitcnt lgkmcnt(1)
	v_mov_b32_e32 v176, v169
	v_mov_b32_e32 v169, v171
	v_mov_b32_e32 v177, v170
	v_pk_mul_f32 v[168:169], v[16:17], v[168:169]
	s_waitcnt lgkmcnt(0)
	v_mov_b32_e32 v182, v173
	v_pk_fma_f32 v[168:169], v[18:19], v[176:177], v[168:169]
	v_mov_b32_e32 v173, v175
	v_add_f32_e32 v168, v168, v169
	v_add_f32_e32 v180, v96, v168
	ds_read_b128 v[168:171], v33 offset:3872
	ds_read_b128 v[176:179], v33 offset:3888
	v_mov_b32_e32 v183, v174
	v_pk_mul_f32 v[172:173], v[20:21], v[172:173]
	v_fmac_f32_e32 v185, 0xbf317218, v184
	v_pk_fma_f32 v[172:173], v[22:23], v[182:183], v[172:173]
	s_waitcnt lgkmcnt(0)
	v_mul_f32_e32 v174, v41, v177
	v_pk_add_f32 v[172:173], v[172:173], v[172:173] op_sel:[0,1] op_sel_hi:[1,0]
	v_mul_f32_e32 v175, v43, v178
	v_mov_b32_e32 v173, v174
	v_mul_f32_e32 v174, v25, v169
	v_pk_fma_f32 v[168:169], v[24:25], v[168:169], v[174:175] op_sel_hi:[1,1,0]
	v_mul_f32_e32 v174, v27, v171
	v_mul_f32_e32 v181, v31, v176
	v_mul_f32_e32 v176, v45, v179
	v_pk_fma_f32 v[170:171], v[26:27], v[170:171], v[174:175] op_sel_hi:[1,1,0]
	v_mov_b32_e32 v169, v175
	v_mov_b32_e32 v171, v176
	v_pk_add_f32 v[172:173], v[180:181], v[172:173]
	v_pk_add_f32 v[168:169], v[168:169], v[170:171]
	s_nop 0
	v_pk_add_f32 v[168:169], v[172:173], v[168:169]
	s_nop 0
	v_add_f32_e32 v186, v168, v169
	v_mul_f32_e64 v168, |v186|, s22
	v_exp_f32_e32 v172, v168
	ds_read_b128 v[168:171], v33 offset:3904
	v_add_f32_e32 v172, 1.0, v172
	v_log_f32_e32 v184, v172
	ds_read_b128 v[172:175], v33 offset:3920
	s_waitcnt lgkmcnt(1)
	v_mov_b32_e32 v176, v169
	v_mov_b32_e32 v169, v171
	v_mov_b32_e32 v177, v170
	v_pk_mul_f32 v[168:169], v[16:17], v[168:169]
	s_waitcnt lgkmcnt(0)
	v_mov_b32_e32 v182, v173
	v_pk_fma_f32 v[168:169], v[18:19], v[176:177], v[168:169]
	v_mov_b32_e32 v173, v175
	v_add_f32_e32 v168, v168, v169
	v_add_f32_e32 v180, v96, v168
	ds_read_b128 v[168:171], v33 offset:3936
	ds_read_b128 v[176:179], v33 offset:3952
	v_mov_b32_e32 v183, v174
	v_pk_mul_f32 v[172:173], v[20:21], v[172:173]
	s_waitcnt lgkmcnt(0)
	v_mul_f32_e32 v174, v41, v177
	v_pk_fma_f32 v[172:173], v[22:23], v[182:183], v[172:173]
	v_mul_f32_e32 v175, v43, v178
	v_pk_add_f32 v[172:173], v[172:173], v[172:173] op_sel:[0,1] op_sel_hi:[1,0]
	v_mul_f32_e32 v181, v31, v176
	v_mov_b32_e32 v173, v174
	v_mul_f32_e32 v174, v25, v169
	v_pk_fma_f32 v[168:169], v[24:25], v[168:169], v[174:175] op_sel_hi:[1,1,0]
	v_mul_f32_e32 v174, v27, v171
	v_mul_f32_e32 v176, v45, v179
	v_pk_fma_f32 v[170:171], v[26:27], v[170:171], v[174:175] op_sel_hi:[1,1,0]
	v_mov_b32_e32 v169, v175
	v_mov_b32_e32 v171, v176
	v_pk_add_f32 v[172:173], v[180:181], v[172:173]
	v_pk_add_f32 v[168:169], v[168:169], v[170:171]
	v_min_f32_e32 v171, 0, v186
	v_pk_add_f32 v[168:169], v[172:173], v[168:169]
	ds_read_b128 v[172:175], v33 offset:3968
	v_add_f32_e32 v168, v168, v169
	v_mul_f32_e64 v169, |v168|, s22
	v_exp_f32_e32 v169, v169
	v_min_f32_e32 v168, 0, v168
	v_fmamk_f32 v170, v185, 0x3d800000, v167
	v_fmac_f32_e32 v171, 0xbf317218, v184
	v_add_f32_e32 v169, 1.0, v169
	v_log_f32_e32 v176, v169
	v_fmamk_f32 v169, v171, 0x3d800000, v170
	v_fmac_f32_e32 v168, 0xbf317218, v176
	ds_read_b128 v[176:179], v33 offset:3984
	s_waitcnt lgkmcnt(1)
; #define LAS __attribute__((address_space(3)))
; __device__ __forceinline__ unsigned f2bf(float f) { unsigned u = __builtin_bit_cast(unsigned, f); return (u + 0x7fffu + ((u >> 16) & 1u)) >> 16; }
; __device__ __forceinline__ void phase_gla_kdec(Frame& F) {
;     ...
;             for (int s = 0; s < CH; ++s) { float a = bgc;
; #pragma unroll
;                 for (int r4 = 0; r4 < 4; ++r4) { const f32x4 gv = *(const LAS f32x4*)(glr + s * 16 + r4 * 4); a += (gv.x * w2c[4 * r4] + gv.y * w2c[4 * r4 + 1]) + (gv.z * w2c[4 * r4 + 2] + gv.w * w2c[4 * r4 + 3]); }
;                 run += fast_logsigmoid(a) * (1.f / 16.f); gc[s] = run; }
; #pragma unroll
;             for (int s = 0; s < CH; ++s) { const float kv = bf2f(kt[s * KP + j]);
;                 kt[s * KP + j] = (bf16_t)f2bf(kv * __builtin_amdgcn_exp2f(1.4426950408889634f * (run - gc[s]))); }
	v_mov_b32_e32 v180, v173
	v_mov_b32_e32 v173, v175
	v_mov_b32_e32 v181, v174
	v_pk_mul_f32 v[172:173], v[16:17], v[172:173]
	s_waitcnt lgkmcnt(0)
	v_mov_b32_e32 v186, v177
	v_pk_fma_f32 v[172:173], v[18:19], v[180:181], v[172:173]
	v_mov_b32_e32 v177, v179
	v_add_f32_e32 v171, v172, v173
	ds_read_b128 v[172:175], v33 offset:4000
	ds_read_b128 v[180:183], v33 offset:4016
	v_mov_b32_e32 v187, v178
	v_pk_mul_f32 v[176:177], v[20:21], v[176:177]
	v_add_f32_e32 v184, v96, v171
	s_waitcnt lgkmcnt(1)
	v_mul_f32_e32 v178, v25, v173
	s_waitcnt lgkmcnt(0)
	v_mul_f32_e32 v179, v43, v182
	v_pk_fma_f32 v[176:177], v[22:23], v[186:187], v[176:177]
	v_pk_fma_f32 v[172:173], v[24:25], v[172:173], v[178:179] op_sel_hi:[1,1,0]
	v_mul_f32_e32 v178, v27, v175
	v_mul_f32_e32 v185, v31, v180
	v_mul_f32_e32 v171, v41, v181
	v_mul_f32_e32 v180, v45, v183
	v_pk_add_f32 v[176:177], v[176:177], v[176:177] op_sel:[0,1] op_sel_hi:[1,0]
	v_pk_fma_f32 v[174:175], v[26:27], v[174:175], v[178:179] op_sel_hi:[1,1,0]
	v_mov_b32_e32 v177, v171
	v_mov_b32_e32 v173, v179
	v_mov_b32_e32 v175, v180
	v_pk_add_f32 v[176:177], v[184:185], v[176:177]
	v_pk_add_f32 v[172:173], v[172:173], v[174:175]
	v_fmamk_f32 v168, v168, 0x3d800000, v169
	v_pk_add_f32 v[176:177], v[176:177], v[172:173]
	ds_read_b128 v[172:175], v33 offset:4032
	v_add_f32_e32 v171, v176, v177
	v_mul_f32_e64 v176, |v171|, s22
	v_exp_f32_e32 v188, v176
	ds_read_b128 v[176:179], v33 offset:4048
	s_waitcnt lgkmcnt(1)
	v_mov_b32_e32 v180, v173
	v_mov_b32_e32 v173, v175
	v_mov_b32_e32 v181, v174
	v_pk_mul_f32 v[172:173], v[16:17], v[172:173]
	s_waitcnt lgkmcnt(0)
	v_mov_b32_e32 v186, v177
	v_pk_fma_f32 v[172:173], v[18:19], v[180:181], v[172:173]
	v_mov_b32_e32 v177, v179
	v_add_f32_e32 v172, v172, v173
	v_add_f32_e32 v184, v96, v172
	ds_read_b128 v[172:175], v33 offset:4064
	ds_read_b128 v[180:183], v33 offset:4080
	v_mov_b32_e32 v187, v178
	v_pk_mul_f32 v[176:177], v[20:21], v[176:177]
	v_min_f32_e32 v171, 0, v171
	v_pk_fma_f32 v[176:177], v[22:23], v[186:187], v[176:177]
	s_waitcnt lgkmcnt(0)
	v_mul_f32_e32 v178, v41, v181
	v_pk_add_f32 v[176:177], v[176:177], v[176:177] op_sel:[0,1] op_sel_hi:[1,0]
	v_mul_f32_e32 v179, v43, v182
	v_mov_b32_e32 v177, v178
	v_mul_f32_e32 v178, v25, v173
	v_pk_fma_f32 v[172:173], v[24:25], v[172:173], v[178:179] op_sel_hi:[1,1,0]
	v_mul_f32_e32 v178, v27, v175
	v_mul_f32_e32 v185, v31, v180
	v_mul_f32_e32 v180, v45, v183
	v_pk_fma_f32 v[174:175], v[26:27], v[174:175], v[178:179] op_sel_hi:[1,1,0]
	v_mov_b32_e32 v173, v179
	v_mov_b32_e32 v175, v180
	v_pk_add_f32 v[176:177], v[184:185], v[176:177]
	v_pk_add_f32 v[172:173], v[172:173], v[174:175]
	v_add_f32_e32 v174, 1.0, v188
	v_pk_add_f32 v[172:173], v[176:177], v[172:173]
	v_log_f32_e32 v174, v174
	v_add_f32_e32 v173, v172, v173
	v_mul_f32_e64 v172, |v173|, s22
	v_exp_f32_e32 v172, v172
	v_fmac_f32_e32 v171, 0xbf317218, v174
	v_add_f32_e32 v172, 1.0, v172
	v_log_f32_e32 v175, v172
	v_fmamk_f32 v172, v171, 0x3d800000, v168
	v_min_f32_e32 v171, 0, v173
	v_fmac_f32_e32 v171, 0xbf317218, v175
	v_fmamk_f32 v171, v171, 0x3d800000, v172
	v_sub_f32_e32 v89, v171, v89
	v_mul_f32_e32 v89, 0x3fb8aa3b, v89
	v_exp_f32_e32 v89, v89
	ds_read_u16 v173, v97 offset:4096
	ds_read_u16 v174, v97 offset:5136
	ds_read_u16 v175, v97 offset:6176
	ds_read_u16 v176, v97 offset:7216
	ds_read_u16 v177, v97 offset:8256
	ds_read_u16 v178, v97 offset:9296
	ds_read_u16 v179, v97 offset:10336
	ds_read_u16 v180, v97 offset:11376
	v_sub_f32_e32 v88, v171, v88
	s_waitcnt lgkmcnt(7)
	v_lshlrev_b32_e32 v173, 16, v173
	v_mul_f32_e32 v88, 0x3fb8aa3b, v88
	v_mul_f32_e32 v89, v89, v173
	v_exp_f32_e32 v88, v88
	v_bfe_u32 v173, v89, 16, 1
	v_add3_u32 v89, v89, v173, s24
	v_sub_f32_e32 v90, v171, v90
	ds_write_b16_d16_hi v97, v89 offset:4096
	s_waitcnt lgkmcnt(7)
	v_lshlrev_b32_e32 v89, 16, v174
	v_mul_f32_e32 v90, 0x3fb8aa3b, v90
	v_mul_f32_e32 v88, v88, v89
	v_exp_f32_e32 v90, v90
	v_bfe_u32 v89, v88, 16, 1
	v_add3_u32 v88, v88, v89, s24
	ds_write_b16_d16_hi v97, v88 offset:5136
	s_waitcnt lgkmcnt(7)
	v_lshlrev_b32_e32 v88, 16, v175
	v_mul_f32_e32 v88, v90, v88
	v_sub_f32_e32 v90, v171, v91
	v_mul_f32_e32 v90, 0x3fb8aa3b, v90
	v_exp_f32_e32 v90, v90
	v_bfe_u32 v89, v88, 16, 1
	v_add3_u32 v88, v88, v89, s24
	ds_write_b16_d16_hi v97, v88 offset:6176
	s_waitcnt lgkmcnt(7)
	v_lshlrev_b32_e32 v88, 16, v176
	v_mul_f32_e32 v88, v90, v88
	v_sub_f32_e32 v90, v171, v92
	v_mul_f32_e32 v90, 0x3fb8aa3b, v90
	v_exp_f32_e32 v90, v90
	v_bfe_u32 v89, v88, 16, 1
	v_add3_u32 v88, v88, v89, s24
	ds_write_b16_d16_hi v97, v88 offset:7216
	s_waitcnt lgkmcnt(7)
	v_lshlrev_b32_e32 v88, 16, v177
	v_mul_f32_e32 v88, v90, v88
	v_sub_f32_e32 v90, v171, v93
	v_mul_f32_e32 v90, 0x3fb8aa3b, v90
	v_exp_f32_e32 v90, v90
	v_bfe_u32 v89, v88, 16, 1
	v_add3_u32 v88, v88, v89, s24
	ds_write_b16_d16_hi v97, v88 offset:8256
	s_waitcnt lgkmcnt(7)
	v_lshlrev_b32_e32 v88, 16, v178
	v_mul_f32_e32 v88, v90, v88
	v_sub_f32_e32 v90, v171, v94
	v_mul_f32_e32 v90, 0x3fb8aa3b, v90
	v_exp_f32_e32 v90, v90
	v_bfe_u32 v89, v88, 16, 1
	v_add3_u32 v88, v88, v89, s24
	ds_write_b16_d16_hi v97, v88 offset:9296
	s_waitcnt lgkmcnt(7)
	v_lshlrev_b32_e32 v88, 16, v179
	v_mul_f32_e32 v88, v90, v88
	v_sub_f32_e32 v90, v171, v118
	v_mul_f32_e32 v90, 0x3fb8aa3b, v90
	v_exp_f32_e32 v90, v90
	v_bfe_u32 v89, v88, 16, 1
	v_add3_u32 v88, v88, v89, s24
	ds_write_b16_d16_hi v97, v88 offset:10336
	s_waitcnt lgkmcnt(7)
; __device__ __forceinline__ unsigned f2bf(float f) { unsigned u = __builtin_bit_cast(unsigned, f); return (u + 0x7fffu + ((u >> 16) & 1u)) >> 16; }
; __device__ __forceinline__ void phase_gla_kdec(Frame& F) {
;     ...
;             for (int s = 0; s < CH; ++s) { const float kv = bf2f(kt[s * KP + j]);
;                 kt[s * KP + j] = (bf16_t)f2bf(kv * __builtin_amdgcn_exp2f(1.4426950408889634f * (run - gc[s]))); }
	v_lshlrev_b32_e32 v88, 16, v180
	v_mul_f32_e32 v88, v90, v88
	v_bfe_u32 v89, v88, 16, 1
	v_add3_u32 v88, v88, v89, s24
	ds_write_b16_d16_hi v97, v88 offset:11376
	v_sub_f32_e32 v88, v171, v117
	v_mul_f32_e32 v88, 0x3fb8aa3b, v88
	v_exp_f32_e32 v88, v88
	ds_read_u16 v89, v97 offset:12416
	ds_read_u16 v90, v97 offset:13456
	ds_read_u16 v91, v97 offset:14496
	ds_read_u16 v92, v97 offset:15536
	ds_read_u16 v93, v97 offset:16576
	ds_read_u16 v94, v97 offset:17616
	ds_read_u16 v117, v97 offset:18656
	ds_read_u16 v118, v97 offset:19696
	s_waitcnt lgkmcnt(7)
	v_lshlrev_b32_e32 v89, 16, v89
	v_sub_f32_e32 v95, v171, v95
	v_mul_f32_e32 v88, v88, v89
	v_mul_f32_e32 v95, 0x3fb8aa3b, v95
	v_bfe_u32 v89, v88, 16, 1
	v_exp_f32_e32 v95, v95
	v_add3_u32 v88, v88, v89, s24
	ds_write_b16_d16_hi v97, v88 offset:12416
	s_waitcnt lgkmcnt(7)
	v_lshlrev_b32_e32 v88, 16, v90
	v_sub_f32_e32 v90, v171, v119
	v_mul_f32_e32 v90, 0x3fb8aa3b, v90
	v_mul_f32_e32 v88, v95, v88
	v_exp_f32_e32 v90, v90
	v_bfe_u32 v89, v88, 16, 1
	v_add3_u32 v88, v88, v89, s24
	ds_write_b16_d16_hi v97, v88 offset:13456
	s_waitcnt lgkmcnt(7)
	v_lshlrev_b32_e32 v88, 16, v91
	v_mul_f32_e32 v88, v90, v88
	v_sub_f32_e32 v90, v171, v120
	v_mul_f32_e32 v90, 0x3fb8aa3b, v90
	v_exp_f32_e32 v90, v90
	v_bfe_u32 v89, v88, 16, 1
	v_add3_u32 v88, v88, v89, s24
	ds_write_b16_d16_hi v97, v88 offset:14496
	s_waitcnt lgkmcnt(7)
	v_lshlrev_b32_e32 v88, 16, v92
	v_mul_f32_e32 v88, v90, v88
	v_sub_f32_e32 v90, v171, v121
	v_mul_f32_e32 v90, 0x3fb8aa3b, v90
	v_exp_f32_e32 v90, v90
	v_bfe_u32 v89, v88, 16, 1
	v_add3_u32 v88, v88, v89, s24
	ds_write_b16_d16_hi v97, v88 offset:15536
	s_waitcnt lgkmcnt(7)
	v_lshlrev_b32_e32 v88, 16, v93
	v_mul_f32_e32 v88, v90, v88
	v_sub_f32_e32 v90, v171, v122
	v_mul_f32_e32 v90, 0x3fb8aa3b, v90
	v_exp_f32_e32 v90, v90
	v_bfe_u32 v89, v88, 16, 1
	v_add3_u32 v88, v88, v89, s24
	ds_write_b16_d16_hi v97, v88 offset:16576
	s_waitcnt lgkmcnt(7)
	v_lshlrev_b32_e32 v88, 16, v94
	v_mul_f32_e32 v88, v90, v88
	v_sub_f32_e32 v90, v171, v123
	v_mul_f32_e32 v90, 0x3fb8aa3b, v90
	v_exp_f32_e32 v90, v90
	v_bfe_u32 v89, v88, 16, 1
	v_add3_u32 v88, v88, v89, s24
	ds_write_b16_d16_hi v97, v88 offset:17616
	s_waitcnt lgkmcnt(7)
	v_lshlrev_b32_e32 v88, 16, v117
	v_mul_f32_e32 v88, v90, v88
	v_sub_f32_e32 v90, v171, v126
	v_mul_f32_e32 v90, 0x3fb8aa3b, v90
	v_exp_f32_e32 v90, v90
	v_bfe_u32 v89, v88, 16, 1
	v_add3_u32 v88, v88, v89, s24
	ds_write_b16_d16_hi v97, v88 offset:18656
	s_waitcnt lgkmcnt(7)
	v_lshlrev_b32_e32 v88, 16, v118
	v_mul_f32_e32 v88, v90, v88
	v_bfe_u32 v89, v88, 16, 1
	v_add3_u32 v88, v88, v89, s24
	ds_write_b16_d16_hi v97, v88 offset:19696
	v_sub_f32_e32 v88, v171, v125
	v_mul_f32_e32 v88, 0x3fb8aa3b, v88
	v_exp_f32_e32 v88, v88
	ds_read_u16 v89, v97 offset:20736
	ds_read_u16 v90, v97 offset:21776
	ds_read_u16 v91, v97 offset:22816
	ds_read_u16 v92, v97 offset:23856
	ds_read_u16 v93, v97 offset:24896
	ds_read_u16 v94, v97 offset:25936
	ds_read_u16 v95, v97 offset:26976
	ds_read_u16 v117, v97 offset:28016
	s_waitcnt lgkmcnt(7)
	v_lshlrev_b32_e32 v89, 16, v89
	v_sub_f32_e32 v118, v171, v124
	v_mul_f32_e32 v88, v88, v89
	v_mul_f32_e32 v118, 0x3fb8aa3b, v118
	v_bfe_u32 v89, v88, 16, 1
	v_exp_f32_e32 v118, v118
	v_add3_u32 v88, v88, v89, s24
	ds_write_b16_d16_hi v97, v88 offset:20736
	s_waitcnt lgkmcnt(7)
	v_lshlrev_b32_e32 v88, 16, v90
	v_sub_f32_e32 v90, v171, v127
	v_mul_f32_e32 v90, 0x3fb8aa3b, v90
	v_mul_f32_e32 v88, v118, v88
	v_exp_f32_e32 v90, v90
	v_bfe_u32 v89, v88, 16, 1
	v_add3_u32 v88, v88, v89, s24
	ds_write_b16_d16_hi v97, v88 offset:21776
	s_waitcnt lgkmcnt(7)
	v_lshlrev_b32_e32 v88, 16, v91
	v_mul_f32_e32 v88, v90, v88
	v_sub_f32_e32 v90, v171, v130
	v_mul_f32_e32 v90, 0x3fb8aa3b, v90
	v_exp_f32_e32 v90, v90
	v_bfe_u32 v89, v88, 16, 1
	v_add3_u32 v88, v88, v89, s24
	ds_write_b16_d16_hi v97, v88 offset:22816
	s_waitcnt lgkmcnt(7)
	v_lshlrev_b32_e32 v88, 16, v92
	v_mul_f32_e32 v88, v90, v88
	v_sub_f32_e32 v90, v171, v131
	v_mul_f32_e32 v90, 0x3fb8aa3b, v90
	v_exp_f32_e32 v90, v90
	v_bfe_u32 v89, v88, 16, 1
	v_add3_u32 v88, v88, v89, s24
	ds_write_b16_d16_hi v97, v88 offset:23856
	s_waitcnt lgkmcnt(7)
	v_lshlrev_b32_e32 v88, 16, v93
	v_mul_f32_e32 v88, v90, v88
	v_sub_f32_e32 v90, v171, v132
	v_mul_f32_e32 v90, 0x3fb8aa3b, v90
	v_exp_f32_e32 v90, v90
	v_bfe_u32 v89, v88, 16, 1
	v_add3_u32 v88, v88, v89, s24
	ds_write_b16_d16_hi v97, v88 offset:24896
	s_waitcnt lgkmcnt(7)
	v_lshlrev_b32_e32 v88, 16, v94
	v_mul_f32_e32 v88, v90, v88
	v_sub_f32_e32 v90, v171, v135
	v_mul_f32_e32 v90, 0x3fb8aa3b, v90
	v_exp_f32_e32 v90, v90
	v_bfe_u32 v89, v88, 16, 1
	v_add3_u32 v88, v88, v89, s24
	ds_write_b16_d16_hi v97, v88 offset:25936
	s_waitcnt lgkmcnt(7)
	v_lshlrev_b32_e32 v88, 16, v95
	v_mul_f32_e32 v88, v90, v88
	v_sub_f32_e32 v90, v171, v139
	v_mul_f32_e32 v90, 0x3fb8aa3b, v90
	v_exp_f32_e32 v90, v90
	v_bfe_u32 v89, v88, 16, 1
	v_add3_u32 v88, v88, v89, s24
	ds_write_b16_d16_hi v97, v88 offset:26976
	s_waitcnt lgkmcnt(7)
	v_lshlrev_b32_e32 v88, 16, v117
	v_mul_f32_e32 v88, v90, v88
	v_bfe_u32 v89, v88, 16, 1
	v_add3_u32 v88, v88, v89, s24
	ds_write_b16_d16_hi v97, v88 offset:28016
	v_sub_f32_e32 v88, v171, v138
	v_mul_f32_e32 v88, 0x3fb8aa3b, v88
	v_exp_f32_e32 v88, v88
	ds_read_u16 v89, v97 offset:29056
	ds_read_u16 v90, v97 offset:30096
	ds_read_u16 v91, v97 offset:31136
	ds_read_u16 v92, v97 offset:32176
	ds_read_u16 v93, v98 offset:62400
	ds_read_u16 v94, v98 offset:63440
	ds_read_u16 v95, v98 offset:64480
	ds_read_u16 v117, v98 offset:65520
	s_waitcnt lgkmcnt(7)
; __device__ __forceinline__ unsigned f2bf(float f) { unsigned u = __builtin_bit_cast(unsigned, f); return (u + 0x7fffu + ((u >> 16) & 1u)) >> 16; }
; __device__ __forceinline__ void phase_gla_kdec(Frame& F) {
;     ...
;             for (int s = 0; s < CH; ++s) { const float kv = bf2f(kt[s * KP + j]);
;                 kt[s * KP + j] = (bf16_t)f2bf(kv * __builtin_amdgcn_exp2f(1.4426950408889634f * (run - gc[s]))); }
	v_lshlrev_b32_e32 v89, 16, v89
	v_sub_f32_e32 v118, v171, v128
	v_mul_f32_e32 v88, v88, v89
	v_mul_f32_e32 v118, 0x3fb8aa3b, v118
	v_bfe_u32 v89, v88, 16, 1
	v_exp_f32_e32 v118, v118
	v_add3_u32 v88, v88, v89, s24
	ds_write_b16_d16_hi v97, v88 offset:29056
	s_waitcnt lgkmcnt(7)
	v_lshlrev_b32_e32 v88, 16, v90
	v_sub_f32_e32 v90, v171, v129
	v_mul_f32_e32 v90, 0x3fb8aa3b, v90
	v_mul_f32_e32 v88, v118, v88
	v_exp_f32_e32 v90, v90
	v_bfe_u32 v89, v88, 16, 1
	v_add3_u32 v88, v88, v89, s24
	ds_write_b16_d16_hi v97, v88 offset:30096
	s_waitcnt lgkmcnt(7)
	v_lshlrev_b32_e32 v88, 16, v91
	v_mul_f32_e32 v88, v90, v88
	v_sub_f32_e32 v90, v171, v133
	v_mul_f32_e32 v90, 0x3fb8aa3b, v90
	v_exp_f32_e32 v90, v90
	v_bfe_u32 v89, v88, 16, 1
	v_add3_u32 v88, v88, v89, s24
	ds_write_b16_d16_hi v97, v88 offset:31136
	s_waitcnt lgkmcnt(7)
	v_lshlrev_b32_e32 v88, 16, v92
	v_mul_f32_e32 v88, v90, v88
	v_bfe_u32 v89, v88, 16, 1
	v_add3_u32 v88, v88, v89, s24
	ds_write_b16_d16_hi v97, v88 offset:32176
	v_sub_f32_e32 v88, v171, v134
	v_mul_f32_e32 v88, 0x3fb8aa3b, v88
	v_exp_f32_e32 v88, v88
	ds_read_u16 v89, v97 offset:33216
	ds_read_u16 v90, v97 offset:34256
	ds_read_u16 v91, v97 offset:35296
	ds_read_u16 v92, v97 offset:36336
	ds_read_u16 v118, v97 offset:37376
	ds_read_u16 v119, v97 offset:38416
	ds_read_u16 v120, v97 offset:39456
	ds_read_u16 v121, v97 offset:40496
	s_waitcnt lgkmcnt(7)
	v_lshlrev_b32_e32 v89, 16, v89
	v_sub_f32_e32 v122, v171, v136
	v_mul_f32_e32 v88, v88, v89
	v_mul_f32_e32 v122, 0x3fb8aa3b, v122
	v_bfe_u32 v89, v88, 16, 1
	v_exp_f32_e32 v122, v122
	v_add3_u32 v88, v88, v89, s24
	ds_write_b16_d16_hi v97, v88 offset:33216
	s_waitcnt lgkmcnt(7)
	v_lshlrev_b32_e32 v88, 16, v90
	v_sub_f32_e32 v90, v171, v137
	v_mul_f32_e32 v90, 0x3fb8aa3b, v90
	v_mul_f32_e32 v88, v122, v88
	v_exp_f32_e32 v90, v90
	v_bfe_u32 v89, v88, 16, 1
	v_add3_u32 v88, v88, v89, s24
	ds_write_b16_d16_hi v97, v88 offset:34256
	s_waitcnt lgkmcnt(7)
	v_lshlrev_b32_e32 v88, 16, v91
	v_mul_f32_e32 v88, v90, v88
	v_sub_f32_e32 v90, v171, v140
	v_mul_f32_e32 v90, 0x3fb8aa3b, v90
	v_exp_f32_e32 v90, v90
	v_bfe_u32 v89, v88, 16, 1
	v_add3_u32 v88, v88, v89, s24
	ds_write_b16_d16_hi v97, v88 offset:35296
	s_waitcnt lgkmcnt(7)
	v_lshlrev_b32_e32 v88, 16, v92
	v_mul_f32_e32 v88, v90, v88
	v_sub_f32_e32 v90, v171, v141
	v_mul_f32_e32 v90, 0x3fb8aa3b, v90
	v_exp_f32_e32 v90, v90
	v_bfe_u32 v89, v88, 16, 1
	v_add3_u32 v88, v88, v89, s24
	ds_write_b16_d16_hi v97, v88 offset:36336
	s_waitcnt lgkmcnt(7)
	v_lshlrev_b32_e32 v88, 16, v118
	v_mul_f32_e32 v88, v90, v88
	v_sub_f32_e32 v90, v171, v142
	v_mul_f32_e32 v90, 0x3fb8aa3b, v90
	v_exp_f32_e32 v90, v90
	v_bfe_u32 v89, v88, 16, 1
	v_add3_u32 v88, v88, v89, s24
	ds_write_b16_d16_hi v97, v88 offset:37376
	s_waitcnt lgkmcnt(7)
	v_lshlrev_b32_e32 v88, 16, v119
	v_mul_f32_e32 v88, v90, v88
	v_sub_f32_e32 v90, v171, v143
	v_mul_f32_e32 v90, 0x3fb8aa3b, v90
	v_exp_f32_e32 v90, v90
	v_bfe_u32 v89, v88, 16, 1
	v_add3_u32 v88, v88, v89, s24
	ds_write_b16_d16_hi v97, v88 offset:38416
	s_waitcnt lgkmcnt(7)
	v_lshlrev_b32_e32 v88, 16, v120
	v_mul_f32_e32 v88, v90, v88
	v_sub_f32_e32 v90, v171, v144
	v_mul_f32_e32 v90, 0x3fb8aa3b, v90
	v_exp_f32_e32 v90, v90
	v_bfe_u32 v89, v88, 16, 1
	v_add3_u32 v88, v88, v89, s24
	ds_write_b16_d16_hi v97, v88 offset:39456
	s_waitcnt lgkmcnt(7)
	v_lshlrev_b32_e32 v88, 16, v121
	v_mul_f32_e32 v88, v90, v88
	v_bfe_u32 v89, v88, 16, 1
	v_add3_u32 v88, v88, v89, s24
	ds_write_b16_d16_hi v97, v88 offset:40496
	v_sub_f32_e32 v88, v171, v145
	v_mul_f32_e32 v88, 0x3fb8aa3b, v88
	v_exp_f32_e32 v88, v88
	ds_read_u16 v89, v97 offset:41536
	ds_read_u16 v90, v97 offset:42576
	ds_read_u16 v91, v97 offset:43616
	ds_read_u16 v92, v97 offset:44656
	ds_read_u16 v118, v97 offset:45696
	ds_read_u16 v119, v97 offset:46736
	ds_read_u16 v120, v97 offset:47776
	ds_read_u16 v121, v97 offset:48816
	s_waitcnt lgkmcnt(7)
	v_lshlrev_b32_e32 v89, 16, v89
	v_sub_f32_e32 v122, v171, v146
	v_mul_f32_e32 v88, v88, v89
	v_mul_f32_e32 v122, 0x3fb8aa3b, v122
	v_bfe_u32 v89, v88, 16, 1
	v_exp_f32_e32 v122, v122
	v_add3_u32 v88, v88, v89, s24
	ds_write_b16_d16_hi v97, v88 offset:41536
	s_waitcnt lgkmcnt(7)
	v_lshlrev_b32_e32 v88, 16, v90
	v_sub_f32_e32 v90, v171, v147
	v_mul_f32_e32 v90, 0x3fb8aa3b, v90
	v_mul_f32_e32 v88, v122, v88
	v_exp_f32_e32 v90, v90
	v_bfe_u32 v89, v88, 16, 1
	v_add3_u32 v88, v88, v89, s24
	ds_write_b16_d16_hi v97, v88 offset:42576
	s_waitcnt lgkmcnt(7)
	v_lshlrev_b32_e32 v88, 16, v91
	v_mul_f32_e32 v88, v90, v88
	v_sub_f32_e32 v90, v171, v148
	v_mul_f32_e32 v90, 0x3fb8aa3b, v90
	v_exp_f32_e32 v90, v90
	v_bfe_u32 v89, v88, 16, 1
	v_add3_u32 v88, v88, v89, s24
	ds_write_b16_d16_hi v97, v88 offset:43616
	s_waitcnt lgkmcnt(7)
	v_lshlrev_b32_e32 v88, 16, v92
	v_mul_f32_e32 v88, v90, v88
	v_sub_f32_e32 v90, v171, v149
	v_mul_f32_e32 v90, 0x3fb8aa3b, v90
	v_exp_f32_e32 v90, v90
	v_bfe_u32 v89, v88, 16, 1
	v_add3_u32 v88, v88, v89, s24
	ds_write_b16_d16_hi v97, v88 offset:44656
	s_waitcnt lgkmcnt(7)
	v_lshlrev_b32_e32 v88, 16, v118
	v_mul_f32_e32 v88, v90, v88
	v_sub_f32_e32 v90, v171, v150
	v_mul_f32_e32 v90, 0x3fb8aa3b, v90
	v_exp_f32_e32 v90, v90
	v_bfe_u32 v89, v88, 16, 1
	v_add3_u32 v88, v88, v89, s24
	ds_write_b16_d16_hi v97, v88 offset:45696
	s_waitcnt lgkmcnt(7)
	v_lshlrev_b32_e32 v88, 16, v119
	v_mul_f32_e32 v88, v90, v88
	v_sub_f32_e32 v90, v171, v151
	v_mul_f32_e32 v90, 0x3fb8aa3b, v90
	v_exp_f32_e32 v90, v90
	v_bfe_u32 v89, v88, 16, 1
	v_add3_u32 v88, v88, v89, s24
	ds_write_b16_d16_hi v97, v88 offset:46736
	s_waitcnt lgkmcnt(7)
; __device__ __forceinline__ unsigned f2bf(float f) { unsigned u = __builtin_bit_cast(unsigned, f); return (u + 0x7fffu + ((u >> 16) & 1u)) >> 16; }
; __device__ __forceinline__ void phase_gla_kdec(Frame& F) {
;     ...
;             for (int s = 0; s < CH; ++s) { const float kv = bf2f(kt[s * KP + j]);
;                 kt[s * KP + j] = (bf16_t)f2bf(kv * __builtin_amdgcn_exp2f(1.4426950408889634f * (run - gc[s]))); }
;             DEC[(size_t)unit * QKW + j] = __builtin_amdgcn_exp2f(1.4426950408889634f * run); }
	v_lshlrev_b32_e32 v88, 16, v120
	v_mul_f32_e32 v88, v90, v88
	v_sub_f32_e32 v90, v171, v152
	v_mul_f32_e32 v90, 0x3fb8aa3b, v90
	v_exp_f32_e32 v90, v90
	v_bfe_u32 v89, v88, 16, 1
	v_add3_u32 v88, v88, v89, s24
	ds_write_b16_d16_hi v97, v88 offset:47776
	s_waitcnt lgkmcnt(7)
	v_lshlrev_b32_e32 v88, 16, v121
	v_mul_f32_e32 v88, v90, v88
	v_bfe_u32 v89, v88, 16, 1
	v_add3_u32 v88, v88, v89, s24
	ds_write_b16_d16_hi v97, v88 offset:48816
	v_sub_f32_e32 v88, v171, v153
	v_mul_f32_e32 v88, 0x3fb8aa3b, v88
	v_exp_f32_e32 v88, v88
	ds_read_u16 v89, v97 offset:49856
	ds_read_u16 v90, v97 offset:50896
	ds_read_u16 v91, v97 offset:51936
	ds_read_u16 v92, v97 offset:52976
	ds_read_u16 v118, v97 offset:54016
	ds_read_u16 v119, v97 offset:55056
	ds_read_u16 v120, v97 offset:56096
	ds_read_u16 v121, v97 offset:57136
	s_waitcnt lgkmcnt(7)
	v_lshlrev_b32_e32 v89, 16, v89
	v_sub_f32_e32 v122, v171, v154
	v_mul_f32_e32 v88, v88, v89
	v_mul_f32_e32 v122, 0x3fb8aa3b, v122
	v_bfe_u32 v89, v88, 16, 1
	v_exp_f32_e32 v122, v122
	v_add3_u32 v88, v88, v89, s24
	ds_write_b16_d16_hi v97, v88 offset:49856
	s_waitcnt lgkmcnt(7)
	v_lshlrev_b32_e32 v88, 16, v90
	v_sub_f32_e32 v90, v171, v155
	v_mul_f32_e32 v90, 0x3fb8aa3b, v90
	v_mul_f32_e32 v88, v122, v88
	v_exp_f32_e32 v90, v90
	v_bfe_u32 v89, v88, 16, 1
	v_add3_u32 v88, v88, v89, s24
	ds_write_b16_d16_hi v97, v88 offset:50896
	s_waitcnt lgkmcnt(7)
	v_lshlrev_b32_e32 v88, 16, v91
	v_mul_f32_e32 v88, v90, v88
	v_sub_f32_e32 v90, v171, v156
	v_mul_f32_e32 v90, 0x3fb8aa3b, v90
	v_exp_f32_e32 v90, v90
	v_bfe_u32 v89, v88, 16, 1
	v_add3_u32 v88, v88, v89, s24
	ds_write_b16_d16_hi v97, v88 offset:51936
	s_waitcnt lgkmcnt(7)
	v_lshlrev_b32_e32 v88, 16, v92
	v_mul_f32_e32 v88, v90, v88
	v_sub_f32_e32 v90, v171, v157
	v_mul_f32_e32 v90, 0x3fb8aa3b, v90
	v_exp_f32_e32 v90, v90
	v_bfe_u32 v89, v88, 16, 1
	v_add3_u32 v88, v88, v89, s24
	ds_write_b16_d16_hi v97, v88 offset:52976
	s_waitcnt lgkmcnt(7)
	v_lshlrev_b32_e32 v88, 16, v118
	v_mul_f32_e32 v88, v90, v88
	v_sub_f32_e32 v90, v171, v158
	v_mul_f32_e32 v90, 0x3fb8aa3b, v90
	v_exp_f32_e32 v90, v90
	v_bfe_u32 v89, v88, 16, 1
	v_add3_u32 v88, v88, v89, s24
	ds_write_b16_d16_hi v97, v88 offset:54016
	s_waitcnt lgkmcnt(7)
	v_lshlrev_b32_e32 v88, 16, v119
	v_mul_f32_e32 v88, v90, v88
	v_sub_f32_e32 v90, v171, v159
	v_mul_f32_e32 v90, 0x3fb8aa3b, v90
	v_exp_f32_e32 v90, v90
	v_bfe_u32 v89, v88, 16, 1
	v_add3_u32 v88, v88, v89, s24
	ds_write_b16_d16_hi v97, v88 offset:55056
	s_waitcnt lgkmcnt(7)
	v_lshlrev_b32_e32 v88, 16, v120
	v_mul_f32_e32 v88, v90, v88
	v_sub_f32_e32 v90, v171, v160
	v_mul_f32_e32 v90, 0x3fb8aa3b, v90
	v_exp_f32_e32 v90, v90
	v_bfe_u32 v89, v88, 16, 1
	v_add3_u32 v88, v88, v89, s24
	ds_write_b16_d16_hi v97, v88 offset:56096
	s_waitcnt lgkmcnt(7)
	v_lshlrev_b32_e32 v88, 16, v121
	v_mul_f32_e32 v88, v90, v88
	v_bfe_u32 v89, v88, 16, 1
	v_add3_u32 v88, v88, v89, s24
	ds_write_b16_d16_hi v97, v88 offset:57136
	v_sub_f32_e32 v88, v171, v161
	v_mul_f32_e32 v88, 0x3fb8aa3b, v88
	v_exp_f32_e32 v88, v88
	ds_read_u16 v89, v97 offset:58176
	ds_read_u16 v90, v97 offset:59216
	ds_read_u16 v91, v97 offset:60256
	ds_read_u16 v92, v97 offset:61296
	ds_read_u16 v118, v97 offset:62336
	ds_read_u16 v119, v97 offset:63376
	ds_read_u16 v120, v97 offset:64416
	ds_read_u16 v121, v97 offset:65456
	s_waitcnt lgkmcnt(7)
	v_lshlrev_b32_e32 v89, 16, v89
	v_sub_f32_e32 v122, v171, v162
	v_mul_f32_e32 v88, v88, v89
	v_mul_f32_e32 v122, 0x3fb8aa3b, v122
	v_bfe_u32 v89, v88, 16, 1
	v_exp_f32_e32 v122, v122
	v_add3_u32 v88, v88, v89, s24
	ds_write_b16_d16_hi v97, v88 offset:58176
	s_waitcnt lgkmcnt(7)
	v_lshlrev_b32_e32 v88, 16, v90
	v_sub_f32_e32 v90, v171, v163
	v_mul_f32_e32 v90, 0x3fb8aa3b, v90
	v_mul_f32_e32 v88, v122, v88
	v_exp_f32_e32 v90, v90
	v_bfe_u32 v89, v88, 16, 1
	v_add3_u32 v88, v88, v89, s24
	ds_write_b16_d16_hi v97, v88 offset:59216
	s_waitcnt lgkmcnt(7)
	v_lshlrev_b32_e32 v88, 16, v91
	v_mul_f32_e32 v88, v90, v88
	v_sub_f32_e32 v90, v171, v164
	v_mul_f32_e32 v90, 0x3fb8aa3b, v90
	v_exp_f32_e32 v90, v90
	v_bfe_u32 v89, v88, 16, 1
	v_add3_u32 v88, v88, v89, s24
	ds_write_b16_d16_hi v97, v88 offset:60256
	s_waitcnt lgkmcnt(7)
	v_lshlrev_b32_e32 v88, 16, v92
	v_mul_f32_e32 v88, v90, v88
	v_sub_f32_e32 v90, v171, v165
	v_mul_f32_e32 v90, 0x3fb8aa3b, v90
	v_exp_f32_e32 v90, v90
	v_bfe_u32 v89, v88, 16, 1
	v_add3_u32 v88, v88, v89, s24
	ds_write_b16_d16_hi v97, v88 offset:61296
	s_waitcnt lgkmcnt(7)
	v_lshlrev_b32_e32 v88, 16, v118
	v_mul_f32_e32 v88, v90, v88
	v_sub_f32_e32 v90, v171, v166
	v_mul_f32_e32 v90, 0x3fb8aa3b, v90
	v_exp_f32_e32 v90, v90
	v_bfe_u32 v89, v88, 16, 1
	v_add3_u32 v88, v88, v89, s24
	ds_write_b16_d16_hi v97, v88 offset:62336
	s_waitcnt lgkmcnt(7)
	v_lshlrev_b32_e32 v88, 16, v119
	v_mul_f32_e32 v88, v90, v88
	v_sub_f32_e32 v90, v171, v167
	v_mul_f32_e32 v90, 0x3fb8aa3b, v90
	v_exp_f32_e32 v90, v90
	v_bfe_u32 v89, v88, 16, 1
	v_add3_u32 v88, v88, v89, s24
	ds_write_b16_d16_hi v97, v88 offset:63376
	s_waitcnt lgkmcnt(7)
	v_lshlrev_b32_e32 v88, 16, v120
	v_mul_f32_e32 v88, v90, v88
	v_sub_f32_e32 v90, v171, v170
	v_mul_f32_e32 v90, 0x3fb8aa3b, v90
	v_exp_f32_e32 v90, v90
	v_bfe_u32 v89, v88, 16, 1
	v_add3_u32 v88, v88, v89, s24
	ds_write_b16_d16_hi v97, v88 offset:64416
	s_waitcnt lgkmcnt(7)
	v_lshlrev_b32_e32 v88, 16, v121
	v_mul_f32_e32 v88, v90, v88
	v_sub_f32_e32 v90, v171, v169
	v_mul_f32_e32 v90, 0x3fb8aa3b, v90
	v_exp_f32_e32 v90, v90
	v_bfe_u32 v89, v88, 16, 1
	v_add3_u32 v88, v88, v89, s24
	ds_write_b16_d16_hi v97, v88 offset:65456
	v_lshlrev_b32_e32 v88, 16, v93
	v_mul_f32_e32 v88, v90, v88
	v_sub_f32_e32 v90, v171, v168
	v_mul_f32_e32 v90, 0x3fb8aa3b, v90
	v_exp_f32_e32 v90, v90
	v_bfe_u32 v89, v88, 16, 1
	v_add3_u32 v88, v88, v89, s24
	ds_write_b16_d16_hi v98, v88 offset:62400
	v_lshlrev_b32_e32 v88, 16, v94
	v_mul_f32_e32 v88, v90, v88
	v_sub_f32_e32 v90, v171, v172
	v_mul_f32_e32 v90, 0x3fb8aa3b, v90
	v_exp_f32_e32 v90, v90
	v_bfe_u32 v89, v88, 16, 1
	v_add3_u32 v88, v88, v89, s24
	ds_write_b16_d16_hi v98, v88 offset:63440
	v_lshlrev_b32_e32 v88, 16, v95
	v_mul_f32_e32 v88, v90, v88
	v_sub_f32_e32 v90, v171, v171
	v_mul_f32_e32 v90, 0x3fb8aa3b, v90
	v_exp_f32_e32 v90, v90
	v_bfe_u32 v89, v88, 16, 1
	v_add3_u32 v88, v88, v89, s24
	ds_write_b16_d16_hi v98, v88 offset:64480
	v_lshlrev_b32_e32 v88, 16, v117
	v_mul_f32_e32 v88, v90, v88
	v_bfe_u32 v89, v88, 16, 1
	v_add3_u32 v88, v88, v89, s24
	v_mul_f32_e32 v89, 0x3fb8aa3b, v171
	v_exp_f32_e32 v90, v89
	ds_write_b16_d16_hi v98, v88 offset:65520
	v_lshl_add_u64 v[88:89], v[28:29], 0, s[0:1]
	v_mov_b64_e32 v[92:93], v[82:83]
	global_store_dword v[88:89], v90, off
	v_mov_b64_e32 v[88:89], v[86:87]
	v_mov_b64_e32 v[90:91], v[84:85]
	v_mov_b64_e32 v[94:95], v[80:81]
	s_mov_b32 s0, 0
	s_branch .LBB0_819
; #define LAS __attribute__((address_space(3)))
; #define GAS __attribute__((address_space(1)))
; __device__ __forceinline__ unsigned cvt_pk_bf16(float lo, float hi) { const f32x2 v = {lo, hi}; const bf16x2_t b = __builtin_convertvector(v, bf16x2_t); return __builtin_bit_cast(unsigned, b); }
; __device__ __forceinline__ v4i16_t lds_tr16(const LAS unsigned char* p) { return __builtin_amdgcn_ds_read_tr16_b64_v4i16((LAS v4i16_t*)p); }
; __device__ __forceinline__ void phase_gla_kdec(Frame& F) {
;     ...
;             f32x4 acc[2][8];
; #pragma unroll
;             for (int e = 0; e < 2; ++e)
; #pragma unroll
;                 for (int dt = 0; dt < 8; ++dt) acc[e][dt] = (f32x4){0.f, 0.f, 0.f, 0.f};
; #pragma unroll
;             for (int ks = 0; ks < 2; ++ks) { const int r0 = 32 * ks + 8 * g + q4; bf16x8 vf[2];
; #pragma unroll
;                 for (int e = 0; e < 2; ++e) { const v4i16_t lo = lds_tr16((const LAS unsigned char*)(vt + r0 * VP + 16 * (2 * w + e) + 4 * p4)), hi = lds_tr16((const LAS unsigned char*)(vt + (r0 + 4) * VP + 16 * (2 * w + e) + 4 * p4));
;                     vf[e] = (bf16x8){lo[0], lo[1], lo[2], lo[3], hi[0], hi[1], hi[2], hi[3]}; }
; #pragma unroll
;                 for (int dt = 0; dt < 8; ++dt) { const v4i16_t lo = lds_tr16((const LAS unsigned char*)(kt + r0 * KP + hh * DK + 16 * dt + 4 * p4)), hi = lds_tr16((const LAS unsigned char*)(kt + (r0 + 4) * KP + hh * DK + 16 * dt + 4 * p4));
;                     const bf16x8 kf = (bf16x8){lo[0], lo[1], lo[2], lo[3], hi[0], hi[1], hi[2], hi[3]};
; #pragma unroll
;                     for (int e = 0; e < 2; ++e) acc[e][dt] = __builtin_amdgcn_mfma_f32_16x16x32_bf16(kf, vf[e], acc[e][dt], 0, 0, 0); } }
;             bf16_t* kvo = KVF + ((size_t)(unit * NH + hh) * 16 + 2 * w) * 4 * 512 + lane * 8;
; #pragma unroll
;             for (int e = 0; e < 2; ++e)
; #pragma unroll
;                 for (int dp = 0; dp < 4; ++dp) { u32x4 o; o.x = cvt_pk_bf16(acc[e][2 * dp][0], acc[e][2 * dp][1]); o.y = cvt_pk_bf16(acc[e][2 * dp][2], acc[e][2 * dp][3]); o.z = cvt_pk_bf16(acc[e][2 * dp + 1][0], acc[e][2 * dp + 1][1]); o.w = cvt_pk_bf16(acc[e][2 * dp + 1][2], acc[e][2 * dp + 1][3]);
;                     *(GAS u32x4*)(kvo + (e * 4 + dp) * 512) = o; }
.LBB0_818:
	v_add_u32_e32 v117, s0, v115
	s_waitcnt lgkmcnt(0)
	s_barrier
	ds_read_b64_tr_b16 v[120:121], v117 offset:8256
	ds_read_b64_tr_b16 v[118:119], v117 offset:4096
	ds_read_b64_tr_b16 v[124:125], v99 offset:2112
	ds_read_b64_tr_b16 v[122:123], v99
	ds_read_b64_tr_b16 v[128:129], v99 offset:2144
	ds_read_b64_tr_b16 v[126:127], v99 offset:32
	ds_read_b64_tr_b16 v[130:131], v117 offset:4128
	ds_read_b64_tr_b16 v[134:135], v117 offset:4160
	ds_read_b64_tr_b16 v[138:139], v117 offset:4192
	ds_read_b64_tr_b16 v[132:133], v117 offset:8288
	ds_read_b64_tr_b16 v[136:137], v117 offset:8320
	ds_read_b64_tr_b16 v[140:141], v117 offset:8352
	s_waitcnt lgkmcnt(8)
	v_mfma_f32_16x16x32_bf16 v[142:145], v[118:121], v[122:125], 0
	ds_read_b64_tr_b16 v[154:155], v117 offset:4224
	ds_read_b64_tr_b16 v[156:157], v117 offset:8384
	ds_read_b64_tr_b16 v[162:163], v117 offset:4256
	ds_read_b64_tr_b16 v[166:167], v117 offset:4288
	ds_read_b64_tr_b16 v[170:171], v117 offset:4320
	ds_read_b64_tr_b16 v[164:165], v117 offset:8416
	ds_read_b64_tr_b16 v[168:169], v117 offset:8448
	ds_read_b64_tr_b16 v[172:173], v117 offset:8480
	s_waitcnt lgkmcnt(10)
	v_mfma_f32_16x16x32_bf16 v[146:149], v[130:133], v[122:125], 0
	ds_read_b64_tr_b16 v[188:189], v100 offset:2112
	ds_read_b64_tr_b16 v[186:187], v100
	ds_read_b64_tr_b16 v[192:193], v100 offset:2144
	ds_read_b64_tr_b16 v[190:191], v100 offset:32
	ds_read_b64_tr_b16 v[194:195], v117 offset:37376
	ds_read_b64_tr_b16 v[198:199], v117 offset:37408
	ds_read_b64_tr_b16 v[202:203], v117 offset:37440
	ds_read_b64_tr_b16 v[206:207], v117 offset:37472
	ds_read_b64_tr_b16 v[196:197], v117 offset:41536
	ds_read_b64_tr_b16 v[200:201], v117 offset:41568
	ds_read_b64_tr_b16 v[204:205], v117 offset:41600
	ds_read_b64_tr_b16 v[208:209], v117 offset:41632
	s_waitcnt lgkmcnt(14)
	v_mfma_f32_16x16x32_bf16 v[150:153], v[134:137], v[122:125], 0
	s_ashr_i32 s17, s16, 31
	s_lshl_b64 s[4:5], s[16:17], 16
	v_lshl_add_u64 v[222:223], v[34:35], 0, s[4:5]
	v_mfma_f32_16x16x32_bf16 v[158:161], v[138:141], v[122:125], 0
	s_add_i32 s16, s16, 1
	s_addk_i32 s0, 0x100
	v_lshl_add_u64 v[94:95], v[94:95], 0, s[12:13]
	s_waitcnt lgkmcnt(3)
	v_mfma_f32_16x16x32_bf16 v[142:145], v[194:197], v[186:189], v[142:145]
	v_lshl_add_u64 v[92:93], v[92:93], 0, s[12:13]
	v_lshl_add_u64 v[90:91], v[90:91], 0, s[12:13]
	s_cmpk_eq_i32 s0, 0x400
	s_waitcnt lgkmcnt(2)
	v_mfma_f32_16x16x32_bf16 v[146:149], v[198:201], v[186:189], v[146:149]
	v_lshl_add_u64 v[88:89], v[88:89], 0, s[12:13]
	s_nop 1
	v_cvt_pk_bf16_f32 v142, v142, v143
	v_cvt_pk_bf16_f32 v143, v144, v145
	v_mfma_f32_16x16x32_bf16 v[118:121], v[118:121], v[126:129], 0
	v_mfma_f32_16x16x32_bf16 v[130:133], v[130:133], v[126:129], 0
	s_nop 0
	v_cvt_pk_bf16_f32 v144, v146, v147
	v_cvt_pk_bf16_f32 v145, v148, v149
	v_mfma_f32_16x16x32_bf16 v[134:137], v[134:137], v[126:129], 0
	v_mfma_f32_16x16x32_bf16 v[138:141], v[138:141], v[126:129], 0
	v_mfma_f32_16x16x32_bf16 v[174:177], v[154:157], v[122:125], 0
	v_mfma_f32_16x16x32_bf16 v[154:157], v[154:157], v[126:129], 0
	v_mfma_f32_16x16x32_bf16 v[178:181], v[162:165], v[122:125], 0
	v_mfma_f32_16x16x32_bf16 v[162:165], v[162:165], v[126:129], 0
	v_mfma_f32_16x16x32_bf16 v[182:185], v[166:169], v[122:125], 0
	v_mfma_f32_16x16x32_bf16 v[166:169], v[166:169], v[126:129], 0
	v_mfma_f32_16x16x32_bf16 v[122:125], v[170:173], v[122:125], 0
	v_mfma_f32_16x16x32_bf16 v[126:129], v[170:173], v[126:129], 0
	ds_read_b64_tr_b16 v[170:171], v117 offset:37504
	ds_read_b64_tr_b16 v[210:211], v117 offset:37536
	ds_read_b64_tr_b16 v[214:215], v117 offset:37568
	ds_read_b64_tr_b16 v[218:219], v117 offset:37600
	ds_read_b64_tr_b16 v[172:173], v117 offset:41664
	ds_read_b64_tr_b16 v[212:213], v117 offset:41696
	ds_read_b64_tr_b16 v[216:217], v117 offset:41728
	ds_read_b64_tr_b16 v[220:221], v117 offset:41760
	global_store_dwordx4 v[222:223], v[142:145], off
	s_waitcnt lgkmcnt(9)
	v_mfma_f32_16x16x32_bf16 v[150:153], v[202:205], v[186:189], v[150:153]
	s_waitcnt lgkmcnt(8)
	v_mfma_f32_16x16x32_bf16 v[158:161], v[206:209], v[186:189], v[158:161]
	s_waitcnt lgkmcnt(3)
	v_mfma_f32_16x16x32_bf16 v[146:149], v[170:173], v[186:189], v[174:177]
	s_nop 3
	v_cvt_pk_bf16_f32 v142, v150, v151
	v_cvt_pk_bf16_f32 v143, v152, v153
	v_cvt_pk_bf16_f32 v144, v158, v159
	s_waitcnt lgkmcnt(2)
	v_mfma_f32_16x16x32_bf16 v[150:153], v[210:213], v[186:189], v[178:181]
	v_cvt_pk_bf16_f32 v145, v160, v161
	global_store_dwordx4 v[222:223], v[142:145], off offset:1024
	s_waitcnt lgkmcnt(0)
	v_mfma_f32_16x16x32_bf16 v[122:125], v[218:221], v[186:189], v[122:125]
	v_cvt_pk_bf16_f32 v142, v146, v147
	v_cvt_pk_bf16_f32 v143, v148, v149
	s_nop 1
	v_cvt_pk_bf16_f32 v144, v150, v151
	v_cvt_pk_bf16_f32 v145, v152, v153
	global_store_dwordx4 v[222:223], v[142:145], off offset:2048
	v_mfma_f32_16x16x32_bf16 v[118:121], v[194:197], v[190:193], v[118:121]
	s_nop 0
	v_cvt_pk_bf16_f32 v144, v122, v123
	v_cvt_pk_bf16_f32 v145, v124, v125
	v_mfma_f32_16x16x32_bf16 v[122:125], v[198:201], v[190:193], v[130:133]
	v_mfma_f32_16x16x32_bf16 v[130:133], v[170:173], v[190:193], v[154:157]
	s_nop 2
	v_cvt_pk_bf16_f32 v118, v118, v119
	v_cvt_pk_bf16_f32 v119, v120, v121
	s_nop 1
	v_cvt_pk_bf16_f32 v120, v122, v123
	v_cvt_pk_bf16_f32 v121, v124, v125
	v_mfma_f32_16x16x32_bf16 v[122:125], v[202:205], v[190:193], v[134:137]
	s_nop 2
	v_add_co_u32_e32 v134, vcc, s18, v222
	v_mfma_f32_16x16x32_bf16 v[146:149], v[214:217], v[186:189], v[182:185]
	s_nop 0
	v_addc_co_u32_e32 v135, vcc, 0, v223, vcc
	global_store_dwordx4 v[134:135], v[118:121], off
	v_cvt_pk_bf16_f32 v122, v122, v123
	v_cvt_pk_bf16_f32 v123, v124, v125
	v_mfma_f32_16x16x32_bf16 v[118:121], v[206:209], v[190:193], v[138:141]
	s_nop 1
	v_cvt_pk_bf16_f32 v142, v146, v147
	v_cvt_pk_bf16_f32 v143, v148, v149
	global_store_dwordx4 v[222:223], v[142:145], off offset:3072
	s_nop 2
	v_cvt_pk_bf16_f32 v124, v118, v119
	v_cvt_pk_bf16_f32 v125, v120, v121
	global_store_dwordx4 v[134:135], v[122:125], off offset:1024
	v_cvt_pk_bf16_f32 v118, v130, v131
	v_cvt_pk_bf16_f32 v119, v132, v133
	v_mfma_f32_16x16x32_bf16 v[120:123], v[210:213], v[190:193], v[162:165]
	s_nop 7
	v_cvt_pk_bf16_f32 v120, v120, v121
	v_cvt_pk_bf16_f32 v121, v122, v123
	v_mfma_f32_16x16x32_bf16 v[122:125], v[214:217], v[190:193], v[166:169]
	global_store_dwordx4 v[134:135], v[118:121], off offset:2048
	s_nop 6
	v_cvt_pk_bf16_f32 v118, v122, v123
	v_mfma_f32_16x16x32_bf16 v[120:123], v[218:221], v[190:193], v[126:129]
	v_cvt_pk_bf16_f32 v119, v124, v125
	s_nop 6
	v_cvt_pk_bf16_f32 v120, v120, v121
	v_cvt_pk_bf16_f32 v121, v122, v123
	global_store_dwordx4 v[134:135], v[118:121], off offset:3072
	s_cbranch_scc1 .LBB0_816

; __device__ __forceinline__ unsigned xb_add(unsigned* p, unsigned v) { return __hip_atomic_fetch_add(p, v, __ATOMIC_RELAXED, __HIP_MEMORY_SCOPE_AGENT); }
;     ...
;             const unsigned old = xb_add(&bar[XB_XSUB(b.x)], 1u);
;             gen_ = old / nloc;
;             if (old + 1u == (gen_ + 1u) * nloc) {
;                 if (!wt_only) __builtin_amdgcn_fence(__ATOMIC_RELEASE, "agent");
;                 asm volatile("s_waitcnt vmcnt(0)" ::: "memory");
;                 __hip_atomic_store(&bar[XB_XGEN(b.x)], gen_ + 1u, __ATOMIC_RELAXED, __HIP_MEMORY_SCOPE_AGENT);
.LBB0_843:
	s_or_b64 exec, exec, s[18:19]
	v_cvt_f32_u32_e32 v4, v1
	s_waitcnt vmcnt(0)
	v_readfirstlane_b32 s0, v3
	v_sub_u32_e32 v3, 0, v1
	v_rcp_iflag_f32_e32 v4, v4
	v_add_u32_e32 v5, s0, v2
	v_mul_f32_e32 v4, 0x4f7ffffe, v4
	v_cvt_u32_f32_e32 v4, v4
	v_mul_lo_u32 v2, v3, v4
	v_mul_hi_u32 v2, v4, v2
	v_add_u32_e32 v2, v4, v2
	v_mul_hi_u32 v2, v5, v2
	v_mul_lo_u32 v3, v2, v1
	v_sub_u32_e32 v3, v5, v3
	v_add_u32_e32 v4, 1, v2
	v_cmp_ge_u32_e32 vcc, v3, v1
	s_nop 1
	v_cndmask_b32_e32 v2, v2, v4, vcc
	v_sub_u32_e32 v4, v3, v1
	v_cndmask_b32_e32 v3, v3, v4, vcc
	v_add_u32_e32 v4, 1, v2
	v_cmp_ge_u32_e32 vcc, v3, v1
	s_nop 1
	v_cndmask_b32_e32 v2, v2, v4, vcc
	v_add_u32_e32 v3, 1, v2
	v_add_u32_e32 v4, 1, v5
	v_mul_lo_u32 v1, v3, v1
	v_cmp_eq_u32_e32 vcc, v4, v1
	s_and_saveexec_b64 s[16:17], vcc
	s_cbranch_execz .LBB0_845
	buffer_wbl2 sc1
	s_waitcnt vmcnt(0)
	v_mov_b32_e32 v1, 0x2000
	global_store_dword v1, v3, s[14:15] offset:1024 sc1

; #define LAS __attribute__((address_space(3)))
; #define GAS __attribute__((address_space(1)))
; __device__ __forceinline__ unsigned cvt_pk_bf16(float lo, float hi) { const f32x2 v = {lo, hi}; const bf16x2_t b = __builtin_convertvector(v, bf16x2_t); return __builtin_bit_cast(unsigned, b); }
; __device__ __forceinline__ void phase_gla_escan(Frame& F) {
;     ...
;         for (int n = 0; n < NCK; ++n) {
;             const u32x4 kv = *(const GAS u32x4*)(kp + (size_t)n * SLABP * 512); const f32x4 d0 = *(const LAS f32x4*)(dl + n * 32 + 4 * g), d1 = *(const LAS f32x4*)(dl + n * 32 + 16 + 4 * g);
;             const f32x4 k0 = (f32x4){__builtin_bit_cast(float, kv.x << 16), __builtin_bit_cast(float, kv.x & 0xffff0000u), __builtin_bit_cast(float, kv.y << 16), __builtin_bit_cast(float, kv.y & 0xffff0000u)};
;             const f32x4 k1 = (f32x4){__builtin_bit_cast(float, kv.z << 16), __builtin_bit_cast(float, kv.z & 0xffff0000u), __builtin_bit_cast(float, kv.w << 16), __builtin_bit_cast(float, kv.w & 0xffff0000u)};
;             S0 = S0 * d0 + k0; S1 = S1 * d1 + k1;
;             u32x4 o; o.x = cvt_pk_bf16(S0[0], S0[1]); o.y = cvt_pk_bf16(S0[2], S0[3]); o.z = cvt_pk_bf16(S1[0], S1[1]); o.w = cvt_pk_bf16(S1[2], S1[3]); *(GAS u32x4*)(kp + (size_t)n * SLABP * 512) = o;
;         }
.LBB0_867:
	v_lshl_add_u64 v[78:79], v[68:69], 0, s[18:19]
	v_add_co_u32_e64 v140, s[10:11], s5, v78
	v_add_co_u32_e32 v138, vcc, 0xa000000, v78
	s_nop 0
	v_addc_co_u32_e64 v141, s[10:11], 0, v79, s[10:11]
	v_add_co_u32_e64 v142, s[10:11], s6, v78
	v_addc_co_u32_e32 v139, vcc, 0, v79, vcc
	s_nop 0
	v_addc_co_u32_e64 v143, s[10:11], 0, v79, s[10:11]
	v_add_co_u32_e64 v144, s[10:11], s7, v78
	ds_read_b128 v[4:7], v89
	ds_read_b128 v[0:3], v89 offset:64
	ds_read_b128 v[12:15], v89 offset:128
	ds_read_b128 v[8:11], v89 offset:192
	ds_read_b128 v[20:23], v89 offset:256
	ds_read_b128 v[16:19], v89 offset:320
	ds_read_b128 v[28:31], v89 offset:384
	ds_read_b128 v[24:27], v89 offset:448
	ds_read_b128 v[36:39], v89 offset:512
	ds_read_b128 v[32:35], v89 offset:576
	ds_read_b128 v[44:47], v89 offset:640
	ds_read_b128 v[40:43], v89 offset:704
	ds_read_b128 v[90:93], v89 offset:768
	ds_read_b128 v[94:97], v89 offset:832
	ds_read_b128 v[98:101], v89 offset:896
	ds_read_b128 v[102:105], v89 offset:960
	v_addc_co_u32_e64 v145, s[10:11], 0, v79, s[10:11]
	v_add_co_u32_e64 v146, s[10:11], s20, v78
	s_add_u32 s18, s18, 0x200000
	s_nop 0
	v_addc_co_u32_e64 v147, s[10:11], 0, v79, s[10:11]
	v_add_co_u32_e64 v148, s[10:11], s21, v78
	s_addc_u32 s19, s19, 0
	s_nop 0
	v_addc_co_u32_e64 v149, s[10:11], 0, v79, s[10:11]
	v_add_co_u32_e64 v150, s[10:11], s22, v78
	v_add_u32_e32 v89, 0x400, v89
	s_nop 0
	v_addc_co_u32_e64 v151, s[10:11], 0, v79, s[10:11]
	v_add_co_u32_e64 v152, s[10:11], s23, v78
	s_cmp_eq_u32 s18, 0x1000000
	s_nop 0
	v_addc_co_u32_e64 v153, s[10:11], 0, v79, s[10:11]
	global_load_dwordx4 v[106:109], v[142:143], off
	global_load_dwordx4 v[110:113], v[144:145], off
	global_load_dwordx4 v[114:117], v[146:147], off
	global_load_dwordx4 v[118:121], v[148:149], off
	global_load_dwordx4 v[122:125], v[150:151], off
	global_load_dwordx4 v[126:129], v[152:153], off
	global_load_dwordx4 v[130:133], v[138:139], off
	global_load_dwordx4 v[134:137], v[140:141], off
	s_waitcnt vmcnt(7)
	v_lshlrev_b32_e32 v78, 16, v106
	v_and_b32_e32 v79, 0xffff0000, v106
	v_lshlrev_b32_e32 v106, 16, v107
	v_and_b32_e32 v107, 0xffff0000, v107
	v_lshlrev_b32_e32 v154, 16, v108
	s_waitcnt vmcnt(1)
	v_lshlrev_b32_e32 v176, 16, v130
	v_and_b32_e32 v177, 0xffff0000, v130
	v_lshlrev_b32_e32 v130, 16, v131
	v_and_b32_e32 v131, 0xffff0000, v131
	v_lshlrev_b32_e32 v178, 16, v132
	v_and_b32_e32 v179, 0xffff0000, v132
	v_lshlrev_b32_e32 v132, 16, v133
	v_and_b32_e32 v133, 0xffff0000, v133
	s_waitcnt vmcnt(0)
	v_lshlrev_b32_e32 v180, 16, v134
	v_and_b32_e32 v181, 0xffff0000, v134
	v_lshlrev_b32_e32 v134, 16, v135
	v_and_b32_e32 v135, 0xffff0000, v135
	v_lshlrev_b32_e32 v182, 16, v136
	v_and_b32_e32 v183, 0xffff0000, v136
	v_lshlrev_b32_e32 v136, 16, v137
	v_and_b32_e32 v137, 0xffff0000, v137
	s_waitcnt lgkmcnt(14)
	v_pk_fma_f32 v[6:7], v[72:73], v[6:7], v[130:131]
	v_pk_fma_f32 v[4:5], v[70:71], v[4:5], v[176:177]
	v_pk_fma_f32 v[70:71], v[76:77], v[2:3], v[132:133]
	v_pk_fma_f32 v[72:73], v[74:75], v[0:1], v[178:179]
	v_and_b32_e32 v155, 0xffff0000, v108
	v_lshlrev_b32_e32 v108, 16, v109
	v_and_b32_e32 v109, 0xffff0000, v109
	v_cvt_pk_bf16_f32 v0, v4, v5
	v_cvt_pk_bf16_f32 v1, v6, v7
	v_cvt_pk_bf16_f32 v2, v72, v73
	v_cvt_pk_bf16_f32 v3, v70, v71
	s_waitcnt lgkmcnt(13)
	v_pk_fma_f32 v[6:7], v[6:7], v[14:15], v[134:135]
	v_pk_fma_f32 v[4:5], v[4:5], v[12:13], v[180:181]
	s_waitcnt lgkmcnt(12)
	v_pk_fma_f32 v[10:11], v[70:71], v[10:11], v[136:137]
	v_pk_fma_f32 v[8:9], v[72:73], v[8:9], v[182:183]
	v_lshlrev_b32_e32 v156, 16, v110
	v_and_b32_e32 v157, 0xffff0000, v110
	v_lshlrev_b32_e32 v110, 16, v111
	v_and_b32_e32 v111, 0xffff0000, v111
	v_lshlrev_b32_e32 v158, 16, v112
	v_and_b32_e32 v159, 0xffff0000, v112
	v_lshlrev_b32_e32 v112, 16, v113
	v_and_b32_e32 v113, 0xffff0000, v113
	global_store_dwordx4 v[138:139], v[0:3], off
	v_lshlrev_b32_e32 v160, 16, v114
	v_and_b32_e32 v161, 0xffff0000, v114
	v_cvt_pk_bf16_f32 v0, v4, v5
	v_cvt_pk_bf16_f32 v1, v6, v7
	v_cvt_pk_bf16_f32 v2, v8, v9
	v_cvt_pk_bf16_f32 v3, v10, v11
	s_waitcnt lgkmcnt(11)
; #define LAS __attribute__((address_space(3)))
; #define GAS __attribute__((address_space(1)))
; __device__ __forceinline__ unsigned cvt_pk_bf16(float lo, float hi) { const f32x2 v = {lo, hi}; const bf16x2_t b = __builtin_convertvector(v, bf16x2_t); return __builtin_bit_cast(unsigned, b); }
; #define LDS_WAIT() asm volatile("s_waitcnt lgkmcnt(0)" ::: "memory")
; __device__ __forceinline__ void phase_gla_escan(Frame& F) {
;     ...
;         for (int n = 0; n < NCK; ++n) {
;             const u32x4 kv = *(const GAS u32x4*)(kp + (size_t)n * SLABP * 512); const f32x4 d0 = *(const LAS f32x4*)(dl + n * 32 + 4 * g), d1 = *(const LAS f32x4*)(dl + n * 32 + 16 + 4 * g);
;             const f32x4 k0 = (f32x4){__builtin_bit_cast(float, kv.x << 16), __builtin_bit_cast(float, kv.x & 0xffff0000u), __builtin_bit_cast(float, kv.y << 16), __builtin_bit_cast(float, kv.y & 0xffff0000u)};
;             const f32x4 k1 = (f32x4){__builtin_bit_cast(float, kv.z << 16), __builtin_bit_cast(float, kv.z & 0xffff0000u), __builtin_bit_cast(float, kv.w << 16), __builtin_bit_cast(float, kv.w & 0xffff0000u)};
;             S0 = S0 * d0 + k0; S1 = S1 * d1 + k1;
;             u32x4 o; o.x = cvt_pk_bf16(S0[0], S0[1]); o.y = cvt_pk_bf16(S0[2], S0[3]); o.z = cvt_pk_bf16(S1[0], S1[1]); o.w = cvt_pk_bf16(S1[2], S1[3]); *(GAS u32x4*)(kp + (size_t)n * SLABP * 512) = o;
;         }
;         LDS_WAIT(); asm volatile("" ::: "memory");
	v_pk_fma_f32 v[6:7], v[6:7], v[22:23], v[106:107]
	v_pk_fma_f32 v[4:5], v[4:5], v[20:21], v[78:79]
	s_waitcnt lgkmcnt(10)
	v_pk_fma_f32 v[10:11], v[10:11], v[18:19], v[108:109]
	v_pk_fma_f32 v[8:9], v[8:9], v[16:17], v[154:155]
	v_lshlrev_b32_e32 v114, 16, v115
	v_and_b32_e32 v115, 0xffff0000, v115
	v_lshlrev_b32_e32 v162, 16, v116
	v_and_b32_e32 v163, 0xffff0000, v116
	v_lshlrev_b32_e32 v116, 16, v117
	v_and_b32_e32 v117, 0xffff0000, v117
	global_store_dwordx4 v[140:141], v[0:3], off
	v_lshlrev_b32_e32 v164, 16, v118
	v_and_b32_e32 v165, 0xffff0000, v118
	v_cvt_pk_bf16_f32 v0, v4, v5
	v_cvt_pk_bf16_f32 v1, v6, v7
	v_cvt_pk_bf16_f32 v2, v8, v9
	v_cvt_pk_bf16_f32 v3, v10, v11
	s_waitcnt lgkmcnt(9)
	v_pk_fma_f32 v[6:7], v[6:7], v[30:31], v[110:111]
	v_pk_fma_f32 v[4:5], v[4:5], v[28:29], v[156:157]
	s_waitcnt lgkmcnt(8)
	v_pk_fma_f32 v[10:11], v[10:11], v[26:27], v[112:113]
	v_pk_fma_f32 v[8:9], v[8:9], v[24:25], v[158:159]
	v_lshlrev_b32_e32 v118, 16, v119
	v_and_b32_e32 v119, 0xffff0000, v119
	v_lshlrev_b32_e32 v166, 16, v120
	v_and_b32_e32 v167, 0xffff0000, v120
	v_lshlrev_b32_e32 v120, 16, v121
	v_and_b32_e32 v121, 0xffff0000, v121
	global_store_dwordx4 v[142:143], v[0:3], off
	v_lshlrev_b32_e32 v168, 16, v122
	v_and_b32_e32 v169, 0xffff0000, v122
	v_cvt_pk_bf16_f32 v0, v4, v5
	v_cvt_pk_bf16_f32 v1, v6, v7
	v_cvt_pk_bf16_f32 v2, v8, v9
	v_cvt_pk_bf16_f32 v3, v10, v11
	s_waitcnt lgkmcnt(7)
	v_pk_fma_f32 v[6:7], v[6:7], v[38:39], v[114:115]
	v_pk_fma_f32 v[4:5], v[4:5], v[36:37], v[160:161]
	s_waitcnt lgkmcnt(6)
	v_pk_fma_f32 v[10:11], v[10:11], v[34:35], v[116:117]
	v_pk_fma_f32 v[8:9], v[8:9], v[32:33], v[162:163]
	v_lshlrev_b32_e32 v122, 16, v123
	v_and_b32_e32 v123, 0xffff0000, v123
	v_lshlrev_b32_e32 v170, 16, v124
	v_and_b32_e32 v171, 0xffff0000, v124
	v_lshlrev_b32_e32 v124, 16, v125
	v_and_b32_e32 v125, 0xffff0000, v125
	global_store_dwordx4 v[144:145], v[0:3], off
	v_lshlrev_b32_e32 v172, 16, v126
	v_and_b32_e32 v173, 0xffff0000, v126
	v_cvt_pk_bf16_f32 v0, v4, v5
	v_cvt_pk_bf16_f32 v1, v6, v7
	v_cvt_pk_bf16_f32 v2, v8, v9
	v_cvt_pk_bf16_f32 v3, v10, v11
	s_waitcnt lgkmcnt(5)
	v_pk_fma_f32 v[6:7], v[6:7], v[46:47], v[118:119]
	v_pk_fma_f32 v[4:5], v[4:5], v[44:45], v[164:165]
	s_waitcnt lgkmcnt(4)
	v_pk_fma_f32 v[10:11], v[10:11], v[42:43], v[120:121]
	v_pk_fma_f32 v[8:9], v[8:9], v[40:41], v[166:167]
	v_lshlrev_b32_e32 v126, 16, v127
	v_and_b32_e32 v127, 0xffff0000, v127
	v_lshlrev_b32_e32 v174, 16, v128
	v_and_b32_e32 v175, 0xffff0000, v128
	v_lshlrev_b32_e32 v128, 16, v129
	v_and_b32_e32 v129, 0xffff0000, v129
	global_store_dwordx4 v[146:147], v[0:3], off
	s_nop 1
	v_cvt_pk_bf16_f32 v0, v4, v5
	v_cvt_pk_bf16_f32 v1, v6, v7
	v_cvt_pk_bf16_f32 v2, v8, v9
	v_cvt_pk_bf16_f32 v3, v10, v11
	s_waitcnt lgkmcnt(3)
	v_pk_fma_f32 v[6:7], v[6:7], v[92:93], v[122:123]
	v_pk_fma_f32 v[4:5], v[4:5], v[90:91], v[168:169]
	s_waitcnt lgkmcnt(2)
	v_pk_fma_f32 v[10:11], v[10:11], v[96:97], v[124:125]
	v_pk_fma_f32 v[8:9], v[8:9], v[94:95], v[170:171]
	global_store_dwordx4 v[148:149], v[0:3], off
	s_waitcnt lgkmcnt(1)
	v_pk_fma_f32 v[72:73], v[6:7], v[100:101], v[126:127]
	v_pk_fma_f32 v[70:71], v[4:5], v[98:99], v[172:173]
	v_cvt_pk_bf16_f32 v0, v4, v5
	v_cvt_pk_bf16_f32 v1, v6, v7
	v_cvt_pk_bf16_f32 v2, v8, v9
	v_cvt_pk_bf16_f32 v3, v10, v11
	s_waitcnt lgkmcnt(0)
	v_pk_fma_f32 v[76:77], v[10:11], v[104:105], v[128:129]
	v_pk_fma_f32 v[74:75], v[8:9], v[102:103], v[174:175]
	global_store_dwordx4 v[150:151], v[0:3], off
	s_nop 1
	v_cvt_pk_bf16_f32 v0, v70, v71
	v_cvt_pk_bf16_f32 v1, v72, v73
	v_cvt_pk_bf16_f32 v2, v74, v75
	v_cvt_pk_bf16_f32 v3, v76, v77
	global_store_dwordx4 v[152:153], v[0:3], off
	s_cbranch_scc0 .LBB0_867
	s_waitcnt lgkmcnt(0)
	v_add_u32_e32 v80, s1, v80
	v_cmp_lt_i32_e32 vcc, s24, v80
	s_or_b64 s[16:17], vcc, s[16:17]
	s_andn2_b64 exec, exec, s[16:17]
	s_cbranch_execnz .LBB0_866

.LBB0_913:
	s_or_b64 exec, exec, s[12:13]
	s_waitcnt lgkmcnt(0)
	s_barrier
	v_add_u32_e32 v136, 0x8800, v167
	ds_read2_b32 v[80:81], v136 offset1:16
	ds_read2_b32 v[82:83], v136 offset0:64 offset1:80
	ds_read2_b32 v[84:85], v136 offset0:128 offset1:144
	ds_read2_b32 v[86:87], v136 offset0:192 offset1:208
	v_add_u32_e32 v137, 0x8c00, v167
	s_waitcnt lgkmcnt(3)
	v_add_f32_e32 v76, 0, v80
	s_waitcnt lgkmcnt(2)
	v_add_f32_e32 v76, v76, v82
	s_waitcnt lgkmcnt(1)
	v_add_f32_e32 v76, v76, v84
	ds_read2_b32 v[92:93], v137 offset1:16
	ds_read2_b32 v[94:95], v137 offset0:64 offset1:80
	ds_read2_b32 v[96:97], v137 offset0:128 offset1:144
	ds_read2_b32 v[98:99], v137 offset0:192 offset1:208
	s_waitcnt lgkmcnt(4)
	v_add_f32_e32 v76, v76, v86
	s_waitcnt lgkmcnt(3)
	v_add_f32_e32 v76, v76, v92
	s_waitcnt lgkmcnt(2)
	v_add_f32_e32 v76, v76, v94
	s_waitcnt lgkmcnt(1)
	v_add_f32_e32 v76, v76, v96
	s_waitcnt lgkmcnt(0)
	v_add_f32_e32 v76, v76, v98
	v_fmamk_f32 v76, v76, 0x3b800000, v170
	v_mul_f32_e32 v77, 0x4f800000, v76
	v_cmp_gt_f32_e32 vcc, s30, v76
	s_lshl_b32 s22, s22, 1
	s_mov_b32 s23, s17
	v_cndmask_b32_e32 v76, v76, v77, vcc
	v_sqrt_f32_e32 v77, v76
	s_nop 0
	v_add_u32_e32 v78, -1, v77
	v_fma_f32 v79, -v78, v77, v76
	v_cmp_ge_f32_e64 s[12:13], 0, v79
	v_add_u32_e32 v79, 1, v77
	s_nop 0
	v_cndmask_b32_e64 v78, v77, v78, s[12:13]
	v_fma_f32 v77, -v79, v77, v76
	v_cmp_lt_f32_e64 s[12:13], 0, v77
	s_nop 1
	v_cndmask_b32_e64 v77, v78, v79, s[12:13]
	v_mul_f32_e32 v78, 0x37800000, v77
	v_cndmask_b32_e32 v77, v77, v78, vcc
	v_cmp_class_f32_e32 vcc, v76, v171
	s_nop 1
	v_cndmask_b32_e32 v78, v77, v76, vcc
	v_div_scale_f32 v76, s[12:13], v78, v78, 1.0
	v_rcp_f32_e32 v77, v76
	s_ashr_i32 s12, s31, 2
	s_ashr_i32 s13, s12, 31
	s_lshl_b64 s[20:21], s[12:13], 6
	v_fma_f32 v79, -v76, v77, 1.0
	v_fmac_f32_e32 v77, v79, v77
	v_div_scale_f32 v79, vcc, 1.0, v78, 1.0
	v_mul_f32_e32 v80, v79, v77
	v_fma_f32 v82, -v76, v80, v79
	v_fmac_f32_e32 v80, v82, v77
	v_fma_f32 v76, -v76, v80, v79
	v_div_fmas_f32 v79, v76, v77, v80
	v_lshlrev_b32_e32 v76, 16, v68
	v_and_b32_e32 v77, 0xffff0000, v68
	v_mul_f32_e32 v68, 0xbfb8aa3b, v76
	v_exp_f32_e32 v80, v68
	v_mul_f32_e32 v68, 0xbfb8aa3b, v77
	v_exp_f32_e32 v82, v68
	v_div_fixup_f32 v68, v79, v78, 1.0
	v_add_f32_e32 v78, 1.0, v80
	v_rcp_f32_e32 v78, v78
	v_add_f32_e32 v79, 1.0, v82
	v_rcp_f32_e32 v79, v79
	v_pk_mul_f32 v[100:101], v[132:133], v[68:69] op_sel_hi:[1,0]
	v_or_b32_e32 v94, s20, v164
	s_waitcnt vmcnt(0)
	v_pk_mul_f32 v[100:101], v[108:109], v[100:101]
	s_nop 0
	v_pk_mul_f32 v[76:77], v[100:101], v[76:77]
	s_nop 0
	v_pk_mul_f32 v[76:77], v[78:79], v[76:77]
	v_lshlrev_b32_e32 v78, 16, v69
	v_and_b32_e32 v79, 0xffff0000, v69
	v_mul_f32_e32 v69, 0xbfb8aa3b, v78
	v_exp_f32_e32 v69, v69
	v_mul_f32_e32 v80, 0xbfb8aa3b, v79
	v_exp_f32_e32 v80, v80
	v_cvt_pk_bf16_f32 v76, v76, v77
	v_add_f32_e32 v69, 1.0, v69
	v_rcp_f32_e32 v100, v69
	v_add_f32_e32 v69, 1.0, v80
	v_rcp_f32_e32 v101, v69
	v_pk_mul_f32 v[102:103], v[134:135], v[68:69] op_sel_hi:[1,0]
	s_nop 0
	v_pk_mul_f32 v[102:103], v[110:111], v[102:103]
	s_nop 0
	v_pk_mul_f32 v[78:79], v[102:103], v[78:79]
	s_nop 0
	v_pk_mul_f32 v[78:79], v[100:101], v[78:79]
	v_lshlrev_b32_e32 v100, 16, v70
	v_and_b32_e32 v101, 0xffff0000, v70
	v_mul_f32_e32 v69, 0xbfb8aa3b, v100
	v_exp_f32_e32 v69, v69
	v_mul_f32_e32 v70, 0xbfb8aa3b, v101
	v_exp_f32_e32 v70, v70
	v_cvt_pk_bf16_f32 v77, v78, v79
	v_add_f32_e32 v69, 1.0, v69
	v_rcp_f32_e32 v78, v69
	v_add_f32_e32 v69, 1.0, v70
	v_lshlrev_b32_e32 v70, 16, v71
	v_rcp_f32_e32 v79, v69
	v_pk_mul_f32 v[102:103], v[128:129], v[68:69] op_sel_hi:[1,0]
	v_and_b32_e32 v71, 0xffff0000, v71
	v_mul_f32_e32 v69, 0xbfb8aa3b, v70
	v_exp_f32_e32 v69, v69
	v_mul_f32_e32 v80, 0xbfb8aa3b, v71
	v_exp_f32_e32 v80, v80
	v_pk_mul_f32 v[102:103], v[104:105], v[102:103]
	v_add_f32_e32 v69, 1.0, v69
	v_pk_mul_f32 v[100:101], v[102:103], v[100:101]
	s_nop 0
	v_pk_mul_f32 v[78:79], v[78:79], v[100:101]
	v_rcp_f32_e32 v100, v69
	v_add_f32_e32 v69, 1.0, v80
	v_add_f32_e32 v80, 0, v81
	v_add_f32_e32 v80, v80, v83
	v_add_f32_e32 v80, v80, v85
	v_add_f32_e32 v80, v80, v87
	v_add_f32_e32 v80, v80, v93
	v_add_f32_e32 v80, v80, v95
	v_add_f32_e32 v80, v80, v97
	v_add_f32_e32 v80, v80, v99
	v_fmamk_f32 v80, v80, 0x3b800000, v170
	v_mul_f32_e32 v81, 0x4f800000, v80
	v_cmp_gt_f32_e32 vcc, s30, v80
	v_rcp_f32_e32 v101, v69
	v_pk_mul_f32 v[68:69], v[130:131], v[68:69] op_sel_hi:[1,0]
	v_cndmask_b32_e32 v80, v80, v81, vcc
	v_sqrt_f32_e32 v81, v80
	v_pk_mul_f32 v[68:69], v[106:107], v[68:69]
	v_cvt_pk_bf16_f32 v78, v78, v79
	v_pk_mul_f32 v[68:69], v[68:69], v[70:71]
	v_or_b32_e32 v70, s20, v152
	v_pk_mul_f32 v[68:69], v[100:101], v[68:69]
	v_add_u32_e32 v82, -1, v81
	v_cvt_pk_bf16_f32 v79, v68, v69
	v_mov_b64_e32 v[68:69], s[18:19]
	v_mad_u64_u32 v[70:71], s[12:13], v70, s1, v[68:69]
	v_fma_f32 v83, -v82, v81, v80
	v_cmp_ge_f32_e64 s[12:13], 0, v83
	v_add_u32_e32 v83, 1, v81
	v_mad_i32_i24 v71, s21, v153, v71
	v_cndmask_b32_e64 v82, v81, v82, s[12:13]
	v_fma_f32 v81, -v83, v81, v80
	v_cmp_lt_f32_e64 s[12:13], 0, v81
	v_lshl_add_u64 v[70:71], v[70:71], 0, s[22:23]
	v_lshl_add_u64 v[70:71], v[70:71], 0, s[16:17]
	v_cndmask_b32_e64 v81, v82, v83, s[12:13]
	v_mul_f32_e32 v82, 0x37800000, v81
	v_cndmask_b32_e32 v81, v81, v82, vcc
	v_cmp_class_f32_e32 vcc, v80, v171
	v_lshl_add_u64 v[70:71], v[70:71], 0, v[158:159]
	global_store_dwordx4 v[70:71], v[76:79], off offset:1024
	v_cndmask_b32_e32 v80, v81, v80, vcc
	v_div_scale_f32 v81, s[12:13], v80, v80, 1.0
	v_rcp_f32_e32 v82, v81
	v_mad_u64_u32 v[94:95], s[12:13], v94, s1, v[68:69]
	v_mad_i32_i24 v95, s21, v153, v95
	v_fma_f32 v70, -v81, v82, 1.0
	v_fmac_f32_e32 v82, v70, v82
	v_div_scale_f32 v70, vcc, 1.0, v80, 1.0
	v_mul_f32_e32 v71, v70, v82
	v_fma_f32 v76, -v81, v71, v70
	v_fmac_f32_e32 v71, v76, v82
	v_fma_f32 v70, -v81, v71, v70
	v_div_fmas_f32 v76, v70, v82, v71
	v_lshlrev_b32_e32 v70, 16, v64
	v_and_b32_e32 v71, 0xffff0000, v64
	v_mul_f32_e32 v64, 0xbfb8aa3b, v70
	v_exp_f32_e32 v64, v64
	v_mul_f32_e32 v77, 0xbfb8aa3b, v71
	v_exp_f32_e32 v77, v77
	v_div_fixup_f32 v76, v76, v80, 1.0
	v_add_f32_e32 v64, 1.0, v64
	v_rcp_f32_e32 v78, v64
	v_add_f32_e32 v64, 1.0, v77
	v_rcp_f32_e32 v79, v64
	v_pk_mul_f32 v[80:81], v[124:125], v[76:77] op_sel_hi:[1,0]
	v_lshl_add_u64 v[94:95], v[94:95], 0, s[22:23]
	v_pk_mul_f32 v[80:81], v[108:109], v[80:81]
	v_lshl_add_u64 v[94:95], v[94:95], 0, s[16:17]
	v_pk_mul_f32 v[70:71], v[80:81], v[70:71]
	v_lshl_add_u64 v[94:95], v[94:95], 0, v[158:159]
	v_pk_mul_f32 v[70:71], v[78:79], v[70:71]
	v_lshlrev_b32_e32 v78, 16, v65
	v_and_b32_e32 v79, 0xffff0000, v65
	v_mul_f32_e32 v64, 0xbfb8aa3b, v78
	v_exp_f32_e32 v65, v64
	v_mul_f32_e32 v64, 0xbfb8aa3b, v79
	v_exp_f32_e32 v77, v64
	v_cvt_pk_bf16_f32 v64, v70, v71
	v_add_f32_e32 v65, 1.0, v65
	v_rcp_f32_e32 v70, v65
	v_add_f32_e32 v65, 1.0, v77
	v_rcp_f32_e32 v71, v65
	v_pk_mul_f32 v[80:81], v[126:127], v[76:77] op_sel_hi:[1,0]
	s_nop 0
	v_pk_mul_f32 v[80:81], v[110:111], v[80:81]
	s_nop 0
	v_pk_mul_f32 v[78:79], v[80:81], v[78:79]
	s_nop 0
	v_pk_mul_f32 v[70:71], v[70:71], v[78:79]
	v_lshlrev_b32_e32 v78, 16, v66
	v_and_b32_e32 v79, 0xffff0000, v66
	v_mul_f32_e32 v65, 0xbfb8aa3b, v78
	v_exp_f32_e32 v66, v65
	v_mul_f32_e32 v65, 0xbfb8aa3b, v79
	v_exp_f32_e32 v77, v65
	v_cvt_pk_bf16_f32 v65, v70, v71
	v_add_f32_e32 v66, 1.0, v66
	v_rcp_f32_e32 v70, v66
	v_add_f32_e32 v66, 1.0, v77
	v_rcp_f32_e32 v71, v66
	v_pk_mul_f32 v[80:81], v[120:121], v[76:77] op_sel_hi:[1,0]
	s_nop 0
	v_pk_mul_f32 v[80:81], v[104:105], v[80:81]
	s_nop 0
	v_pk_mul_f32 v[78:79], v[80:81], v[78:79]
	s_nop 0
	v_pk_mul_f32 v[70:71], v[70:71], v[78:79]
	v_lshlrev_b32_e32 v78, 16, v67
	v_and_b32_e32 v79, 0xffff0000, v67
	v_mul_f32_e32 v66, 0xbfb8aa3b, v78
	v_exp_f32_e32 v67, v66
	v_mul_f32_e32 v66, 0xbfb8aa3b, v79
	v_exp_f32_e32 v77, v66
	v_cvt_pk_bf16_f32 v66, v70, v71
	v_add_f32_e32 v67, 1.0, v67
	v_rcp_f32_e32 v70, v67
	v_add_f32_e32 v67, 1.0, v77
	v_rcp_f32_e32 v71, v67
	v_pk_mul_f32 v[76:77], v[122:123], v[76:77] op_sel_hi:[1,0]
	s_nop 0
	v_pk_mul_f32 v[76:77], v[106:107], v[76:77]
	s_nop 0
	v_pk_mul_f32 v[76:77], v[76:77], v[78:79]
	s_nop 0
	v_pk_mul_f32 v[70:71], v[70:71], v[76:77]
	ds_read2_b32 v[76:77], v136 offset0:32 offset1:48
	ds_read2_b32 v[78:79], v136 offset0:96 offset1:112
	ds_read2_b32 v[80:81], v136 offset0:160 offset1:176
	v_cvt_pk_bf16_f32 v67, v70, v71
	s_waitcnt lgkmcnt(2)
	v_add_f32_e32 v70, 0, v76
	s_waitcnt lgkmcnt(1)
	v_add_f32_e32 v70, v70, v78
	s_waitcnt lgkmcnt(0)
	v_add_f32_e32 v76, v70, v80
	ds_read2_b32 v[70:71], v136 offset0:224 offset1:240
	ds_read2_b32 v[82:83], v137 offset0:32 offset1:48
	ds_read2_b32 v[84:85], v137 offset0:96 offset1:112
	ds_read2_b32 v[86:87], v137 offset0:160 offset1:176
	ds_read2_b32 v[92:93], v137 offset0:224 offset1:240
	s_waitcnt lgkmcnt(4)
	v_add_f32_e32 v70, v76, v70
	s_waitcnt lgkmcnt(3)
	v_add_f32_e32 v70, v70, v82
	s_waitcnt lgkmcnt(2)
	v_add_f32_e32 v70, v70, v84
	s_waitcnt lgkmcnt(1)
	v_add_f32_e32 v70, v70, v86
	s_waitcnt lgkmcnt(0)
	v_add_f32_e32 v70, v70, v92
	v_fmamk_f32 v70, v70, 0x3b800000, v170
	v_mul_f32_e32 v76, 0x4f800000, v70
	v_cmp_gt_f32_e32 vcc, s30, v70
	global_store_dwordx4 v[94:95], v[64:67], off offset:1024
	s_nop 0
	v_cndmask_b32_e32 v70, v70, v76, vcc
	v_sqrt_f32_e32 v76, v70
	s_nop 0
	v_add_u32_e32 v78, -1, v76
	v_fma_f32 v80, -v78, v76, v70
	v_cmp_ge_f32_e64 s[12:13], 0, v80
	v_add_u32_e32 v80, 1, v76
	s_nop 0
	v_cndmask_b32_e64 v78, v76, v78, s[12:13]
	v_fma_f32 v76, -v80, v76, v70
	v_cmp_lt_f32_e64 s[12:13], 0, v76
	s_nop 1
	v_cndmask_b32_e64 v76, v78, v80, s[12:13]
	v_mul_f32_e32 v78, 0x37800000, v76
	v_cndmask_b32_e32 v76, v76, v78, vcc
	v_cmp_class_f32_e32 vcc, v70, v171
	s_nop 1
	v_cndmask_b32_e32 v70, v76, v70, vcc
	v_div_scale_f32 v76, s[12:13], v70, v70, 1.0
	v_rcp_f32_e32 v78, v76
	s_nop 0
	v_fma_f32 v64, -v76, v78, 1.0
	v_fmac_f32_e32 v78, v64, v78
	v_div_scale_f32 v64, vcc, 1.0, v70, 1.0
	v_mul_f32_e32 v65, v64, v78
	v_fma_f32 v66, -v76, v65, v64
	v_fmac_f32_e32 v65, v66, v78
	v_fma_f32 v64, -v76, v65, v64
	v_div_fmas_f32 v66, v64, v78, v65
	v_lshlrev_b32_e32 v64, 16, v60
	v_and_b32_e32 v65, 0xffff0000, v60
	v_mul_f32_e32 v60, 0xbfb8aa3b, v64
	v_exp_f32_e32 v60, v60
	v_mul_f32_e32 v67, 0xbfb8aa3b, v65
	v_exp_f32_e32 v67, v67
	v_div_fixup_f32 v66, v66, v70, 1.0
	v_add_f32_e32 v60, 1.0, v60
	v_rcp_f32_e32 v94, v60
	v_add_f32_e32 v60, 1.0, v67
	v_rcp_f32_e32 v95, v60
	v_pk_mul_f32 v[96:97], v[116:117], v[66:67] op_sel_hi:[1,0]
	s_nop 0
	v_pk_mul_f32 v[96:97], v[108:109], v[96:97]
	s_nop 0
	v_pk_mul_f32 v[64:65], v[96:97], v[64:65]
	s_nop 0
	v_pk_mul_f32 v[64:65], v[94:95], v[64:65]
	v_lshlrev_b32_e32 v94, 16, v61
	v_and_b32_e32 v95, 0xffff0000, v61
	v_mul_f32_e32 v60, 0xbfb8aa3b, v94
	v_exp_f32_e32 v61, v60
	v_mul_f32_e32 v60, 0xbfb8aa3b, v95
	v_exp_f32_e32 v67, v60
	v_cvt_pk_bf16_f32 v60, v64, v65
	v_add_f32_e32 v61, 1.0, v61
	v_rcp_f32_e32 v64, v61
	v_add_f32_e32 v61, 1.0, v67
	v_rcp_f32_e32 v65, v61
	v_pk_mul_f32 v[96:97], v[118:119], v[66:67] op_sel_hi:[1,0]
	s_nop 0
	v_pk_mul_f32 v[96:97], v[110:111], v[96:97]
	s_nop 0
	v_pk_mul_f32 v[94:95], v[96:97], v[94:95]
	s_nop 0
	v_pk_mul_f32 v[64:65], v[64:65], v[94:95]
	v_lshlrev_b32_e32 v94, 16, v62
	v_and_b32_e32 v95, 0xffff0000, v62
	v_mul_f32_e32 v61, 0xbfb8aa3b, v94
	v_exp_f32_e32 v62, v61
	v_mul_f32_e32 v61, 0xbfb8aa3b, v95
	v_exp_f32_e32 v67, v61
	v_cvt_pk_bf16_f32 v61, v64, v65
	v_add_f32_e32 v62, 1.0, v62
	v_rcp_f32_e32 v64, v62
	v_add_f32_e32 v62, 1.0, v67
	v_rcp_f32_e32 v65, v62
	v_pk_mul_f32 v[96:97], v[112:113], v[66:67] op_sel_hi:[1,0]
	s_nop 0
	v_pk_mul_f32 v[96:97], v[104:105], v[96:97]
	s_nop 0
	v_pk_mul_f32 v[94:95], v[96:97], v[94:95]
	s_nop 0
	v_pk_mul_f32 v[64:65], v[64:65], v[94:95]
	v_lshlrev_b32_e32 v94, 16, v63
	v_and_b32_e32 v95, 0xffff0000, v63
	v_mul_f32_e32 v62, 0xbfb8aa3b, v94
	v_exp_f32_e32 v63, v62
	v_mul_f32_e32 v62, 0xbfb8aa3b, v95
	v_exp_f32_e32 v67, v62
	v_cvt_pk_bf16_f32 v62, v64, v65
	v_add_f32_e32 v63, 1.0, v63
	v_rcp_f32_e32 v64, v63
	v_add_f32_e32 v63, 1.0, v67
	v_rcp_f32_e32 v65, v63
	v_pk_mul_f32 v[66:67], v[114:115], v[66:67] op_sel_hi:[1,0]
	s_nop 0
	v_pk_mul_f32 v[66:67], v[106:107], v[66:67]
	s_nop 0
	v_pk_mul_f32 v[66:67], v[66:67], v[94:95]
	s_nop 0
	v_pk_mul_f32 v[64:65], v[64:65], v[66:67]
	s_nop 0
	v_cvt_pk_bf16_f32 v63, v64, v65
	v_add_f32_e32 v65, 0, v77
	v_add_f32_e32 v65, v65, v79
	v_add_f32_e32 v65, v65, v81
	v_add_f32_e32 v65, v65, v71
	v_add_f32_e32 v65, v65, v83
	v_add_f32_e32 v65, v65, v85
	v_add_f32_e32 v65, v65, v87
	v_add_f32_e32 v65, v65, v93
	v_fmamk_f32 v65, v65, 0x3b800000, v170
	v_mul_f32_e32 v66, 0x4f800000, v65
	v_cmp_gt_f32_e32 vcc, s30, v65
	v_or_b32_e32 v64, s20, v166
	s_nop 0
	v_cndmask_b32_e32 v66, v65, v66, vcc
	v_sqrt_f32_e32 v67, v66
	v_mad_u64_u32 v[64:65], s[12:13], v64, s1, v[68:69]
	v_mad_i32_i24 v65, s21, v153, v65
	v_add_u32_e32 v70, -1, v67
	v_fma_f32 v71, -v70, v67, v66
	v_cmp_ge_f32_e64 s[12:13], 0, v71
	v_add_u32_e32 v71, 1, v67
	v_lshl_add_u64 v[64:65], v[64:65], 0, s[22:23]
	v_cndmask_b32_e64 v70, v67, v70, s[12:13]
	v_fma_f32 v67, -v71, v67, v66
	v_cmp_lt_f32_e64 s[12:13], 0, v67
	v_lshl_add_u64 v[64:65], v[64:65], 0, s[16:17]
	v_lshl_add_u64 v[64:65], v[64:65], 0, v[158:159]
	v_cndmask_b32_e64 v67, v70, v71, s[12:13]
	v_mul_f32_e32 v70, 0x37800000, v67
	v_cndmask_b32_e32 v67, v67, v70, vcc
	v_cmp_class_f32_e32 vcc, v66, v171
	global_store_dwordx4 v[64:65], v[60:63], off offset:1024
	s_nop 0
	v_cndmask_b32_e32 v66, v67, v66, vcc
	v_div_scale_f32 v67, s[12:13], v66, v66, 1.0
	v_rcp_f32_e32 v70, v67
	s_nop 0
	v_fma_f32 v60, -v67, v70, 1.0
	v_fmac_f32_e32 v70, v60, v70
	v_div_scale_f32 v60, vcc, 1.0, v66, 1.0
	v_mul_f32_e32 v61, v60, v70
	v_fma_f32 v62, -v67, v61, v60
	v_fmac_f32_e32 v61, v62, v70
	v_fma_f32 v60, -v67, v61, v60
	v_div_fmas_f32 v62, v60, v70, v61
	v_lshlrev_b32_e32 v60, 16, v56
	v_and_b32_e32 v61, 0xffff0000, v56
	v_mul_f32_e32 v56, 0xbfb8aa3b, v60
	v_exp_f32_e32 v56, v56
	v_mul_f32_e32 v63, 0xbfb8aa3b, v61
	v_exp_f32_e32 v63, v63
	v_div_fixup_f32 v62, v62, v66, 1.0
	v_add_f32_e32 v56, 1.0, v56
	v_rcp_f32_e32 v64, v56
	v_add_f32_e32 v56, 1.0, v63
	v_rcp_f32_e32 v65, v56
	v_pk_mul_f32 v[66:67], v[88:89], v[62:63] op_sel_hi:[1,0]
	s_nop 0
	v_pk_mul_f32 v[66:67], v[108:109], v[66:67]
	s_nop 0
	v_pk_mul_f32 v[60:61], v[66:67], v[60:61]
	s_nop 0
	v_pk_mul_f32 v[60:61], v[64:65], v[60:61]
	v_lshlrev_b32_e32 v64, 16, v57
	v_and_b32_e32 v65, 0xffff0000, v57
	v_mul_f32_e32 v56, 0xbfb8aa3b, v64
	v_exp_f32_e32 v57, v56
	v_mul_f32_e32 v56, 0xbfb8aa3b, v65
	v_exp_f32_e32 v63, v56
	v_cvt_pk_bf16_f32 v56, v60, v61
	v_add_f32_e32 v57, 1.0, v57
	v_rcp_f32_e32 v60, v57
	v_add_f32_e32 v57, 1.0, v63
	v_rcp_f32_e32 v61, v57
	v_pk_mul_f32 v[66:67], v[90:91], v[62:63] op_sel_hi:[1,0]
	s_nop 0
	v_pk_mul_f32 v[66:67], v[110:111], v[66:67]
	s_nop 0
	v_pk_mul_f32 v[64:65], v[66:67], v[64:65]
	s_nop 0
	v_pk_mul_f32 v[60:61], v[60:61], v[64:65]
	v_lshlrev_b32_e32 v64, 16, v58
	v_and_b32_e32 v65, 0xffff0000, v58
	v_mul_f32_e32 v57, 0xbfb8aa3b, v64
	v_exp_f32_e32 v58, v57
	v_mul_f32_e32 v57, 0xbfb8aa3b, v65
	v_exp_f32_e32 v63, v57
	v_cvt_pk_bf16_f32 v57, v60, v61
	v_add_f32_e32 v58, 1.0, v58
	v_rcp_f32_e32 v60, v58
	v_add_f32_e32 v58, 1.0, v63
	v_rcp_f32_e32 v61, v58
	v_pk_mul_f32 v[66:67], v[72:73], v[62:63] op_sel_hi:[1,0]
	s_nop 0
	v_pk_mul_f32 v[66:67], v[104:105], v[66:67]
	s_nop 0
	v_pk_mul_f32 v[64:65], v[66:67], v[64:65]
	s_nop 0
	v_pk_mul_f32 v[60:61], v[60:61], v[64:65]
	v_lshlrev_b32_e32 v64, 16, v59
	v_and_b32_e32 v65, 0xffff0000, v59
	v_mul_f32_e32 v58, 0xbfb8aa3b, v64
	v_exp_f32_e32 v59, v58
	v_mul_f32_e32 v58, 0xbfb8aa3b, v65
	v_exp_f32_e32 v63, v58
	v_cvt_pk_bf16_f32 v58, v60, v61
	v_add_f32_e32 v59, 1.0, v59
	v_rcp_f32_e32 v60, v59
	v_add_f32_e32 v59, 1.0, v63
	v_rcp_f32_e32 v61, v59
	v_pk_mul_f32 v[62:63], v[74:75], v[62:63] op_sel_hi:[1,0]
	s_nop 0
	v_pk_mul_f32 v[62:63], v[106:107], v[62:63]
	s_nop 0
	v_pk_mul_f32 v[62:63], v[62:63], v[64:65]
	s_nop 0
	v_pk_mul_f32 v[60:61], v[60:61], v[62:63]
	s_nop 0
	v_cvt_pk_bf16_f32 v59, v60, v61
	v_or_b32_e32 v60, s20, v168
	v_mad_u64_u32 v[60:61], s[12:13], v60, s1, v[68:69]
	v_mad_i32_i24 v61, s21, v153, v61
	v_lshl_add_u64 v[60:61], v[60:61], 0, s[22:23]
	v_lshl_add_u64 v[60:61], v[60:61], 0, s[16:17]
	v_lshl_add_u64 v[60:61], v[60:61], 0, v[158:159]
	global_store_dwordx4 v[60:61], v[56:59], off offset:1024

.LBB0_917:
	s_or_b64 exec, exec, s[12:13]
	s_waitcnt lgkmcnt(0)
	s_barrier
	v_add_u32_e32 v202, 0x8000, v167
	ds_read2_b32 v[182:183], v202 offset1:16
	ds_read2_b32 v[184:185], v202 offset0:64 offset1:80
	ds_read2_b32 v[186:187], v202 offset0:128 offset1:144
	ds_read2_b32 v[188:189], v202 offset0:192 offset1:208
	v_lshlrev_b32_e32 v198, 16, v32
	s_waitcnt lgkmcnt(3)
	v_add_f32_e32 v182, 0, v182
	s_waitcnt lgkmcnt(2)
	v_add_f32_e32 v182, v182, v184
	s_waitcnt lgkmcnt(1)
	v_add_f32_e32 v182, v182, v186
	v_add_u32_e32 v186, 0x8400, v167
	ds_read2_b32 v[190:191], v186 offset1:16
	ds_read2_b32 v[192:193], v186 offset0:64 offset1:80
	ds_read2_b32 v[194:195], v186 offset0:128 offset1:144
	ds_read2_b32 v[196:197], v186 offset0:192 offset1:208
	s_waitcnt lgkmcnt(4)
	v_add_f32_e32 v182, v182, v188
	s_waitcnt lgkmcnt(3)
	v_add_f32_e32 v182, v182, v190
	s_waitcnt lgkmcnt(2)
	v_add_f32_e32 v182, v182, v192
	s_waitcnt lgkmcnt(1)
	v_add_f32_e32 v182, v182, v194
	s_waitcnt lgkmcnt(0)
	v_add_f32_e32 v182, v182, v196
	v_fmamk_f32 v182, v182, 0x3b800000, v170
	v_mul_f32_e32 v184, 0x4f800000, v182
	v_cmp_gt_f32_e32 vcc, s30, v182
	v_and_b32_e32 v199, 0xffff0000, v32
	s_lshl_b32 s24, s24, 1
	v_cndmask_b32_e32 v182, v182, v184, vcc
	v_sqrt_f32_e32 v184, v182
	s_mov_b32 s25, s17
	v_add_u32_e32 v188, -1, v184
	v_fma_f32 v190, -v188, v184, v182
	v_cmp_ge_f32_e64 s[12:13], 0, v190
	v_add_u32_e32 v190, 1, v184
	s_nop 0
	v_cndmask_b32_e64 v188, v184, v188, s[12:13]
	v_fma_f32 v184, -v190, v184, v182
	v_cmp_lt_f32_e64 s[12:13], 0, v184
	s_nop 1
	v_cndmask_b32_e64 v184, v188, v190, s[12:13]
	v_mul_f32_e32 v188, 0x37800000, v184
	v_cndmask_b32_e32 v184, v184, v188, vcc
	v_cmp_class_f32_e32 vcc, v182, v171
	s_nop 1
	v_cndmask_b32_e32 v182, v184, v182, vcc
	v_div_scale_f32 v184, s[12:13], v182, v182, 1.0
	v_rcp_f32_e32 v188, v184
	s_ashr_i32 s12, s36, 2
	s_ashr_i32 s13, s12, 31
	s_lshl_b64 s[22:23], s[12:13], 6
	v_fma_f32 v190, -v184, v188, 1.0
	v_fmac_f32_e32 v188, v190, v188
	v_div_scale_f32 v190, vcc, 1.0, v182, 1.0
	v_mul_f32_e32 v192, v190, v188
	v_fma_f32 v194, -v184, v192, v190
	v_fmac_f32_e32 v192, v194, v188
	v_fma_f32 v184, -v184, v192, v190
	v_div_fmas_f32 v184, v184, v188, v192
	v_mul_f32_e32 v188, 0xbfb8aa3b, v198
	v_exp_f32_e32 v188, v188
	v_mul_f32_e32 v190, 0xbfb8aa3b, v199
	v_exp_f32_e32 v190, v190
	v_div_fixup_f32 v182, v184, v182, 1.0
	v_pk_mul_f32 v[148:149], v[148:149], v[182:183] op_sel_hi:[1,0]
	v_add_f32_e32 v184, 1.0, v188
	s_waitcnt vmcnt(0)
	v_pk_mul_f32 v[148:149], v[116:117], v[148:149]
	v_rcp_f32_e32 v200, v184
	v_add_f32_e32 v184, 1.0, v190
	v_pk_mul_f32 v[148:149], v[148:149], v[198:199]
	v_lshlrev_b32_e32 v198, 16, v33
	v_rcp_f32_e32 v201, v184
	v_and_b32_e32 v199, 0xffff0000, v33
	v_mul_f32_e32 v184, 0xbfb8aa3b, v198
	v_exp_f32_e32 v184, v184
	v_mul_f32_e32 v188, 0xbfb8aa3b, v199
	v_exp_f32_e32 v188, v188
	v_pk_mul_f32 v[148:149], v[200:201], v[148:149]
	v_pk_mul_f32 v[150:151], v[150:151], v[182:183] op_sel_hi:[1,0]
	v_cvt_pk_bf16_f32 v148, v148, v149
	v_add_f32_e32 v149, 1.0, v184
	v_pk_mul_f32 v[150:151], v[118:119], v[150:151]
	v_rcp_f32_e32 v200, v149
	v_add_f32_e32 v149, 1.0, v188
	v_pk_mul_f32 v[150:151], v[150:151], v[198:199]
	v_lshlrev_b32_e32 v198, 16, v34
	v_rcp_f32_e32 v201, v149
	v_and_b32_e32 v199, 0xffff0000, v34
	v_mul_f32_e32 v149, 0xbfb8aa3b, v198
	v_exp_f32_e32 v184, v149
	v_mul_f32_e32 v149, 0xbfb8aa3b, v199
	v_exp_f32_e32 v188, v149
	v_pk_mul_f32 v[150:151], v[200:201], v[150:151]
	v_pk_mul_f32 v[144:145], v[144:145], v[182:183] op_sel_hi:[1,0]
	v_cvt_pk_bf16_f32 v149, v150, v151
	v_add_f32_e32 v150, 1.0, v184
	v_add_f32_e32 v151, 1.0, v188
	v_rcp_f32_e32 v150, v150
	v_rcp_f32_e32 v151, v151
	v_pk_mul_f32 v[146:147], v[146:147], v[182:183] op_sel_hi:[1,0]
	v_add_f32_e32 v182, 0, v183
	v_pk_mul_f32 v[144:145], v[112:113], v[144:145]
	v_add_f32_e32 v182, v182, v185
	v_pk_mul_f32 v[144:145], v[144:145], v[198:199]
	v_lshlrev_b32_e32 v198, 16, v35
	v_add_f32_e32 v182, v182, v187
	v_pk_mul_f32 v[144:145], v[150:151], v[144:145]
	v_and_b32_e32 v199, 0xffff0000, v35
	v_mul_f32_e32 v150, 0xbfb8aa3b, v198
	v_add_f32_e32 v182, v182, v189
	v_exp_f32_e32 v151, v150
	v_mul_f32_e32 v150, 0xbfb8aa3b, v199
	v_add_f32_e32 v182, v182, v191
	v_exp_f32_e32 v184, v150
	v_add_f32_e32 v182, v182, v193
	v_add_f32_e32 v182, v182, v195
	v_add_f32_e32 v182, v182, v197
	v_fmamk_f32 v182, v182, 0x3b800000, v170
	v_cvt_pk_bf16_f32 v150, v144, v145
	v_add_f32_e32 v144, 1.0, v151
	v_add_f32_e32 v145, 1.0, v184
	v_mul_f32_e32 v183, 0x4f800000, v182
	v_cmp_gt_f32_e32 vcc, s30, v182
	v_rcp_f32_e32 v144, v144
	v_rcp_f32_e32 v145, v145
	v_cndmask_b32_e32 v182, v182, v183, vcc
	v_sqrt_f32_e32 v183, v182
	v_pk_mul_f32 v[146:147], v[114:115], v[146:147]
	v_or_b32_e32 v188, s22, v164
	v_pk_mul_f32 v[146:147], v[146:147], v[198:199]
	v_add_u32_e32 v184, -1, v183
	v_pk_mul_f32 v[144:145], v[144:145], v[146:147]
	v_or_b32_e32 v146, s22, v152
	v_cvt_pk_bf16_f32 v151, v144, v145
	v_mov_b64_e32 v[144:145], s[18:19]
	v_mad_u64_u32 v[146:147], s[12:13], v146, s1, v[144:145]
	v_fma_f32 v185, -v184, v183, v182
	v_cmp_ge_f32_e64 s[12:13], 0, v185
	v_add_u32_e32 v185, 1, v183
	v_mad_i32_i24 v147, s23, v153, v147
	v_cndmask_b32_e64 v184, v183, v184, s[12:13]
	v_fma_f32 v183, -v185, v183, v182
	v_cmp_lt_f32_e64 s[12:13], 0, v183
	v_lshl_add_u64 v[146:147], v[146:147], 0, s[24:25]
	v_lshl_add_u64 v[146:147], v[146:147], 0, s[16:17]
	v_cndmask_b32_e64 v183, v184, v185, s[12:13]
	v_mul_f32_e32 v184, 0x37800000, v183
	v_cndmask_b32_e32 v183, v183, v184, vcc
	v_cmp_class_f32_e32 vcc, v182, v171
	v_lshl_add_u64 v[146:147], v[146:147], 0, v[158:159]
	global_store_dwordx4 v[146:147], v[148:151], off offset:1024
	v_cndmask_b32_e32 v182, v183, v182, vcc
	v_div_scale_f32 v183, s[12:13], v182, v182, 1.0
	v_rcp_f32_e32 v184, v183
	v_mad_u64_u32 v[188:189], s[12:13], v188, s1, v[144:145]
	v_mad_i32_i24 v189, s23, v153, v189
	v_fma_f32 v146, -v183, v184, 1.0
	v_fmac_f32_e32 v184, v146, v184
	v_div_scale_f32 v146, vcc, 1.0, v182, 1.0
	v_mul_f32_e32 v147, v146, v184
	v_fma_f32 v148, -v183, v147, v146
	v_fmac_f32_e32 v147, v148, v184
	v_fma_f32 v146, -v183, v147, v146
	v_div_fmas_f32 v148, v146, v184, v147
	v_lshlrev_b32_e32 v146, 16, v36
	v_and_b32_e32 v147, 0xffff0000, v36
	v_mul_f32_e32 v149, 0xbfb8aa3b, v146
	v_exp_f32_e32 v149, v149
	v_mul_f32_e32 v150, 0xbfb8aa3b, v147
	v_exp_f32_e32 v151, v150
	v_div_fixup_f32 v148, v148, v182, 1.0
	v_add_f32_e32 v149, 1.0, v149
	v_rcp_f32_e32 v150, v149
	v_add_f32_e32 v149, 1.0, v151
	v_rcp_f32_e32 v151, v149
	v_pk_mul_f32 v[140:141], v[140:141], v[148:149] op_sel_hi:[1,0]
	v_lshl_add_u64 v[188:189], v[188:189], 0, s[24:25]
	v_pk_mul_f32 v[140:141], v[116:117], v[140:141]
	v_lshl_add_u64 v[188:189], v[188:189], 0, s[16:17]
	v_pk_mul_f32 v[140:141], v[140:141], v[146:147]
	v_lshlrev_b32_e32 v146, 16, v37
	v_and_b32_e32 v147, 0xffff0000, v37
	v_mul_f32_e32 v149, 0xbfb8aa3b, v146
	v_pk_mul_f32 v[140:141], v[150:151], v[140:141]
	v_exp_f32_e32 v149, v149
	v_mul_f32_e32 v150, 0xbfb8aa3b, v147
	v_exp_f32_e32 v151, v150
	v_cvt_pk_bf16_f32 v140, v140, v141
	v_add_f32_e32 v141, 1.0, v149
	v_rcp_f32_e32 v150, v141
	v_add_f32_e32 v141, 1.0, v151
	v_pk_mul_f32 v[142:143], v[142:143], v[148:149] op_sel_hi:[1,0]
	v_rcp_f32_e32 v151, v141
	v_pk_mul_f32 v[142:143], v[118:119], v[142:143]
	v_lshl_add_u64 v[188:189], v[188:189], 0, v[158:159]
	v_pk_mul_f32 v[142:143], v[142:143], v[146:147]
	v_lshlrev_b32_e32 v146, 16, v38
	v_and_b32_e32 v147, 0xffff0000, v38
	v_mul_f32_e32 v141, 0xbfb8aa3b, v146
	v_exp_f32_e32 v149, v141
	v_mul_f32_e32 v141, 0xbfb8aa3b, v147
	v_pk_mul_f32 v[142:143], v[150:151], v[142:143]
	v_exp_f32_e32 v150, v141
	v_cvt_pk_bf16_f32 v141, v142, v143
	v_add_f32_e32 v142, 1.0, v149
	v_rcp_f32_e32 v142, v142
	v_add_f32_e32 v143, 1.0, v150
	v_rcp_f32_e32 v143, v143
	v_pk_mul_f32 v[136:137], v[136:137], v[148:149] op_sel_hi:[1,0]
	s_nop 0
	v_pk_mul_f32 v[136:137], v[112:113], v[136:137]
	s_nop 0
	v_pk_mul_f32 v[136:137], v[136:137], v[146:147]
	v_lshlrev_b32_e32 v146, 16, v39
	v_pk_mul_f32 v[136:137], v[142:143], v[136:137]
	v_and_b32_e32 v147, 0xffff0000, v39
	v_mul_f32_e32 v142, 0xbfb8aa3b, v146
	v_exp_f32_e32 v143, v142
	v_mul_f32_e32 v142, 0xbfb8aa3b, v147
	v_exp_f32_e32 v149, v142
	v_cvt_pk_bf16_f32 v142, v136, v137
	v_add_f32_e32 v136, 1.0, v143
	v_rcp_f32_e32 v136, v136
	v_add_f32_e32 v137, 1.0, v149
	v_rcp_f32_e32 v137, v137
	v_pk_mul_f32 v[138:139], v[138:139], v[148:149] op_sel_hi:[1,0]
	s_nop 0
	v_pk_mul_f32 v[138:139], v[114:115], v[138:139]
	s_nop 0
	v_pk_mul_f32 v[138:139], v[138:139], v[146:147]
	s_nop 0
	v_pk_mul_f32 v[136:137], v[136:137], v[138:139]
	ds_read2_b32 v[138:139], v202 offset0:32 offset1:48
	ds_read2_b32 v[146:147], v202 offset0:96 offset1:112
	ds_read2_b32 v[148:149], v202 offset0:160 offset1:176
	v_cvt_pk_bf16_f32 v143, v136, v137
	s_waitcnt lgkmcnt(2)
	v_add_f32_e32 v136, 0, v138
	s_waitcnt lgkmcnt(1)
	v_add_f32_e32 v136, v136, v146
	s_waitcnt lgkmcnt(0)
	v_add_f32_e32 v138, v136, v148
	ds_read2_b32 v[136:137], v202 offset0:224 offset1:240
	ds_read2_b32 v[150:151], v186 offset0:32 offset1:48
	ds_read2_b32 v[182:183], v186 offset0:96 offset1:112
	ds_read2_b32 v[184:185], v186 offset0:160 offset1:176
	ds_read2_b32 v[186:187], v186 offset0:224 offset1:240
	s_waitcnt lgkmcnt(4)
	v_add_f32_e32 v136, v138, v136
	s_waitcnt lgkmcnt(3)
	v_add_f32_e32 v136, v136, v150
	s_waitcnt lgkmcnt(2)
	v_add_f32_e32 v136, v136, v182
	s_waitcnt lgkmcnt(1)
	v_add_f32_e32 v136, v136, v184
	s_waitcnt lgkmcnt(0)
	v_add_f32_e32 v136, v136, v186
	v_fmamk_f32 v136, v136, 0x3b800000, v170
	v_mul_f32_e32 v138, 0x4f800000, v136
	v_cmp_gt_f32_e32 vcc, s30, v136
	global_store_dwordx4 v[188:189], v[140:143], off offset:1024
	s_nop 0
	v_cndmask_b32_e32 v136, v136, v138, vcc
	v_sqrt_f32_e32 v138, v136
	s_nop 0
	v_add_u32_e32 v146, -1, v138
	v_fma_f32 v148, -v146, v138, v136
	v_cmp_ge_f32_e64 s[12:13], 0, v148
	v_add_u32_e32 v148, 1, v138
	s_nop 0
	v_cndmask_b32_e64 v146, v138, v146, s[12:13]
	v_fma_f32 v138, -v148, v138, v136
	v_cmp_lt_f32_e64 s[12:13], 0, v138
	s_nop 1
	v_cndmask_b32_e64 v138, v146, v148, s[12:13]
	v_mul_f32_e32 v146, 0x37800000, v138
	v_cndmask_b32_e32 v138, v138, v146, vcc
	v_cmp_class_f32_e32 vcc, v136, v171
	s_nop 1
	v_cndmask_b32_e32 v136, v138, v136, vcc
	v_div_scale_f32 v138, s[12:13], v136, v136, 1.0
	v_rcp_f32_e32 v146, v138
	s_nop 0
	v_fma_f32 v140, -v138, v146, 1.0
	v_fmac_f32_e32 v146, v140, v146
	v_div_scale_f32 v140, vcc, 1.0, v136, 1.0
	v_mul_f32_e32 v141, v140, v146
	v_fma_f32 v142, -v138, v141, v140
	v_fmac_f32_e32 v141, v142, v146
	v_fma_f32 v138, -v138, v141, v140
	v_lshlrev_b32_e32 v140, 16, v40
	v_div_fmas_f32 v138, v138, v146, v141
	v_and_b32_e32 v141, 0xffff0000, v40
	v_mul_f32_e32 v142, 0xbfb8aa3b, v140
	v_exp_f32_e32 v142, v142
	v_mul_f32_e32 v143, 0xbfb8aa3b, v141
	v_exp_f32_e32 v143, v143
	v_div_fixup_f32 v136, v138, v136, 1.0
	v_add_f32_e32 v138, 1.0, v142
	v_rcp_f32_e32 v142, v138
	v_add_f32_e32 v138, 1.0, v143
	v_rcp_f32_e32 v143, v138
	v_pk_mul_f32 v[132:133], v[132:133], v[136:137] op_sel_hi:[1,0]
	v_pk_mul_f32 v[134:135], v[134:135], v[136:137] op_sel_hi:[1,0]
	v_pk_mul_f32 v[132:133], v[116:117], v[132:133]
	v_pk_mul_f32 v[134:135], v[118:119], v[134:135]
	v_pk_mul_f32 v[132:133], v[132:133], v[140:141]
	v_lshlrev_b32_e32 v140, 16, v41
	v_and_b32_e32 v141, 0xffff0000, v41
	v_mul_f32_e32 v138, 0xbfb8aa3b, v140
	v_pk_mul_f32 v[132:133], v[142:143], v[132:133]
	v_exp_f32_e32 v138, v138
	v_mul_f32_e32 v142, 0xbfb8aa3b, v141
	v_exp_f32_e32 v143, v142
	v_cvt_pk_bf16_f32 v132, v132, v133
	v_add_f32_e32 v133, 1.0, v138
	v_rcp_f32_e32 v142, v133
	v_add_f32_e32 v133, 1.0, v143
	v_rcp_f32_e32 v143, v133
	v_pk_mul_f32 v[134:135], v[134:135], v[140:141]
	v_lshlrev_b32_e32 v140, 16, v42
	v_and_b32_e32 v141, 0xffff0000, v42
	v_mul_f32_e32 v133, 0xbfb8aa3b, v140
	v_exp_f32_e32 v138, v133
	v_mul_f32_e32 v133, 0xbfb8aa3b, v141
	v_pk_mul_f32 v[134:135], v[142:143], v[134:135]
	v_exp_f32_e32 v142, v133
	v_cvt_pk_bf16_f32 v133, v134, v135
	v_add_f32_e32 v134, 1.0, v138
	v_rcp_f32_e32 v134, v134
	v_add_f32_e32 v135, 1.0, v142
	v_rcp_f32_e32 v135, v135
	v_pk_mul_f32 v[128:129], v[128:129], v[136:137] op_sel_hi:[1,0]
	v_pk_mul_f32 v[130:131], v[130:131], v[136:137] op_sel_hi:[1,0]
	v_pk_mul_f32 v[128:129], v[112:113], v[128:129]
	v_pk_mul_f32 v[130:131], v[114:115], v[130:131]
	v_pk_mul_f32 v[128:129], v[128:129], v[140:141]
	v_lshlrev_b32_e32 v140, 16, v43
	v_pk_mul_f32 v[128:129], v[134:135], v[128:129]
	v_and_b32_e32 v141, 0xffff0000, v43
	v_mul_f32_e32 v134, 0xbfb8aa3b, v140
	v_exp_f32_e32 v135, v134
	v_mul_f32_e32 v134, 0xbfb8aa3b, v141
	v_exp_f32_e32 v138, v134
	v_cvt_pk_bf16_f32 v134, v128, v129
	v_add_f32_e32 v128, 1.0, v135
	v_rcp_f32_e32 v128, v128
	v_add_f32_e32 v129, 1.0, v138
	v_rcp_f32_e32 v129, v129
	v_pk_mul_f32 v[130:131], v[130:131], v[140:141]
	s_nop 0
	v_pk_mul_f32 v[128:129], v[128:129], v[130:131]
	s_nop 0
	v_cvt_pk_bf16_f32 v135, v128, v129
	v_add_f32_e32 v129, 0, v139
	v_add_f32_e32 v129, v129, v147
	v_add_f32_e32 v129, v129, v149
	v_add_f32_e32 v129, v129, v137
	v_add_f32_e32 v129, v129, v151
	v_add_f32_e32 v129, v129, v183
	v_add_f32_e32 v129, v129, v185
	v_add_f32_e32 v129, v129, v187
	v_fmamk_f32 v129, v129, 0x3b800000, v170
	v_mul_f32_e32 v130, 0x4f800000, v129
	v_cmp_gt_f32_e32 vcc, s30, v129
	v_or_b32_e32 v128, s22, v166
	s_nop 0
	v_cndmask_b32_e32 v130, v129, v130, vcc
	v_sqrt_f32_e32 v131, v130
	v_mad_u64_u32 v[128:129], s[12:13], v128, s1, v[144:145]
	v_mad_i32_i24 v129, s23, v153, v129
	v_add_u32_e32 v136, -1, v131
	v_fma_f32 v137, -v136, v131, v130
	v_cmp_ge_f32_e64 s[12:13], 0, v137
	v_add_u32_e32 v137, 1, v131
	v_lshl_add_u64 v[128:129], v[128:129], 0, s[24:25]
	v_cndmask_b32_e64 v136, v131, v136, s[12:13]
	v_fma_f32 v131, -v137, v131, v130
	v_cmp_lt_f32_e64 s[12:13], 0, v131
	v_lshl_add_u64 v[128:129], v[128:129], 0, s[16:17]
	v_lshl_add_u64 v[128:129], v[128:129], 0, v[158:159]
	v_cndmask_b32_e64 v131, v136, v137, s[12:13]
	v_mul_f32_e32 v136, 0x37800000, v131
	v_cndmask_b32_e32 v131, v131, v136, vcc
	v_cmp_class_f32_e32 vcc, v130, v171
	global_store_dwordx4 v[128:129], v[132:135], off offset:1024
	s_nop 0
	v_cndmask_b32_e32 v130, v131, v130, vcc
	v_div_scale_f32 v131, s[12:13], v130, v130, 1.0
	v_rcp_f32_e32 v136, v131
	s_nop 0
	v_fma_f32 v128, -v131, v136, 1.0
	v_fmac_f32_e32 v136, v128, v136
	v_div_scale_f32 v128, vcc, 1.0, v130, 1.0
	v_mul_f32_e32 v129, v128, v136
	v_fma_f32 v132, -v131, v129, v128
	v_fmac_f32_e32 v129, v132, v136
	v_fma_f32 v128, -v131, v129, v128
	v_div_fmas_f32 v131, v128, v136, v129
	v_lshlrev_b32_e32 v128, 16, v44
	v_and_b32_e32 v129, 0xffff0000, v44
	v_mul_f32_e32 v132, 0xbfb8aa3b, v128
	v_exp_f32_e32 v132, v132
	v_mul_f32_e32 v133, 0xbfb8aa3b, v129
	v_exp_f32_e32 v133, v133
	v_div_fixup_f32 v130, v131, v130, 1.0
	v_add_f32_e32 v131, 1.0, v132
	v_rcp_f32_e32 v132, v131
	v_add_f32_e32 v131, 1.0, v133
	v_pk_mul_f32 v[124:125], v[124:125], v[130:131] op_sel_hi:[1,0]
	v_rcp_f32_e32 v133, v131
	v_pk_mul_f32 v[116:117], v[116:117], v[124:125]
	v_lshlrev_b32_e32 v124, 16, v45
	v_pk_mul_f32 v[116:117], v[116:117], v[128:129]
	v_and_b32_e32 v125, 0xffff0000, v45
	v_mul_f32_e32 v128, 0xbfb8aa3b, v124
	v_exp_f32_e32 v128, v128
	v_mul_f32_e32 v129, 0xbfb8aa3b, v125
	v_exp_f32_e32 v129, v129
	v_pk_mul_f32 v[116:117], v[132:133], v[116:117]
	v_pk_mul_f32 v[126:127], v[126:127], v[130:131] op_sel_hi:[1,0]
	v_cvt_pk_bf16_f32 v116, v116, v117
	v_add_f32_e32 v117, 1.0, v128
	v_pk_mul_f32 v[118:119], v[118:119], v[126:127]
	v_rcp_f32_e32 v128, v117
	v_add_f32_e32 v117, 1.0, v129
	v_pk_mul_f32 v[118:119], v[118:119], v[124:125]
	v_lshlrev_b32_e32 v124, 16, v46
	v_rcp_f32_e32 v129, v117
	v_and_b32_e32 v125, 0xffff0000, v46
	v_mul_f32_e32 v117, 0xbfb8aa3b, v124
	v_exp_f32_e32 v126, v117
	v_mul_f32_e32 v117, 0xbfb8aa3b, v125
	v_exp_f32_e32 v127, v117
	v_pk_mul_f32 v[118:119], v[128:129], v[118:119]
	v_pk_mul_f32 v[120:121], v[120:121], v[130:131] op_sel_hi:[1,0]
	v_cvt_pk_bf16_f32 v117, v118, v119
	v_add_f32_e32 v118, 1.0, v126
	v_add_f32_e32 v119, 1.0, v127
	v_rcp_f32_e32 v118, v118
	v_rcp_f32_e32 v119, v119
	v_pk_mul_f32 v[112:113], v[112:113], v[120:121]
	v_lshlrev_b32_e32 v120, 16, v47
	v_pk_mul_f32 v[112:113], v[112:113], v[124:125]
	v_and_b32_e32 v121, 0xffff0000, v47
	v_pk_mul_f32 v[112:113], v[118:119], v[112:113]
	v_mul_f32_e32 v118, 0xbfb8aa3b, v120
	v_exp_f32_e32 v119, v118
	v_mul_f32_e32 v118, 0xbfb8aa3b, v121
	v_exp_f32_e32 v124, v118
	v_cvt_pk_bf16_f32 v118, v112, v113
	v_add_f32_e32 v112, 1.0, v119
	v_rcp_f32_e32 v112, v112
	v_add_f32_e32 v113, 1.0, v124
	v_rcp_f32_e32 v113, v113
	v_pk_mul_f32 v[122:123], v[122:123], v[130:131] op_sel_hi:[1,0]
	s_andn2_b64 vcc, exec, s[20:21]
	v_pk_mul_f32 v[114:115], v[114:115], v[122:123]
	s_nop 0
	v_pk_mul_f32 v[114:115], v[114:115], v[120:121]
	s_nop 0
	v_pk_mul_f32 v[112:113], v[112:113], v[114:115]
	s_nop 0
	v_cvt_pk_bf16_f32 v119, v112, v113
	v_or_b32_e32 v112, s22, v168
	v_mad_u64_u32 v[112:113], s[12:13], v112, s1, v[144:145]
	v_mad_i32_i24 v113, s23, v153, v113
	v_lshl_add_u64 v[112:113], v[112:113], 0, s[24:25]
	v_lshl_add_u64 v[112:113], v[112:113], 0, s[16:17]
	v_lshl_add_u64 v[112:113], v[112:113], 0, v[158:159]
	global_store_dwordx4 v[112:113], v[116:119], off offset:1024
	s_cbranch_vccnz .LBB0_914
; __device__ __forceinline__ void phase_gla_out(Frame& F) {
;     ...
;         if (u1 < NU) { GO_LOAD(u2 < NU ? u2 : u1, sA, rA, qA); GO_COMPUTE(u1, 1, sB, rB, qB); }
	s_add_i32 s12, s28, s36
	s_cmpk_lt_i32 s12, 0x400
	s_cselect_b32 s12, s12, s31
	s_and_b32 s24, s12, 3
	s_ashr_i32 s12, s12, 2
	s_ashr_i32 s13, s12, 31
	s_lshl_b32 s22, s24, 6
	s_lshl_b64 s[20:21], s[12:13], 8
	s_add_i32 s25, s22, s0
	s_add_u32 s22, s20, s25
	s_addc_u32 s23, s21, 0
	s_lshl_b64 s[22:23], s[22:23], 10
	v_lshl_add_u64 v[12:13], v[160:161], 0, s[22:23]
	s_or_b32 s22, s25, 4
	s_add_u32 s20, s20, s22
	s_addc_u32 s21, s21, 0
	s_lshl_b64 s[20:21], s[20:21], 10
	v_lshl_add_u64 v[28:29], v[160:161], 0, s[20:21]
	s_lshl_b64 s[20:21], s[12:13], 6
	v_or_b32_e32 v34, s20, v152
	v_mov_b64_e32 v[32:33], s[18:19]
	v_mad_u64_u32 v[32:33], s[22:23], v34, s1, v[32:33]
	v_mad_i32_i24 v33, s21, v153, v33
	s_lshl_b32 s20, s24, 9
	s_mov_b32 s21, s17
	v_lshl_add_u64 v[32:33], v[32:33], 0, s[20:21]
	v_lshl_add_u64 v[32:33], v[32:33], 0, s[16:17]
	v_lshl_add_u64 v[40:41], v[32:33], 0, v[158:159]
	s_lshl_b32 s13, s24, 8
	v_add_co_u32_e32 v32, vcc, s4, v40
	s_mul_hi_i32 s20, s12, 0x60000
	s_mul_i32 s12, s12, 0x60000
	v_addc_co_u32_e32 v33, vcc, 0, v41, vcc
	s_add_u32 s12, s18, s12
	v_add_co_u32_e32 v36, vcc, s5, v40
	s_addc_u32 s20, s19, s20
	s_nop 0
	v_addc_co_u32_e32 v37, vcc, 0, v41, vcc
	s_add_u32 s12, s12, s13
	v_add_co_u32_e32 v42, vcc, s6, v40
	s_addc_u32 s13, s20, 0
	s_nop 0
	v_addc_co_u32_e32 v43, vcc, 0, v41, vcc
	v_lshl_add_u64 v[48:49], v[154:155], 1, s[12:13]
	v_lshl_add_u64 v[52:53], v[156:157], 1, s[12:13]
	s_add_i32 s12, s29, s26
	v_add_co_u32_e32 v44, vcc, s7, v40
	s_and_b32 s22, s12, 0x300
	s_nop 0
	v_addc_co_u32_e32 v45, vcc, 0, v41, vcc
	s_lshl_b32 s12, s22, 2
	s_mov_b32 s13, s17
	global_load_dwordx4 v[0:3], v[12:13], off
	global_load_dwordx4 v[4:7], v[12:13], off offset:1024
	global_load_dwordx4 v[8:11], v[12:13], off offset:2048
	s_nop 0
	global_load_dwordx4 v[12:15], v[12:13], off offset:3072
	s_nop 0
	global_load_dwordx4 v[16:19], v[28:29], off
	global_load_dwordx4 v[20:23], v[28:29], off offset:1024
	global_load_dwordx4 v[24:27], v[28:29], off offset:2048
	s_nop 0
	global_load_dwordx4 v[28:31], v[28:29], off offset:3072
	s_nop 0
	global_load_dwordx4 v[32:35], v[32:33], off
	s_nop 0
	global_load_dwordx4 v[36:39], v[36:37], off
	s_nop 0
	global_load_dwordx4 v[40:43], v[42:43], off
	s_nop 0
	global_load_dwordx4 v[44:47], v[44:45], off
	s_nop 0
	global_load_dwordx4 v[48:51], v[48:49], off
	s_nop 0
	global_load_dwordx4 v[52:55], v[52:53], off
	ds_write_b128 v172, v[104:107] offset:16384
	ds_write_b128 v173, v[108:111] offset:16384
	v_lshl_add_u64 v[108:109], v[162:163], 0, s[12:13]
	global_load_dwordx4 v[104:107], v[108:109], off offset:16
	s_nop 0
	global_load_dwordx4 v[108:111], v[108:109], off
	s_waitcnt lgkmcnt(0)
	s_barrier
	ds_read2st64_b64 v[112:115], v174 offset0:32 offset1:40
	ds_read2st64_b64 v[116:119], v175 offset0:32 offset1:40
	ds_read2st64_b64 v[124:127], v176 offset0:32 offset1:40
	ds_read2st64_b64 v[138:141], v177 offset0:32 offset1:40
	ds_read2st64_b64 v[134:137], v178 offset0:32 offset1:40
	s_waitcnt lgkmcnt(4)
	v_mov_b32_e32 v120, v112
	v_mov_b32_e32 v121, v113
	s_waitcnt lgkmcnt(3)
	v_mov_b32_e32 v122, v116
	v_mov_b32_e32 v123, v117
	ds_read2st64_b64 v[142:145], v179 offset0:32 offset1:40
	s_waitcnt lgkmcnt(3)
	v_mov_b32_e32 v128, v124
	v_mfma_f32_16x16x32_bf16 v[182:185], v[100:103], v[120:123], 0
	v_mov_b32_e32 v129, v125
	s_waitcnt lgkmcnt(2)
	v_mov_b32_e32 v130, v138
	v_mov_b32_e32 v131, v139
	s_waitcnt lgkmcnt(1)
	v_mov_b32_e32 v146, v134
	v_mov_b32_e32 v147, v135
	v_mfma_f32_16x16x32_bf16 v[132:135], v[96:99], v[128:131], v[182:185]
	ds_read2st64_b64 v[186:189], v180 offset0:32 offset1:40
	s_waitcnt lgkmcnt(1)
	v_mov_b32_e32 v148, v142
	v_mov_b32_e32 v149, v143
	ds_read2st64_b64 v[182:185], v181 offset0:32 offset1:40
	v_mfma_f32_16x16x32_bf16 v[120:123], v[84:87], v[120:123], 0
	s_waitcnt lgkmcnt(1)
	v_mov_b32_e32 v190, v186
	v_mov_b32_e32 v191, v187
	v_mov_b32_e32 v116, v114
	v_mfma_f32_16x16x32_bf16 v[132:135], v[92:95], v[146:149], v[132:135]
	s_waitcnt lgkmcnt(0)
	v_mov_b32_e32 v192, v182
	v_mov_b32_e32 v193, v183
	v_mov_b32_e32 v117, v115
	v_mfma_f32_16x16x32_bf16 v[120:123], v[80:83], v[128:131], v[120:123]
	v_mov_b32_e32 v138, v126
	v_mov_b32_e32 v139, v127
	v_mov_b32_e32 v142, v136
	v_mfma_f32_16x16x32_bf16 v[132:135], v[88:91], v[190:193], v[132:135]
	v_mov_b32_e32 v143, v137
	v_mov_b32_e32 v182, v188
	v_mov_b32_e32 v183, v189
	v_mfma_f32_16x16x32_bf16 v[120:123], v[76:79], v[146:149], v[120:123]
	ds_read2st64_b64 v[194:197], v179 offset0:48 offset1:56
	s_nop 2
	v_mul_f32_e32 v112, v133, v133
	v_mul_f32_e32 v113, v135, v135
	v_fmac_f32_e32 v112, v132, v132
	v_fmac_f32_e32 v113, v134, v134
	v_add_f32_e32 v146, v112, v113
	v_mfma_f32_16x16x32_bf16 v[112:115], v[100:103], v[116:119], 0
	ds_read2st64_b64 v[202:205], v180 offset0:48 offset1:56
	ds_read2st64_b64 v[206:209], v181 offset0:48 offset1:56
	s_waitcnt lgkmcnt(2)
; __device__ __forceinline__ float sum_groups16(float x) {
;     const unsigned u = __builtin_bit_cast(unsigned, x);
;     auto r = __builtin_amdgcn_permlane16_swap(u, u, false, false);
;     const float y = __builtin_bit_cast(float, (unsigned)r[0]) + __builtin_bit_cast(float, (unsigned)r[1]);
;     const unsigned v = __builtin_bit_cast(unsigned, y);
;     auto q = __builtin_amdgcn_permlane32_swap(v, v, false, false);
;     return __builtin_bit_cast(float, (unsigned)q[0]) + __builtin_bit_cast(float, (unsigned)q[1]);
; }
	v_mov_b32_e32 v200, v194
	v_mfma_f32_16x16x32_bf16 v[112:115], v[96:99], v[138:141], v[112:115]
	v_mov_b32_e32 v201, v195
	s_waitcnt lgkmcnt(1)
	v_mov_b32_e32 v210, v202
	v_mov_b32_e32 v211, v203
	v_mfma_f32_16x16x32_bf16 v[128:131], v[72:75], v[190:193], v[120:123]
	ds_read2st64_b64 v[190:193], v178 offset0:48 offset1:56
	s_waitcnt lgkmcnt(1)
	v_mov_b32_e32 v212, v206
	v_mov_b32_e32 v213, v207
	v_mfma_f32_16x16x32_bf16 v[112:115], v[92:95], v[142:145], v[112:115]
	v_mov_b32_e32 v206, v204
	s_nop 1
	v_mul_f32_e32 v120, v129, v129
	v_mul_f32_e32 v121, v131, v131
	v_fmac_f32_e32 v120, v128, v128
	v_fmac_f32_e32 v121, v130, v130
	v_mfma_f32_16x16x32_bf16 v[124:127], v[88:91], v[182:185], v[112:115]
	s_waitcnt lgkmcnt(0)
	v_mov_b32_e32 v198, v190
	v_mov_b32_e32 v199, v191
	v_mov_b32_e32 v194, v192
	v_add_f32_e32 v112, v120, v121
	v_add_f32_e32 v120, v146, v112
	v_mfma_f32_16x16x32_bf16 v[112:115], v[84:87], v[116:119], 0
	v_mov_b32_e32 v121, v120
	s_nop 1
	v_permlane16_swap_b32_e32 v120, v121
	v_mfma_f32_16x16x32_bf16 v[112:115], v[80:83], v[138:141], v[112:115]
	ds_read2st64_b64 v[138:141], v174 offset0:48 offset1:56
	v_add_f32_e32 v136, v120, v121
	v_mul_f32_e32 v116, v125, v125
	v_mfma_f32_16x16x32_bf16 v[112:115], v[76:79], v[142:145], v[112:115]
	ds_read2st64_b64 v[142:145], v175 offset0:48 offset1:56
	v_mul_f32_e32 v117, v127, v127
	ds_read2st64_b64 v[146:149], v176 offset0:48 offset1:56
	v_mfma_f32_16x16x32_bf16 v[120:123], v[72:75], v[182:185], v[112:115]
	ds_read2st64_b64 v[182:185], v177 offset0:48 offset1:56
	v_fmac_f32_e32 v116, v124, v124
	v_fmac_f32_e32 v117, v126, v126
	s_waitcnt lgkmcnt(3)
	v_mov_b32_e32 v112, v138
	v_mov_b32_e32 v113, v139
	s_waitcnt lgkmcnt(2)
	v_mov_b32_e32 v114, v142
	v_mov_b32_e32 v115, v143
	v_add_f32_e32 v150, v116, v117
	s_waitcnt lgkmcnt(1)
	v_mov_b32_e32 v186, v146
	v_mfma_f32_16x16x32_bf16 v[116:119], v[100:103], v[112:115], 0
	v_mov_b32_e32 v187, v147
	s_waitcnt lgkmcnt(0)
	v_mov_b32_e32 v188, v182
	v_mov_b32_e32 v189, v183
	v_mfma_f32_16x16x32_bf16 v[112:115], v[84:87], v[112:115], 0
	v_mov_b32_e32 v182, v148
	v_mov_b32_e32 v183, v149
	v_mov_b32_e32 v195, v193
	v_mfma_f32_16x16x32_bf16 v[116:119], v[96:99], v[186:189], v[116:119]
	v_mov_b32_e32 v207, v205
	v_mul_f32_e32 v151, v121, v121
	v_mul_f32_e32 v214, v123, v123
	v_mfma_f32_16x16x32_bf16 v[116:119], v[92:95], v[198:201], v[116:119]
	v_fmac_f32_e32 v151, v120, v120
	v_fmac_f32_e32 v214, v122, v122
	v_add_f32_e32 v138, v151, v214
	v_mfma_f32_16x16x32_bf16 v[116:119], v[88:91], v[210:213], v[116:119]
	v_add_f32_e32 v138, v150, v138
	v_mov_b32_e32 v139, v138
	s_nop 1
	v_permlane16_swap_b32_e32 v138, v139
	v_mfma_f32_16x16x32_bf16 v[112:115], v[80:83], v[186:189], v[112:115]
	s_nop 1
	v_mul_f32_e32 v142, v117, v117
	v_mul_f32_e32 v143, v119, v119
	v_fmac_f32_e32 v142, v116, v116
	v_fmac_f32_e32 v143, v118, v118
	v_add_f32_e32 v146, v142, v143
	v_mov_b32_e32 v142, v140
	v_mov_b32_e32 v143, v141
	v_mfma_f32_16x16x32_bf16 v[112:115], v[76:79], v[198:201], v[112:115]
	v_add_f32_e32 v138, v138, v139
	v_mov_b32_e32 v137, v136
	v_mov_b32_e32 v139, v138
	v_mfma_f32_16x16x32_bf16 v[100:103], v[100:103], v[142:145], 0
	v_permlane32_swap_b32_e32 v136, v137
	v_permlane32_swap_b32_e32 v138, v139
	v_mfma_f32_16x16x32_bf16 v[96:99], v[96:99], v[182:185], v[100:103]
	v_mfma_f32_16x16x32_bf16 v[112:115], v[72:75], v[210:213], v[112:115]
	v_mfma_f32_16x16x32_bf16 v[92:95], v[92:95], v[194:197], v[96:99]
	v_mfma_f32_16x16x32_bf16 v[88:91], v[88:91], v[206:209], v[92:95]
	s_nop 5
	v_mul_f32_e32 v147, v113, v113
	v_mul_f32_e32 v100, v115, v115
	v_fmac_f32_e32 v147, v112, v112
	v_fmac_f32_e32 v100, v114, v114
	v_add_f32_e32 v92, v147, v100
	v_add_f32_e32 v96, v146, v92
	v_mfma_f32_16x16x32_bf16 v[92:95], v[84:87], v[142:145], 0
	v_mul_f32_e32 v86, v89, v89
	v_fmac_f32_e32 v86, v88, v88
	v_mov_b32_e32 v97, v96
	v_mfma_f32_16x16x32_bf16 v[80:83], v[80:83], v[182:185], v[92:95]
	s_nop 0
	v_permlane16_swap_b32_e32 v96, v97
	v_add_f32_e32 v84, v96, v97
	v_mfma_f32_16x16x32_bf16 v[76:79], v[76:79], v[194:197], v[80:83]
	v_mov_b32_e32 v85, v84
	s_nop 1
	v_permlane32_swap_b32_e32 v84, v85
	v_mfma_f32_16x16x32_bf16 v[72:75], v[72:75], v[206:209], v[76:79]
	v_mul_f32_e32 v80, v91, v91
	v_fmac_f32_e32 v80, v90, v90
	v_add_f32_e32 v80, v86, v80
	s_nop 4
	v_mul_f32_e32 v76, v73, v73
	v_mul_f32_e32 v77, v75, v75
	v_fmac_f32_e32 v76, v72, v72
	v_fmac_f32_e32 v77, v74, v74
	v_add_f32_e32 v76, v76, v77
	v_add_f32_e32 v76, v80, v76
	v_mov_b32_e32 v77, v76
	s_nop 1
	v_permlane16_swap_b32_e32 v76, v77
	v_add_f32_e32 v76, v76, v77
	v_mov_b32_e32 v77, v76
	s_nop 1
	v_permlane32_swap_b32_e32 v76, v77
	s_and_saveexec_b64 s[12:13], s[10:11]
	s_cbranch_execz .LBB0_913
	v_add_f32_e32 v78, v138, v139
	v_add_f32_e32 v79, v136, v137
	v_add_u32_e32 v80, 0x8800, v165
	v_add_f32_e32 v76, v76, v77
	v_add_f32_e32 v77, v84, v85
	ds_write2_b32 v80, v79, v78 offset1:16
	ds_write2_b32 v80, v77, v76 offset0:32 offset1:48
	s_branch .LBB0_913

;     __device__ __forceinline__ void epi(AccT& acc, const Unit& u, LAS unsigned char* lds, int wr, int wc, int fr, int fq) const {
;     ...
;         if (wid == 0) {
;             bool dead = false; const unsigned long long t0 = __builtin_amdgcn_s_memrealtime();
;             for (;;) {
;                 if ((unsigned)__builtin_amdgcn_readfirstlane(__hip_atomic_load(cnt + 64 * u.pm, __ATOMIC_RELAXED, __HIP_MEMORY_SCOPE_AGENT)) >= 32u) break;
;                 if (__builtin_amdgcn_s_memrealtime() - t0 > 2000000ull) { if (lane == 0) __hip_atomic_store(tmo, 1u, __ATOMIC_RELAXED, __HIP_MEMORY_SCOPE_AGENT); dead = true; break; }
;                 __builtin_amdgcn_s_sleep(2);
;             }
;             __builtin_amdgcn_fence(__ATOMIC_ACQUIRE, "agent");
;             if (lane == 0) flag[0] = dead ? 1u : 0u;
;         }
;         asm volatile("s_waitcnt vmcnt(0) lgkmcnt(0)" ::: "memory"); __builtin_amdgcn_s_barrier(); asm volatile("" ::: "memory");
.LBB0_1036:
	s_waitcnt vmcnt(0)
	s_and_b64 exec, exec, s[14:15]
	v_cndmask_b32_e64 v66, 0, 1, s[74:75]
	v_mov_b32_e32 v67, s60
	ds_write_b32 v67, v66

; __device__ __forceinline__ unsigned cvt_pk_bf16(float lo, float hi) { const f32x2 v = {lo, hi}; const bf16x2_t b = __builtin_convertvector(v, bf16x2_t); return __builtin_bit_cast(unsigned, b); }
; __device__ __forceinline__ void store16_wt(void* p, u32x4 v) { asm volatile("global_store_dwordx4 %0, %1, off sc1\n\ts_nop 1" :: "v"(p), "v"(v) : "memory"); }
; __device__ __forceinline__ u32x4 ror8_u4(u32x4 v) { const unsigned a = ror8_u(v.x), b = ror8_u(v.y), c = ror8_u(v.z), d = ror8_u(v.w); return (u32x4){a, b, c, d}; }
; #define PG8_STAGE(bufoff, gbase, voff, aux) do { _Pragma("unroll") for (int _i = 0; _i < 2; ++_i) \
;         __builtin_amdgcn_raw_ptr_buffer_load_lds(rs, (LAS void*)(lds + (bufoff) + ldsw + _i * 8192), 16, (voff)[_i], (unsigned)((const char*)(gbase) - wsb), 0, (aux)); } while (0)
; template <class Prob, bool ALIGN_EPI, bool SP2>
; __device__ __forceinline__ void gemm_phase(LAS unsigned char* lds, const Prob& Pb, int wave, const char* wsb) {
;     ...
;         if constexpr (SP2 && Prob::EPI_VM > 0) { static_assert(ALIGN_EPI, "early stage needs the aligned epilogue"); const char* e1 = nA + kstepA + hstepA; asm volatile("" : "+s"(e1)); PG8_STAGE(PG8_SA(1, 1), e1, voffA, Prob::A_AUX); }
;     __device__ __forceinline__ void epi(AccT& acc, const Unit& u, LAS unsigned char* lds, int wr, int wc, int fr, int fq) const {
;     ...
; #pragma unroll
;         for (int ai = 0; ai < 2; ++ai)
; #pragma unroll
;             for (int m = 0; m < 4; ++m) { const bool lo = fr < 8; bf16_t* rp = O + (size_t)(u.pm * 256 + ai * 128 + wr * 64 + m * 16 + (fr & 7)) * ldc + u.pn * 256 + wc * 64 + (lo ? 0 : 32) + 8 * fq; u32x4 w[2];
; #pragma unroll
;                 for (int bj = 0; bj < 2; ++bj) { f32x4 v0 = acc[ai][bj][m][0], v1 = acc[ai][bj][m][1];
;                     if (ACT == 1) { v0 = __builtin_elementwise_max(v0, (f32x4){0.f, 0.f, 0.f, 0.f}); v1 = __builtin_elementwise_max(v1, (f32x4){0.f, 0.f, 0.f, 0.f}); v0 = v0 * v0; v1 = v1 * v1; }
;                     w[bj].x = cvt_pk_bf16(v0[0], v0[1]); w[bj].y = cvt_pk_bf16(v0[2], v0[3]); w[bj].z = cvt_pk_bf16(v1[0], v1[1]); w[bj].w = cvt_pk_bf16(v1[2], v1[3]); }
;                 const u32x4 r0 = ror8_u4(w[0]), r1 = ror8_u4(w[1]); store16_wt(rp, lo ? w[0] : r1); store16_wt(rp + (size_t)8 * ldc, lo ? r0 : w[1]); }
.LBB0_1141:
	s_add_u32 s46, s54, 0x40080
	s_addc_u32 s47, s37, 0
	s_mov_b32 m0, s73
	s_sub_i32 s31, s46, s34
	s_mov_b32 s12, s34
	buffer_load_dwordx4 v138, s[12:15], s31 offen lds
	s_mov_b32 m0, s74
	v_lshl_add_u32 v136, s44, 8, v142
	buffer_load_dwordx4 v140, s[12:15], s31 offen lds
	s_lshl_b32 s44, s45, 8
	v_ashrrev_i32_e32 v137, 31, v136
	s_ashr_i32 s45, s44, 31
	v_lshlrev_b64 v[148:149], 13, v[136:137]
	v_max_f32_e32 v121, 0, v121
	v_max_f32_e32 v120, 0, v120
	v_max_f32_e32 v123, 0, v123
	v_max_f32_e32 v122, 0, v122
	v_max_f32_e32 v117, 0, v117
	v_max_f32_e32 v116, 0, v116
	v_lshl_add_u64 v[148:149], s[22:23], 0, v[148:149]
	s_lshl_b64 s[44:45], s[44:45], 1
	v_max_f32_e32 v125, 0, v125
	v_max_f32_e32 v124, 0, v124
	v_pk_mul_f32 v[122:123], v[122:123], v[122:123]
	v_pk_mul_f32 v[120:121], v[120:121], v[120:121]
	v_max_f32_e32 v119, 0, v119
	v_max_f32_e32 v118, 0, v118
	v_max_f32_e32 v113, 0, v113
	v_max_f32_e32 v112, 0, v112
	v_max_f32_e32 v115, 0, v115
	v_max_f32_e32 v114, 0, v114
	v_pk_mul_f32 v[116:117], v[116:117], v[116:117]
	v_lshl_add_u64 v[148:149], v[148:149], 0, s[44:45]
	v_max_f32_e32 v127, 0, v127
	v_max_f32_e32 v126, 0, v126
	v_pk_mul_f32 v[124:125], v[124:125], v[124:125]
	v_cvt_pk_bf16_f32 v120, v120, v121
	v_cvt_pk_bf16_f32 v121, v122, v123
	v_pk_mul_f32 v[118:119], v[118:119], v[118:119]
	v_pk_mul_f32 v[114:115], v[114:115], v[114:115]
	v_pk_mul_f32 v[112:113], v[112:113], v[112:113]
	v_cvt_pk_bf16_f32 v122, v116, v117
	v_lshl_add_u64 v[148:149], v[148:149], 0, s[20:21]
	v_pk_mul_f32 v[126:127], v[126:127], v[126:127]
	v_cvt_pk_bf16_f32 v124, v124, v125
	v_cvt_pk_bf16_f32 v118, v118, v119
	v_cvt_pk_bf16_f32 v119, v112, v113
	v_cvt_pk_bf16_f32 v123, v114, v115
	v_mov_b32_dpp v112, v122 row_ror:8 row_mask:0xf bank_mask:0xf bound_ctrl:1
	v_lshl_add_u64 v[148:149], v[148:149], 0, v[128:129]
	v_cvt_pk_bf16_f32 v125, v126, v127
	v_mov_b32_dpp v126, v124 row_ror:8 row_mask:0xf bank_mask:0xf bound_ctrl:1
	v_mov_b32_dpp v113, v118 row_ror:8 row_mask:0xf bank_mask:0xf bound_ctrl:1
	v_mov_b32_dpp v114, v119 row_ror:8 row_mask:0xf bank_mask:0xf bound_ctrl:1
	v_mov_b32_dpp v115, v123 row_ror:8 row_mask:0xf bank_mask:0xf bound_ctrl:1
	v_cndmask_b32_e64 v112, v112, v124, s[6:7]
	v_lshl_add_u64 v[116:117], v[148:149], 0, v[134:135]
	v_mov_b32_dpp v127, v125 row_ror:8 row_mask:0xf bank_mask:0xf bound_ctrl:1
	v_mov_b32_dpp v137, v120 row_ror:8 row_mask:0xf bank_mask:0xf bound_ctrl:1
	v_mov_b32_dpp v148, v121 row_ror:8 row_mask:0xf bank_mask:0xf bound_ctrl:1
	v_cndmask_b32_e64 v115, v115, v121, s[6:7]
	v_cndmask_b32_e64 v114, v114, v120, s[6:7]
	v_cndmask_b32_e64 v113, v113, v125, s[6:7]
	global_store_dwordx4 v[116:117], v[112:115], off sc1
	s_nop 1
	v_cndmask_b32_e64 v112, v122, v126, s[6:7]
	v_lshl_add_u64 v[116:117], v[116:117], 0, s[26:27]
	v_cndmask_b32_e64 v115, v123, v148, s[6:7]
	v_cndmask_b32_e64 v114, v119, v137, s[6:7]
	v_cndmask_b32_e64 v113, v118, v127, s[6:7]
	global_store_dwordx4 v[116:117], v[112:115], off sc1
	s_nop 1
	v_or_b32_e32 v112, 16, v136
	v_ashrrev_i32_e32 v113, 31, v112
	v_lshlrev_b64 v[112:113], 13, v[112:113]
	v_max_f32_e32 v105, 0, v105
	v_max_f32_e32 v104, 0, v104
	v_max_f32_e32 v107, 0, v107
	v_max_f32_e32 v106, 0, v106
	v_max_f32_e32 v101, 0, v101
	v_max_f32_e32 v100, 0, v100
	v_lshl_add_u64 v[112:113], s[22:23], 0, v[112:113]
	v_max_f32_e32 v109, 0, v109
	v_max_f32_e32 v108, 0, v108
	v_pk_mul_f32 v[106:107], v[106:107], v[106:107]
	v_pk_mul_f32 v[104:105], v[104:105], v[104:105]
	v_max_f32_e32 v103, 0, v103
	v_max_f32_e32 v102, 0, v102
	v_max_f32_e32 v97, 0, v97
	v_max_f32_e32 v96, 0, v96
	v_max_f32_e32 v99, 0, v99
	v_max_f32_e32 v98, 0, v98
	v_pk_mul_f32 v[100:101], v[100:101], v[100:101]
	v_lshl_add_u64 v[112:113], v[112:113], 0, s[44:45]
	v_max_f32_e32 v111, 0, v111
	v_max_f32_e32 v110, 0, v110
	v_pk_mul_f32 v[108:109], v[108:109], v[108:109]
	v_cvt_pk_bf16_f32 v104, v104, v105
	v_cvt_pk_bf16_f32 v105, v106, v107
	v_pk_mul_f32 v[102:103], v[102:103], v[102:103]
	v_pk_mul_f32 v[98:99], v[98:99], v[98:99]
	v_pk_mul_f32 v[96:97], v[96:97], v[96:97]
	v_cvt_pk_bf16_f32 v106, v100, v101
	v_lshl_add_u64 v[112:113], v[112:113], 0, s[20:21]
	v_pk_mul_f32 v[110:111], v[110:111], v[110:111]
	v_cvt_pk_bf16_f32 v108, v108, v109
	v_cvt_pk_bf16_f32 v102, v102, v103
	v_cvt_pk_bf16_f32 v103, v96, v97
	v_cvt_pk_bf16_f32 v107, v98, v99
	v_mov_b32_dpp v96, v106 row_ror:8 row_mask:0xf bank_mask:0xf bound_ctrl:1
	v_lshl_add_u64 v[112:113], v[112:113], 0, v[128:129]
	v_cvt_pk_bf16_f32 v109, v110, v111
	v_mov_b32_dpp v110, v108 row_ror:8 row_mask:0xf bank_mask:0xf bound_ctrl:1
	v_mov_b32_dpp v97, v102 row_ror:8 row_mask:0xf bank_mask:0xf bound_ctrl:1
	v_mov_b32_dpp v98, v103 row_ror:8 row_mask:0xf bank_mask:0xf bound_ctrl:1
	v_mov_b32_dpp v99, v107 row_ror:8 row_mask:0xf bank_mask:0xf bound_ctrl:1
	v_cndmask_b32_e64 v96, v96, v108, s[6:7]
	v_lshl_add_u64 v[100:101], v[112:113], 0, v[134:135]
	v_mov_b32_dpp v111, v109 row_ror:8 row_mask:0xf bank_mask:0xf bound_ctrl:1
	v_mov_b32_dpp v112, v104 row_ror:8 row_mask:0xf bank_mask:0xf bound_ctrl:1
	v_mov_b32_dpp v113, v105 row_ror:8 row_mask:0xf bank_mask:0xf bound_ctrl:1
	v_cndmask_b32_e64 v99, v99, v105, s[6:7]
	v_cndmask_b32_e64 v98, v98, v104, s[6:7]
	v_cndmask_b32_e64 v97, v97, v109, s[6:7]
	global_store_dwordx4 v[100:101], v[96:99], off sc1
	s_nop 1
	v_cndmask_b32_e64 v96, v106, v110, s[6:7]
	v_lshl_add_u64 v[100:101], v[100:101], 0, s[26:27]
	v_cndmask_b32_e64 v99, v107, v113, s[6:7]
	v_cndmask_b32_e64 v98, v103, v112, s[6:7]
	v_cndmask_b32_e64 v97, v102, v111, s[6:7]
	global_store_dwordx4 v[100:101], v[96:99], off sc1
	s_nop 1
	v_or_b32_e32 v96, 32, v136
; __device__ __forceinline__ unsigned cvt_pk_bf16(float lo, float hi) { const f32x2 v = {lo, hi}; const bf16x2_t b = __builtin_convertvector(v, bf16x2_t); return __builtin_bit_cast(unsigned, b); }
; __device__ __forceinline__ void store16_wt(void* p, u32x4 v) { asm volatile("global_store_dwordx4 %0, %1, off sc1\n\ts_nop 1" :: "v"(p), "v"(v) : "memory"); }
; __device__ __forceinline__ u32x4 ror8_u4(u32x4 v) { const unsigned a = ror8_u(v.x), b = ror8_u(v.y), c = ror8_u(v.z), d = ror8_u(v.w); return (u32x4){a, b, c, d}; }
;     __device__ __forceinline__ void epi(AccT& acc, const Unit& u, LAS unsigned char* lds, int wr, int wc, int fr, int fq) const {
;     ...
; #pragma unroll
;         for (int ai = 0; ai < 2; ++ai)
; #pragma unroll
;             for (int m = 0; m < 4; ++m) { const bool lo = fr < 8; bf16_t* rp = O + (size_t)(u.pm * 256 + ai * 128 + wr * 64 + m * 16 + (fr & 7)) * ldc + u.pn * 256 + wc * 64 + (lo ? 0 : 32) + 8 * fq; u32x4 w[2];
; #pragma unroll
;                 for (int bj = 0; bj < 2; ++bj) { f32x4 v0 = acc[ai][bj][m][0], v1 = acc[ai][bj][m][1];
;                     if (ACT == 1) { v0 = __builtin_elementwise_max(v0, (f32x4){0.f, 0.f, 0.f, 0.f}); v1 = __builtin_elementwise_max(v1, (f32x4){0.f, 0.f, 0.f, 0.f}); v0 = v0 * v0; v1 = v1 * v1; }
;                     w[bj].x = cvt_pk_bf16(v0[0], v0[1]); w[bj].y = cvt_pk_bf16(v0[2], v0[3]); w[bj].z = cvt_pk_bf16(v1[0], v1[1]); w[bj].w = cvt_pk_bf16(v1[2], v1[3]); }
;                 const u32x4 r0 = ror8_u4(w[0]), r1 = ror8_u4(w[1]); store16_wt(rp, lo ? w[0] : r1); store16_wt(rp + (size_t)8 * ldc, lo ? r0 : w[1]); }
	v_ashrrev_i32_e32 v97, 31, v96
	v_lshlrev_b64 v[96:97], 13, v[96:97]
	v_max_f32_e32 v89, 0, v89
	v_max_f32_e32 v88, 0, v88
	v_max_f32_e32 v91, 0, v91
	v_max_f32_e32 v90, 0, v90
	v_max_f32_e32 v85, 0, v85
	v_max_f32_e32 v84, 0, v84
	v_lshl_add_u64 v[96:97], s[22:23], 0, v[96:97]
	v_max_f32_e32 v93, 0, v93
	v_max_f32_e32 v92, 0, v92
	v_pk_mul_f32 v[90:91], v[90:91], v[90:91]
	v_pk_mul_f32 v[88:89], v[88:89], v[88:89]
	v_max_f32_e32 v87, 0, v87
	v_max_f32_e32 v86, 0, v86
	v_max_f32_e32 v81, 0, v81
	v_max_f32_e32 v80, 0, v80
	v_max_f32_e32 v83, 0, v83
	v_max_f32_e32 v82, 0, v82
	v_pk_mul_f32 v[84:85], v[84:85], v[84:85]
	v_lshl_add_u64 v[96:97], v[96:97], 0, s[44:45]
	v_max_f32_e32 v95, 0, v95
	v_max_f32_e32 v94, 0, v94
	v_pk_mul_f32 v[92:93], v[92:93], v[92:93]
	v_cvt_pk_bf16_f32 v88, v88, v89
	v_cvt_pk_bf16_f32 v89, v90, v91
	v_pk_mul_f32 v[86:87], v[86:87], v[86:87]
	v_pk_mul_f32 v[82:83], v[82:83], v[82:83]
	v_pk_mul_f32 v[80:81], v[80:81], v[80:81]
	v_cvt_pk_bf16_f32 v90, v84, v85
	v_lshl_add_u64 v[96:97], v[96:97], 0, s[20:21]
	v_pk_mul_f32 v[94:95], v[94:95], v[94:95]
	v_cvt_pk_bf16_f32 v92, v92, v93
	v_cvt_pk_bf16_f32 v86, v86, v87
	v_cvt_pk_bf16_f32 v87, v80, v81
	v_cvt_pk_bf16_f32 v91, v82, v83
	v_mov_b32_dpp v80, v90 row_ror:8 row_mask:0xf bank_mask:0xf bound_ctrl:1
	v_lshl_add_u64 v[96:97], v[96:97], 0, v[128:129]
	v_cvt_pk_bf16_f32 v93, v94, v95
	v_mov_b32_dpp v94, v92 row_ror:8 row_mask:0xf bank_mask:0xf bound_ctrl:1
	v_mov_b32_dpp v81, v86 row_ror:8 row_mask:0xf bank_mask:0xf bound_ctrl:1
	v_mov_b32_dpp v82, v87 row_ror:8 row_mask:0xf bank_mask:0xf bound_ctrl:1
	v_mov_b32_dpp v83, v91 row_ror:8 row_mask:0xf bank_mask:0xf bound_ctrl:1
	v_cndmask_b32_e64 v80, v80, v92, s[6:7]
	v_lshl_add_u64 v[84:85], v[96:97], 0, v[134:135]
	v_mov_b32_dpp v95, v93 row_ror:8 row_mask:0xf bank_mask:0xf bound_ctrl:1
	v_mov_b32_dpp v96, v88 row_ror:8 row_mask:0xf bank_mask:0xf bound_ctrl:1
	v_mov_b32_dpp v97, v89 row_ror:8 row_mask:0xf bank_mask:0xf bound_ctrl:1
	v_cndmask_b32_e64 v83, v83, v89, s[6:7]
	v_cndmask_b32_e64 v82, v82, v88, s[6:7]
	v_cndmask_b32_e64 v81, v81, v93, s[6:7]
	global_store_dwordx4 v[84:85], v[80:83], off sc1
	s_nop 1
	v_cndmask_b32_e64 v80, v90, v94, s[6:7]
	v_lshl_add_u64 v[84:85], v[84:85], 0, s[26:27]
	v_cndmask_b32_e64 v83, v91, v97, s[6:7]
	v_cndmask_b32_e64 v82, v87, v96, s[6:7]
	v_cndmask_b32_e64 v81, v86, v95, s[6:7]
	global_store_dwordx4 v[84:85], v[80:83], off sc1
	s_nop 1
	v_or_b32_e32 v80, 48, v136
	v_ashrrev_i32_e32 v81, 31, v80
	v_lshlrev_b64 v[80:81], 13, v[80:81]
	v_max_f32_e32 v73, 0, v73
	v_max_f32_e32 v72, 0, v72
	v_max_f32_e32 v75, 0, v75
	v_max_f32_e32 v74, 0, v74
	v_max_f32_e32 v69, 0, v69
	v_max_f32_e32 v68, 0, v68
	v_lshl_add_u64 v[80:81], s[22:23], 0, v[80:81]
	v_max_f32_e32 v77, 0, v77
	v_max_f32_e32 v76, 0, v76
	v_pk_mul_f32 v[74:75], v[74:75], v[74:75]
	v_pk_mul_f32 v[72:73], v[72:73], v[72:73]
	v_max_f32_e32 v71, 0, v71
	v_max_f32_e32 v70, 0, v70
	v_max_f32_e32 v65, 0, v65
	v_max_f32_e32 v64, 0, v64
	v_max_f32_e32 v67, 0, v67
	v_max_f32_e32 v66, 0, v66
	v_pk_mul_f32 v[68:69], v[68:69], v[68:69]
	v_lshl_add_u64 v[80:81], v[80:81], 0, s[44:45]
	v_max_f32_e32 v79, 0, v79
	v_max_f32_e32 v78, 0, v78
	v_pk_mul_f32 v[76:77], v[76:77], v[76:77]
	v_cvt_pk_bf16_f32 v72, v72, v73
	v_cvt_pk_bf16_f32 v73, v74, v75
	v_pk_mul_f32 v[70:71], v[70:71], v[70:71]
	v_pk_mul_f32 v[66:67], v[66:67], v[66:67]
	v_pk_mul_f32 v[64:65], v[64:65], v[64:65]
	v_cvt_pk_bf16_f32 v74, v68, v69
	v_lshl_add_u64 v[80:81], v[80:81], 0, s[20:21]
	v_pk_mul_f32 v[78:79], v[78:79], v[78:79]
	v_cvt_pk_bf16_f32 v76, v76, v77
	v_cvt_pk_bf16_f32 v70, v70, v71
	v_cvt_pk_bf16_f32 v71, v64, v65
	v_cvt_pk_bf16_f32 v75, v66, v67
	v_mov_b32_dpp v64, v74 row_ror:8 row_mask:0xf bank_mask:0xf bound_ctrl:1
	v_lshl_add_u64 v[80:81], v[80:81], 0, v[128:129]
	v_cvt_pk_bf16_f32 v77, v78, v79
	v_mov_b32_dpp v78, v76 row_ror:8 row_mask:0xf bank_mask:0xf bound_ctrl:1
	v_mov_b32_dpp v65, v70 row_ror:8 row_mask:0xf bank_mask:0xf bound_ctrl:1
	v_mov_b32_dpp v66, v71 row_ror:8 row_mask:0xf bank_mask:0xf bound_ctrl:1
	v_mov_b32_dpp v67, v75 row_ror:8 row_mask:0xf bank_mask:0xf bound_ctrl:1
	v_cndmask_b32_e64 v64, v64, v76, s[6:7]
	v_lshl_add_u64 v[68:69], v[80:81], 0, v[134:135]
	v_mov_b32_dpp v79, v77 row_ror:8 row_mask:0xf bank_mask:0xf bound_ctrl:1
	v_mov_b32_dpp v80, v72 row_ror:8 row_mask:0xf bank_mask:0xf bound_ctrl:1
	v_mov_b32_dpp v81, v73 row_ror:8 row_mask:0xf bank_mask:0xf bound_ctrl:1
	v_cndmask_b32_e64 v67, v67, v73, s[6:7]
	v_cndmask_b32_e64 v66, v66, v72, s[6:7]
	v_cndmask_b32_e64 v65, v65, v77, s[6:7]
	global_store_dwordx4 v[68:69], v[64:67], off sc1
	s_nop 1
	v_cndmask_b32_e64 v64, v74, v78, s[6:7]
	v_lshl_add_u64 v[68:69], v[68:69], 0, s[26:27]
	v_cndmask_b32_e64 v67, v75, v81, s[6:7]
	v_cndmask_b32_e64 v66, v71, v80, s[6:7]
	v_cndmask_b32_e64 v65, v70, v79, s[6:7]
	global_store_dwordx4 v[68:69], v[64:67], off sc1
	s_nop 1
	v_add_u32_e32 v64, 0x80, v136
	v_ashrrev_i32_e32 v65, 31, v64
	v_lshlrev_b64 v[64:65], 13, v[64:65]
	v_max_f32_e32 v57, 0, v57
	v_max_f32_e32 v56, 0, v56
	v_max_f32_e32 v59, 0, v59
	v_max_f32_e32 v58, 0, v58
	v_max_f32_e32 v53, 0, v53
	v_max_f32_e32 v52, 0, v52
	v_lshl_add_u64 v[64:65], s[22:23], 0, v[64:65]
	v_max_f32_e32 v61, 0, v61
	v_max_f32_e32 v60, 0, v60
	v_pk_mul_f32 v[58:59], v[58:59], v[58:59]
	v_pk_mul_f32 v[56:57], v[56:57], v[56:57]
	v_max_f32_e32 v55, 0, v55
	v_max_f32_e32 v54, 0, v54
	v_max_f32_e32 v49, 0, v49
	v_max_f32_e32 v48, 0, v48
	v_max_f32_e32 v51, 0, v51
	v_max_f32_e32 v50, 0, v50
	v_pk_mul_f32 v[52:53], v[52:53], v[52:53]
	v_lshl_add_u64 v[64:65], v[64:65], 0, s[44:45]
	v_max_f32_e32 v63, 0, v63
; __device__ __forceinline__ unsigned cvt_pk_bf16(float lo, float hi) { const f32x2 v = {lo, hi}; const bf16x2_t b = __builtin_convertvector(v, bf16x2_t); return __builtin_bit_cast(unsigned, b); }
; __device__ __forceinline__ void store16_wt(void* p, u32x4 v) { asm volatile("global_store_dwordx4 %0, %1, off sc1\n\ts_nop 1" :: "v"(p), "v"(v) : "memory"); }
; __device__ __forceinline__ u32x4 ror8_u4(u32x4 v) { const unsigned a = ror8_u(v.x), b = ror8_u(v.y), c = ror8_u(v.z), d = ror8_u(v.w); return (u32x4){a, b, c, d}; }
;     __device__ __forceinline__ void epi(AccT& acc, const Unit& u, LAS unsigned char* lds, int wr, int wc, int fr, int fq) const {
;     ...
; #pragma unroll
;         for (int ai = 0; ai < 2; ++ai)
; #pragma unroll
;             for (int m = 0; m < 4; ++m) { const bool lo = fr < 8; bf16_t* rp = O + (size_t)(u.pm * 256 + ai * 128 + wr * 64 + m * 16 + (fr & 7)) * ldc + u.pn * 256 + wc * 64 + (lo ? 0 : 32) + 8 * fq; u32x4 w[2];
; #pragma unroll
;                 for (int bj = 0; bj < 2; ++bj) { f32x4 v0 = acc[ai][bj][m][0], v1 = acc[ai][bj][m][1];
;                     if (ACT == 1) { v0 = __builtin_elementwise_max(v0, (f32x4){0.f, 0.f, 0.f, 0.f}); v1 = __builtin_elementwise_max(v1, (f32x4){0.f, 0.f, 0.f, 0.f}); v0 = v0 * v0; v1 = v1 * v1; }
;                     w[bj].x = cvt_pk_bf16(v0[0], v0[1]); w[bj].y = cvt_pk_bf16(v0[2], v0[3]); w[bj].z = cvt_pk_bf16(v1[0], v1[1]); w[bj].w = cvt_pk_bf16(v1[2], v1[3]); }
;                 const u32x4 r0 = ror8_u4(w[0]), r1 = ror8_u4(w[1]); store16_wt(rp, lo ? w[0] : r1); store16_wt(rp + (size_t)8 * ldc, lo ? r0 : w[1]); }
	v_max_f32_e32 v62, 0, v62
	v_pk_mul_f32 v[60:61], v[60:61], v[60:61]
	v_cvt_pk_bf16_f32 v56, v56, v57
	v_cvt_pk_bf16_f32 v57, v58, v59
	v_pk_mul_f32 v[54:55], v[54:55], v[54:55]
	v_pk_mul_f32 v[50:51], v[50:51], v[50:51]
	v_pk_mul_f32 v[48:49], v[48:49], v[48:49]
	v_cvt_pk_bf16_f32 v58, v52, v53
	v_lshl_add_u64 v[64:65], v[64:65], 0, s[20:21]
	v_pk_mul_f32 v[62:63], v[62:63], v[62:63]
	v_cvt_pk_bf16_f32 v60, v60, v61
	v_cvt_pk_bf16_f32 v54, v54, v55
	v_cvt_pk_bf16_f32 v55, v48, v49
	v_cvt_pk_bf16_f32 v59, v50, v51
	v_mov_b32_dpp v48, v58 row_ror:8 row_mask:0xf bank_mask:0xf bound_ctrl:1
	v_lshl_add_u64 v[64:65], v[64:65], 0, v[128:129]
	v_cvt_pk_bf16_f32 v61, v62, v63
	v_mov_b32_dpp v62, v60 row_ror:8 row_mask:0xf bank_mask:0xf bound_ctrl:1
	v_mov_b32_dpp v49, v54 row_ror:8 row_mask:0xf bank_mask:0xf bound_ctrl:1
	v_mov_b32_dpp v50, v55 row_ror:8 row_mask:0xf bank_mask:0xf bound_ctrl:1
	v_mov_b32_dpp v51, v59 row_ror:8 row_mask:0xf bank_mask:0xf bound_ctrl:1
	v_cndmask_b32_e64 v48, v48, v60, s[6:7]
	v_lshl_add_u64 v[52:53], v[64:65], 0, v[134:135]
	v_mov_b32_dpp v63, v61 row_ror:8 row_mask:0xf bank_mask:0xf bound_ctrl:1
	v_mov_b32_dpp v64, v56 row_ror:8 row_mask:0xf bank_mask:0xf bound_ctrl:1
	v_mov_b32_dpp v65, v57 row_ror:8 row_mask:0xf bank_mask:0xf bound_ctrl:1
	v_cndmask_b32_e64 v51, v51, v57, s[6:7]
	v_cndmask_b32_e64 v50, v50, v56, s[6:7]
	v_cndmask_b32_e64 v49, v49, v61, s[6:7]
	global_store_dwordx4 v[52:53], v[48:51], off sc1
	s_nop 1
	v_cndmask_b32_e64 v48, v58, v62, s[6:7]
	v_lshl_add_u64 v[52:53], v[52:53], 0, s[26:27]
	v_cndmask_b32_e64 v51, v59, v65, s[6:7]
	v_cndmask_b32_e64 v50, v55, v64, s[6:7]
	v_cndmask_b32_e64 v49, v54, v63, s[6:7]
	global_store_dwordx4 v[52:53], v[48:51], off sc1
	s_nop 1
	v_add_u32_e32 v48, 0x90, v136
	v_ashrrev_i32_e32 v49, 31, v48
	v_lshlrev_b64 v[48:49], 13, v[48:49]
	v_max_f32_e32 v41, 0, v41
	v_max_f32_e32 v40, 0, v40
	v_max_f32_e32 v43, 0, v43
	v_max_f32_e32 v42, 0, v42
	v_max_f32_e32 v37, 0, v37
	v_max_f32_e32 v36, 0, v36
	v_lshl_add_u64 v[48:49], s[22:23], 0, v[48:49]
	v_max_f32_e32 v45, 0, v45
	v_max_f32_e32 v44, 0, v44
	v_pk_mul_f32 v[42:43], v[42:43], v[42:43]
	v_pk_mul_f32 v[40:41], v[40:41], v[40:41]
	v_max_f32_e32 v39, 0, v39
	v_max_f32_e32 v38, 0, v38
	v_max_f32_e32 v33, 0, v33
	v_max_f32_e32 v32, 0, v32
	v_max_f32_e32 v35, 0, v35
	v_max_f32_e32 v34, 0, v34
	v_pk_mul_f32 v[36:37], v[36:37], v[36:37]
	v_lshl_add_u64 v[48:49], v[48:49], 0, s[44:45]
	v_max_f32_e32 v47, 0, v47
	v_max_f32_e32 v46, 0, v46
	v_pk_mul_f32 v[44:45], v[44:45], v[44:45]
	v_cvt_pk_bf16_f32 v40, v40, v41
	v_cvt_pk_bf16_f32 v41, v42, v43
	v_pk_mul_f32 v[38:39], v[38:39], v[38:39]
	v_pk_mul_f32 v[34:35], v[34:35], v[34:35]
	v_pk_mul_f32 v[32:33], v[32:33], v[32:33]
	v_cvt_pk_bf16_f32 v42, v36, v37
	v_lshl_add_u64 v[48:49], v[48:49], 0, s[20:21]
	v_pk_mul_f32 v[46:47], v[46:47], v[46:47]
	v_cvt_pk_bf16_f32 v44, v44, v45
	v_cvt_pk_bf16_f32 v38, v38, v39
	v_cvt_pk_bf16_f32 v39, v32, v33
	v_cvt_pk_bf16_f32 v43, v34, v35
	v_mov_b32_dpp v32, v42 row_ror:8 row_mask:0xf bank_mask:0xf bound_ctrl:1
	v_lshl_add_u64 v[48:49], v[48:49], 0, v[128:129]
	v_cvt_pk_bf16_f32 v45, v46, v47
	v_mov_b32_dpp v46, v44 row_ror:8 row_mask:0xf bank_mask:0xf bound_ctrl:1
	v_mov_b32_dpp v33, v38 row_ror:8 row_mask:0xf bank_mask:0xf bound_ctrl:1
	v_mov_b32_dpp v34, v39 row_ror:8 row_mask:0xf bank_mask:0xf bound_ctrl:1
	v_mov_b32_dpp v35, v43 row_ror:8 row_mask:0xf bank_mask:0xf bound_ctrl:1
	v_cndmask_b32_e64 v32, v32, v44, s[6:7]
	v_lshl_add_u64 v[36:37], v[48:49], 0, v[134:135]
	v_mov_b32_dpp v47, v45 row_ror:8 row_mask:0xf bank_mask:0xf bound_ctrl:1
	v_mov_b32_dpp v48, v40 row_ror:8 row_mask:0xf bank_mask:0xf bound_ctrl:1
	v_mov_b32_dpp v49, v41 row_ror:8 row_mask:0xf bank_mask:0xf bound_ctrl:1
	v_cndmask_b32_e64 v35, v35, v41, s[6:7]
	v_cndmask_b32_e64 v34, v34, v40, s[6:7]
	v_cndmask_b32_e64 v33, v33, v45, s[6:7]
	global_store_dwordx4 v[36:37], v[32:35], off sc1
	s_nop 1
	v_cndmask_b32_e64 v32, v42, v46, s[6:7]
	v_lshl_add_u64 v[36:37], v[36:37], 0, s[26:27]
	v_cndmask_b32_e64 v35, v43, v49, s[6:7]
	v_cndmask_b32_e64 v34, v39, v48, s[6:7]
	v_cndmask_b32_e64 v33, v38, v47, s[6:7]
	global_store_dwordx4 v[36:37], v[32:35], off sc1
	s_nop 1
	v_add_u32_e32 v32, 0xa0, v136
	v_ashrrev_i32_e32 v33, 31, v32
	v_lshlrev_b64 v[32:33], 13, v[32:33]
	v_max_f32_e32 v25, 0, v25
	v_max_f32_e32 v24, 0, v24
	v_max_f32_e32 v27, 0, v27
	v_max_f32_e32 v26, 0, v26
	v_max_f32_e32 v21, 0, v21
	v_max_f32_e32 v20, 0, v20
	v_lshl_add_u64 v[32:33], s[22:23], 0, v[32:33]
	v_max_f32_e32 v29, 0, v29
	v_max_f32_e32 v28, 0, v28
	v_pk_mul_f32 v[26:27], v[26:27], v[26:27]
; __device__ __forceinline__ unsigned cvt_pk_bf16(float lo, float hi) { const f32x2 v = {lo, hi}; const bf16x2_t b = __builtin_convertvector(v, bf16x2_t); return __builtin_bit_cast(unsigned, b); }
; __device__ __forceinline__ void store16_wt(void* p, u32x4 v) { asm volatile("global_store_dwordx4 %0, %1, off sc1\n\ts_nop 1" :: "v"(p), "v"(v) : "memory"); }
; __device__ __forceinline__ u32x4 ror8_u4(u32x4 v) { const unsigned a = ror8_u(v.x), b = ror8_u(v.y), c = ror8_u(v.z), d = ror8_u(v.w); return (u32x4){a, b, c, d}; }
; #define PG8_BAR __builtin_amdgcn_s_barrier()
; template <class Prob, bool ALIGN_EPI, bool SP2>
; __device__ __forceinline__ void gemm_phase(LAS unsigned char* lds, const Prob& Pb, int wave, const char* wsb) {
;     ...
;         if (!has_next) break;
; #pragma unroll
;         for (int a = 0; a < 2; ++a)
; #pragma unroll
;             for (int b = 0; b < 2; ++b)
; #pragma unroll
;                 for (int m = 0; m < 4; ++m)
; #pragma unroll
;                     for (int n = 0; n < 2; ++n) acc[a][b][m][n] = (f32x4){0.f, 0.f, 0.f, 0.f};
;         cur = nxt; cA = nA; cB = nB; ++ui;
;         if constexpr (ALIGN_EPI) { if (wr == 1) PG8_BAR; }
;     __device__ __forceinline__ void epi(AccT& acc, const Unit& u, LAS unsigned char* lds, int wr, int wc, int fr, int fq) const {
;     ...
; #pragma unroll
;         for (int ai = 0; ai < 2; ++ai)
; #pragma unroll
;             for (int m = 0; m < 4; ++m) { const bool lo = fr < 8; bf16_t* rp = O + (size_t)(u.pm * 256 + ai * 128 + wr * 64 + m * 16 + (fr & 7)) * ldc + u.pn * 256 + wc * 64 + (lo ? 0 : 32) + 8 * fq; u32x4 w[2];
; #pragma unroll
;                 for (int bj = 0; bj < 2; ++bj) { f32x4 v0 = acc[ai][bj][m][0], v1 = acc[ai][bj][m][1];
;                     if (ACT == 1) { v0 = __builtin_elementwise_max(v0, (f32x4){0.f, 0.f, 0.f, 0.f}); v1 = __builtin_elementwise_max(v1, (f32x4){0.f, 0.f, 0.f, 0.f}); v0 = v0 * v0; v1 = v1 * v1; }
;                     w[bj].x = cvt_pk_bf16(v0[0], v0[1]); w[bj].y = cvt_pk_bf16(v0[2], v0[3]); w[bj].z = cvt_pk_bf16(v1[0], v1[1]); w[bj].w = cvt_pk_bf16(v1[2], v1[3]); }
;                 const u32x4 r0 = ror8_u4(w[0]), r1 = ror8_u4(w[1]); store16_wt(rp, lo ? w[0] : r1); store16_wt(rp + (size_t)8 * ldc, lo ? r0 : w[1]); }
	v_pk_mul_f32 v[24:25], v[24:25], v[24:25]
	v_max_f32_e32 v23, 0, v23
	v_max_f32_e32 v22, 0, v22
	v_max_f32_e32 v17, 0, v17
	v_max_f32_e32 v16, 0, v16
	v_max_f32_e32 v19, 0, v19
	v_max_f32_e32 v18, 0, v18
	v_pk_mul_f32 v[20:21], v[20:21], v[20:21]
	v_lshl_add_u64 v[32:33], v[32:33], 0, s[44:45]
	v_max_f32_e32 v31, 0, v31
	v_max_f32_e32 v30, 0, v30
	v_pk_mul_f32 v[28:29], v[28:29], v[28:29]
	v_cvt_pk_bf16_f32 v24, v24, v25
	v_cvt_pk_bf16_f32 v25, v26, v27
	v_pk_mul_f32 v[22:23], v[22:23], v[22:23]
	v_pk_mul_f32 v[18:19], v[18:19], v[18:19]
	v_pk_mul_f32 v[16:17], v[16:17], v[16:17]
	v_cvt_pk_bf16_f32 v26, v20, v21
	v_lshl_add_u64 v[32:33], v[32:33], 0, s[20:21]
	v_pk_mul_f32 v[30:31], v[30:31], v[30:31]
	v_cvt_pk_bf16_f32 v28, v28, v29
	v_cvt_pk_bf16_f32 v22, v22, v23
	v_cvt_pk_bf16_f32 v23, v16, v17
	v_cvt_pk_bf16_f32 v27, v18, v19
	v_mov_b32_dpp v16, v26 row_ror:8 row_mask:0xf bank_mask:0xf bound_ctrl:1
	v_lshl_add_u64 v[32:33], v[32:33], 0, v[128:129]
	v_cvt_pk_bf16_f32 v29, v30, v31
	v_mov_b32_dpp v30, v28 row_ror:8 row_mask:0xf bank_mask:0xf bound_ctrl:1
	v_mov_b32_dpp v17, v22 row_ror:8 row_mask:0xf bank_mask:0xf bound_ctrl:1
	v_mov_b32_dpp v18, v23 row_ror:8 row_mask:0xf bank_mask:0xf bound_ctrl:1
	v_mov_b32_dpp v19, v27 row_ror:8 row_mask:0xf bank_mask:0xf bound_ctrl:1
	v_cndmask_b32_e64 v16, v16, v28, s[6:7]
	v_lshl_add_u64 v[20:21], v[32:33], 0, v[134:135]
	v_mov_b32_dpp v31, v29 row_ror:8 row_mask:0xf bank_mask:0xf bound_ctrl:1
	v_mov_b32_dpp v32, v24 row_ror:8 row_mask:0xf bank_mask:0xf bound_ctrl:1
	v_mov_b32_dpp v33, v25 row_ror:8 row_mask:0xf bank_mask:0xf bound_ctrl:1
	v_cndmask_b32_e64 v19, v19, v25, s[6:7]
	v_cndmask_b32_e64 v18, v18, v24, s[6:7]
	v_cndmask_b32_e64 v17, v17, v29, s[6:7]
	global_store_dwordx4 v[20:21], v[16:19], off sc1
	s_nop 1
	v_cndmask_b32_e64 v16, v26, v30, s[6:7]
	v_lshl_add_u64 v[20:21], v[20:21], 0, s[26:27]
	v_cndmask_b32_e64 v19, v27, v33, s[6:7]
	v_cndmask_b32_e64 v18, v23, v32, s[6:7]
	v_cndmask_b32_e64 v17, v22, v31, s[6:7]
	global_store_dwordx4 v[20:21], v[16:19], off sc1
	s_nop 1
	v_add_u32_e32 v16, 0xb0, v136
	v_ashrrev_i32_e32 v17, 31, v16
	v_lshlrev_b64 v[16:17], 13, v[16:17]
	v_lshl_add_u64 v[16:17], s[22:23], 0, v[16:17]
	v_max_f32_e32 v9, 0, v9
	v_max_f32_e32 v8, 0, v8
	v_max_f32_e32 v11, 0, v11
	v_max_f32_e32 v10, 0, v10
	v_max_f32_e32 v5, 0, v5
	v_max_f32_e32 v4, 0, v4
	v_max_f32_e32 v7, 0, v7
	v_max_f32_e32 v6, 0, v6
	v_max_f32_e32 v1, 0, v1
	v_max_f32_e32 v0, 0, v0
	v_max_f32_e32 v3, 0, v3
	v_max_f32_e32 v2, 0, v2
	v_lshl_add_u64 v[16:17], v[16:17], 0, s[44:45]
	v_max_f32_e32 v13, 0, v13
	v_max_f32_e32 v12, 0, v12
	v_max_f32_e32 v15, 0, v15
	v_max_f32_e32 v14, 0, v14
	v_pk_mul_f32 v[10:11], v[10:11], v[10:11]
	v_pk_mul_f32 v[8:9], v[8:9], v[8:9]
	v_pk_mul_f32 v[6:7], v[6:7], v[6:7]
	v_pk_mul_f32 v[4:5], v[4:5], v[4:5]
	v_pk_mul_f32 v[2:3], v[2:3], v[2:3]
	v_pk_mul_f32 v[0:1], v[0:1], v[0:1]
	v_lshl_add_u64 v[16:17], v[16:17], 0, s[20:21]
	v_pk_mul_f32 v[14:15], v[14:15], v[14:15]
	v_pk_mul_f32 v[12:13], v[12:13], v[12:13]
	v_cvt_pk_bf16_f32 v8, v8, v9
	v_cvt_pk_bf16_f32 v9, v10, v11
	v_cvt_pk_bf16_f32 v10, v4, v5
	v_cvt_pk_bf16_f32 v6, v6, v7
	v_cvt_pk_bf16_f32 v7, v0, v1
	v_cvt_pk_bf16_f32 v11, v2, v3
	v_lshl_add_u64 v[16:17], v[16:17], 0, v[128:129]
	v_cvt_pk_bf16_f32 v12, v12, v13
	v_cvt_pk_bf16_f32 v13, v14, v15
	v_mov_b32_dpp v0, v10 row_ror:8 row_mask:0xf bank_mask:0xf bound_ctrl:1
	v_mov_b32_dpp v1, v6 row_ror:8 row_mask:0xf bank_mask:0xf bound_ctrl:1
	v_mov_b32_dpp v2, v7 row_ror:8 row_mask:0xf bank_mask:0xf bound_ctrl:1
	v_mov_b32_dpp v3, v11 row_ror:8 row_mask:0xf bank_mask:0xf bound_ctrl:1
	v_lshl_add_u64 v[4:5], v[16:17], 0, v[134:135]
	v_mov_b32_dpp v14, v12 row_ror:8 row_mask:0xf bank_mask:0xf bound_ctrl:1
	v_mov_b32_dpp v15, v13 row_ror:8 row_mask:0xf bank_mask:0xf bound_ctrl:1
	v_mov_b32_dpp v16, v8 row_ror:8 row_mask:0xf bank_mask:0xf bound_ctrl:1
	v_mov_b32_dpp v17, v9 row_ror:8 row_mask:0xf bank_mask:0xf bound_ctrl:1
	v_cndmask_b32_e64 v3, v3, v9, s[6:7]
	v_cndmask_b32_e64 v2, v2, v8, s[6:7]
	v_cndmask_b32_e64 v1, v1, v13, s[6:7]
	v_cndmask_b32_e64 v0, v0, v12, s[6:7]
	global_store_dwordx4 v[4:5], v[0:3], off sc1
	s_nop 1
	v_lshl_add_u64 v[4:5], v[4:5], 0, s[26:27]
	v_cndmask_b32_e64 v3, v11, v17, s[6:7]
	v_cndmask_b32_e64 v2, v7, v16, s[6:7]
	v_cndmask_b32_e64 v1, v6, v15, s[6:7]
	v_cndmask_b32_e64 v0, v10, v14, s[6:7]
	global_store_dwordx4 v[4:5], v[0:3], off sc1
	s_nop 1
	s_andn2_b64 vcc, exec, s[10:11]
	s_mov_b64 s[10:11], -1
	s_cbranch_vccnz .LBB0_1127
	s_andn2_b64 vcc, exec, s[18:19]
	s_cbranch_vccnz .LBB0_1126
	s_barrier
	s_branch .LBB0_1126

;     __device__ __forceinline__ void epi(AccT& acc, const Unit& u, LAS unsigned char* lds, int wr, int wc, int fr, int fq) const {
;     ...
;         if (wid == 0) {
;             bool dead = false; const unsigned long long t0 = __builtin_amdgcn_s_memrealtime();
;             for (;;) {
;                 if ((unsigned)__builtin_amdgcn_readfirstlane(__hip_atomic_load(cnt + 64 * u.pm, __ATOMIC_RELAXED, __HIP_MEMORY_SCOPE_AGENT)) >= 32u) break;
;                 if (__builtin_amdgcn_s_memrealtime() - t0 > 2000000ull) { if (lane == 0) __hip_atomic_store(tmo, 1u, __ATOMIC_RELAXED, __HIP_MEMORY_SCOPE_AGENT); dead = true; break; }
;                 __builtin_amdgcn_s_sleep(2);
;             }
;             __builtin_amdgcn_fence(__ATOMIC_ACQUIRE, "agent");
;             if (lane == 0) flag[0] = dead ? 1u : 0u;
;         }
;         asm volatile("s_waitcnt vmcnt(0) lgkmcnt(0)" ::: "memory"); __builtin_amdgcn_s_barrier(); asm volatile("" ::: "memory");
.LBB0_1258:
	s_waitcnt vmcnt(0)
	s_and_b64 exec, exec, s[4:5]
	v_cndmask_b32_e64 v2, 0, 1, s[14:15]
	v_mov_b32_e32 v3, s7
	ds_write_b32 v3, v2
